# test: H row stores (full-line, consumed by the next GEMM phase) non-temporal in P1/P6
# baseline (speedup 1.0000x reference)
; __device__ __forceinline__ unsigned cvt_pk_bf16(float lo, float hi) { unsigned r; asm volatile("v_cvt_pk_bf16_f32 %0, %1, %2" : "=v"(r) : "v"(lo), "v"(hi)); return r; }
; __device__ __forceinline__ void load_row_f32(const float* p, int lane, f32x4 (&v)[8]) {
; #pragma unroll
;     for (int j = 0; j < 8; ++j) v[j] = *(const f32x4*)(p + 4 * lane + 256 * j);
; }
; __device__ __forceinline__ float sumsq8(const f32x4 (&v)[8]) {
;     float s = 0.f;
; #pragma unroll
;     for (int j = 0; j < 8; ++j) s += (v[j][0] * v[j][0] + v[j][1] * v[j][1]) + (v[j][2] * v[j][2] + v[j][3] * v[j][3]);
;     return wave_sum(s);
; }
; __device__ __forceinline__ void modulate_store(const f32x4 (&v)[8], float rstd, const float* pn, const float* modr, bf16_t* orow, int lane) {
; #pragma unroll
;     for (int j = 0; j < 8; ++j) { const int col = 4 * lane + 256 * j;
;         const f32x4 g = *(const f32x4*)(pn + col), sh = *(const f32x4*)(modr + col), sc = *(const f32x4*)(modr + DM + col);
;         const f32x4 hh = v[j] * rstd * g * (sc + 1.f) + sh;
;         u32x2 w; w.x = cvt_pk_bf16(hh[0], hh[1]); w.y = cvt_pk_bf16(hh[2], hh[3]);
;         *(u32x2*)(orow + col) = w; }
; }
; __global__ void __launch_bounds__(NWAVES * 64, 2) mk_fwd(Args args) {
;     ...
;         for (int row0 = F.gw * 3; row0 < MT; row0 += F.NGW * 3) {
;             f32x4 v[3][8];
; #pragma unroll
;             for (int q = 0; q < 3; ++q) { const int row = row0 + q; const float* src = row < ML ? x + (size_t)row * DM : ctx + (size_t)(row - ML) * DM; load_row_f32(src, F.lane, v[q]); }
; #pragma unroll
;             for (int q = 0; q < 3; ++q) { const int row = row0 + q; const int r = row < ML ? row / SEQ : 8;
;                 const float rstd = __builtin_amdgcn_rsqf(sumsq8(v[q]) * (1.f / DM) + EPS);
;                 modulate_store(v[q], rstd, pre_norm, mod + (size_t)r * 6144, H + (size_t)row * DM, F.lane); }
.Lp1_np0:
	s_add_i32 s4, s6, 1
	s_cmp_lt_u32 s4, 0x4000
	s_cselect_b32 s10, s68, s72
	s_cselect_b32 s11, s69, s73
	s_cselect_b32 s5, 0, 0x4000
	s_sub_i32 s5, s4, s5
	s_lshl_b32 s5, s5, 13
	s_add_u32 s10, s10, s5
	s_addc_u32 s11, s11, 0
	global_load_dwordx4 v[32:35], v128, s[10:11] offset:0 nt
	global_load_dwordx4 v[36:39], v128, s[10:11] offset:1024 nt
	global_load_dwordx4 v[40:43], v128, s[10:11] offset:2048 nt
	global_load_dwordx4 v[44:47], v128, s[10:11] offset:3072 nt
	global_load_dwordx4 v[48:51], v129, s[10:11] offset:0 nt
	global_load_dwordx4 v[52:55], v129, s[10:11] offset:1024 nt
	global_load_dwordx4 v[56:59], v129, s[10:11] offset:2048 nt
	global_load_dwordx4 v[60:63], v129, s[10:11] offset:3072 nt
	s_waitcnt vmcnt(8)
	v_mul_f32_e32 v140, v0, v0
	v_mul_f32_e32 v141, v1, v1
	v_fmac_f32_e32 v140, v2, v2
	v_fmac_f32_e32 v141, v3, v3
	v_fmac_f32_e32 v140, v4, v4
	v_fmac_f32_e32 v141, v5, v5
	v_fmac_f32_e32 v140, v6, v6
	v_fmac_f32_e32 v141, v7, v7
	v_fmac_f32_e32 v140, v8, v8
	v_fmac_f32_e32 v141, v9, v9
	v_fmac_f32_e32 v140, v10, v10
	v_fmac_f32_e32 v141, v11, v11
	v_fmac_f32_e32 v140, v12, v12
	v_fmac_f32_e32 v141, v13, v13
	v_fmac_f32_e32 v140, v14, v14
	v_fmac_f32_e32 v141, v15, v15
	v_fmac_f32_e32 v140, v16, v16
	v_fmac_f32_e32 v141, v17, v17
	v_fmac_f32_e32 v140, v18, v18
	v_fmac_f32_e32 v141, v19, v19
	v_fmac_f32_e32 v140, v20, v20
	v_fmac_f32_e32 v141, v21, v21
	v_fmac_f32_e32 v140, v22, v22
	v_fmac_f32_e32 v141, v23, v23
	v_fmac_f32_e32 v140, v24, v24
	v_fmac_f32_e32 v141, v25, v25
	v_fmac_f32_e32 v140, v26, v26
	v_fmac_f32_e32 v141, v27, v27
	v_fmac_f32_e32 v140, v28, v28
	v_fmac_f32_e32 v141, v29, v29
	v_fmac_f32_e32 v140, v30, v30
	v_fmac_f32_e32 v141, v31, v31
	v_add_f32_e32 v140, v140, v141
	s_nop 1
	v_add_f32_dpp v142, v140, v140 quad_perm:[1,0,3,2] row_mask:0xf bank_mask:0xf
	s_nop 1
	v_add_f32_dpp v142, v142, v142 quad_perm:[2,3,0,1] row_mask:0xf bank_mask:0xf
	s_nop 1
	v_add_f32_dpp v142, v142, v142 row_half_mirror row_mask:0xf bank_mask:0xf
	s_nop 1
	v_add_f32_dpp v142, v142, v142 row_mirror row_mask:0xf bank_mask:0xf
	s_nop 1
	v_readlane_b32 s20, v142, 0
	v_readlane_b32 s21, v142, 16
	v_readlane_b32 s22, v142, 32
	v_readlane_b32 s23, v142, 48
	s_nop 1
	v_mov_b32_e32 v143, s20
	v_add_f32_e32 v143, s21, v143
	v_add_f32_e32 v143, s22, v143
	v_add_f32_e32 v143, s23, v143
	v_fmamk_f32 v143, v143, 0x3a000000, v131
	v_rsq_f32_e32 v143, v143
	s_nop 0
	s_add_i32 s4, s6, 0
	s_lshl_b32 s5, s4, 12
	s_add_u32 s14, s84, s5
	s_addc_u32 s15, s85, 0
	s_add_u32 s14, s14, 0x4000000
	s_addc_u32 s15, s15, 0
	v_mul_f32_e32 v136, v143, v0
	v_mul_f32_e32 v137, v143, v1
	v_mul_f32_e32 v138, v143, v2
	v_mul_f32_e32 v139, v143, v3
	v_fma_f32 v136, v136, v64, v96
	v_fma_f32 v137, v137, v65, v97
	v_fma_f32 v138, v138, v66, v98
	v_fma_f32 v139, v139, v67, v99
	v_cvt_pk_bf16_f32 v132, v136, v137
	v_cvt_pk_bf16_f32 v133, v138, v139
	global_store_dwordx2 v130, v[132:133], s[14:15] offset:0 nt
	v_mul_f32_e32 v136, v143, v4
	v_mul_f32_e32 v137, v143, v5
	v_mul_f32_e32 v138, v143, v6
	v_mul_f32_e32 v139, v143, v7
	v_fma_f32 v136, v136, v68, v100
	v_fma_f32 v137, v137, v69, v101
	v_fma_f32 v138, v138, v70, v102
	v_fma_f32 v139, v139, v71, v103
	v_cvt_pk_bf16_f32 v134, v136, v137
	v_cvt_pk_bf16_f32 v135, v138, v139
	global_store_dwordx2 v130, v[134:135], s[14:15] offset:512 nt
	v_mul_f32_e32 v136, v143, v8
	v_mul_f32_e32 v137, v143, v9
	v_mul_f32_e32 v138, v143, v10
	v_mul_f32_e32 v139, v143, v11
	v_fma_f32 v136, v136, v72, v104
	v_fma_f32 v137, v137, v73, v105
	v_fma_f32 v138, v138, v74, v106
	v_fma_f32 v139, v139, v75, v107
	v_cvt_pk_bf16_f32 v132, v136, v137
	v_cvt_pk_bf16_f32 v133, v138, v139
	global_store_dwordx2 v130, v[132:133], s[14:15] offset:1024 nt
	v_mul_f32_e32 v136, v143, v12
	v_mul_f32_e32 v137, v143, v13
	v_mul_f32_e32 v138, v143, v14
	v_mul_f32_e32 v139, v143, v15
	v_fma_f32 v136, v136, v76, v108
	v_fma_f32 v137, v137, v77, v109
	v_fma_f32 v138, v138, v78, v110
	v_fma_f32 v139, v139, v79, v111
	v_cvt_pk_bf16_f32 v134, v136, v137
	v_cvt_pk_bf16_f32 v135, v138, v139
	global_store_dwordx2 v130, v[134:135], s[14:15] offset:1536 nt
	v_mul_f32_e32 v136, v143, v16
	v_mul_f32_e32 v137, v143, v17
	v_mul_f32_e32 v138, v143, v18
	v_mul_f32_e32 v139, v143, v19
	v_fma_f32 v136, v136, v80, v112
	v_fma_f32 v137, v137, v81, v113
	v_fma_f32 v138, v138, v82, v114
	v_fma_f32 v139, v139, v83, v115
	v_cvt_pk_bf16_f32 v132, v136, v137
	v_cvt_pk_bf16_f32 v133, v138, v139
	global_store_dwordx2 v130, v[132:133], s[14:15] offset:2048 nt
	v_mul_f32_e32 v136, v143, v20
	v_mul_f32_e32 v137, v143, v21
	v_mul_f32_e32 v138, v143, v22
	v_mul_f32_e32 v139, v143, v23
	v_fma_f32 v136, v136, v84, v116
	v_fma_f32 v137, v137, v85, v117
	v_fma_f32 v138, v138, v86, v118
	v_fma_f32 v139, v139, v87, v119
	v_cvt_pk_bf16_f32 v134, v136, v137
	v_cvt_pk_bf16_f32 v135, v138, v139
	global_store_dwordx2 v130, v[134:135], s[14:15] offset:2560 nt
	v_mul_f32_e32 v136, v143, v24
	v_mul_f32_e32 v137, v143, v25
	v_mul_f32_e32 v138, v143, v26
	v_mul_f32_e32 v139, v143, v27
	v_fma_f32 v136, v136, v88, v120
	v_fma_f32 v137, v137, v89, v121
	v_fma_f32 v138, v138, v90, v122
	v_fma_f32 v139, v139, v91, v123
	v_cvt_pk_bf16_f32 v132, v136, v137
	v_cvt_pk_bf16_f32 v133, v138, v139
	global_store_dwordx2 v130, v[132:133], s[14:15] offset:3072 nt
	v_mul_f32_e32 v136, v143, v28
	v_mul_f32_e32 v137, v143, v29
	v_mul_f32_e32 v138, v143, v30
	v_mul_f32_e32 v139, v143, v31
	v_fma_f32 v136, v136, v92, v124
	v_fma_f32 v137, v137, v93, v125
	v_fma_f32 v138, v138, v94, v126
	v_fma_f32 v139, v139, v95, v127
	v_cvt_pk_bf16_f32 v134, v136, v137
	v_cvt_pk_bf16_f32 v135, v138, v139
	global_store_dwordx2 v130, v[134:135], s[14:15] offset:3584 nt
	s_add_i32 s4, s6, 2
	s_cmp_lt_u32 s4, 0x4000
	s_cselect_b32 s10, s68, s72
	s_cselect_b32 s11, s69, s73
	s_cselect_b32 s5, 0, 0x4000
	s_sub_i32 s5, s4, s5
	s_lshl_b32 s5, s5, 13
	s_add_u32 s10, s10, s5
	s_addc_u32 s11, s11, 0
	global_load_dwordx4 v[0:3], v128, s[10:11] offset:0 nt
	global_load_dwordx4 v[4:7], v128, s[10:11] offset:1024 nt
	global_load_dwordx4 v[8:11], v128, s[10:11] offset:2048 nt
	global_load_dwordx4 v[12:15], v128, s[10:11] offset:3072 nt
	global_load_dwordx4 v[16:19], v129, s[10:11] offset:0 nt
	global_load_dwordx4 v[20:23], v129, s[10:11] offset:1024 nt
	global_load_dwordx4 v[24:27], v129, s[10:11] offset:2048 nt
	global_load_dwordx4 v[28:31], v129, s[10:11] offset:3072 nt
	s_add_i32 s4, s6, 1
	s_add_i32 s4, s6, 1
	s_lshr_b32 s8, s4, 11
	s_cmp_lt_u32 s4, 0x4000
	s_cselect_b32 s8, s8, 8
	s_cmp_eq_u32 s8, s7
	s_cbranch_scc1 .Lp1_np1
; __device__ __forceinline__ unsigned cvt_pk_bf16(float lo, float hi) { unsigned r; asm volatile("v_cvt_pk_bf16_f32 %0, %1, %2" : "=v"(r) : "v"(lo), "v"(hi)); return r; }
; __device__ __forceinline__ float sumsq8(const f32x4 (&v)[8]) {
;     float s = 0.f;
; #pragma unroll
;     for (int j = 0; j < 8; ++j) s += (v[j][0] * v[j][0] + v[j][1] * v[j][1]) + (v[j][2] * v[j][2] + v[j][3] * v[j][3]);
;     return wave_sum(s);
; __device__ __forceinline__ void modulate_store(const f32x4 (&v)[8], float rstd, const float* pn, const float* modr, bf16_t* orow, int lane) {
; #pragma unroll
;     for (int j = 0; j < 8; ++j) { const int col = 4 * lane + 256 * j;
;         const f32x4 g = *(const f32x4*)(pn + col), sh = *(const f32x4*)(modr + col), sc = *(const f32x4*)(modr + DM + col);
;         const f32x4 hh = v[j] * rstd * g * (sc + 1.f) + sh;
;         u32x2 w; w.x = cvt_pk_bf16(hh[0], hh[1]); w.y = cvt_pk_bf16(hh[2], hh[3]);
;         *(u32x2*)(orow + col) = w; }
; }
	s_mov_b32 s7, s8
	s_add_i32 s5, s8, 0
	s_mul_i32 s5, s5, 0x6000
	s_add_u32 s24, s84, s5
	s_addc_u32 s25, s85, 0
	s_add_u32 s24, s24, 0x2000
	s_addc_u32 s25, s25, 0
	s_add_i32 s5, s8, 0
	s_mul_i32 s5, s5, 0x6000
	s_add_u32 s16, s84, s5
	s_addc_u32 s17, s85, 0
	s_add_u32 s18, s80, 0x0
	s_addc_u32 s19, s81, 0
	global_load_dwordx4 v[64:67], v128, s[18:19] offset:0
	global_load_dwordx4 v[96:99], v128, s[16:17] offset:0
	global_load_dwordx4 v[68:71], v128, s[18:19] offset:1024
	global_load_dwordx4 v[100:103], v128, s[16:17] offset:1024
	global_load_dwordx4 v[72:75], v128, s[18:19] offset:2048
	global_load_dwordx4 v[104:107], v128, s[16:17] offset:2048
	global_load_dwordx4 v[76:79], v128, s[18:19] offset:3072
	global_load_dwordx4 v[108:111], v128, s[16:17] offset:3072
	global_load_dwordx4 v[80:83], v129, s[18:19] offset:0
	global_load_dwordx4 v[112:115], v129, s[16:17] offset:0
	global_load_dwordx4 v[84:87], v129, s[18:19] offset:1024
	global_load_dwordx4 v[116:119], v129, s[16:17] offset:1024
	global_load_dwordx4 v[88:91], v129, s[18:19] offset:2048
	global_load_dwordx4 v[120:123], v129, s[16:17] offset:2048
	global_load_dwordx4 v[92:95], v129, s[18:19] offset:3072
	global_load_dwordx4 v[124:127], v129, s[16:17] offset:3072
	global_load_dwordx4 v[136:139], v128, s[24:25] offset:0
	s_waitcnt vmcnt(0)
	v_add_f32_e32 v136, 1.0, v136
	v_add_f32_e32 v137, 1.0, v137
	v_add_f32_e32 v138, 1.0, v138
	v_add_f32_e32 v139, 1.0, v139
	v_mul_f32_e32 v64, v64, v136
	v_mul_f32_e32 v65, v65, v137
	v_mul_f32_e32 v66, v66, v138
	v_mul_f32_e32 v67, v67, v139
	global_load_dwordx4 v[136:139], v128, s[24:25] offset:1024
	s_waitcnt vmcnt(0)
	v_add_f32_e32 v136, 1.0, v136
	v_add_f32_e32 v137, 1.0, v137
	v_add_f32_e32 v138, 1.0, v138
	v_add_f32_e32 v139, 1.0, v139
	v_mul_f32_e32 v68, v68, v136
	v_mul_f32_e32 v69, v69, v137
	v_mul_f32_e32 v70, v70, v138
	v_mul_f32_e32 v71, v71, v139
	global_load_dwordx4 v[136:139], v128, s[24:25] offset:2048
	s_waitcnt vmcnt(0)
	v_add_f32_e32 v136, 1.0, v136
	v_add_f32_e32 v137, 1.0, v137
	v_add_f32_e32 v138, 1.0, v138
	v_add_f32_e32 v139, 1.0, v139
	v_mul_f32_e32 v72, v72, v136
	v_mul_f32_e32 v73, v73, v137
	v_mul_f32_e32 v74, v74, v138
	v_mul_f32_e32 v75, v75, v139
	global_load_dwordx4 v[136:139], v128, s[24:25] offset:3072
	s_waitcnt vmcnt(0)
	v_add_f32_e32 v136, 1.0, v136
	v_add_f32_e32 v137, 1.0, v137
	v_add_f32_e32 v138, 1.0, v138
	v_add_f32_e32 v139, 1.0, v139
	v_mul_f32_e32 v76, v76, v136
	v_mul_f32_e32 v77, v77, v137
	v_mul_f32_e32 v78, v78, v138
	v_mul_f32_e32 v79, v79, v139
	global_load_dwordx4 v[136:139], v129, s[24:25] offset:0
	s_waitcnt vmcnt(0)
	v_add_f32_e32 v136, 1.0, v136
	v_add_f32_e32 v137, 1.0, v137
	v_add_f32_e32 v138, 1.0, v138
	v_add_f32_e32 v139, 1.0, v139
	v_mul_f32_e32 v80, v80, v136
	v_mul_f32_e32 v81, v81, v137
	v_mul_f32_e32 v82, v82, v138
	v_mul_f32_e32 v83, v83, v139
	global_load_dwordx4 v[136:139], v129, s[24:25] offset:1024
	s_waitcnt vmcnt(0)
	v_add_f32_e32 v136, 1.0, v136
	v_add_f32_e32 v137, 1.0, v137
	v_add_f32_e32 v138, 1.0, v138
	v_add_f32_e32 v139, 1.0, v139
	v_mul_f32_e32 v84, v84, v136
	v_mul_f32_e32 v85, v85, v137
	v_mul_f32_e32 v86, v86, v138
	v_mul_f32_e32 v87, v87, v139
	global_load_dwordx4 v[136:139], v129, s[24:25] offset:2048
	s_waitcnt vmcnt(0)
	v_add_f32_e32 v136, 1.0, v136
	v_add_f32_e32 v137, 1.0, v137
	v_add_f32_e32 v138, 1.0, v138
	v_add_f32_e32 v139, 1.0, v139
	v_mul_f32_e32 v88, v88, v136
	v_mul_f32_e32 v89, v89, v137
	v_mul_f32_e32 v90, v90, v138
	v_mul_f32_e32 v91, v91, v139
	global_load_dwordx4 v[136:139], v129, s[24:25] offset:3072
	s_waitcnt vmcnt(0)
	v_add_f32_e32 v136, 1.0, v136
	v_add_f32_e32 v137, 1.0, v137
	v_add_f32_e32 v138, 1.0, v138
	v_add_f32_e32 v139, 1.0, v139
	v_mul_f32_e32 v92, v92, v136
	v_mul_f32_e32 v93, v93, v137
	v_mul_f32_e32 v94, v94, v138
	v_mul_f32_e32 v95, v95, v139
.Lp1_np1:
	s_waitcnt vmcnt(16)
	v_mul_f32_e32 v140, v32, v32
	v_mul_f32_e32 v141, v33, v33
	v_fmac_f32_e32 v140, v34, v34
	v_fmac_f32_e32 v141, v35, v35
	v_fmac_f32_e32 v140, v36, v36
	v_fmac_f32_e32 v141, v37, v37
	v_fmac_f32_e32 v140, v38, v38
	v_fmac_f32_e32 v141, v39, v39
	v_fmac_f32_e32 v140, v40, v40
	v_fmac_f32_e32 v141, v41, v41
	v_fmac_f32_e32 v140, v42, v42
	v_fmac_f32_e32 v141, v43, v43
	v_fmac_f32_e32 v140, v44, v44
	v_fmac_f32_e32 v141, v45, v45
	v_fmac_f32_e32 v140, v46, v46
	v_fmac_f32_e32 v141, v47, v47
	v_fmac_f32_e32 v140, v48, v48
	v_fmac_f32_e32 v141, v49, v49
	v_fmac_f32_e32 v140, v50, v50
	v_fmac_f32_e32 v141, v51, v51
	v_fmac_f32_e32 v140, v52, v52
	v_fmac_f32_e32 v141, v53, v53
	v_fmac_f32_e32 v140, v54, v54
	v_fmac_f32_e32 v141, v55, v55
	v_fmac_f32_e32 v140, v56, v56
	v_fmac_f32_e32 v141, v57, v57
	v_fmac_f32_e32 v140, v58, v58
	v_fmac_f32_e32 v141, v59, v59
	v_fmac_f32_e32 v140, v60, v60
	v_fmac_f32_e32 v141, v61, v61
	v_fmac_f32_e32 v140, v62, v62
	v_fmac_f32_e32 v141, v63, v63
	v_add_f32_e32 v140, v140, v141
	s_nop 1
	v_add_f32_dpp v142, v140, v140 quad_perm:[1,0,3,2] row_mask:0xf bank_mask:0xf
	s_nop 1
	v_add_f32_dpp v142, v142, v142 quad_perm:[2,3,0,1] row_mask:0xf bank_mask:0xf
	s_nop 1
	v_add_f32_dpp v142, v142, v142 row_half_mirror row_mask:0xf bank_mask:0xf
	s_nop 1
	v_add_f32_dpp v142, v142, v142 row_mirror row_mask:0xf bank_mask:0xf
	s_nop 1
	v_readlane_b32 s20, v142, 0
	v_readlane_b32 s21, v142, 16
	v_readlane_b32 s22, v142, 32
	v_readlane_b32 s23, v142, 48
	s_nop 1
	v_mov_b32_e32 v143, s20
	v_add_f32_e32 v143, s21, v143
	v_add_f32_e32 v143, s22, v143
	v_add_f32_e32 v143, s23, v143
	v_fmamk_f32 v143, v143, 0x3a000000, v131
	v_rsq_f32_e32 v143, v143
	s_nop 0
	s_add_i32 s4, s6, 1
	s_lshl_b32 s5, s4, 12
	s_add_u32 s14, s84, s5
	s_addc_u32 s15, s85, 0
; __device__ __forceinline__ unsigned cvt_pk_bf16(float lo, float hi) { unsigned r; asm volatile("v_cvt_pk_bf16_f32 %0, %1, %2" : "=v"(r) : "v"(lo), "v"(hi)); return r; }
; __device__ __forceinline__ void modulate_store(const f32x4 (&v)[8], float rstd, const float* pn, const float* modr, bf16_t* orow, int lane) {
; #pragma unroll
;     for (int j = 0; j < 8; ++j) { const int col = 4 * lane + 256 * j;
;         const f32x4 g = *(const f32x4*)(pn + col), sh = *(const f32x4*)(modr + col), sc = *(const f32x4*)(modr + DM + col);
;         const f32x4 hh = v[j] * rstd * g * (sc + 1.f) + sh;
;         u32x2 w; w.x = cvt_pk_bf16(hh[0], hh[1]); w.y = cvt_pk_bf16(hh[2], hh[3]);
;         *(u32x2*)(orow + col) = w; }
; }
; __global__ void __launch_bounds__(NWAVES * 64, 2) mk_fwd(Args args) {
;     ...
;         for (int row0 = F.gw * 3; row0 < MT; row0 += F.NGW * 3) {
;             f32x4 v[3][8];
; #pragma unroll
;             for (int q = 0; q < 3; ++q) { const int row = row0 + q; const float* src = row < ML ? x + (size_t)row * DM : ctx + (size_t)(row - ML) * DM; load_row_f32(src, F.lane, v[q]); }
; #pragma unroll
;             for (int q = 0; q < 3; ++q) { const int row = row0 + q; const int r = row < ML ? row / SEQ : 8;
;                 const float rstd = __builtin_amdgcn_rsqf(sumsq8(v[q]) * (1.f / DM) + EPS);
;                 modulate_store(v[q], rstd, pre_norm, mod + (size_t)r * 6144, H + (size_t)row * DM, F.lane); }
	s_add_u32 s14, s14, 0x4000000
	s_addc_u32 s15, s15, 0
	v_mul_f32_e32 v136, v143, v32
	v_mul_f32_e32 v137, v143, v33
	v_mul_f32_e32 v138, v143, v34
	v_mul_f32_e32 v139, v143, v35
	v_fma_f32 v136, v136, v64, v96
	v_fma_f32 v137, v137, v65, v97
	v_fma_f32 v138, v138, v66, v98
	v_fma_f32 v139, v139, v67, v99
	v_cvt_pk_bf16_f32 v132, v136, v137
	v_cvt_pk_bf16_f32 v133, v138, v139
	global_store_dwordx2 v130, v[132:133], s[14:15] offset:0 nt
	v_mul_f32_e32 v136, v143, v36
	v_mul_f32_e32 v137, v143, v37
	v_mul_f32_e32 v138, v143, v38
	v_mul_f32_e32 v139, v143, v39
	v_fma_f32 v136, v136, v68, v100
	v_fma_f32 v137, v137, v69, v101
	v_fma_f32 v138, v138, v70, v102
	v_fma_f32 v139, v139, v71, v103
	v_cvt_pk_bf16_f32 v134, v136, v137
	v_cvt_pk_bf16_f32 v135, v138, v139
	global_store_dwordx2 v130, v[134:135], s[14:15] offset:512 nt
	v_mul_f32_e32 v136, v143, v40
	v_mul_f32_e32 v137, v143, v41
	v_mul_f32_e32 v138, v143, v42
	v_mul_f32_e32 v139, v143, v43
	v_fma_f32 v136, v136, v72, v104
	v_fma_f32 v137, v137, v73, v105
	v_fma_f32 v138, v138, v74, v106
	v_fma_f32 v139, v139, v75, v107
	v_cvt_pk_bf16_f32 v132, v136, v137
	v_cvt_pk_bf16_f32 v133, v138, v139
	global_store_dwordx2 v130, v[132:133], s[14:15] offset:1024 nt
	v_mul_f32_e32 v136, v143, v44
	v_mul_f32_e32 v137, v143, v45
	v_mul_f32_e32 v138, v143, v46
	v_mul_f32_e32 v139, v143, v47
	v_fma_f32 v136, v136, v76, v108
	v_fma_f32 v137, v137, v77, v109
	v_fma_f32 v138, v138, v78, v110
	v_fma_f32 v139, v139, v79, v111
	v_cvt_pk_bf16_f32 v134, v136, v137
	v_cvt_pk_bf16_f32 v135, v138, v139
	global_store_dwordx2 v130, v[134:135], s[14:15] offset:1536 nt
	v_mul_f32_e32 v136, v143, v48
	v_mul_f32_e32 v137, v143, v49
	v_mul_f32_e32 v138, v143, v50
	v_mul_f32_e32 v139, v143, v51
	v_fma_f32 v136, v136, v80, v112
	v_fma_f32 v137, v137, v81, v113
	v_fma_f32 v138, v138, v82, v114
	v_fma_f32 v139, v139, v83, v115
	v_cvt_pk_bf16_f32 v132, v136, v137
	v_cvt_pk_bf16_f32 v133, v138, v139
	global_store_dwordx2 v130, v[132:133], s[14:15] offset:2048 nt
	v_mul_f32_e32 v136, v143, v52
	v_mul_f32_e32 v137, v143, v53
	v_mul_f32_e32 v138, v143, v54
	v_mul_f32_e32 v139, v143, v55
	v_fma_f32 v136, v136, v84, v116
	v_fma_f32 v137, v137, v85, v117
	v_fma_f32 v138, v138, v86, v118
	v_fma_f32 v139, v139, v87, v119
	v_cvt_pk_bf16_f32 v134, v136, v137
	v_cvt_pk_bf16_f32 v135, v138, v139
	global_store_dwordx2 v130, v[134:135], s[14:15] offset:2560 nt
	v_mul_f32_e32 v136, v143, v56
	v_mul_f32_e32 v137, v143, v57
	v_mul_f32_e32 v138, v143, v58
	v_mul_f32_e32 v139, v143, v59
	v_fma_f32 v136, v136, v88, v120
	v_fma_f32 v137, v137, v89, v121
	v_fma_f32 v138, v138, v90, v122
	v_fma_f32 v139, v139, v91, v123
	v_cvt_pk_bf16_f32 v132, v136, v137
	v_cvt_pk_bf16_f32 v133, v138, v139
	global_store_dwordx2 v130, v[132:133], s[14:15] offset:3072 nt
	v_mul_f32_e32 v136, v143, v60
	v_mul_f32_e32 v137, v143, v61
	v_mul_f32_e32 v138, v143, v62
	v_mul_f32_e32 v139, v143, v63
	v_fma_f32 v136, v136, v92, v124
	v_fma_f32 v137, v137, v93, v125
	v_fma_f32 v138, v138, v94, v126
	v_fma_f32 v139, v139, v95, v127
	v_cvt_pk_bf16_f32 v134, v136, v137
	v_cvt_pk_bf16_f32 v135, v138, v139
	global_store_dwordx2 v130, v[134:135], s[14:15] offset:3584 nt
	s_add_i32 s4, s6, 3
	s_cmp_lt_u32 s4, 0x4000
	s_cselect_b32 s10, s68, s72
	s_cselect_b32 s11, s69, s73
	s_cselect_b32 s5, 0, 0x4000
	s_sub_i32 s5, s4, s5
	s_lshl_b32 s5, s5, 13
	s_add_u32 s10, s10, s5
	s_addc_u32 s11, s11, 0
	global_load_dwordx4 v[32:35], v128, s[10:11] offset:0 nt
	global_load_dwordx4 v[36:39], v128, s[10:11] offset:1024 nt
	global_load_dwordx4 v[40:43], v128, s[10:11] offset:2048 nt
	global_load_dwordx4 v[44:47], v128, s[10:11] offset:3072 nt
	global_load_dwordx4 v[48:51], v129, s[10:11] offset:0 nt
	global_load_dwordx4 v[52:55], v129, s[10:11] offset:1024 nt
	global_load_dwordx4 v[56:59], v129, s[10:11] offset:2048 nt
	global_load_dwordx4 v[60:63], v129, s[10:11] offset:3072 nt
	s_add_i32 s4, s6, 2
	s_add_i32 s4, s6, 2
	s_lshr_b32 s8, s4, 11
	s_cmp_lt_u32 s4, 0x4000
	s_cselect_b32 s8, s8, 8
	s_cmp_eq_u32 s8, s7
	s_cbranch_scc1 .Lp1_np2
	s_mov_b32 s7, s8
	s_add_i32 s5, s8, 0
	s_mul_i32 s5, s5, 0x6000
	s_add_u32 s24, s84, s5
	s_addc_u32 s25, s85, 0
	s_add_u32 s24, s24, 0x2000
	s_addc_u32 s25, s25, 0
	s_add_i32 s5, s8, 0
	s_mul_i32 s5, s5, 0x6000
	s_add_u32 s16, s84, s5
	s_addc_u32 s17, s85, 0
	s_add_u32 s18, s80, 0x0
	s_addc_u32 s19, s81, 0
	global_load_dwordx4 v[64:67], v128, s[18:19] offset:0
	global_load_dwordx4 v[96:99], v128, s[16:17] offset:0
	global_load_dwordx4 v[68:71], v128, s[18:19] offset:1024
	global_load_dwordx4 v[100:103], v128, s[16:17] offset:1024
	global_load_dwordx4 v[72:75], v128, s[18:19] offset:2048
	global_load_dwordx4 v[104:107], v128, s[16:17] offset:2048
	global_load_dwordx4 v[76:79], v128, s[18:19] offset:3072
	global_load_dwordx4 v[108:111], v128, s[16:17] offset:3072
	global_load_dwordx4 v[80:83], v129, s[18:19] offset:0
	global_load_dwordx4 v[112:115], v129, s[16:17] offset:0
	global_load_dwordx4 v[84:87], v129, s[18:19] offset:1024
	global_load_dwordx4 v[116:119], v129, s[16:17] offset:1024
	global_load_dwordx4 v[88:91], v129, s[18:19] offset:2048
	global_load_dwordx4 v[120:123], v129, s[16:17] offset:2048
	global_load_dwordx4 v[92:95], v129, s[18:19] offset:3072
	global_load_dwordx4 v[124:127], v129, s[16:17] offset:3072
	global_load_dwordx4 v[136:139], v128, s[24:25] offset:0
	s_waitcnt vmcnt(0)
	v_add_f32_e32 v136, 1.0, v136
	v_add_f32_e32 v137, 1.0, v137
	v_add_f32_e32 v138, 1.0, v138
	v_add_f32_e32 v139, 1.0, v139
	v_mul_f32_e32 v64, v64, v136
	v_mul_f32_e32 v65, v65, v137
	v_mul_f32_e32 v66, v66, v138
	v_mul_f32_e32 v67, v67, v139
	global_load_dwordx4 v[136:139], v128, s[24:25] offset:1024
	s_waitcnt vmcnt(0)
; __device__ __forceinline__ unsigned cvt_pk_bf16(float lo, float hi) { unsigned r; asm volatile("v_cvt_pk_bf16_f32 %0, %1, %2" : "=v"(r) : "v"(lo), "v"(hi)); return r; }
; __device__ __forceinline__ float sumsq8(const f32x4 (&v)[8]) {
;     float s = 0.f;
; #pragma unroll
;     for (int j = 0; j < 8; ++j) s += (v[j][0] * v[j][0] + v[j][1] * v[j][1]) + (v[j][2] * v[j][2] + v[j][3] * v[j][3]);
;     return wave_sum(s);
; __device__ __forceinline__ void modulate_store(const f32x4 (&v)[8], float rstd, const float* pn, const float* modr, bf16_t* orow, int lane) {
; #pragma unroll
;     for (int j = 0; j < 8; ++j) { const int col = 4 * lane + 256 * j;
;         const f32x4 g = *(const f32x4*)(pn + col), sh = *(const f32x4*)(modr + col), sc = *(const f32x4*)(modr + DM + col);
;         const f32x4 hh = v[j] * rstd * g * (sc + 1.f) + sh;
;         u32x2 w; w.x = cvt_pk_bf16(hh[0], hh[1]); w.y = cvt_pk_bf16(hh[2], hh[3]);
;         *(u32x2*)(orow + col) = w; }
; }
	v_add_f32_e32 v136, 1.0, v136
	v_add_f32_e32 v137, 1.0, v137
	v_add_f32_e32 v138, 1.0, v138
	v_add_f32_e32 v139, 1.0, v139
	v_mul_f32_e32 v68, v68, v136
	v_mul_f32_e32 v69, v69, v137
	v_mul_f32_e32 v70, v70, v138
	v_mul_f32_e32 v71, v71, v139
	global_load_dwordx4 v[136:139], v128, s[24:25] offset:2048
	s_waitcnt vmcnt(0)
	v_add_f32_e32 v136, 1.0, v136
	v_add_f32_e32 v137, 1.0, v137
	v_add_f32_e32 v138, 1.0, v138
	v_add_f32_e32 v139, 1.0, v139
	v_mul_f32_e32 v72, v72, v136
	v_mul_f32_e32 v73, v73, v137
	v_mul_f32_e32 v74, v74, v138
	v_mul_f32_e32 v75, v75, v139
	global_load_dwordx4 v[136:139], v128, s[24:25] offset:3072
	s_waitcnt vmcnt(0)
	v_add_f32_e32 v136, 1.0, v136
	v_add_f32_e32 v137, 1.0, v137
	v_add_f32_e32 v138, 1.0, v138
	v_add_f32_e32 v139, 1.0, v139
	v_mul_f32_e32 v76, v76, v136
	v_mul_f32_e32 v77, v77, v137
	v_mul_f32_e32 v78, v78, v138
	v_mul_f32_e32 v79, v79, v139
	global_load_dwordx4 v[136:139], v129, s[24:25] offset:0
	s_waitcnt vmcnt(0)
	v_add_f32_e32 v136, 1.0, v136
	v_add_f32_e32 v137, 1.0, v137
	v_add_f32_e32 v138, 1.0, v138
	v_add_f32_e32 v139, 1.0, v139
	v_mul_f32_e32 v80, v80, v136
	v_mul_f32_e32 v81, v81, v137
	v_mul_f32_e32 v82, v82, v138
	v_mul_f32_e32 v83, v83, v139
	global_load_dwordx4 v[136:139], v129, s[24:25] offset:1024
	s_waitcnt vmcnt(0)
	v_add_f32_e32 v136, 1.0, v136
	v_add_f32_e32 v137, 1.0, v137
	v_add_f32_e32 v138, 1.0, v138
	v_add_f32_e32 v139, 1.0, v139
	v_mul_f32_e32 v84, v84, v136
	v_mul_f32_e32 v85, v85, v137
	v_mul_f32_e32 v86, v86, v138
	v_mul_f32_e32 v87, v87, v139
	global_load_dwordx4 v[136:139], v129, s[24:25] offset:2048
	s_waitcnt vmcnt(0)
	v_add_f32_e32 v136, 1.0, v136
	v_add_f32_e32 v137, 1.0, v137
	v_add_f32_e32 v138, 1.0, v138
	v_add_f32_e32 v139, 1.0, v139
	v_mul_f32_e32 v88, v88, v136
	v_mul_f32_e32 v89, v89, v137
	v_mul_f32_e32 v90, v90, v138
	v_mul_f32_e32 v91, v91, v139
	global_load_dwordx4 v[136:139], v129, s[24:25] offset:3072
	s_waitcnt vmcnt(0)
	v_add_f32_e32 v136, 1.0, v136
	v_add_f32_e32 v137, 1.0, v137
	v_add_f32_e32 v138, 1.0, v138
	v_add_f32_e32 v139, 1.0, v139
	v_mul_f32_e32 v92, v92, v136
	v_mul_f32_e32 v93, v93, v137
	v_mul_f32_e32 v94, v94, v138
	v_mul_f32_e32 v95, v95, v139
.Lp1_np2:
	s_waitcnt vmcnt(16)
	v_mul_f32_e32 v140, v0, v0
	v_mul_f32_e32 v141, v1, v1
	v_fmac_f32_e32 v140, v2, v2
	v_fmac_f32_e32 v141, v3, v3
	v_fmac_f32_e32 v140, v4, v4
	v_fmac_f32_e32 v141, v5, v5
	v_fmac_f32_e32 v140, v6, v6
	v_fmac_f32_e32 v141, v7, v7
	v_fmac_f32_e32 v140, v8, v8
	v_fmac_f32_e32 v141, v9, v9
	v_fmac_f32_e32 v140, v10, v10
	v_fmac_f32_e32 v141, v11, v11
	v_fmac_f32_e32 v140, v12, v12
	v_fmac_f32_e32 v141, v13, v13
	v_fmac_f32_e32 v140, v14, v14
	v_fmac_f32_e32 v141, v15, v15
	v_fmac_f32_e32 v140, v16, v16
	v_fmac_f32_e32 v141, v17, v17
	v_fmac_f32_e32 v140, v18, v18
	v_fmac_f32_e32 v141, v19, v19
	v_fmac_f32_e32 v140, v20, v20
	v_fmac_f32_e32 v141, v21, v21
	v_fmac_f32_e32 v140, v22, v22
	v_fmac_f32_e32 v141, v23, v23
	v_fmac_f32_e32 v140, v24, v24
	v_fmac_f32_e32 v141, v25, v25
	v_fmac_f32_e32 v140, v26, v26
	v_fmac_f32_e32 v141, v27, v27
	v_fmac_f32_e32 v140, v28, v28
	v_fmac_f32_e32 v141, v29, v29
	v_fmac_f32_e32 v140, v30, v30
	v_fmac_f32_e32 v141, v31, v31
	v_add_f32_e32 v140, v140, v141
	s_nop 1
	v_add_f32_dpp v142, v140, v140 quad_perm:[1,0,3,2] row_mask:0xf bank_mask:0xf
	s_nop 1
	v_add_f32_dpp v142, v142, v142 quad_perm:[2,3,0,1] row_mask:0xf bank_mask:0xf
	s_nop 1
	v_add_f32_dpp v142, v142, v142 row_half_mirror row_mask:0xf bank_mask:0xf
	s_nop 1
	v_add_f32_dpp v142, v142, v142 row_mirror row_mask:0xf bank_mask:0xf
	s_nop 1
	v_readlane_b32 s20, v142, 0
	v_readlane_b32 s21, v142, 16
	v_readlane_b32 s22, v142, 32
	v_readlane_b32 s23, v142, 48
	s_nop 1
	v_mov_b32_e32 v143, s20
	v_add_f32_e32 v143, s21, v143
	v_add_f32_e32 v143, s22, v143
	v_add_f32_e32 v143, s23, v143
	v_fmamk_f32 v143, v143, 0x3a000000, v131
	v_rsq_f32_e32 v143, v143
	s_nop 0
	s_add_i32 s4, s6, 2
	s_lshl_b32 s5, s4, 12
	s_add_u32 s14, s84, s5
	s_addc_u32 s15, s85, 0
	s_add_u32 s14, s14, 0x4000000
	s_addc_u32 s15, s15, 0
	v_mul_f32_e32 v136, v143, v0
	v_mul_f32_e32 v137, v143, v1
	v_mul_f32_e32 v138, v143, v2
	v_mul_f32_e32 v139, v143, v3
	v_fma_f32 v136, v136, v64, v96
	v_fma_f32 v137, v137, v65, v97
	v_fma_f32 v138, v138, v66, v98
	v_fma_f32 v139, v139, v67, v99
	v_cvt_pk_bf16_f32 v132, v136, v137
	v_cvt_pk_bf16_f32 v133, v138, v139
	global_store_dwordx2 v130, v[132:133], s[14:15] offset:0 nt
	v_mul_f32_e32 v136, v143, v4
	v_mul_f32_e32 v137, v143, v5
	v_mul_f32_e32 v138, v143, v6
	v_mul_f32_e32 v139, v143, v7
	v_fma_f32 v136, v136, v68, v100
	v_fma_f32 v137, v137, v69, v101
	v_fma_f32 v138, v138, v70, v102
	v_fma_f32 v139, v139, v71, v103
	v_cvt_pk_bf16_f32 v134, v136, v137
	v_cvt_pk_bf16_f32 v135, v138, v139
	global_store_dwordx2 v130, v[134:135], s[14:15] offset:512 nt
	v_mul_f32_e32 v136, v143, v8
	v_mul_f32_e32 v137, v143, v9
	v_mul_f32_e32 v138, v143, v10
	v_mul_f32_e32 v139, v143, v11
	v_fma_f32 v136, v136, v72, v104
	v_fma_f32 v137, v137, v73, v105
	v_fma_f32 v138, v138, v74, v106
	v_fma_f32 v139, v139, v75, v107
	v_cvt_pk_bf16_f32 v132, v136, v137
	v_cvt_pk_bf16_f32 v133, v138, v139
	global_store_dwordx2 v130, v[132:133], s[14:15] offset:1024 nt
	v_mul_f32_e32 v136, v143, v12
	v_mul_f32_e32 v137, v143, v13
	v_mul_f32_e32 v138, v143, v14
	v_mul_f32_e32 v139, v143, v15
	v_fma_f32 v136, v136, v76, v108
	v_fma_f32 v137, v137, v77, v109
	v_fma_f32 v138, v138, v78, v110
	v_fma_f32 v139, v139, v79, v111
	v_cvt_pk_bf16_f32 v134, v136, v137
	v_cvt_pk_bf16_f32 v135, v138, v139
	global_store_dwordx2 v130, v[134:135], s[14:15] offset:1536 nt
	v_mul_f32_e32 v136, v143, v16
	v_mul_f32_e32 v137, v143, v17
; __device__ __forceinline__ unsigned cvt_pk_bf16(float lo, float hi) { unsigned r; asm volatile("v_cvt_pk_bf16_f32 %0, %1, %2" : "=v"(r) : "v"(lo), "v"(hi)); return r; }
; __device__ __forceinline__ void modulate_store(const f32x4 (&v)[8], float rstd, const float* pn, const float* modr, bf16_t* orow, int lane) {
; #pragma unroll
;     for (int j = 0; j < 8; ++j) { const int col = 4 * lane + 256 * j;
;         const f32x4 g = *(const f32x4*)(pn + col), sh = *(const f32x4*)(modr + col), sc = *(const f32x4*)(modr + DM + col);
;         const f32x4 hh = v[j] * rstd * g * (sc + 1.f) + sh;
;         u32x2 w; w.x = cvt_pk_bf16(hh[0], hh[1]); w.y = cvt_pk_bf16(hh[2], hh[3]);
;         *(u32x2*)(orow + col) = w; }
; }
; __global__ void __launch_bounds__(NWAVES * 64, 2) mk_fwd(Args args) {
;     ...
;         for (int row0 = F.gw * 3; row0 < MT; row0 += F.NGW * 3) {
;             f32x4 v[3][8];
; #pragma unroll
;             for (int q = 0; q < 3; ++q) { const int row = row0 + q; const float* src = row < ML ? x + (size_t)row * DM : ctx + (size_t)(row - ML) * DM; load_row_f32(src, F.lane, v[q]); }
; #pragma unroll
;             for (int q = 0; q < 3; ++q) { const int row = row0 + q; const int r = row < ML ? row / SEQ : 8;
;                 const float rstd = __builtin_amdgcn_rsqf(sumsq8(v[q]) * (1.f / DM) + EPS);
;                 modulate_store(v[q], rstd, pre_norm, mod + (size_t)r * 6144, H + (size_t)row * DM, F.lane); }
	v_mul_f32_e32 v138, v143, v18
	v_mul_f32_e32 v139, v143, v19
	v_fma_f32 v136, v136, v80, v112
	v_fma_f32 v137, v137, v81, v113
	v_fma_f32 v138, v138, v82, v114
	v_fma_f32 v139, v139, v83, v115
	v_cvt_pk_bf16_f32 v132, v136, v137
	v_cvt_pk_bf16_f32 v133, v138, v139
	global_store_dwordx2 v130, v[132:133], s[14:15] offset:2048 nt
	v_mul_f32_e32 v136, v143, v20
	v_mul_f32_e32 v137, v143, v21
	v_mul_f32_e32 v138, v143, v22
	v_mul_f32_e32 v139, v143, v23
	v_fma_f32 v136, v136, v84, v116
	v_fma_f32 v137, v137, v85, v117
	v_fma_f32 v138, v138, v86, v118
	v_fma_f32 v139, v139, v87, v119
	v_cvt_pk_bf16_f32 v134, v136, v137
	v_cvt_pk_bf16_f32 v135, v138, v139
	global_store_dwordx2 v130, v[134:135], s[14:15] offset:2560 nt
	v_mul_f32_e32 v136, v143, v24
	v_mul_f32_e32 v137, v143, v25
	v_mul_f32_e32 v138, v143, v26
	v_mul_f32_e32 v139, v143, v27
	v_fma_f32 v136, v136, v88, v120
	v_fma_f32 v137, v137, v89, v121
	v_fma_f32 v138, v138, v90, v122
	v_fma_f32 v139, v139, v91, v123
	v_cvt_pk_bf16_f32 v132, v136, v137
	v_cvt_pk_bf16_f32 v133, v138, v139
	global_store_dwordx2 v130, v[132:133], s[14:15] offset:3072 nt
	v_mul_f32_e32 v136, v143, v28
	v_mul_f32_e32 v137, v143, v29
	v_mul_f32_e32 v138, v143, v30
	v_mul_f32_e32 v139, v143, v31
	v_fma_f32 v136, v136, v92, v124
	v_fma_f32 v137, v137, v93, v125
	v_fma_f32 v138, v138, v94, v126
	v_fma_f32 v139, v139, v95, v127
	v_cvt_pk_bf16_f32 v134, v136, v137
	v_cvt_pk_bf16_f32 v135, v138, v139
	global_store_dwordx2 v130, v[134:135], s[14:15] offset:3584 nt
	s_add_i32 s4, s6, 4
	s_cmp_lt_u32 s4, 0x4000
	s_cselect_b32 s10, s68, s72
	s_cselect_b32 s11, s69, s73
	s_cselect_b32 s5, 0, 0x4000
	s_sub_i32 s5, s4, s5
	s_lshl_b32 s5, s5, 13
	s_add_u32 s10, s10, s5
	s_addc_u32 s11, s11, 0
	global_load_dwordx4 v[0:3], v128, s[10:11] offset:0 nt
	global_load_dwordx4 v[4:7], v128, s[10:11] offset:1024 nt
	global_load_dwordx4 v[8:11], v128, s[10:11] offset:2048 nt
	global_load_dwordx4 v[12:15], v128, s[10:11] offset:3072 nt
	global_load_dwordx4 v[16:19], v129, s[10:11] offset:0 nt
	global_load_dwordx4 v[20:23], v129, s[10:11] offset:1024 nt
	global_load_dwordx4 v[24:27], v129, s[10:11] offset:2048 nt
	global_load_dwordx4 v[28:31], v129, s[10:11] offset:3072 nt
	s_add_i32 s4, s6, 3
	s_add_i32 s4, s6, 3
	s_lshr_b32 s8, s4, 11
	s_cmp_lt_u32 s4, 0x4000
	s_cselect_b32 s8, s8, 8
	s_cmp_eq_u32 s8, s7
	s_cbranch_scc1 .Lp1_np3
	s_mov_b32 s7, s8
	s_add_i32 s5, s8, 0
	s_mul_i32 s5, s5, 0x6000
	s_add_u32 s24, s84, s5
	s_addc_u32 s25, s85, 0
	s_add_u32 s24, s24, 0x2000
	s_addc_u32 s25, s25, 0
	s_add_i32 s5, s8, 0
	s_mul_i32 s5, s5, 0x6000
	s_add_u32 s16, s84, s5
	s_addc_u32 s17, s85, 0
	s_add_u32 s18, s80, 0x0
	s_addc_u32 s19, s81, 0
	global_load_dwordx4 v[64:67], v128, s[18:19] offset:0
	global_load_dwordx4 v[96:99], v128, s[16:17] offset:0
	global_load_dwordx4 v[68:71], v128, s[18:19] offset:1024
	global_load_dwordx4 v[100:103], v128, s[16:17] offset:1024
	global_load_dwordx4 v[72:75], v128, s[18:19] offset:2048
	global_load_dwordx4 v[104:107], v128, s[16:17] offset:2048
	global_load_dwordx4 v[76:79], v128, s[18:19] offset:3072
	global_load_dwordx4 v[108:111], v128, s[16:17] offset:3072
	global_load_dwordx4 v[80:83], v129, s[18:19] offset:0
	global_load_dwordx4 v[112:115], v129, s[16:17] offset:0
	global_load_dwordx4 v[84:87], v129, s[18:19] offset:1024
	global_load_dwordx4 v[116:119], v129, s[16:17] offset:1024
	global_load_dwordx4 v[88:91], v129, s[18:19] offset:2048
	global_load_dwordx4 v[120:123], v129, s[16:17] offset:2048
	global_load_dwordx4 v[92:95], v129, s[18:19] offset:3072
	global_load_dwordx4 v[124:127], v129, s[16:17] offset:3072
	global_load_dwordx4 v[136:139], v128, s[24:25] offset:0
	s_waitcnt vmcnt(0)
	v_add_f32_e32 v136, 1.0, v136
	v_add_f32_e32 v137, 1.0, v137
	v_add_f32_e32 v138, 1.0, v138
	v_add_f32_e32 v139, 1.0, v139
	v_mul_f32_e32 v64, v64, v136
	v_mul_f32_e32 v65, v65, v137
	v_mul_f32_e32 v66, v66, v138
	v_mul_f32_e32 v67, v67, v139
	global_load_dwordx4 v[136:139], v128, s[24:25] offset:1024
	s_waitcnt vmcnt(0)
	v_add_f32_e32 v136, 1.0, v136
	v_add_f32_e32 v137, 1.0, v137
	v_add_f32_e32 v138, 1.0, v138
	v_add_f32_e32 v139, 1.0, v139
	v_mul_f32_e32 v68, v68, v136
	v_mul_f32_e32 v69, v69, v137
	v_mul_f32_e32 v70, v70, v138
	v_mul_f32_e32 v71, v71, v139
	global_load_dwordx4 v[136:139], v128, s[24:25] offset:2048
	s_waitcnt vmcnt(0)
	v_add_f32_e32 v136, 1.0, v136
	v_add_f32_e32 v137, 1.0, v137
	v_add_f32_e32 v138, 1.0, v138
	v_add_f32_e32 v139, 1.0, v139
	v_mul_f32_e32 v72, v72, v136
	v_mul_f32_e32 v73, v73, v137
	v_mul_f32_e32 v74, v74, v138
	v_mul_f32_e32 v75, v75, v139
	global_load_dwordx4 v[136:139], v128, s[24:25] offset:3072
	s_waitcnt vmcnt(0)
	v_add_f32_e32 v136, 1.0, v136
	v_add_f32_e32 v137, 1.0, v137
	v_add_f32_e32 v138, 1.0, v138
	v_add_f32_e32 v139, 1.0, v139
	v_mul_f32_e32 v76, v76, v136
	v_mul_f32_e32 v77, v77, v137
	v_mul_f32_e32 v78, v78, v138
	v_mul_f32_e32 v79, v79, v139
	global_load_dwordx4 v[136:139], v129, s[24:25] offset:0
	s_waitcnt vmcnt(0)
	v_add_f32_e32 v136, 1.0, v136
	v_add_f32_e32 v137, 1.0, v137
	v_add_f32_e32 v138, 1.0, v138
	v_add_f32_e32 v139, 1.0, v139
	v_mul_f32_e32 v80, v80, v136
	v_mul_f32_e32 v81, v81, v137
	v_mul_f32_e32 v82, v82, v138
	v_mul_f32_e32 v83, v83, v139
	global_load_dwordx4 v[136:139], v129, s[24:25] offset:1024
	s_waitcnt vmcnt(0)
	v_add_f32_e32 v136, 1.0, v136
	v_add_f32_e32 v137, 1.0, v137
	v_add_f32_e32 v138, 1.0, v138
	v_add_f32_e32 v139, 1.0, v139
	v_mul_f32_e32 v84, v84, v136
	v_mul_f32_e32 v85, v85, v137
	v_mul_f32_e32 v86, v86, v138
	v_mul_f32_e32 v87, v87, v139
	global_load_dwordx4 v[136:139], v129, s[24:25] offset:2048
	s_waitcnt vmcnt(0)
	v_add_f32_e32 v136, 1.0, v136
	v_add_f32_e32 v137, 1.0, v137
	v_add_f32_e32 v138, 1.0, v138
	v_add_f32_e32 v139, 1.0, v139
	v_mul_f32_e32 v88, v88, v136
	v_mul_f32_e32 v89, v89, v137
	v_mul_f32_e32 v90, v90, v138
	v_mul_f32_e32 v91, v91, v139
	global_load_dwordx4 v[136:139], v129, s[24:25] offset:3072
	s_waitcnt vmcnt(0)
	v_add_f32_e32 v136, 1.0, v136
	v_add_f32_e32 v137, 1.0, v137
	v_add_f32_e32 v138, 1.0, v138
	v_add_f32_e32 v139, 1.0, v139
	v_mul_f32_e32 v92, v92, v136
	v_mul_f32_e32 v93, v93, v137
	v_mul_f32_e32 v94, v94, v138
	v_mul_f32_e32 v95, v95, v139
; __device__ __forceinline__ unsigned cvt_pk_bf16(float lo, float hi) { unsigned r; asm volatile("v_cvt_pk_bf16_f32 %0, %1, %2" : "=v"(r) : "v"(lo), "v"(hi)); return r; }
; __device__ __forceinline__ float sumsq8(const f32x4 (&v)[8]) {
;     float s = 0.f;
; #pragma unroll
;     for (int j = 0; j < 8; ++j) s += (v[j][0] * v[j][0] + v[j][1] * v[j][1]) + (v[j][2] * v[j][2] + v[j][3] * v[j][3]);
;     return wave_sum(s);
; }
; __device__ __forceinline__ void modulate_store(const f32x4 (&v)[8], float rstd, const float* pn, const float* modr, bf16_t* orow, int lane) {
; #pragma unroll
;     for (int j = 0; j < 8; ++j) { const int col = 4 * lane + 256 * j;
;         const f32x4 g = *(const f32x4*)(pn + col), sh = *(const f32x4*)(modr + col), sc = *(const f32x4*)(modr + DM + col);
;         const f32x4 hh = v[j] * rstd * g * (sc + 1.f) + sh;
;         u32x2 w; w.x = cvt_pk_bf16(hh[0], hh[1]); w.y = cvt_pk_bf16(hh[2], hh[3]);
;         *(u32x2*)(orow + col) = w; }
; }
; __global__ void __launch_bounds__(NWAVES * 64, 2) mk_fwd(Args args) {
;     ...
;         for (int row0 = F.gw * 3; row0 < MT; row0 += F.NGW * 3) {
;             f32x4 v[3][8];
; #pragma unroll
;             for (int q = 0; q < 3; ++q) { const int row = row0 + q; const float* src = row < ML ? x + (size_t)row * DM : ctx + (size_t)(row - ML) * DM; load_row_f32(src, F.lane, v[q]); }
; #pragma unroll
;             for (int q = 0; q < 3; ++q) { const int row = row0 + q; const int r = row < ML ? row / SEQ : 8;
;                 const float rstd = __builtin_amdgcn_rsqf(sumsq8(v[q]) * (1.f / DM) + EPS);
;                 modulate_store(v[q], rstd, pre_norm, mod + (size_t)r * 6144, H + (size_t)row * DM, F.lane); }
.Lp1_np3:
	s_waitcnt vmcnt(16)
	v_mul_f32_e32 v140, v32, v32
	v_mul_f32_e32 v141, v33, v33
	v_fmac_f32_e32 v140, v34, v34
	v_fmac_f32_e32 v141, v35, v35
	v_fmac_f32_e32 v140, v36, v36
	v_fmac_f32_e32 v141, v37, v37
	v_fmac_f32_e32 v140, v38, v38
	v_fmac_f32_e32 v141, v39, v39
	v_fmac_f32_e32 v140, v40, v40
	v_fmac_f32_e32 v141, v41, v41
	v_fmac_f32_e32 v140, v42, v42
	v_fmac_f32_e32 v141, v43, v43
	v_fmac_f32_e32 v140, v44, v44
	v_fmac_f32_e32 v141, v45, v45
	v_fmac_f32_e32 v140, v46, v46
	v_fmac_f32_e32 v141, v47, v47
	v_fmac_f32_e32 v140, v48, v48
	v_fmac_f32_e32 v141, v49, v49
	v_fmac_f32_e32 v140, v50, v50
	v_fmac_f32_e32 v141, v51, v51
	v_fmac_f32_e32 v140, v52, v52
	v_fmac_f32_e32 v141, v53, v53
	v_fmac_f32_e32 v140, v54, v54
	v_fmac_f32_e32 v141, v55, v55
	v_fmac_f32_e32 v140, v56, v56
	v_fmac_f32_e32 v141, v57, v57
	v_fmac_f32_e32 v140, v58, v58
	v_fmac_f32_e32 v141, v59, v59
	v_fmac_f32_e32 v140, v60, v60
	v_fmac_f32_e32 v141, v61, v61
	v_fmac_f32_e32 v140, v62, v62
	v_fmac_f32_e32 v141, v63, v63
	v_add_f32_e32 v140, v140, v141
	s_nop 1
	v_add_f32_dpp v142, v140, v140 quad_perm:[1,0,3,2] row_mask:0xf bank_mask:0xf
	s_nop 1
	v_add_f32_dpp v142, v142, v142 quad_perm:[2,3,0,1] row_mask:0xf bank_mask:0xf
	s_nop 1
	v_add_f32_dpp v142, v142, v142 row_half_mirror row_mask:0xf bank_mask:0xf
	s_nop 1
	v_add_f32_dpp v142, v142, v142 row_mirror row_mask:0xf bank_mask:0xf
	s_nop 1
	v_readlane_b32 s20, v142, 0
	v_readlane_b32 s21, v142, 16
	v_readlane_b32 s22, v142, 32
	v_readlane_b32 s23, v142, 48
	s_nop 1
	v_mov_b32_e32 v143, s20
	v_add_f32_e32 v143, s21, v143
	v_add_f32_e32 v143, s22, v143
	v_add_f32_e32 v143, s23, v143
	v_fmamk_f32 v143, v143, 0x3a000000, v131
	v_rsq_f32_e32 v143, v143
	s_nop 0
	s_add_i32 s4, s6, 3
	s_lshl_b32 s5, s4, 12
	s_add_u32 s14, s84, s5
	s_addc_u32 s15, s85, 0
	s_add_u32 s14, s14, 0x4000000
	s_addc_u32 s15, s15, 0
	v_mul_f32_e32 v136, v143, v32
	v_mul_f32_e32 v137, v143, v33
	v_mul_f32_e32 v138, v143, v34
	v_mul_f32_e32 v139, v143, v35
	v_fma_f32 v136, v136, v64, v96
	v_fma_f32 v137, v137, v65, v97
	v_fma_f32 v138, v138, v66, v98
	v_fma_f32 v139, v139, v67, v99
	v_cvt_pk_bf16_f32 v132, v136, v137
	v_cvt_pk_bf16_f32 v133, v138, v139
	global_store_dwordx2 v130, v[132:133], s[14:15] offset:0 nt
	v_mul_f32_e32 v136, v143, v36
	v_mul_f32_e32 v137, v143, v37
	v_mul_f32_e32 v138, v143, v38
	v_mul_f32_e32 v139, v143, v39
	v_fma_f32 v136, v136, v68, v100
	v_fma_f32 v137, v137, v69, v101
	v_fma_f32 v138, v138, v70, v102
	v_fma_f32 v139, v139, v71, v103
	v_cvt_pk_bf16_f32 v134, v136, v137
	v_cvt_pk_bf16_f32 v135, v138, v139
	global_store_dwordx2 v130, v[134:135], s[14:15] offset:512 nt
	v_mul_f32_e32 v136, v143, v40
	v_mul_f32_e32 v137, v143, v41
	v_mul_f32_e32 v138, v143, v42
	v_mul_f32_e32 v139, v143, v43
	v_fma_f32 v136, v136, v72, v104
	v_fma_f32 v137, v137, v73, v105
	v_fma_f32 v138, v138, v74, v106
	v_fma_f32 v139, v139, v75, v107
	v_cvt_pk_bf16_f32 v132, v136, v137
	v_cvt_pk_bf16_f32 v133, v138, v139
	global_store_dwordx2 v130, v[132:133], s[14:15] offset:1024 nt
	v_mul_f32_e32 v136, v143, v44
	v_mul_f32_e32 v137, v143, v45
	v_mul_f32_e32 v138, v143, v46
	v_mul_f32_e32 v139, v143, v47
	v_fma_f32 v136, v136, v76, v108
	v_fma_f32 v137, v137, v77, v109
	v_fma_f32 v138, v138, v78, v110
	v_fma_f32 v139, v139, v79, v111
	v_cvt_pk_bf16_f32 v134, v136, v137
	v_cvt_pk_bf16_f32 v135, v138, v139
	global_store_dwordx2 v130, v[134:135], s[14:15] offset:1536 nt
	v_mul_f32_e32 v136, v143, v48
	v_mul_f32_e32 v137, v143, v49
	v_mul_f32_e32 v138, v143, v50
	v_mul_f32_e32 v139, v143, v51
	v_fma_f32 v136, v136, v80, v112
	v_fma_f32 v137, v137, v81, v113
	v_fma_f32 v138, v138, v82, v114
	v_fma_f32 v139, v139, v83, v115
	v_cvt_pk_bf16_f32 v132, v136, v137
	v_cvt_pk_bf16_f32 v133, v138, v139
	global_store_dwordx2 v130, v[132:133], s[14:15] offset:2048 nt
	v_mul_f32_e32 v136, v143, v52
	v_mul_f32_e32 v137, v143, v53
	v_mul_f32_e32 v138, v143, v54
	v_mul_f32_e32 v139, v143, v55
	v_fma_f32 v136, v136, v84, v116
	v_fma_f32 v137, v137, v85, v117
	v_fma_f32 v138, v138, v86, v118
	v_fma_f32 v139, v139, v87, v119
	v_cvt_pk_bf16_f32 v134, v136, v137
	v_cvt_pk_bf16_f32 v135, v138, v139
	global_store_dwordx2 v130, v[134:135], s[14:15] offset:2560 nt
	v_mul_f32_e32 v136, v143, v56
	v_mul_f32_e32 v137, v143, v57
	v_mul_f32_e32 v138, v143, v58
	v_mul_f32_e32 v139, v143, v59
	v_fma_f32 v136, v136, v88, v120
	v_fma_f32 v137, v137, v89, v121
	v_fma_f32 v138, v138, v90, v122
	v_fma_f32 v139, v139, v91, v123
	v_cvt_pk_bf16_f32 v132, v136, v137
	v_cvt_pk_bf16_f32 v133, v138, v139
	global_store_dwordx2 v130, v[132:133], s[14:15] offset:3072 nt
	v_mul_f32_e32 v136, v143, v60
	v_mul_f32_e32 v137, v143, v61
	v_mul_f32_e32 v138, v143, v62
	v_mul_f32_e32 v139, v143, v63
	v_fma_f32 v136, v136, v92, v124
	v_fma_f32 v137, v137, v93, v125
	v_fma_f32 v138, v138, v94, v126
	v_fma_f32 v139, v139, v95, v127
	v_cvt_pk_bf16_f32 v134, v136, v137
	v_cvt_pk_bf16_f32 v135, v138, v139
	global_store_dwordx2 v130, v[134:135], s[14:15] offset:3584 nt
	s_add_i32 s4, s6, 5
	s_cmp_lt_u32 s4, 0x4000
	s_cselect_b32 s10, s68, s72
	s_cselect_b32 s11, s69, s73
	s_cselect_b32 s5, 0, 0x4000
	s_sub_i32 s5, s4, s5
	s_lshl_b32 s5, s5, 13
	s_add_u32 s10, s10, s5
	s_addc_u32 s11, s11, 0
	global_load_dwordx4 v[32:35], v128, s[10:11] offset:0 nt
	global_load_dwordx4 v[36:39], v128, s[10:11] offset:1024 nt
	global_load_dwordx4 v[40:43], v128, s[10:11] offset:2048 nt
	global_load_dwordx4 v[44:47], v128, s[10:11] offset:3072 nt
	global_load_dwordx4 v[48:51], v129, s[10:11] offset:0 nt
	global_load_dwordx4 v[52:55], v129, s[10:11] offset:1024 nt
	global_load_dwordx4 v[56:59], v129, s[10:11] offset:2048 nt
	global_load_dwordx4 v[60:63], v129, s[10:11] offset:3072 nt
	s_add_i32 s4, s6, 4
	s_add_i32 s4, s6, 4
	s_lshr_b32 s8, s4, 11
	s_cmp_lt_u32 s4, 0x4000
	s_cselect_b32 s8, s8, 8
	s_cmp_eq_u32 s8, s7
	s_cbranch_scc1 .Lp1_np4
; __device__ __forceinline__ unsigned cvt_pk_bf16(float lo, float hi) { unsigned r; asm volatile("v_cvt_pk_bf16_f32 %0, %1, %2" : "=v"(r) : "v"(lo), "v"(hi)); return r; }
; __device__ __forceinline__ float sumsq8(const f32x4 (&v)[8]) {
;     float s = 0.f;
; #pragma unroll
;     for (int j = 0; j < 8; ++j) s += (v[j][0] * v[j][0] + v[j][1] * v[j][1]) + (v[j][2] * v[j][2] + v[j][3] * v[j][3]);
;     return wave_sum(s);
; __device__ __forceinline__ void modulate_store(const f32x4 (&v)[8], float rstd, const float* pn, const float* modr, bf16_t* orow, int lane) {
; #pragma unroll
;     for (int j = 0; j < 8; ++j) { const int col = 4 * lane + 256 * j;
;         const f32x4 g = *(const f32x4*)(pn + col), sh = *(const f32x4*)(modr + col), sc = *(const f32x4*)(modr + DM + col);
;         const f32x4 hh = v[j] * rstd * g * (sc + 1.f) + sh;
;         u32x2 w; w.x = cvt_pk_bf16(hh[0], hh[1]); w.y = cvt_pk_bf16(hh[2], hh[3]);
;         *(u32x2*)(orow + col) = w; }
; }
	s_mov_b32 s7, s8
	s_add_i32 s5, s8, 0
	s_mul_i32 s5, s5, 0x6000
	s_add_u32 s24, s84, s5
	s_addc_u32 s25, s85, 0
	s_add_u32 s24, s24, 0x2000
	s_addc_u32 s25, s25, 0
	s_add_i32 s5, s8, 0
	s_mul_i32 s5, s5, 0x6000
	s_add_u32 s16, s84, s5
	s_addc_u32 s17, s85, 0
	s_add_u32 s18, s80, 0x0
	s_addc_u32 s19, s81, 0
	global_load_dwordx4 v[64:67], v128, s[18:19] offset:0
	global_load_dwordx4 v[96:99], v128, s[16:17] offset:0
	global_load_dwordx4 v[68:71], v128, s[18:19] offset:1024
	global_load_dwordx4 v[100:103], v128, s[16:17] offset:1024
	global_load_dwordx4 v[72:75], v128, s[18:19] offset:2048
	global_load_dwordx4 v[104:107], v128, s[16:17] offset:2048
	global_load_dwordx4 v[76:79], v128, s[18:19] offset:3072
	global_load_dwordx4 v[108:111], v128, s[16:17] offset:3072
	global_load_dwordx4 v[80:83], v129, s[18:19] offset:0
	global_load_dwordx4 v[112:115], v129, s[16:17] offset:0
	global_load_dwordx4 v[84:87], v129, s[18:19] offset:1024
	global_load_dwordx4 v[116:119], v129, s[16:17] offset:1024
	global_load_dwordx4 v[88:91], v129, s[18:19] offset:2048
	global_load_dwordx4 v[120:123], v129, s[16:17] offset:2048
	global_load_dwordx4 v[92:95], v129, s[18:19] offset:3072
	global_load_dwordx4 v[124:127], v129, s[16:17] offset:3072
	global_load_dwordx4 v[136:139], v128, s[24:25] offset:0
	s_waitcnt vmcnt(0)
	v_add_f32_e32 v136, 1.0, v136
	v_add_f32_e32 v137, 1.0, v137
	v_add_f32_e32 v138, 1.0, v138
	v_add_f32_e32 v139, 1.0, v139
	v_mul_f32_e32 v64, v64, v136
	v_mul_f32_e32 v65, v65, v137
	v_mul_f32_e32 v66, v66, v138
	v_mul_f32_e32 v67, v67, v139
	global_load_dwordx4 v[136:139], v128, s[24:25] offset:1024
	s_waitcnt vmcnt(0)
	v_add_f32_e32 v136, 1.0, v136
	v_add_f32_e32 v137, 1.0, v137
	v_add_f32_e32 v138, 1.0, v138
	v_add_f32_e32 v139, 1.0, v139
	v_mul_f32_e32 v68, v68, v136
	v_mul_f32_e32 v69, v69, v137
	v_mul_f32_e32 v70, v70, v138
	v_mul_f32_e32 v71, v71, v139
	global_load_dwordx4 v[136:139], v128, s[24:25] offset:2048
	s_waitcnt vmcnt(0)
	v_add_f32_e32 v136, 1.0, v136
	v_add_f32_e32 v137, 1.0, v137
	v_add_f32_e32 v138, 1.0, v138
	v_add_f32_e32 v139, 1.0, v139
	v_mul_f32_e32 v72, v72, v136
	v_mul_f32_e32 v73, v73, v137
	v_mul_f32_e32 v74, v74, v138
	v_mul_f32_e32 v75, v75, v139
	global_load_dwordx4 v[136:139], v128, s[24:25] offset:3072
	s_waitcnt vmcnt(0)
	v_add_f32_e32 v136, 1.0, v136
	v_add_f32_e32 v137, 1.0, v137
	v_add_f32_e32 v138, 1.0, v138
	v_add_f32_e32 v139, 1.0, v139
	v_mul_f32_e32 v76, v76, v136
	v_mul_f32_e32 v77, v77, v137
	v_mul_f32_e32 v78, v78, v138
	v_mul_f32_e32 v79, v79, v139
	global_load_dwordx4 v[136:139], v129, s[24:25] offset:0
	s_waitcnt vmcnt(0)
	v_add_f32_e32 v136, 1.0, v136
	v_add_f32_e32 v137, 1.0, v137
	v_add_f32_e32 v138, 1.0, v138
	v_add_f32_e32 v139, 1.0, v139
	v_mul_f32_e32 v80, v80, v136
	v_mul_f32_e32 v81, v81, v137
	v_mul_f32_e32 v82, v82, v138
	v_mul_f32_e32 v83, v83, v139
	global_load_dwordx4 v[136:139], v129, s[24:25] offset:1024
	s_waitcnt vmcnt(0)
	v_add_f32_e32 v136, 1.0, v136
	v_add_f32_e32 v137, 1.0, v137
	v_add_f32_e32 v138, 1.0, v138
	v_add_f32_e32 v139, 1.0, v139
	v_mul_f32_e32 v84, v84, v136
	v_mul_f32_e32 v85, v85, v137
	v_mul_f32_e32 v86, v86, v138
	v_mul_f32_e32 v87, v87, v139
	global_load_dwordx4 v[136:139], v129, s[24:25] offset:2048
	s_waitcnt vmcnt(0)
	v_add_f32_e32 v136, 1.0, v136
	v_add_f32_e32 v137, 1.0, v137
	v_add_f32_e32 v138, 1.0, v138
	v_add_f32_e32 v139, 1.0, v139
	v_mul_f32_e32 v88, v88, v136
	v_mul_f32_e32 v89, v89, v137
	v_mul_f32_e32 v90, v90, v138
	v_mul_f32_e32 v91, v91, v139
	global_load_dwordx4 v[136:139], v129, s[24:25] offset:3072
	s_waitcnt vmcnt(0)
	v_add_f32_e32 v136, 1.0, v136
	v_add_f32_e32 v137, 1.0, v137
	v_add_f32_e32 v138, 1.0, v138
	v_add_f32_e32 v139, 1.0, v139
	v_mul_f32_e32 v92, v92, v136
	v_mul_f32_e32 v93, v93, v137
	v_mul_f32_e32 v94, v94, v138
	v_mul_f32_e32 v95, v95, v139
.Lp1_np4:
	s_waitcnt vmcnt(16)
	v_mul_f32_e32 v140, v0, v0
	v_mul_f32_e32 v141, v1, v1
	v_fmac_f32_e32 v140, v2, v2
	v_fmac_f32_e32 v141, v3, v3
	v_fmac_f32_e32 v140, v4, v4
	v_fmac_f32_e32 v141, v5, v5
	v_fmac_f32_e32 v140, v6, v6
	v_fmac_f32_e32 v141, v7, v7
	v_fmac_f32_e32 v140, v8, v8
	v_fmac_f32_e32 v141, v9, v9
	v_fmac_f32_e32 v140, v10, v10
	v_fmac_f32_e32 v141, v11, v11
	v_fmac_f32_e32 v140, v12, v12
	v_fmac_f32_e32 v141, v13, v13
	v_fmac_f32_e32 v140, v14, v14
	v_fmac_f32_e32 v141, v15, v15
	v_fmac_f32_e32 v140, v16, v16
	v_fmac_f32_e32 v141, v17, v17
	v_fmac_f32_e32 v140, v18, v18
	v_fmac_f32_e32 v141, v19, v19
	v_fmac_f32_e32 v140, v20, v20
	v_fmac_f32_e32 v141, v21, v21
	v_fmac_f32_e32 v140, v22, v22
	v_fmac_f32_e32 v141, v23, v23
	v_fmac_f32_e32 v140, v24, v24
	v_fmac_f32_e32 v141, v25, v25
	v_fmac_f32_e32 v140, v26, v26
	v_fmac_f32_e32 v141, v27, v27
	v_fmac_f32_e32 v140, v28, v28
	v_fmac_f32_e32 v141, v29, v29
	v_fmac_f32_e32 v140, v30, v30
	v_fmac_f32_e32 v141, v31, v31
	v_add_f32_e32 v140, v140, v141
	s_nop 1
	v_add_f32_dpp v142, v140, v140 quad_perm:[1,0,3,2] row_mask:0xf bank_mask:0xf
	s_nop 1
	v_add_f32_dpp v142, v142, v142 quad_perm:[2,3,0,1] row_mask:0xf bank_mask:0xf
	s_nop 1
	v_add_f32_dpp v142, v142, v142 row_half_mirror row_mask:0xf bank_mask:0xf
	s_nop 1
	v_add_f32_dpp v142, v142, v142 row_mirror row_mask:0xf bank_mask:0xf
	s_nop 1
	v_readlane_b32 s20, v142, 0
	v_readlane_b32 s21, v142, 16
	v_readlane_b32 s22, v142, 32
	v_readlane_b32 s23, v142, 48
	s_nop 1
	v_mov_b32_e32 v143, s20
	v_add_f32_e32 v143, s21, v143
	v_add_f32_e32 v143, s22, v143
	v_add_f32_e32 v143, s23, v143
	v_fmamk_f32 v143, v143, 0x3a000000, v131
	v_rsq_f32_e32 v143, v143
	s_nop 0
	s_add_i32 s4, s6, 4
	s_lshl_b32 s5, s4, 12
	s_add_u32 s14, s84, s5
	s_addc_u32 s15, s85, 0
	s_add_u32 s14, s14, 0x4000000
; __device__ __forceinline__ unsigned cvt_pk_bf16(float lo, float hi) { unsigned r; asm volatile("v_cvt_pk_bf16_f32 %0, %1, %2" : "=v"(r) : "v"(lo), "v"(hi)); return r; }
; __device__ __forceinline__ void modulate_store(const f32x4 (&v)[8], float rstd, const float* pn, const float* modr, bf16_t* orow, int lane) {
; #pragma unroll
;     for (int j = 0; j < 8; ++j) { const int col = 4 * lane + 256 * j;
;         const f32x4 g = *(const f32x4*)(pn + col), sh = *(const f32x4*)(modr + col), sc = *(const f32x4*)(modr + DM + col);
;         const f32x4 hh = v[j] * rstd * g * (sc + 1.f) + sh;
;         u32x2 w; w.x = cvt_pk_bf16(hh[0], hh[1]); w.y = cvt_pk_bf16(hh[2], hh[3]);
;         *(u32x2*)(orow + col) = w; }
; }
; __global__ void __launch_bounds__(NWAVES * 64, 2) mk_fwd(Args args) {
;     ...
;         for (int row0 = F.gw * 3; row0 < MT; row0 += F.NGW * 3) {
;             f32x4 v[3][8];
; #pragma unroll
;             for (int q = 0; q < 3; ++q) { const int row = row0 + q; const float* src = row < ML ? x + (size_t)row * DM : ctx + (size_t)(row - ML) * DM; load_row_f32(src, F.lane, v[q]); }
; #pragma unroll
;             for (int q = 0; q < 3; ++q) { const int row = row0 + q; const int r = row < ML ? row / SEQ : 8;
;                 const float rstd = __builtin_amdgcn_rsqf(sumsq8(v[q]) * (1.f / DM) + EPS);
;                 modulate_store(v[q], rstd, pre_norm, mod + (size_t)r * 6144, H + (size_t)row * DM, F.lane); }
	s_addc_u32 s15, s15, 0
	v_mul_f32_e32 v136, v143, v0
	v_mul_f32_e32 v137, v143, v1
	v_mul_f32_e32 v138, v143, v2
	v_mul_f32_e32 v139, v143, v3
	v_fma_f32 v136, v136, v64, v96
	v_fma_f32 v137, v137, v65, v97
	v_fma_f32 v138, v138, v66, v98
	v_fma_f32 v139, v139, v67, v99
	v_cvt_pk_bf16_f32 v132, v136, v137
	v_cvt_pk_bf16_f32 v133, v138, v139
	global_store_dwordx2 v130, v[132:133], s[14:15] offset:0 nt
	v_mul_f32_e32 v136, v143, v4
	v_mul_f32_e32 v137, v143, v5
	v_mul_f32_e32 v138, v143, v6
	v_mul_f32_e32 v139, v143, v7
	v_fma_f32 v136, v136, v68, v100
	v_fma_f32 v137, v137, v69, v101
	v_fma_f32 v138, v138, v70, v102
	v_fma_f32 v139, v139, v71, v103
	v_cvt_pk_bf16_f32 v134, v136, v137
	v_cvt_pk_bf16_f32 v135, v138, v139
	global_store_dwordx2 v130, v[134:135], s[14:15] offset:512 nt
	v_mul_f32_e32 v136, v143, v8
	v_mul_f32_e32 v137, v143, v9
	v_mul_f32_e32 v138, v143, v10
	v_mul_f32_e32 v139, v143, v11
	v_fma_f32 v136, v136, v72, v104
	v_fma_f32 v137, v137, v73, v105
	v_fma_f32 v138, v138, v74, v106
	v_fma_f32 v139, v139, v75, v107
	v_cvt_pk_bf16_f32 v132, v136, v137
	v_cvt_pk_bf16_f32 v133, v138, v139
	global_store_dwordx2 v130, v[132:133], s[14:15] offset:1024 nt
	v_mul_f32_e32 v136, v143, v12
	v_mul_f32_e32 v137, v143, v13
	v_mul_f32_e32 v138, v143, v14
	v_mul_f32_e32 v139, v143, v15
	v_fma_f32 v136, v136, v76, v108
	v_fma_f32 v137, v137, v77, v109
	v_fma_f32 v138, v138, v78, v110
	v_fma_f32 v139, v139, v79, v111
	v_cvt_pk_bf16_f32 v134, v136, v137
	v_cvt_pk_bf16_f32 v135, v138, v139
	global_store_dwordx2 v130, v[134:135], s[14:15] offset:1536 nt
	v_mul_f32_e32 v136, v143, v16
	v_mul_f32_e32 v137, v143, v17
	v_mul_f32_e32 v138, v143, v18
	v_mul_f32_e32 v139, v143, v19
	v_fma_f32 v136, v136, v80, v112
	v_fma_f32 v137, v137, v81, v113
	v_fma_f32 v138, v138, v82, v114
	v_fma_f32 v139, v139, v83, v115
	v_cvt_pk_bf16_f32 v132, v136, v137
	v_cvt_pk_bf16_f32 v133, v138, v139
	global_store_dwordx2 v130, v[132:133], s[14:15] offset:2048 nt
	v_mul_f32_e32 v136, v143, v20
	v_mul_f32_e32 v137, v143, v21
	v_mul_f32_e32 v138, v143, v22
	v_mul_f32_e32 v139, v143, v23
	v_fma_f32 v136, v136, v84, v116
	v_fma_f32 v137, v137, v85, v117
	v_fma_f32 v138, v138, v86, v118
	v_fma_f32 v139, v139, v87, v119
	v_cvt_pk_bf16_f32 v134, v136, v137
	v_cvt_pk_bf16_f32 v135, v138, v139
	global_store_dwordx2 v130, v[134:135], s[14:15] offset:2560 nt
	v_mul_f32_e32 v136, v143, v24
	v_mul_f32_e32 v137, v143, v25
	v_mul_f32_e32 v138, v143, v26
	v_mul_f32_e32 v139, v143, v27
	v_fma_f32 v136, v136, v88, v120
	v_fma_f32 v137, v137, v89, v121
	v_fma_f32 v138, v138, v90, v122
	v_fma_f32 v139, v139, v91, v123
	v_cvt_pk_bf16_f32 v132, v136, v137
	v_cvt_pk_bf16_f32 v133, v138, v139
	global_store_dwordx2 v130, v[132:133], s[14:15] offset:3072 nt
	v_mul_f32_e32 v136, v143, v28
	v_mul_f32_e32 v137, v143, v29
	v_mul_f32_e32 v138, v143, v30
	v_mul_f32_e32 v139, v143, v31
	v_fma_f32 v136, v136, v92, v124
	v_fma_f32 v137, v137, v93, v125
	v_fma_f32 v138, v138, v94, v126
	v_fma_f32 v139, v139, v95, v127
	v_cvt_pk_bf16_f32 v134, v136, v137
	v_cvt_pk_bf16_f32 v135, v138, v139
	global_store_dwordx2 v130, v[134:135], s[14:15] offset:3584 nt
	s_add_i32 s4, s6, 6
	s_cmp_lt_u32 s4, 0x4000
	s_cselect_b32 s10, s68, s72
	s_cselect_b32 s11, s69, s73
	s_cselect_b32 s5, 0, 0x4000
	s_sub_i32 s5, s4, s5
	s_lshl_b32 s5, s5, 13
	s_add_u32 s10, s10, s5
	s_addc_u32 s11, s11, 0
	global_load_dwordx4 v[0:3], v128, s[10:11] offset:0 nt
	global_load_dwordx4 v[4:7], v128, s[10:11] offset:1024 nt
	global_load_dwordx4 v[8:11], v128, s[10:11] offset:2048 nt
	global_load_dwordx4 v[12:15], v128, s[10:11] offset:3072 nt
	global_load_dwordx4 v[16:19], v129, s[10:11] offset:0 nt
	global_load_dwordx4 v[20:23], v129, s[10:11] offset:1024 nt
	global_load_dwordx4 v[24:27], v129, s[10:11] offset:2048 nt
	global_load_dwordx4 v[28:31], v129, s[10:11] offset:3072 nt
	s_add_i32 s4, s6, 5
	s_add_i32 s4, s6, 5
	s_lshr_b32 s8, s4, 11
	s_cmp_lt_u32 s4, 0x4000
	s_cselect_b32 s8, s8, 8
	s_cmp_eq_u32 s8, s7
	s_cbranch_scc1 .Lp1_np5
	s_mov_b32 s7, s8
	s_add_i32 s5, s8, 0
	s_mul_i32 s5, s5, 0x6000
	s_add_u32 s24, s84, s5
	s_addc_u32 s25, s85, 0
	s_add_u32 s24, s24, 0x2000
	s_addc_u32 s25, s25, 0
	s_add_i32 s5, s8, 0
	s_mul_i32 s5, s5, 0x6000
	s_add_u32 s16, s84, s5
	s_addc_u32 s17, s85, 0
	s_add_u32 s18, s80, 0x0
	s_addc_u32 s19, s81, 0
	global_load_dwordx4 v[64:67], v128, s[18:19] offset:0
	global_load_dwordx4 v[96:99], v128, s[16:17] offset:0
	global_load_dwordx4 v[68:71], v128, s[18:19] offset:1024
	global_load_dwordx4 v[100:103], v128, s[16:17] offset:1024
	global_load_dwordx4 v[72:75], v128, s[18:19] offset:2048
	global_load_dwordx4 v[104:107], v128, s[16:17] offset:2048
	global_load_dwordx4 v[76:79], v128, s[18:19] offset:3072
	global_load_dwordx4 v[108:111], v128, s[16:17] offset:3072
	global_load_dwordx4 v[80:83], v129, s[18:19] offset:0
	global_load_dwordx4 v[112:115], v129, s[16:17] offset:0
	global_load_dwordx4 v[84:87], v129, s[18:19] offset:1024
	global_load_dwordx4 v[116:119], v129, s[16:17] offset:1024
	global_load_dwordx4 v[88:91], v129, s[18:19] offset:2048
	global_load_dwordx4 v[120:123], v129, s[16:17] offset:2048
	global_load_dwordx4 v[92:95], v129, s[18:19] offset:3072
	global_load_dwordx4 v[124:127], v129, s[16:17] offset:3072
	global_load_dwordx4 v[136:139], v128, s[24:25] offset:0
	s_waitcnt vmcnt(0)
	v_add_f32_e32 v136, 1.0, v136
	v_add_f32_e32 v137, 1.0, v137
	v_add_f32_e32 v138, 1.0, v138
	v_add_f32_e32 v139, 1.0, v139
	v_mul_f32_e32 v64, v64, v136
	v_mul_f32_e32 v65, v65, v137
	v_mul_f32_e32 v66, v66, v138
	v_mul_f32_e32 v67, v67, v139
	global_load_dwordx4 v[136:139], v128, s[24:25] offset:1024
	s_waitcnt vmcnt(0)
; __device__ __forceinline__ unsigned cvt_pk_bf16(float lo, float hi) { unsigned r; asm volatile("v_cvt_pk_bf16_f32 %0, %1, %2" : "=v"(r) : "v"(lo), "v"(hi)); return r; }
; __device__ __forceinline__ float sumsq8(const f32x4 (&v)[8]) {
;     float s = 0.f;
; #pragma unroll
;     for (int j = 0; j < 8; ++j) s += (v[j][0] * v[j][0] + v[j][1] * v[j][1]) + (v[j][2] * v[j][2] + v[j][3] * v[j][3]);
;     return wave_sum(s);
; }
; __device__ __forceinline__ void modulate_store(const f32x4 (&v)[8], float rstd, const float* pn, const float* modr, bf16_t* orow, int lane) {
; #pragma unroll
;     for (int j = 0; j < 8; ++j) { const int col = 4 * lane + 256 * j;
;         const f32x4 g = *(const f32x4*)(pn + col), sh = *(const f32x4*)(modr + col), sc = *(const f32x4*)(modr + DM + col);
;         const f32x4 hh = v[j] * rstd * g * (sc + 1.f) + sh;
;         u32x2 w; w.x = cvt_pk_bf16(hh[0], hh[1]); w.y = cvt_pk_bf16(hh[2], hh[3]);
;         *(u32x2*)(orow + col) = w; }
; }
	v_add_f32_e32 v136, 1.0, v136
	v_add_f32_e32 v137, 1.0, v137
	v_add_f32_e32 v138, 1.0, v138
	v_add_f32_e32 v139, 1.0, v139
	v_mul_f32_e32 v68, v68, v136
	v_mul_f32_e32 v69, v69, v137
	v_mul_f32_e32 v70, v70, v138
	v_mul_f32_e32 v71, v71, v139
	global_load_dwordx4 v[136:139], v128, s[24:25] offset:2048
	s_waitcnt vmcnt(0)
	v_add_f32_e32 v136, 1.0, v136
	v_add_f32_e32 v137, 1.0, v137
	v_add_f32_e32 v138, 1.0, v138
	v_add_f32_e32 v139, 1.0, v139
	v_mul_f32_e32 v72, v72, v136
	v_mul_f32_e32 v73, v73, v137
	v_mul_f32_e32 v74, v74, v138
	v_mul_f32_e32 v75, v75, v139
	global_load_dwordx4 v[136:139], v128, s[24:25] offset:3072
	s_waitcnt vmcnt(0)
	v_add_f32_e32 v136, 1.0, v136
	v_add_f32_e32 v137, 1.0, v137
	v_add_f32_e32 v138, 1.0, v138
	v_add_f32_e32 v139, 1.0, v139
	v_mul_f32_e32 v76, v76, v136
	v_mul_f32_e32 v77, v77, v137
	v_mul_f32_e32 v78, v78, v138
	v_mul_f32_e32 v79, v79, v139
	global_load_dwordx4 v[136:139], v129, s[24:25] offset:0
	s_waitcnt vmcnt(0)
	v_add_f32_e32 v136, 1.0, v136
	v_add_f32_e32 v137, 1.0, v137
	v_add_f32_e32 v138, 1.0, v138
	v_add_f32_e32 v139, 1.0, v139
	v_mul_f32_e32 v80, v80, v136
	v_mul_f32_e32 v81, v81, v137
	v_mul_f32_e32 v82, v82, v138
	v_mul_f32_e32 v83, v83, v139
	global_load_dwordx4 v[136:139], v129, s[24:25] offset:1024
	s_waitcnt vmcnt(0)
	v_add_f32_e32 v136, 1.0, v136
	v_add_f32_e32 v137, 1.0, v137
	v_add_f32_e32 v138, 1.0, v138
	v_add_f32_e32 v139, 1.0, v139
	v_mul_f32_e32 v84, v84, v136
	v_mul_f32_e32 v85, v85, v137
	v_mul_f32_e32 v86, v86, v138
	v_mul_f32_e32 v87, v87, v139
	global_load_dwordx4 v[136:139], v129, s[24:25] offset:2048
	s_waitcnt vmcnt(0)
	v_add_f32_e32 v136, 1.0, v136
	v_add_f32_e32 v137, 1.0, v137
	v_add_f32_e32 v138, 1.0, v138
	v_add_f32_e32 v139, 1.0, v139
	v_mul_f32_e32 v88, v88, v136
	v_mul_f32_e32 v89, v89, v137
	v_mul_f32_e32 v90, v90, v138
	v_mul_f32_e32 v91, v91, v139
	global_load_dwordx4 v[136:139], v129, s[24:25] offset:3072
	s_waitcnt vmcnt(0)
	v_add_f32_e32 v136, 1.0, v136
	v_add_f32_e32 v137, 1.0, v137
	v_add_f32_e32 v138, 1.0, v138
	v_add_f32_e32 v139, 1.0, v139
	v_mul_f32_e32 v92, v92, v136
	v_mul_f32_e32 v93, v93, v137
	v_mul_f32_e32 v94, v94, v138
	v_mul_f32_e32 v95, v95, v139
.Lp1_np5:
	s_waitcnt vmcnt(16)
	v_mul_f32_e32 v140, v32, v32
	v_mul_f32_e32 v141, v33, v33
	v_fmac_f32_e32 v140, v34, v34
	v_fmac_f32_e32 v141, v35, v35
	v_fmac_f32_e32 v140, v36, v36
	v_fmac_f32_e32 v141, v37, v37
	v_fmac_f32_e32 v140, v38, v38
	v_fmac_f32_e32 v141, v39, v39
	v_fmac_f32_e32 v140, v40, v40
	v_fmac_f32_e32 v141, v41, v41
	v_fmac_f32_e32 v140, v42, v42
	v_fmac_f32_e32 v141, v43, v43
	v_fmac_f32_e32 v140, v44, v44
	v_fmac_f32_e32 v141, v45, v45
	v_fmac_f32_e32 v140, v46, v46
	v_fmac_f32_e32 v141, v47, v47
	v_fmac_f32_e32 v140, v48, v48
	v_fmac_f32_e32 v141, v49, v49
	v_fmac_f32_e32 v140, v50, v50
	v_fmac_f32_e32 v141, v51, v51
	v_fmac_f32_e32 v140, v52, v52
	v_fmac_f32_e32 v141, v53, v53
	v_fmac_f32_e32 v140, v54, v54
	v_fmac_f32_e32 v141, v55, v55
	v_fmac_f32_e32 v140, v56, v56
	v_fmac_f32_e32 v141, v57, v57
	v_fmac_f32_e32 v140, v58, v58
	v_fmac_f32_e32 v141, v59, v59
	v_fmac_f32_e32 v140, v60, v60
	v_fmac_f32_e32 v141, v61, v61
	v_fmac_f32_e32 v140, v62, v62
	v_fmac_f32_e32 v141, v63, v63
	v_add_f32_e32 v140, v140, v141
	s_nop 1
	v_add_f32_dpp v142, v140, v140 quad_perm:[1,0,3,2] row_mask:0xf bank_mask:0xf
	s_nop 1
	v_add_f32_dpp v142, v142, v142 quad_perm:[2,3,0,1] row_mask:0xf bank_mask:0xf
	s_nop 1
	v_add_f32_dpp v142, v142, v142 row_half_mirror row_mask:0xf bank_mask:0xf
	s_nop 1
	v_add_f32_dpp v142, v142, v142 row_mirror row_mask:0xf bank_mask:0xf
	s_nop 1
	v_readlane_b32 s20, v142, 0
	v_readlane_b32 s21, v142, 16
	v_readlane_b32 s22, v142, 32
	v_readlane_b32 s23, v142, 48
	s_nop 1
	v_mov_b32_e32 v143, s20
	v_add_f32_e32 v143, s21, v143
	v_add_f32_e32 v143, s22, v143
	v_add_f32_e32 v143, s23, v143
	v_fmamk_f32 v143, v143, 0x3a000000, v131
	v_rsq_f32_e32 v143, v143
	s_nop 0
	s_add_i32 s4, s6, 5
	s_lshl_b32 s5, s4, 12
	s_add_u32 s14, s84, s5
	s_addc_u32 s15, s85, 0
	s_add_u32 s14, s14, 0x4000000
	s_addc_u32 s15, s15, 0
	v_mul_f32_e32 v136, v143, v32
	v_mul_f32_e32 v137, v143, v33
	v_mul_f32_e32 v138, v143, v34
	v_mul_f32_e32 v139, v143, v35
	v_fma_f32 v136, v136, v64, v96
	v_fma_f32 v137, v137, v65, v97
	v_fma_f32 v138, v138, v66, v98
	v_fma_f32 v139, v139, v67, v99
	v_cvt_pk_bf16_f32 v132, v136, v137
	v_cvt_pk_bf16_f32 v133, v138, v139
	global_store_dwordx2 v130, v[132:133], s[14:15] offset:0 nt
	v_mul_f32_e32 v136, v143, v36
	v_mul_f32_e32 v137, v143, v37
	v_mul_f32_e32 v138, v143, v38
	v_mul_f32_e32 v139, v143, v39
	v_fma_f32 v136, v136, v68, v100
	v_fma_f32 v137, v137, v69, v101
	v_fma_f32 v138, v138, v70, v102
	v_fma_f32 v139, v139, v71, v103
	v_cvt_pk_bf16_f32 v134, v136, v137
	v_cvt_pk_bf16_f32 v135, v138, v139
	global_store_dwordx2 v130, v[134:135], s[14:15] offset:512 nt
	v_mul_f32_e32 v136, v143, v40
	v_mul_f32_e32 v137, v143, v41
	v_mul_f32_e32 v138, v143, v42
	v_mul_f32_e32 v139, v143, v43
	v_fma_f32 v136, v136, v72, v104
	v_fma_f32 v137, v137, v73, v105
	v_fma_f32 v138, v138, v74, v106
	v_fma_f32 v139, v139, v75, v107
	v_cvt_pk_bf16_f32 v132, v136, v137
	v_cvt_pk_bf16_f32 v133, v138, v139
	global_store_dwordx2 v130, v[132:133], s[14:15] offset:1024 nt
	v_mul_f32_e32 v136, v143, v44
	v_mul_f32_e32 v137, v143, v45
	v_mul_f32_e32 v138, v143, v46
	v_mul_f32_e32 v139, v143, v47
	v_fma_f32 v136, v136, v76, v108
	v_fma_f32 v137, v137, v77, v109
	v_fma_f32 v138, v138, v78, v110
	v_fma_f32 v139, v139, v79, v111
	v_cvt_pk_bf16_f32 v134, v136, v137
	v_cvt_pk_bf16_f32 v135, v138, v139
	global_store_dwordx2 v130, v[134:135], s[14:15] offset:1536 nt
	v_mul_f32_e32 v136, v143, v48
; __device__ __forceinline__ unsigned cvt_pk_bf16(float lo, float hi) { unsigned r; asm volatile("v_cvt_pk_bf16_f32 %0, %1, %2" : "=v"(r) : "v"(lo), "v"(hi)); return r; }
; __device__ __forceinline__ void modulate_store(const f32x4 (&v)[8], float rstd, const float* pn, const float* modr, bf16_t* orow, int lane) {
; #pragma unroll
;     for (int j = 0; j < 8; ++j) { const int col = 4 * lane + 256 * j;
;         const f32x4 g = *(const f32x4*)(pn + col), sh = *(const f32x4*)(modr + col), sc = *(const f32x4*)(modr + DM + col);
;         const f32x4 hh = v[j] * rstd * g * (sc + 1.f) + sh;
;         u32x2 w; w.x = cvt_pk_bf16(hh[0], hh[1]); w.y = cvt_pk_bf16(hh[2], hh[3]);
;         *(u32x2*)(orow + col) = w; }
; }
; __global__ void __launch_bounds__(NWAVES * 64, 2) mk_fwd(Args args) {
;     ...
;         for (int row0 = F.gw * 3; row0 < MT; row0 += F.NGW * 3) {
;             f32x4 v[3][8];
; #pragma unroll
;             for (int q = 0; q < 3; ++q) { const int row = row0 + q; const float* src = row < ML ? x + (size_t)row * DM : ctx + (size_t)(row - ML) * DM; load_row_f32(src, F.lane, v[q]); }
; #pragma unroll
;             for (int q = 0; q < 3; ++q) { const int row = row0 + q; const int r = row < ML ? row / SEQ : 8;
;                 const float rstd = __builtin_amdgcn_rsqf(sumsq8(v[q]) * (1.f / DM) + EPS);
;                 modulate_store(v[q], rstd, pre_norm, mod + (size_t)r * 6144, H + (size_t)row * DM, F.lane); }
	v_mul_f32_e32 v137, v143, v49
	v_mul_f32_e32 v138, v143, v50
	v_mul_f32_e32 v139, v143, v51
	v_fma_f32 v136, v136, v80, v112
	v_fma_f32 v137, v137, v81, v113
	v_fma_f32 v138, v138, v82, v114
	v_fma_f32 v139, v139, v83, v115
	v_cvt_pk_bf16_f32 v132, v136, v137
	v_cvt_pk_bf16_f32 v133, v138, v139
	global_store_dwordx2 v130, v[132:133], s[14:15] offset:2048 nt
	v_mul_f32_e32 v136, v143, v52
	v_mul_f32_e32 v137, v143, v53
	v_mul_f32_e32 v138, v143, v54
	v_mul_f32_e32 v139, v143, v55
	v_fma_f32 v136, v136, v84, v116
	v_fma_f32 v137, v137, v85, v117
	v_fma_f32 v138, v138, v86, v118
	v_fma_f32 v139, v139, v87, v119
	v_cvt_pk_bf16_f32 v134, v136, v137
	v_cvt_pk_bf16_f32 v135, v138, v139
	global_store_dwordx2 v130, v[134:135], s[14:15] offset:2560 nt
	v_mul_f32_e32 v136, v143, v56
	v_mul_f32_e32 v137, v143, v57
	v_mul_f32_e32 v138, v143, v58
	v_mul_f32_e32 v139, v143, v59
	v_fma_f32 v136, v136, v88, v120
	v_fma_f32 v137, v137, v89, v121
	v_fma_f32 v138, v138, v90, v122
	v_fma_f32 v139, v139, v91, v123
	v_cvt_pk_bf16_f32 v132, v136, v137
	v_cvt_pk_bf16_f32 v133, v138, v139
	global_store_dwordx2 v130, v[132:133], s[14:15] offset:3072 nt
	v_mul_f32_e32 v136, v143, v60
	v_mul_f32_e32 v137, v143, v61
	v_mul_f32_e32 v138, v143, v62
	v_mul_f32_e32 v139, v143, v63
	v_fma_f32 v136, v136, v92, v124
	v_fma_f32 v137, v137, v93, v125
	v_fma_f32 v138, v138, v94, v126
	v_fma_f32 v139, v139, v95, v127
	v_cvt_pk_bf16_f32 v134, v136, v137
	v_cvt_pk_bf16_f32 v135, v138, v139
	global_store_dwordx2 v130, v[134:135], s[14:15] offset:3584 nt
	s_add_i32 s4, s6, 7
	s_cmp_lt_u32 s4, 0x4000
	s_cselect_b32 s10, s68, s72
	s_cselect_b32 s11, s69, s73
	s_cselect_b32 s5, 0, 0x4000
	s_sub_i32 s5, s4, s5
	s_lshl_b32 s5, s5, 13
	s_add_u32 s10, s10, s5
	s_addc_u32 s11, s11, 0
	global_load_dwordx4 v[32:35], v128, s[10:11] offset:0 nt
	global_load_dwordx4 v[36:39], v128, s[10:11] offset:1024 nt
	global_load_dwordx4 v[40:43], v128, s[10:11] offset:2048 nt
	global_load_dwordx4 v[44:47], v128, s[10:11] offset:3072 nt
	global_load_dwordx4 v[48:51], v129, s[10:11] offset:0 nt
	global_load_dwordx4 v[52:55], v129, s[10:11] offset:1024 nt
	global_load_dwordx4 v[56:59], v129, s[10:11] offset:2048 nt
	global_load_dwordx4 v[60:63], v129, s[10:11] offset:3072 nt
	s_add_i32 s4, s6, 6
	s_add_i32 s4, s6, 6
	s_lshr_b32 s8, s4, 11
	s_cmp_lt_u32 s4, 0x4000
	s_cselect_b32 s8, s8, 8
	s_cmp_eq_u32 s8, s7
	s_cbranch_scc1 .Lp1_np6
	s_mov_b32 s7, s8
	s_add_i32 s5, s8, 0
	s_mul_i32 s5, s5, 0x6000
	s_add_u32 s24, s84, s5
	s_addc_u32 s25, s85, 0
	s_add_u32 s24, s24, 0x2000
	s_addc_u32 s25, s25, 0
	s_add_i32 s5, s8, 0
	s_mul_i32 s5, s5, 0x6000
	s_add_u32 s16, s84, s5
	s_addc_u32 s17, s85, 0
	s_add_u32 s18, s80, 0x0
	s_addc_u32 s19, s81, 0
	global_load_dwordx4 v[64:67], v128, s[18:19] offset:0
	global_load_dwordx4 v[96:99], v128, s[16:17] offset:0
	global_load_dwordx4 v[68:71], v128, s[18:19] offset:1024
	global_load_dwordx4 v[100:103], v128, s[16:17] offset:1024
	global_load_dwordx4 v[72:75], v128, s[18:19] offset:2048
	global_load_dwordx4 v[104:107], v128, s[16:17] offset:2048
	global_load_dwordx4 v[76:79], v128, s[18:19] offset:3072
	global_load_dwordx4 v[108:111], v128, s[16:17] offset:3072
	global_load_dwordx4 v[80:83], v129, s[18:19] offset:0
	global_load_dwordx4 v[112:115], v129, s[16:17] offset:0
	global_load_dwordx4 v[84:87], v129, s[18:19] offset:1024
	global_load_dwordx4 v[116:119], v129, s[16:17] offset:1024
	global_load_dwordx4 v[88:91], v129, s[18:19] offset:2048
	global_load_dwordx4 v[120:123], v129, s[16:17] offset:2048
	global_load_dwordx4 v[92:95], v129, s[18:19] offset:3072
	global_load_dwordx4 v[124:127], v129, s[16:17] offset:3072
	global_load_dwordx4 v[136:139], v128, s[24:25] offset:0
	s_waitcnt vmcnt(0)
	v_add_f32_e32 v136, 1.0, v136
	v_add_f32_e32 v137, 1.0, v137
	v_add_f32_e32 v138, 1.0, v138
	v_add_f32_e32 v139, 1.0, v139
	v_mul_f32_e32 v64, v64, v136
	v_mul_f32_e32 v65, v65, v137
	v_mul_f32_e32 v66, v66, v138
	v_mul_f32_e32 v67, v67, v139
	global_load_dwordx4 v[136:139], v128, s[24:25] offset:1024
	s_waitcnt vmcnt(0)
	v_add_f32_e32 v136, 1.0, v136
	v_add_f32_e32 v137, 1.0, v137
	v_add_f32_e32 v138, 1.0, v138
	v_add_f32_e32 v139, 1.0, v139
	v_mul_f32_e32 v68, v68, v136
	v_mul_f32_e32 v69, v69, v137
	v_mul_f32_e32 v70, v70, v138
	v_mul_f32_e32 v71, v71, v139
	global_load_dwordx4 v[136:139], v128, s[24:25] offset:2048
	s_waitcnt vmcnt(0)
	v_add_f32_e32 v136, 1.0, v136
	v_add_f32_e32 v137, 1.0, v137
	v_add_f32_e32 v138, 1.0, v138
	v_add_f32_e32 v139, 1.0, v139
	v_mul_f32_e32 v72, v72, v136
	v_mul_f32_e32 v73, v73, v137
	v_mul_f32_e32 v74, v74, v138
	v_mul_f32_e32 v75, v75, v139
	global_load_dwordx4 v[136:139], v128, s[24:25] offset:3072
	s_waitcnt vmcnt(0)
	v_add_f32_e32 v136, 1.0, v136
	v_add_f32_e32 v137, 1.0, v137
	v_add_f32_e32 v138, 1.0, v138
	v_add_f32_e32 v139, 1.0, v139
	v_mul_f32_e32 v76, v76, v136
	v_mul_f32_e32 v77, v77, v137
	v_mul_f32_e32 v78, v78, v138
	v_mul_f32_e32 v79, v79, v139
	global_load_dwordx4 v[136:139], v129, s[24:25] offset:0
	s_waitcnt vmcnt(0)
	v_add_f32_e32 v136, 1.0, v136
	v_add_f32_e32 v137, 1.0, v137
	v_add_f32_e32 v138, 1.0, v138
	v_add_f32_e32 v139, 1.0, v139
	v_mul_f32_e32 v80, v80, v136
	v_mul_f32_e32 v81, v81, v137
	v_mul_f32_e32 v82, v82, v138
	v_mul_f32_e32 v83, v83, v139
	global_load_dwordx4 v[136:139], v129, s[24:25] offset:1024
	s_waitcnt vmcnt(0)
	v_add_f32_e32 v136, 1.0, v136
	v_add_f32_e32 v137, 1.0, v137
	v_add_f32_e32 v138, 1.0, v138
	v_add_f32_e32 v139, 1.0, v139
	v_mul_f32_e32 v84, v84, v136
	v_mul_f32_e32 v85, v85, v137
	v_mul_f32_e32 v86, v86, v138
	v_mul_f32_e32 v87, v87, v139
	global_load_dwordx4 v[136:139], v129, s[24:25] offset:2048
	s_waitcnt vmcnt(0)
	v_add_f32_e32 v136, 1.0, v136
	v_add_f32_e32 v137, 1.0, v137
	v_add_f32_e32 v138, 1.0, v138
	v_add_f32_e32 v139, 1.0, v139
	v_mul_f32_e32 v88, v88, v136
	v_mul_f32_e32 v89, v89, v137
	v_mul_f32_e32 v90, v90, v138
	v_mul_f32_e32 v91, v91, v139
	global_load_dwordx4 v[136:139], v129, s[24:25] offset:3072
	s_waitcnt vmcnt(0)
	v_add_f32_e32 v136, 1.0, v136
	v_add_f32_e32 v137, 1.0, v137
	v_add_f32_e32 v138, 1.0, v138
	v_add_f32_e32 v139, 1.0, v139
	v_mul_f32_e32 v92, v92, v136
	v_mul_f32_e32 v93, v93, v137
	v_mul_f32_e32 v94, v94, v138
	v_mul_f32_e32 v95, v95, v139
; __device__ __forceinline__ unsigned cvt_pk_bf16(float lo, float hi) { unsigned r; asm volatile("v_cvt_pk_bf16_f32 %0, %1, %2" : "=v"(r) : "v"(lo), "v"(hi)); return r; }
; __device__ __forceinline__ float sumsq8(const f32x4 (&v)[8]) {
;     float s = 0.f;
; #pragma unroll
;     for (int j = 0; j < 8; ++j) s += (v[j][0] * v[j][0] + v[j][1] * v[j][1]) + (v[j][2] * v[j][2] + v[j][3] * v[j][3]);
;     return wave_sum(s);
; }
; __device__ __forceinline__ void modulate_store(const f32x4 (&v)[8], float rstd, const float* pn, const float* modr, bf16_t* orow, int lane) {
; #pragma unroll
;     for (int j = 0; j < 8; ++j) { const int col = 4 * lane + 256 * j;
;         const f32x4 g = *(const f32x4*)(pn + col), sh = *(const f32x4*)(modr + col), sc = *(const f32x4*)(modr + DM + col);
;         const f32x4 hh = v[j] * rstd * g * (sc + 1.f) + sh;
;         u32x2 w; w.x = cvt_pk_bf16(hh[0], hh[1]); w.y = cvt_pk_bf16(hh[2], hh[3]);
;         *(u32x2*)(orow + col) = w; }
; }
; __global__ void __launch_bounds__(NWAVES * 64, 2) mk_fwd(Args args) {
;     ...
;             for (int q = 0; q < 3; ++q) { const int row = row0 + q; const float* src = row < ML ? x + (size_t)row * DM : ctx + (size_t)(row - ML) * DM; load_row_f32(src, F.lane, v[q]); }
.Lp1_np6:
	s_waitcnt vmcnt(16)
	v_mul_f32_e32 v140, v0, v0
	v_mul_f32_e32 v141, v1, v1
	v_fmac_f32_e32 v140, v2, v2
	v_fmac_f32_e32 v141, v3, v3
	v_fmac_f32_e32 v140, v4, v4
	v_fmac_f32_e32 v141, v5, v5
	v_fmac_f32_e32 v140, v6, v6
	v_fmac_f32_e32 v141, v7, v7
	v_fmac_f32_e32 v140, v8, v8
	v_fmac_f32_e32 v141, v9, v9
	v_fmac_f32_e32 v140, v10, v10
	v_fmac_f32_e32 v141, v11, v11
	v_fmac_f32_e32 v140, v12, v12
	v_fmac_f32_e32 v141, v13, v13
	v_fmac_f32_e32 v140, v14, v14
	v_fmac_f32_e32 v141, v15, v15
	v_fmac_f32_e32 v140, v16, v16
	v_fmac_f32_e32 v141, v17, v17
	v_fmac_f32_e32 v140, v18, v18
	v_fmac_f32_e32 v141, v19, v19
	v_fmac_f32_e32 v140, v20, v20
	v_fmac_f32_e32 v141, v21, v21
	v_fmac_f32_e32 v140, v22, v22
	v_fmac_f32_e32 v141, v23, v23
	v_fmac_f32_e32 v140, v24, v24
	v_fmac_f32_e32 v141, v25, v25
	v_fmac_f32_e32 v140, v26, v26
	v_fmac_f32_e32 v141, v27, v27
	v_fmac_f32_e32 v140, v28, v28
	v_fmac_f32_e32 v141, v29, v29
	v_fmac_f32_e32 v140, v30, v30
	v_fmac_f32_e32 v141, v31, v31
	v_add_f32_e32 v140, v140, v141
	s_nop 1
	v_add_f32_dpp v142, v140, v140 quad_perm:[1,0,3,2] row_mask:0xf bank_mask:0xf
	s_nop 1
	v_add_f32_dpp v142, v142, v142 quad_perm:[2,3,0,1] row_mask:0xf bank_mask:0xf
	s_nop 1
	v_add_f32_dpp v142, v142, v142 row_half_mirror row_mask:0xf bank_mask:0xf
	s_nop 1
	v_add_f32_dpp v142, v142, v142 row_mirror row_mask:0xf bank_mask:0xf
	s_nop 1
	v_readlane_b32 s20, v142, 0
	v_readlane_b32 s21, v142, 16
	v_readlane_b32 s22, v142, 32
	v_readlane_b32 s23, v142, 48
	s_nop 1
	v_mov_b32_e32 v143, s20
	v_add_f32_e32 v143, s21, v143
	v_add_f32_e32 v143, s22, v143
	v_add_f32_e32 v143, s23, v143
	v_fmamk_f32 v143, v143, 0x3a000000, v131
	v_rsq_f32_e32 v143, v143
	s_nop 0
	s_add_i32 s4, s6, 6
	s_lshl_b32 s5, s4, 12
	s_add_u32 s14, s84, s5
	s_addc_u32 s15, s85, 0
	s_add_u32 s14, s14, 0x4000000
	s_addc_u32 s15, s15, 0
	v_mul_f32_e32 v136, v143, v0
	v_mul_f32_e32 v137, v143, v1
	v_mul_f32_e32 v138, v143, v2
	v_mul_f32_e32 v139, v143, v3
	v_fma_f32 v136, v136, v64, v96
	v_fma_f32 v137, v137, v65, v97
	v_fma_f32 v138, v138, v66, v98
	v_fma_f32 v139, v139, v67, v99
	v_cvt_pk_bf16_f32 v132, v136, v137
	v_cvt_pk_bf16_f32 v133, v138, v139
	global_store_dwordx2 v130, v[132:133], s[14:15] offset:0 nt
	v_mul_f32_e32 v136, v143, v4
	v_mul_f32_e32 v137, v143, v5
	v_mul_f32_e32 v138, v143, v6
	v_mul_f32_e32 v139, v143, v7
	v_fma_f32 v136, v136, v68, v100
	v_fma_f32 v137, v137, v69, v101
	v_fma_f32 v138, v138, v70, v102
	v_fma_f32 v139, v139, v71, v103
	v_cvt_pk_bf16_f32 v134, v136, v137
	v_cvt_pk_bf16_f32 v135, v138, v139
	global_store_dwordx2 v130, v[134:135], s[14:15] offset:512 nt
	v_mul_f32_e32 v136, v143, v8
	v_mul_f32_e32 v137, v143, v9
	v_mul_f32_e32 v138, v143, v10
	v_mul_f32_e32 v139, v143, v11
	v_fma_f32 v136, v136, v72, v104
	v_fma_f32 v137, v137, v73, v105
	v_fma_f32 v138, v138, v74, v106
	v_fma_f32 v139, v139, v75, v107
	v_cvt_pk_bf16_f32 v132, v136, v137
	v_cvt_pk_bf16_f32 v133, v138, v139
	global_store_dwordx2 v130, v[132:133], s[14:15] offset:1024 nt
	v_mul_f32_e32 v136, v143, v12
	v_mul_f32_e32 v137, v143, v13
	v_mul_f32_e32 v138, v143, v14
	v_mul_f32_e32 v139, v143, v15
	v_fma_f32 v136, v136, v76, v108
	v_fma_f32 v137, v137, v77, v109
	v_fma_f32 v138, v138, v78, v110
	v_fma_f32 v139, v139, v79, v111
	v_cvt_pk_bf16_f32 v134, v136, v137
	v_cvt_pk_bf16_f32 v135, v138, v139
	global_store_dwordx2 v130, v[134:135], s[14:15] offset:1536 nt
	v_mul_f32_e32 v136, v143, v16
	v_mul_f32_e32 v137, v143, v17
	v_mul_f32_e32 v138, v143, v18
	v_mul_f32_e32 v139, v143, v19
	v_fma_f32 v136, v136, v80, v112
	v_fma_f32 v137, v137, v81, v113
	v_fma_f32 v138, v138, v82, v114
	v_fma_f32 v139, v139, v83, v115
	v_cvt_pk_bf16_f32 v132, v136, v137
	v_cvt_pk_bf16_f32 v133, v138, v139
	global_store_dwordx2 v130, v[132:133], s[14:15] offset:2048 nt
	v_mul_f32_e32 v136, v143, v20
	v_mul_f32_e32 v137, v143, v21
	v_mul_f32_e32 v138, v143, v22
	v_mul_f32_e32 v139, v143, v23
	v_fma_f32 v136, v136, v84, v116
	v_fma_f32 v137, v137, v85, v117
	v_fma_f32 v138, v138, v86, v118
	v_fma_f32 v139, v139, v87, v119
	v_cvt_pk_bf16_f32 v134, v136, v137
	v_cvt_pk_bf16_f32 v135, v138, v139
	global_store_dwordx2 v130, v[134:135], s[14:15] offset:2560 nt
	v_mul_f32_e32 v136, v143, v24
	v_mul_f32_e32 v137, v143, v25
	v_mul_f32_e32 v138, v143, v26
	v_mul_f32_e32 v139, v143, v27
	v_fma_f32 v136, v136, v88, v120
	v_fma_f32 v137, v137, v89, v121
	v_fma_f32 v138, v138, v90, v122
	v_fma_f32 v139, v139, v91, v123
	v_cvt_pk_bf16_f32 v132, v136, v137
	v_cvt_pk_bf16_f32 v133, v138, v139
	global_store_dwordx2 v130, v[132:133], s[14:15] offset:3072 nt
	v_mul_f32_e32 v136, v143, v28
	v_mul_f32_e32 v137, v143, v29
	v_mul_f32_e32 v138, v143, v30
	v_mul_f32_e32 v139, v143, v31
	v_fma_f32 v136, v136, v92, v124
	v_fma_f32 v137, v137, v93, v125
	v_fma_f32 v138, v138, v94, v126
	v_fma_f32 v139, v139, v95, v127
	v_cvt_pk_bf16_f32 v134, v136, v137
	v_cvt_pk_bf16_f32 v135, v138, v139
	global_store_dwordx2 v130, v[134:135], s[14:15] offset:3584 nt
	s_add_i32 s4, s6, 8
	s_cmp_lt_u32 s4, 0x4000
	s_cselect_b32 s10, s68, s72
	s_cselect_b32 s11, s69, s73
	s_cselect_b32 s5, 0, 0x4000
	s_sub_i32 s5, s4, s5
	s_lshl_b32 s5, s5, 13
	s_add_u32 s10, s10, s5
	s_addc_u32 s11, s11, 0
	global_load_dwordx4 v[0:3], v128, s[10:11] offset:0 nt
	global_load_dwordx4 v[4:7], v128, s[10:11] offset:1024 nt
	global_load_dwordx4 v[8:11], v128, s[10:11] offset:2048 nt
	global_load_dwordx4 v[12:15], v128, s[10:11] offset:3072 nt
	global_load_dwordx4 v[16:19], v129, s[10:11] offset:0 nt
	global_load_dwordx4 v[20:23], v129, s[10:11] offset:1024 nt
	global_load_dwordx4 v[24:27], v129, s[10:11] offset:2048 nt
	global_load_dwordx4 v[28:31], v129, s[10:11] offset:3072 nt
	s_add_i32 s4, s6, 7
	s_add_i32 s4, s6, 7
	s_lshr_b32 s8, s4, 11
	s_cmp_lt_u32 s4, 0x4000
	s_cselect_b32 s8, s8, 8
	s_cmp_eq_u32 s8, s7
	s_cbranch_scc1 .Lp1_np7
; __device__ __forceinline__ unsigned cvt_pk_bf16(float lo, float hi) { unsigned r; asm volatile("v_cvt_pk_bf16_f32 %0, %1, %2" : "=v"(r) : "v"(lo), "v"(hi)); return r; }
; __device__ __forceinline__ float sumsq8(const f32x4 (&v)[8]) {
;     float s = 0.f;
; #pragma unroll
;     for (int j = 0; j < 8; ++j) s += (v[j][0] * v[j][0] + v[j][1] * v[j][1]) + (v[j][2] * v[j][2] + v[j][3] * v[j][3]);
;     return wave_sum(s);
; }
; __device__ __forceinline__ void modulate_store(const f32x4 (&v)[8], float rstd, const float* pn, const float* modr, bf16_t* orow, int lane) {
; #pragma unroll
;     for (int j = 0; j < 8; ++j) { const int col = 4 * lane + 256 * j;
;         const f32x4 g = *(const f32x4*)(pn + col), sh = *(const f32x4*)(modr + col), sc = *(const f32x4*)(modr + DM + col);
;         const f32x4 hh = v[j] * rstd * g * (sc + 1.f) + sh;
;         u32x2 w; w.x = cvt_pk_bf16(hh[0], hh[1]); w.y = cvt_pk_bf16(hh[2], hh[3]);
	s_mov_b32 s7, s8
	s_add_i32 s5, s8, 0
	s_mul_i32 s5, s5, 0x6000
	s_add_u32 s24, s84, s5
	s_addc_u32 s25, s85, 0
	s_add_u32 s24, s24, 0x2000
	s_addc_u32 s25, s25, 0
	s_add_i32 s5, s8, 0
	s_mul_i32 s5, s5, 0x6000
	s_add_u32 s16, s84, s5
	s_addc_u32 s17, s85, 0
	s_add_u32 s18, s80, 0x0
	s_addc_u32 s19, s81, 0
	global_load_dwordx4 v[64:67], v128, s[18:19] offset:0
	global_load_dwordx4 v[96:99], v128, s[16:17] offset:0
	global_load_dwordx4 v[68:71], v128, s[18:19] offset:1024
	global_load_dwordx4 v[100:103], v128, s[16:17] offset:1024
	global_load_dwordx4 v[72:75], v128, s[18:19] offset:2048
	global_load_dwordx4 v[104:107], v128, s[16:17] offset:2048
	global_load_dwordx4 v[76:79], v128, s[18:19] offset:3072
	global_load_dwordx4 v[108:111], v128, s[16:17] offset:3072
	global_load_dwordx4 v[80:83], v129, s[18:19] offset:0
	global_load_dwordx4 v[112:115], v129, s[16:17] offset:0
	global_load_dwordx4 v[84:87], v129, s[18:19] offset:1024
	global_load_dwordx4 v[116:119], v129, s[16:17] offset:1024
	global_load_dwordx4 v[88:91], v129, s[18:19] offset:2048
	global_load_dwordx4 v[120:123], v129, s[16:17] offset:2048
	global_load_dwordx4 v[92:95], v129, s[18:19] offset:3072
	global_load_dwordx4 v[124:127], v129, s[16:17] offset:3072
	global_load_dwordx4 v[136:139], v128, s[24:25] offset:0
	s_waitcnt vmcnt(0)
	v_add_f32_e32 v136, 1.0, v136
	v_add_f32_e32 v137, 1.0, v137
	v_add_f32_e32 v138, 1.0, v138
	v_add_f32_e32 v139, 1.0, v139
	v_mul_f32_e32 v64, v64, v136
	v_mul_f32_e32 v65, v65, v137
	v_mul_f32_e32 v66, v66, v138
	v_mul_f32_e32 v67, v67, v139
	global_load_dwordx4 v[136:139], v128, s[24:25] offset:1024
	s_waitcnt vmcnt(0)
	v_add_f32_e32 v136, 1.0, v136
	v_add_f32_e32 v137, 1.0, v137
	v_add_f32_e32 v138, 1.0, v138
	v_add_f32_e32 v139, 1.0, v139
	v_mul_f32_e32 v68, v68, v136
	v_mul_f32_e32 v69, v69, v137
	v_mul_f32_e32 v70, v70, v138
	v_mul_f32_e32 v71, v71, v139
	global_load_dwordx4 v[136:139], v128, s[24:25] offset:2048
	s_waitcnt vmcnt(0)
	v_add_f32_e32 v136, 1.0, v136
	v_add_f32_e32 v137, 1.0, v137
	v_add_f32_e32 v138, 1.0, v138
	v_add_f32_e32 v139, 1.0, v139
	v_mul_f32_e32 v72, v72, v136
	v_mul_f32_e32 v73, v73, v137
	v_mul_f32_e32 v74, v74, v138
	v_mul_f32_e32 v75, v75, v139
	global_load_dwordx4 v[136:139], v128, s[24:25] offset:3072
	s_waitcnt vmcnt(0)
	v_add_f32_e32 v136, 1.0, v136
	v_add_f32_e32 v137, 1.0, v137
	v_add_f32_e32 v138, 1.0, v138
	v_add_f32_e32 v139, 1.0, v139
	v_mul_f32_e32 v76, v76, v136
	v_mul_f32_e32 v77, v77, v137
	v_mul_f32_e32 v78, v78, v138
	v_mul_f32_e32 v79, v79, v139
	global_load_dwordx4 v[136:139], v129, s[24:25] offset:0
	s_waitcnt vmcnt(0)
	v_add_f32_e32 v136, 1.0, v136
	v_add_f32_e32 v137, 1.0, v137
	v_add_f32_e32 v138, 1.0, v138
	v_add_f32_e32 v139, 1.0, v139
	v_mul_f32_e32 v80, v80, v136
	v_mul_f32_e32 v81, v81, v137
	v_mul_f32_e32 v82, v82, v138
	v_mul_f32_e32 v83, v83, v139
	global_load_dwordx4 v[136:139], v129, s[24:25] offset:1024
	s_waitcnt vmcnt(0)
	v_add_f32_e32 v136, 1.0, v136
	v_add_f32_e32 v137, 1.0, v137
	v_add_f32_e32 v138, 1.0, v138
	v_add_f32_e32 v139, 1.0, v139
	v_mul_f32_e32 v84, v84, v136
	v_mul_f32_e32 v85, v85, v137
	v_mul_f32_e32 v86, v86, v138
	v_mul_f32_e32 v87, v87, v139
	global_load_dwordx4 v[136:139], v129, s[24:25] offset:2048
	s_waitcnt vmcnt(0)
	v_add_f32_e32 v136, 1.0, v136
	v_add_f32_e32 v137, 1.0, v137
	v_add_f32_e32 v138, 1.0, v138
	v_add_f32_e32 v139, 1.0, v139
	v_mul_f32_e32 v88, v88, v136
	v_mul_f32_e32 v89, v89, v137
	v_mul_f32_e32 v90, v90, v138
	v_mul_f32_e32 v91, v91, v139
	global_load_dwordx4 v[136:139], v129, s[24:25] offset:3072
	s_waitcnt vmcnt(0)
	v_add_f32_e32 v136, 1.0, v136
	v_add_f32_e32 v137, 1.0, v137
	v_add_f32_e32 v138, 1.0, v138
	v_add_f32_e32 v139, 1.0, v139
	v_mul_f32_e32 v92, v92, v136
	v_mul_f32_e32 v93, v93, v137
	v_mul_f32_e32 v94, v94, v138
	v_mul_f32_e32 v95, v95, v139
.Lp1_np7:
	s_waitcnt vmcnt(16)
	v_mul_f32_e32 v140, v32, v32
	v_mul_f32_e32 v141, v33, v33
	v_fmac_f32_e32 v140, v34, v34
	v_fmac_f32_e32 v141, v35, v35
	v_fmac_f32_e32 v140, v36, v36
	v_fmac_f32_e32 v141, v37, v37
	v_fmac_f32_e32 v140, v38, v38
	v_fmac_f32_e32 v141, v39, v39
	v_fmac_f32_e32 v140, v40, v40
	v_fmac_f32_e32 v141, v41, v41
	v_fmac_f32_e32 v140, v42, v42
	v_fmac_f32_e32 v141, v43, v43
	v_fmac_f32_e32 v140, v44, v44
	v_fmac_f32_e32 v141, v45, v45
	v_fmac_f32_e32 v140, v46, v46
	v_fmac_f32_e32 v141, v47, v47
	v_fmac_f32_e32 v140, v48, v48
	v_fmac_f32_e32 v141, v49, v49
	v_fmac_f32_e32 v140, v50, v50
	v_fmac_f32_e32 v141, v51, v51
	v_fmac_f32_e32 v140, v52, v52
	v_fmac_f32_e32 v141, v53, v53
	v_fmac_f32_e32 v140, v54, v54
	v_fmac_f32_e32 v141, v55, v55
	v_fmac_f32_e32 v140, v56, v56
	v_fmac_f32_e32 v141, v57, v57
	v_fmac_f32_e32 v140, v58, v58
	v_fmac_f32_e32 v141, v59, v59
	v_fmac_f32_e32 v140, v60, v60
	v_fmac_f32_e32 v141, v61, v61
	v_fmac_f32_e32 v140, v62, v62
	v_fmac_f32_e32 v141, v63, v63
	v_add_f32_e32 v140, v140, v141
	s_nop 1
	v_add_f32_dpp v142, v140, v140 quad_perm:[1,0,3,2] row_mask:0xf bank_mask:0xf
	s_nop 1
	v_add_f32_dpp v142, v142, v142 quad_perm:[2,3,0,1] row_mask:0xf bank_mask:0xf
	s_nop 1
	v_add_f32_dpp v142, v142, v142 row_half_mirror row_mask:0xf bank_mask:0xf
	s_nop 1
	v_add_f32_dpp v142, v142, v142 row_mirror row_mask:0xf bank_mask:0xf
	s_nop 1
	v_readlane_b32 s20, v142, 0
	v_readlane_b32 s21, v142, 16
	v_readlane_b32 s22, v142, 32
	v_readlane_b32 s23, v142, 48
	s_nop 1
	v_mov_b32_e32 v143, s20
	v_add_f32_e32 v143, s21, v143
	v_add_f32_e32 v143, s22, v143
	v_add_f32_e32 v143, s23, v143
	v_fmamk_f32 v143, v143, 0x3a000000, v131
	v_rsq_f32_e32 v143, v143
	s_nop 0
	s_add_i32 s4, s6, 7
	s_lshl_b32 s5, s4, 12
	s_add_u32 s14, s84, s5
	s_addc_u32 s15, s85, 0
; __device__ __forceinline__ unsigned cvt_pk_bf16(float lo, float hi) { unsigned r; asm volatile("v_cvt_pk_bf16_f32 %0, %1, %2" : "=v"(r) : "v"(lo), "v"(hi)); return r; }
; __device__ __forceinline__ void modulate_store(const f32x4 (&v)[8], float rstd, const float* pn, const float* modr, bf16_t* orow, int lane) {
; #pragma unroll
;     for (int j = 0; j < 8; ++j) { const int col = 4 * lane + 256 * j;
;         const f32x4 g = *(const f32x4*)(pn + col), sh = *(const f32x4*)(modr + col), sc = *(const f32x4*)(modr + DM + col);
;         const f32x4 hh = v[j] * rstd * g * (sc + 1.f) + sh;
;         u32x2 w; w.x = cvt_pk_bf16(hh[0], hh[1]); w.y = cvt_pk_bf16(hh[2], hh[3]);
;         *(u32x2*)(orow + col) = w; }
; }
; __global__ void __launch_bounds__(NWAVES * 64, 2) mk_fwd(Args args) {
;     ...
;         for (int row0 = F.gw * 3; row0 < MT; row0 += F.NGW * 3) {
;             f32x4 v[3][8];
; #pragma unroll
;             for (int q = 0; q < 3; ++q) { const int row = row0 + q; const float* src = row < ML ? x + (size_t)row * DM : ctx + (size_t)(row - ML) * DM; load_row_f32(src, F.lane, v[q]); }
; #pragma unroll
;             for (int q = 0; q < 3; ++q) { const int row = row0 + q; const int r = row < ML ? row / SEQ : 8;
;                 const float rstd = __builtin_amdgcn_rsqf(sumsq8(v[q]) * (1.f / DM) + EPS);
;                 modulate_store(v[q], rstd, pre_norm, mod + (size_t)r * 6144, H + (size_t)row * DM, F.lane); }
	s_add_u32 s14, s14, 0x4000000
	s_addc_u32 s15, s15, 0
	v_mul_f32_e32 v136, v143, v32
	v_mul_f32_e32 v137, v143, v33
	v_mul_f32_e32 v138, v143, v34
	v_mul_f32_e32 v139, v143, v35
	v_fma_f32 v136, v136, v64, v96
	v_fma_f32 v137, v137, v65, v97
	v_fma_f32 v138, v138, v66, v98
	v_fma_f32 v139, v139, v67, v99
	v_cvt_pk_bf16_f32 v132, v136, v137
	v_cvt_pk_bf16_f32 v133, v138, v139
	global_store_dwordx2 v130, v[132:133], s[14:15] offset:0 nt
	v_mul_f32_e32 v136, v143, v36
	v_mul_f32_e32 v137, v143, v37
	v_mul_f32_e32 v138, v143, v38
	v_mul_f32_e32 v139, v143, v39
	v_fma_f32 v136, v136, v68, v100
	v_fma_f32 v137, v137, v69, v101
	v_fma_f32 v138, v138, v70, v102
	v_fma_f32 v139, v139, v71, v103
	v_cvt_pk_bf16_f32 v134, v136, v137
	v_cvt_pk_bf16_f32 v135, v138, v139
	global_store_dwordx2 v130, v[134:135], s[14:15] offset:512 nt
	v_mul_f32_e32 v136, v143, v40
	v_mul_f32_e32 v137, v143, v41
	v_mul_f32_e32 v138, v143, v42
	v_mul_f32_e32 v139, v143, v43
	v_fma_f32 v136, v136, v72, v104
	v_fma_f32 v137, v137, v73, v105
	v_fma_f32 v138, v138, v74, v106
	v_fma_f32 v139, v139, v75, v107
	v_cvt_pk_bf16_f32 v132, v136, v137
	v_cvt_pk_bf16_f32 v133, v138, v139
	global_store_dwordx2 v130, v[132:133], s[14:15] offset:1024 nt
	v_mul_f32_e32 v136, v143, v44
	v_mul_f32_e32 v137, v143, v45
	v_mul_f32_e32 v138, v143, v46
	v_mul_f32_e32 v139, v143, v47
	v_fma_f32 v136, v136, v76, v108
	v_fma_f32 v137, v137, v77, v109
	v_fma_f32 v138, v138, v78, v110
	v_fma_f32 v139, v139, v79, v111
	v_cvt_pk_bf16_f32 v134, v136, v137
	v_cvt_pk_bf16_f32 v135, v138, v139
	global_store_dwordx2 v130, v[134:135], s[14:15] offset:1536 nt
	v_mul_f32_e32 v136, v143, v48
	v_mul_f32_e32 v137, v143, v49
	v_mul_f32_e32 v138, v143, v50
	v_mul_f32_e32 v139, v143, v51
	v_fma_f32 v136, v136, v80, v112
	v_fma_f32 v137, v137, v81, v113
	v_fma_f32 v138, v138, v82, v114
	v_fma_f32 v139, v139, v83, v115
	v_cvt_pk_bf16_f32 v132, v136, v137
	v_cvt_pk_bf16_f32 v133, v138, v139
	global_store_dwordx2 v130, v[132:133], s[14:15] offset:2048 nt
	v_mul_f32_e32 v136, v143, v52
	v_mul_f32_e32 v137, v143, v53
	v_mul_f32_e32 v138, v143, v54
	v_mul_f32_e32 v139, v143, v55
	v_fma_f32 v136, v136, v84, v116
	v_fma_f32 v137, v137, v85, v117
	v_fma_f32 v138, v138, v86, v118
	v_fma_f32 v139, v139, v87, v119
	v_cvt_pk_bf16_f32 v134, v136, v137
	v_cvt_pk_bf16_f32 v135, v138, v139
	global_store_dwordx2 v130, v[134:135], s[14:15] offset:2560 nt
	v_mul_f32_e32 v136, v143, v56
	v_mul_f32_e32 v137, v143, v57
	v_mul_f32_e32 v138, v143, v58
	v_mul_f32_e32 v139, v143, v59
	v_fma_f32 v136, v136, v88, v120
	v_fma_f32 v137, v137, v89, v121
	v_fma_f32 v138, v138, v90, v122
	v_fma_f32 v139, v139, v91, v123
	v_cvt_pk_bf16_f32 v132, v136, v137
	v_cvt_pk_bf16_f32 v133, v138, v139
	global_store_dwordx2 v130, v[132:133], s[14:15] offset:3072 nt
	v_mul_f32_e32 v136, v143, v60
	v_mul_f32_e32 v137, v143, v61
	v_mul_f32_e32 v138, v143, v62
	v_mul_f32_e32 v139, v143, v63
	v_fma_f32 v136, v136, v92, v124
	v_fma_f32 v137, v137, v93, v125
	v_fma_f32 v138, v138, v94, v126
	v_fma_f32 v139, v139, v95, v127
	v_cvt_pk_bf16_f32 v134, v136, v137
	v_cvt_pk_bf16_f32 v135, v138, v139
	global_store_dwordx2 v130, v[134:135], s[14:15] offset:3584 nt
	s_add_i32 s4, s6, 8
	s_add_i32 s4, s6, 8
	s_lshr_b32 s8, s4, 11
	s_cmp_lt_u32 s4, 0x4000
	s_cselect_b32 s8, s8, 8
	s_cmp_eq_u32 s8, s7
	s_cbranch_scc1 .Lp1_np8
	s_mov_b32 s7, s8
	s_add_i32 s5, s8, 0
	s_mul_i32 s5, s5, 0x6000
	s_add_u32 s24, s84, s5
	s_addc_u32 s25, s85, 0
	s_add_u32 s24, s24, 0x2000
	s_addc_u32 s25, s25, 0
	s_add_i32 s5, s8, 0
	s_mul_i32 s5, s5, 0x6000
	s_add_u32 s16, s84, s5
	s_addc_u32 s17, s85, 0
	s_add_u32 s18, s80, 0x0
	s_addc_u32 s19, s81, 0
	global_load_dwordx4 v[64:67], v128, s[18:19] offset:0
	global_load_dwordx4 v[96:99], v128, s[16:17] offset:0
	global_load_dwordx4 v[68:71], v128, s[18:19] offset:1024
	global_load_dwordx4 v[100:103], v128, s[16:17] offset:1024
	global_load_dwordx4 v[72:75], v128, s[18:19] offset:2048
	global_load_dwordx4 v[104:107], v128, s[16:17] offset:2048
	global_load_dwordx4 v[76:79], v128, s[18:19] offset:3072
	global_load_dwordx4 v[108:111], v128, s[16:17] offset:3072
	global_load_dwordx4 v[80:83], v129, s[18:19] offset:0
	global_load_dwordx4 v[112:115], v129, s[16:17] offset:0
	global_load_dwordx4 v[84:87], v129, s[18:19] offset:1024
	global_load_dwordx4 v[116:119], v129, s[16:17] offset:1024
	global_load_dwordx4 v[88:91], v129, s[18:19] offset:2048
	global_load_dwordx4 v[120:123], v129, s[16:17] offset:2048
	global_load_dwordx4 v[92:95], v129, s[18:19] offset:3072
	global_load_dwordx4 v[124:127], v129, s[16:17] offset:3072
	global_load_dwordx4 v[136:139], v128, s[24:25] offset:0
	s_waitcnt vmcnt(0)
	v_add_f32_e32 v136, 1.0, v136
	v_add_f32_e32 v137, 1.0, v137
	v_add_f32_e32 v138, 1.0, v138
	v_add_f32_e32 v139, 1.0, v139
	v_mul_f32_e32 v64, v64, v136
	v_mul_f32_e32 v65, v65, v137
	v_mul_f32_e32 v66, v66, v138
	v_mul_f32_e32 v67, v67, v139
	global_load_dwordx4 v[136:139], v128, s[24:25] offset:1024
	s_waitcnt vmcnt(0)
	v_add_f32_e32 v136, 1.0, v136
	v_add_f32_e32 v137, 1.0, v137
	v_add_f32_e32 v138, 1.0, v138
	v_add_f32_e32 v139, 1.0, v139
	v_mul_f32_e32 v68, v68, v136
	v_mul_f32_e32 v69, v69, v137
	v_mul_f32_e32 v70, v70, v138
	v_mul_f32_e32 v71, v71, v139
	global_load_dwordx4 v[136:139], v128, s[24:25] offset:2048
	s_waitcnt vmcnt(0)
	v_add_f32_e32 v136, 1.0, v136
	v_add_f32_e32 v137, 1.0, v137
	v_add_f32_e32 v138, 1.0, v138
	v_add_f32_e32 v139, 1.0, v139
	v_mul_f32_e32 v72, v72, v136
	v_mul_f32_e32 v73, v73, v137
	v_mul_f32_e32 v74, v74, v138
	v_mul_f32_e32 v75, v75, v139
	global_load_dwordx4 v[136:139], v128, s[24:25] offset:3072
	s_waitcnt vmcnt(0)
; __device__ __forceinline__ unsigned cvt_pk_bf16(float lo, float hi) { unsigned r; asm volatile("v_cvt_pk_bf16_f32 %0, %1, %2" : "=v"(r) : "v"(lo), "v"(hi)); return r; }
; __device__ __forceinline__ float sumsq8(const f32x4 (&v)[8]) {
;     float s = 0.f;
; #pragma unroll
;     for (int j = 0; j < 8; ++j) s += (v[j][0] * v[j][0] + v[j][1] * v[j][1]) + (v[j][2] * v[j][2] + v[j][3] * v[j][3]);
;     return wave_sum(s);
; }
; __device__ __forceinline__ void modulate_store(const f32x4 (&v)[8], float rstd, const float* pn, const float* modr, bf16_t* orow, int lane) {
; #pragma unroll
;     for (int j = 0; j < 8; ++j) { const int col = 4 * lane + 256 * j;
;         const f32x4 g = *(const f32x4*)(pn + col), sh = *(const f32x4*)(modr + col), sc = *(const f32x4*)(modr + DM + col);
;         const f32x4 hh = v[j] * rstd * g * (sc + 1.f) + sh;
;         u32x2 w; w.x = cvt_pk_bf16(hh[0], hh[1]); w.y = cvt_pk_bf16(hh[2], hh[3]);
;         *(u32x2*)(orow + col) = w; }
; }
	v_add_f32_e32 v136, 1.0, v136
	v_add_f32_e32 v137, 1.0, v137
	v_add_f32_e32 v138, 1.0, v138
	v_add_f32_e32 v139, 1.0, v139
	v_mul_f32_e32 v76, v76, v136
	v_mul_f32_e32 v77, v77, v137
	v_mul_f32_e32 v78, v78, v138
	v_mul_f32_e32 v79, v79, v139
	global_load_dwordx4 v[136:139], v129, s[24:25] offset:0
	s_waitcnt vmcnt(0)
	v_add_f32_e32 v136, 1.0, v136
	v_add_f32_e32 v137, 1.0, v137
	v_add_f32_e32 v138, 1.0, v138
	v_add_f32_e32 v139, 1.0, v139
	v_mul_f32_e32 v80, v80, v136
	v_mul_f32_e32 v81, v81, v137
	v_mul_f32_e32 v82, v82, v138
	v_mul_f32_e32 v83, v83, v139
	global_load_dwordx4 v[136:139], v129, s[24:25] offset:1024
	s_waitcnt vmcnt(0)
	v_add_f32_e32 v136, 1.0, v136
	v_add_f32_e32 v137, 1.0, v137
	v_add_f32_e32 v138, 1.0, v138
	v_add_f32_e32 v139, 1.0, v139
	v_mul_f32_e32 v84, v84, v136
	v_mul_f32_e32 v85, v85, v137
	v_mul_f32_e32 v86, v86, v138
	v_mul_f32_e32 v87, v87, v139
	global_load_dwordx4 v[136:139], v129, s[24:25] offset:2048
	s_waitcnt vmcnt(0)
	v_add_f32_e32 v136, 1.0, v136
	v_add_f32_e32 v137, 1.0, v137
	v_add_f32_e32 v138, 1.0, v138
	v_add_f32_e32 v139, 1.0, v139
	v_mul_f32_e32 v88, v88, v136
	v_mul_f32_e32 v89, v89, v137
	v_mul_f32_e32 v90, v90, v138
	v_mul_f32_e32 v91, v91, v139
	global_load_dwordx4 v[136:139], v129, s[24:25] offset:3072
	s_waitcnt vmcnt(0)
	v_add_f32_e32 v136, 1.0, v136
	v_add_f32_e32 v137, 1.0, v137
	v_add_f32_e32 v138, 1.0, v138
	v_add_f32_e32 v139, 1.0, v139
	v_mul_f32_e32 v92, v92, v136
	v_mul_f32_e32 v93, v93, v137
	v_mul_f32_e32 v94, v94, v138
	v_mul_f32_e32 v95, v95, v139
.Lp1_np8:
	s_waitcnt vmcnt(8)
	v_mul_f32_e32 v140, v0, v0
	v_mul_f32_e32 v141, v1, v1
	v_fmac_f32_e32 v140, v2, v2
	v_fmac_f32_e32 v141, v3, v3
	v_fmac_f32_e32 v140, v4, v4
	v_fmac_f32_e32 v141, v5, v5
	v_fmac_f32_e32 v140, v6, v6
	v_fmac_f32_e32 v141, v7, v7
	v_fmac_f32_e32 v140, v8, v8
	v_fmac_f32_e32 v141, v9, v9
	v_fmac_f32_e32 v140, v10, v10
	v_fmac_f32_e32 v141, v11, v11
	v_fmac_f32_e32 v140, v12, v12
	v_fmac_f32_e32 v141, v13, v13
	v_fmac_f32_e32 v140, v14, v14
	v_fmac_f32_e32 v141, v15, v15
	v_fmac_f32_e32 v140, v16, v16
	v_fmac_f32_e32 v141, v17, v17
	v_fmac_f32_e32 v140, v18, v18
	v_fmac_f32_e32 v141, v19, v19
	v_fmac_f32_e32 v140, v20, v20
	v_fmac_f32_e32 v141, v21, v21
	v_fmac_f32_e32 v140, v22, v22
	v_fmac_f32_e32 v141, v23, v23
	v_fmac_f32_e32 v140, v24, v24
	v_fmac_f32_e32 v141, v25, v25
	v_fmac_f32_e32 v140, v26, v26
	v_fmac_f32_e32 v141, v27, v27
	v_fmac_f32_e32 v140, v28, v28
	v_fmac_f32_e32 v141, v29, v29
	v_fmac_f32_e32 v140, v30, v30
	v_fmac_f32_e32 v141, v31, v31
	v_add_f32_e32 v140, v140, v141
	s_nop 1
	v_add_f32_dpp v142, v140, v140 quad_perm:[1,0,3,2] row_mask:0xf bank_mask:0xf
	s_nop 1
	v_add_f32_dpp v142, v142, v142 quad_perm:[2,3,0,1] row_mask:0xf bank_mask:0xf
	s_nop 1
	v_add_f32_dpp v142, v142, v142 row_half_mirror row_mask:0xf bank_mask:0xf
	s_nop 1
	v_add_f32_dpp v142, v142, v142 row_mirror row_mask:0xf bank_mask:0xf
	s_nop 1
	v_readlane_b32 s20, v142, 0
	v_readlane_b32 s21, v142, 16
	v_readlane_b32 s22, v142, 32
	v_readlane_b32 s23, v142, 48
	s_nop 1
	v_mov_b32_e32 v143, s20
	v_add_f32_e32 v143, s21, v143
	v_add_f32_e32 v143, s22, v143
	v_add_f32_e32 v143, s23, v143
	v_fmamk_f32 v143, v143, 0x3a000000, v131
	v_rsq_f32_e32 v143, v143
	s_nop 0
	s_add_i32 s4, s6, 8
	s_lshl_b32 s5, s4, 12
	s_add_u32 s14, s84, s5
	s_addc_u32 s15, s85, 0
	s_add_u32 s14, s14, 0x4000000
	s_addc_u32 s15, s15, 0
	v_mul_f32_e32 v136, v143, v0
	v_mul_f32_e32 v137, v143, v1
	v_mul_f32_e32 v138, v143, v2
	v_mul_f32_e32 v139, v143, v3
	v_fma_f32 v136, v136, v64, v96
	v_fma_f32 v137, v137, v65, v97
	v_fma_f32 v138, v138, v66, v98
	v_fma_f32 v139, v139, v67, v99
	v_cvt_pk_bf16_f32 v132, v136, v137
	v_cvt_pk_bf16_f32 v133, v138, v139
	global_store_dwordx2 v130, v[132:133], s[14:15] offset:0 nt
	v_mul_f32_e32 v136, v143, v4
	v_mul_f32_e32 v137, v143, v5
	v_mul_f32_e32 v138, v143, v6
	v_mul_f32_e32 v139, v143, v7
	v_fma_f32 v136, v136, v68, v100
	v_fma_f32 v137, v137, v69, v101
	v_fma_f32 v138, v138, v70, v102
	v_fma_f32 v139, v139, v71, v103
	v_cvt_pk_bf16_f32 v134, v136, v137
	v_cvt_pk_bf16_f32 v135, v138, v139
	global_store_dwordx2 v130, v[134:135], s[14:15] offset:512 nt
	v_mul_f32_e32 v136, v143, v8
	v_mul_f32_e32 v137, v143, v9
	v_mul_f32_e32 v138, v143, v10
	v_mul_f32_e32 v139, v143, v11
	v_fma_f32 v136, v136, v72, v104
	v_fma_f32 v137, v137, v73, v105
	v_fma_f32 v138, v138, v74, v106
	v_fma_f32 v139, v139, v75, v107
	v_cvt_pk_bf16_f32 v132, v136, v137
	v_cvt_pk_bf16_f32 v133, v138, v139
	global_store_dwordx2 v130, v[132:133], s[14:15] offset:1024 nt
	v_mul_f32_e32 v136, v143, v12
	v_mul_f32_e32 v137, v143, v13
	v_mul_f32_e32 v138, v143, v14
	v_mul_f32_e32 v139, v143, v15
	v_fma_f32 v136, v136, v76, v108
	v_fma_f32 v137, v137, v77, v109
	v_fma_f32 v138, v138, v78, v110
	v_fma_f32 v139, v139, v79, v111
	v_cvt_pk_bf16_f32 v134, v136, v137
	v_cvt_pk_bf16_f32 v135, v138, v139
	global_store_dwordx2 v130, v[134:135], s[14:15] offset:1536 nt
	v_mul_f32_e32 v136, v143, v16
	v_mul_f32_e32 v137, v143, v17
	v_mul_f32_e32 v138, v143, v18
	v_mul_f32_e32 v139, v143, v19
	v_fma_f32 v136, v136, v80, v112
	v_fma_f32 v137, v137, v81, v113
	v_fma_f32 v138, v138, v82, v114
	v_fma_f32 v139, v139, v83, v115
	v_cvt_pk_bf16_f32 v132, v136, v137
	v_cvt_pk_bf16_f32 v133, v138, v139
	global_store_dwordx2 v130, v[132:133], s[14:15] offset:2048 nt
	v_mul_f32_e32 v136, v143, v20
	v_mul_f32_e32 v137, v143, v21
	v_mul_f32_e32 v138, v143, v22
	v_mul_f32_e32 v139, v143, v23
	v_fma_f32 v136, v136, v84, v116
	v_fma_f32 v137, v137, v85, v117
	v_fma_f32 v138, v138, v86, v118
	v_fma_f32 v139, v139, v87, v119
	v_cvt_pk_bf16_f32 v134, v136, v137
	v_cvt_pk_bf16_f32 v135, v138, v139
	global_store_dwordx2 v130, v[134:135], s[14:15] offset:2560 nt
	v_mul_f32_e32 v136, v143, v24
	v_mul_f32_e32 v137, v143, v25
	v_mul_f32_e32 v138, v143, v26
	v_mul_f32_e32 v139, v143, v27
	v_fma_f32 v136, v136, v88, v120
	v_fma_f32 v137, v137, v89, v121
	v_fma_f32 v138, v138, v90, v122
	v_fma_f32 v139, v139, v91, v123
	v_cvt_pk_bf16_f32 v132, v136, v137
	v_cvt_pk_bf16_f32 v133, v138, v139
	global_store_dwordx2 v130, v[132:133], s[14:15] offset:3072 nt
	v_mul_f32_e32 v136, v143, v28
	v_mul_f32_e32 v137, v143, v29
	v_mul_f32_e32 v138, v143, v30
	v_mul_f32_e32 v139, v143, v31
	v_fma_f32 v136, v136, v92, v124
	v_fma_f32 v137, v137, v93, v125
	v_fma_f32 v138, v138, v94, v126
	v_fma_f32 v139, v139, v95, v127
	v_cvt_pk_bf16_f32 v134, v136, v137
	v_cvt_pk_bf16_f32 v135, v138, v139
	global_store_dwordx2 v130, v[134:135], s[14:15] offset:3584 nt
	s_branch .LBB0_194

; __device__ __forceinline__ float bf_lo(unsigned w) { return __uint_as_float(w << 16); }
; __device__ __forceinline__ float bf_hi(unsigned w) { return __uint_as_float(w & 0xffff0000u); }
; __global__ void __launch_bounds__(NWAVES * 64, 2) mk_fwd(Args args) {
;     ...
;             for (int q = 0; q < 3; ++q) { const int row = row0 + q; const bool lat = row < ML; const int r = lat ? row / SEQ : 8;
;                 float sy = 0.f;
; #pragma unroll
;                 for (int j = 0; j < 8; ++j) { const float a = bf_lo(yw[q][j].x), b = bf_hi(yw[q][j].x), c2 = bf_lo(yw[q][j].y), d = bf_hi(yw[q][j].y); sy += (a * a + b * b) + (c2 * c2 + d * d); }
;                 const float rsy = __builtin_amdgcn_rsqf(wave_sum(sy) * (1.f / DM) + EPS);
;                 const float* m0 = mod + (size_t)r * 6144;
; #pragma unroll
;                 for (int j = 0; j < 8; ++j) { const int col = 4 * F.lane + 256 * j; const f32x4 gt = *(const f32x4*)(m0 + 2 * DM + col), pn = *(const f32x4*)(post_norm + col);
;                     const f32x4 y4 = (f32x4){bf_lo(yw[q][j].x), bf_hi(yw[q][j].x), bf_lo(yw[q][j].y), bf_hi(yw[q][j].y)};
;                     v[q][j] = v[q][j] + gt * (y4 * rsy * pn);
.Lp6_np0:
	s_waitcnt vmcnt(16)
	v_lshlrev_b32_e32 v216, 16, v32
	v_and_b32_e32 v217, 0xffff0000, v32
	v_lshlrev_b32_e32 v218, 16, v33
	v_and_b32_e32 v219, 0xffff0000, v33
	v_mul_f32_e32 v222, v216, v216
	v_mul_f32_e32 v223, v217, v217
	v_fmac_f32_e32 v222, v218, v218
	v_fmac_f32_e32 v223, v219, v219
	v_lshlrev_b32_e32 v216, 16, v34
	v_and_b32_e32 v217, 0xffff0000, v34
	v_lshlrev_b32_e32 v218, 16, v35
	v_and_b32_e32 v219, 0xffff0000, v35
	v_fmac_f32_e32 v222, v216, v216
	v_fmac_f32_e32 v223, v217, v217
	v_fmac_f32_e32 v222, v218, v218
	v_fmac_f32_e32 v223, v219, v219
	v_lshlrev_b32_e32 v216, 16, v36
	v_and_b32_e32 v217, 0xffff0000, v36
	v_lshlrev_b32_e32 v218, 16, v37
	v_and_b32_e32 v219, 0xffff0000, v37
	v_fmac_f32_e32 v222, v216, v216
	v_fmac_f32_e32 v223, v217, v217
	v_fmac_f32_e32 v222, v218, v218
	v_fmac_f32_e32 v223, v219, v219
	v_lshlrev_b32_e32 v216, 16, v38
	v_and_b32_e32 v217, 0xffff0000, v38
	v_lshlrev_b32_e32 v218, 16, v39
	v_and_b32_e32 v219, 0xffff0000, v39
	v_fmac_f32_e32 v222, v216, v216
	v_fmac_f32_e32 v223, v217, v217
	v_fmac_f32_e32 v222, v218, v218
	v_fmac_f32_e32 v223, v219, v219
	v_lshlrev_b32_e32 v216, 16, v40
	v_and_b32_e32 v217, 0xffff0000, v40
	v_lshlrev_b32_e32 v218, 16, v41
	v_and_b32_e32 v219, 0xffff0000, v41
	v_fmac_f32_e32 v222, v216, v216
	v_fmac_f32_e32 v223, v217, v217
	v_fmac_f32_e32 v222, v218, v218
	v_fmac_f32_e32 v223, v219, v219
	v_lshlrev_b32_e32 v216, 16, v42
	v_and_b32_e32 v217, 0xffff0000, v42
	v_lshlrev_b32_e32 v218, 16, v43
	v_and_b32_e32 v219, 0xffff0000, v43
	v_fmac_f32_e32 v222, v216, v216
	v_fmac_f32_e32 v223, v217, v217
	v_fmac_f32_e32 v222, v218, v218
	v_fmac_f32_e32 v223, v219, v219
	v_lshlrev_b32_e32 v216, 16, v44
	v_and_b32_e32 v217, 0xffff0000, v44
	v_lshlrev_b32_e32 v218, 16, v45
	v_and_b32_e32 v219, 0xffff0000, v45
	v_fmac_f32_e32 v222, v216, v216
	v_fmac_f32_e32 v223, v217, v217
	v_fmac_f32_e32 v222, v218, v218
	v_fmac_f32_e32 v223, v219, v219
	v_lshlrev_b32_e32 v216, 16, v46
	v_and_b32_e32 v217, 0xffff0000, v46
	v_lshlrev_b32_e32 v218, 16, v47
	v_and_b32_e32 v219, 0xffff0000, v47
	v_fmac_f32_e32 v222, v216, v216
	v_fmac_f32_e32 v223, v217, v217
	v_fmac_f32_e32 v222, v218, v218
	v_fmac_f32_e32 v223, v219, v219
	v_add_f32_e32 v222, v222, v223
	s_nop 1
	v_add_f32_dpp v224, v222, v222 quad_perm:[1,0,3,2] row_mask:0xf bank_mask:0xf
	s_nop 1
	v_add_f32_dpp v224, v224, v224 quad_perm:[2,3,0,1] row_mask:0xf bank_mask:0xf
	s_nop 1
	v_add_f32_dpp v224, v224, v224 row_half_mirror row_mask:0xf bank_mask:0xf
	s_nop 1
	v_add_f32_dpp v224, v224, v224 row_mirror row_mask:0xf bank_mask:0xf
	s_nop 1
	v_readlane_b32 s40, v224, 0
	v_readlane_b32 s41, v224, 16
	v_readlane_b32 s42, v224, 32
	v_readlane_b32 s43, v224, 48
	s_nop 1
	v_mov_b32_e32 v225, s40
	v_add_f32_e32 v225, s41, v225
	v_add_f32_e32 v225, s42, v225
	v_add_f32_e32 v225, s43, v225
	v_fmamk_f32 v225, v225, 0x3a000000, v195
	v_rsq_f32_e32 v225, v225
	s_nop 0
	v_lshlrev_b32_e32 v216, 16, v32
	v_and_b32_e32 v217, 0xffff0000, v32
	v_lshlrev_b32_e32 v218, 16, v33
	v_and_b32_e32 v219, 0xffff0000, v33
	v_mul_f32_e32 v216, v225, v216
	v_mul_f32_e32 v217, v225, v217
	v_mul_f32_e32 v218, v225, v218
	v_mul_f32_e32 v219, v225, v219
	v_fmac_f32_e32 v0, v96, v216
	v_fmac_f32_e32 v1, v97, v217
	v_fmac_f32_e32 v2, v98, v218
	v_fmac_f32_e32 v3, v99, v219
	v_lshlrev_b32_e32 v216, 16, v34
	v_and_b32_e32 v217, 0xffff0000, v34
	v_lshlrev_b32_e32 v218, 16, v35
	v_and_b32_e32 v219, 0xffff0000, v35
	v_mul_f32_e32 v216, v225, v216
	v_mul_f32_e32 v217, v225, v217
	v_mul_f32_e32 v218, v225, v218
	v_mul_f32_e32 v219, v225, v219
	v_fmac_f32_e32 v4, v100, v216
	v_fmac_f32_e32 v5, v101, v217
	v_fmac_f32_e32 v6, v102, v218
	v_fmac_f32_e32 v7, v103, v219
	v_lshlrev_b32_e32 v216, 16, v36
	v_and_b32_e32 v217, 0xffff0000, v36
	v_lshlrev_b32_e32 v218, 16, v37
	v_and_b32_e32 v219, 0xffff0000, v37
	v_mul_f32_e32 v216, v225, v216
	v_mul_f32_e32 v217, v225, v217
	v_mul_f32_e32 v218, v225, v218
	v_mul_f32_e32 v219, v225, v219
	v_fmac_f32_e32 v8, v104, v216
	v_fmac_f32_e32 v9, v105, v217
	v_fmac_f32_e32 v10, v106, v218
	v_fmac_f32_e32 v11, v107, v219
	v_lshlrev_b32_e32 v216, 16, v38
	v_and_b32_e32 v217, 0xffff0000, v38
	v_lshlrev_b32_e32 v218, 16, v39
	v_and_b32_e32 v219, 0xffff0000, v39
	v_mul_f32_e32 v216, v225, v216
	v_mul_f32_e32 v217, v225, v217
	v_mul_f32_e32 v218, v225, v218
	v_mul_f32_e32 v219, v225, v219
	v_fmac_f32_e32 v12, v108, v216
	v_fmac_f32_e32 v13, v109, v217
	v_fmac_f32_e32 v14, v110, v218
	v_fmac_f32_e32 v15, v111, v219
	v_lshlrev_b32_e32 v216, 16, v40
	v_and_b32_e32 v217, 0xffff0000, v40
	v_lshlrev_b32_e32 v218, 16, v41
	v_and_b32_e32 v219, 0xffff0000, v41
	v_mul_f32_e32 v216, v225, v216
	v_mul_f32_e32 v217, v225, v217
	v_mul_f32_e32 v218, v225, v218
	v_mul_f32_e32 v219, v225, v219
	v_fmac_f32_e32 v16, v112, v216
	v_fmac_f32_e32 v17, v113, v217
	v_fmac_f32_e32 v18, v114, v218
	v_fmac_f32_e32 v19, v115, v219
	v_lshlrev_b32_e32 v216, 16, v42
	v_and_b32_e32 v217, 0xffff0000, v42
	v_lshlrev_b32_e32 v218, 16, v43
	v_and_b32_e32 v219, 0xffff0000, v43
	v_mul_f32_e32 v216, v225, v216
	v_mul_f32_e32 v217, v225, v217
	v_mul_f32_e32 v218, v225, v218
	v_mul_f32_e32 v219, v225, v219
	v_fmac_f32_e32 v20, v116, v216
	v_fmac_f32_e32 v21, v117, v217
	v_fmac_f32_e32 v22, v118, v218
	v_fmac_f32_e32 v23, v119, v219
	v_lshlrev_b32_e32 v216, 16, v44
	v_and_b32_e32 v217, 0xffff0000, v44
	v_lshlrev_b32_e32 v218, 16, v45
	v_and_b32_e32 v219, 0xffff0000, v45
	v_mul_f32_e32 v216, v225, v216
	v_mul_f32_e32 v217, v225, v217
	v_mul_f32_e32 v218, v225, v218
	v_mul_f32_e32 v219, v225, v219
	v_fmac_f32_e32 v24, v120, v216
	v_fmac_f32_e32 v25, v121, v217
	v_fmac_f32_e32 v26, v122, v218
; __device__ __forceinline__ unsigned cvt_pk_bf16(float lo, float hi) { unsigned r; asm volatile("v_cvt_pk_bf16_f32 %0, %1, %2" : "=v"(r) : "v"(lo), "v"(hi)); return r; }
; __device__ __forceinline__ float bf_lo(unsigned w) { return __uint_as_float(w << 16); }
; __device__ __forceinline__ float bf_hi(unsigned w) { return __uint_as_float(w & 0xffff0000u); }
; __device__ __forceinline__ void modulate_store(const f32x4 (&v)[8], float rstd, const float* pn, const float* modr, bf16_t* orow, int lane) {
; #pragma unroll
;     for (int j = 0; j < 8; ++j) { const int col = 4 * lane + 256 * j;
;         const f32x4 g = *(const f32x4*)(pn + col), sh = *(const f32x4*)(modr + col), sc = *(const f32x4*)(modr + DM + col);
;         const f32x4 hh = v[j] * rstd * g * (sc + 1.f) + sh;
;         u32x2 w; w.x = cvt_pk_bf16(hh[0], hh[1]); w.y = cvt_pk_bf16(hh[2], hh[3]);
;         *(u32x2*)(orow + col) = w; }
; __global__ void __launch_bounds__(NWAVES * 64, 2) mk_fwd(Args args) {
;     ...
;             for (int q = 0; q < 3; ++q) { const int row = row0 + q; const bool lat = row < ML; const int r = lat ? row / SEQ : 8;
;                 float sy = 0.f;
; #pragma unroll
;                 for (int j = 0; j < 8; ++j) { const float a = bf_lo(yw[q][j].x), b = bf_hi(yw[q][j].x), c2 = bf_lo(yw[q][j].y), d = bf_hi(yw[q][j].y); sy += (a * a + b * b) + (c2 * c2 + d * d); }
;                 const float rsy = __builtin_amdgcn_rsqf(wave_sum(sy) * (1.f / DM) + EPS);
;                 const float* m0 = mod + (size_t)r * 6144;
; #pragma unroll
;                 for (int j = 0; j < 8; ++j) { const int col = 4 * F.lane + 256 * j; const f32x4 gt = *(const f32x4*)(m0 + 2 * DM + col), pn = *(const f32x4*)(post_norm + col);
;                     const f32x4 y4 = (f32x4){bf_lo(yw[q][j].x), bf_hi(yw[q][j].x), bf_lo(yw[q][j].y), bf_hi(yw[q][j].y)};
;                     v[q][j] = v[q][j] + gt * (y4 * rsy * pn);
;                     if (lat) *(f32x4*)(args.out + (size_t)row * DM + col) = v[q][j]; }
;                 const float rstd = __builtin_amdgcn_rsqf(sumsq8(v[q]) * (1.f / DM) + EPS);
;                 modulate_store(v[q], rstd, pre_norm + DM, mod + (size_t)(9 + r) * 6144, H + (size_t)row * DM, F.lane); }
	v_fmac_f32_e32 v27, v123, v219
	v_lshlrev_b32_e32 v216, 16, v46
	v_and_b32_e32 v217, 0xffff0000, v46
	v_lshlrev_b32_e32 v218, 16, v47
	v_and_b32_e32 v219, 0xffff0000, v47
	v_mul_f32_e32 v216, v225, v216
	v_mul_f32_e32 v217, v225, v217
	v_mul_f32_e32 v218, v225, v218
	v_mul_f32_e32 v219, v225, v219
	v_fmac_f32_e32 v28, v124, v216
	v_fmac_f32_e32 v29, v125, v217
	v_fmac_f32_e32 v30, v126, v218
	v_fmac_f32_e32 v31, v127, v219
	v_mul_f32_e32 v222, v0, v0
	v_mul_f32_e32 v223, v1, v1
	v_fmac_f32_e32 v222, v2, v2
	v_fmac_f32_e32 v223, v3, v3
	v_fmac_f32_e32 v222, v4, v4
	v_fmac_f32_e32 v223, v5, v5
	v_fmac_f32_e32 v222, v6, v6
	v_fmac_f32_e32 v223, v7, v7
	v_fmac_f32_e32 v222, v8, v8
	v_fmac_f32_e32 v223, v9, v9
	v_fmac_f32_e32 v222, v10, v10
	v_fmac_f32_e32 v223, v11, v11
	v_fmac_f32_e32 v222, v12, v12
	v_fmac_f32_e32 v223, v13, v13
	v_fmac_f32_e32 v222, v14, v14
	v_fmac_f32_e32 v223, v15, v15
	v_fmac_f32_e32 v222, v16, v16
	v_fmac_f32_e32 v223, v17, v17
	v_fmac_f32_e32 v222, v18, v18
	v_fmac_f32_e32 v223, v19, v19
	v_fmac_f32_e32 v222, v20, v20
	v_fmac_f32_e32 v223, v21, v21
	v_fmac_f32_e32 v222, v22, v22
	v_fmac_f32_e32 v223, v23, v23
	v_fmac_f32_e32 v222, v24, v24
	v_fmac_f32_e32 v223, v25, v25
	v_fmac_f32_e32 v222, v26, v26
	v_fmac_f32_e32 v223, v27, v27
	v_fmac_f32_e32 v222, v28, v28
	v_fmac_f32_e32 v223, v29, v29
	v_fmac_f32_e32 v222, v30, v30
	v_fmac_f32_e32 v223, v31, v31
	v_add_f32_e32 v222, v222, v223
	s_nop 1
	v_add_f32_dpp v224, v222, v222 quad_perm:[1,0,3,2] row_mask:0xf bank_mask:0xf
	s_nop 1
	v_add_f32_dpp v224, v224, v224 quad_perm:[2,3,0,1] row_mask:0xf bank_mask:0xf
	s_nop 1
	v_add_f32_dpp v224, v224, v224 row_half_mirror row_mask:0xf bank_mask:0xf
	s_nop 1
	v_add_f32_dpp v224, v224, v224 row_mirror row_mask:0xf bank_mask:0xf
	s_nop 1
	v_readlane_b32 s40, v224, 0
	v_readlane_b32 s41, v224, 16
	v_readlane_b32 s42, v224, 32
	v_readlane_b32 s43, v224, 48
	s_nop 1
	v_mov_b32_e32 v225, s40
	v_add_f32_e32 v225, s41, v225
	v_add_f32_e32 v225, s42, v225
	v_add_f32_e32 v225, s43, v225
	v_fmamk_f32 v225, v225, 0x3a000000, v195
	v_rsq_f32_e32 v225, v225
	s_nop 0
	s_add_i32 s0, s6, 0
	s_lshl_b32 s1, s0, 12
	s_add_u32 s26, s84, s1
	s_addc_u32 s27, s85, 0
	s_add_u32 s26, s26, 0x4000000
	s_addc_u32 s27, s27, 0
	v_mul_f32_e32 v216, v225, v0
	v_mul_f32_e32 v217, v225, v1
	v_mul_f32_e32 v218, v225, v2
	v_mul_f32_e32 v219, v225, v3
	v_fma_f32 v216, v216, v128, v160
	v_fma_f32 v217, v217, v129, v161
	v_fma_f32 v218, v218, v130, v162
	v_fma_f32 v219, v219, v131, v163
	v_cvt_pk_bf16_f32 v196, v216, v217
	v_cvt_pk_bf16_f32 v197, v218, v219
	global_store_dwordx2 v194, v[196:197], s[26:27] offset:0 nt
	v_mul_f32_e32 v216, v225, v4
	v_mul_f32_e32 v217, v225, v5
	v_mul_f32_e32 v218, v225, v6
	v_mul_f32_e32 v219, v225, v7
	v_fma_f32 v216, v216, v132, v164
	v_fma_f32 v217, v217, v133, v165
	v_fma_f32 v218, v218, v134, v166
	v_fma_f32 v219, v219, v135, v167
	v_cvt_pk_bf16_f32 v220, v216, v217
	v_cvt_pk_bf16_f32 v221, v218, v219
	global_store_dwordx2 v194, v[220:221], s[26:27] offset:512 nt
	v_mul_f32_e32 v216, v225, v8
	v_mul_f32_e32 v217, v225, v9
	v_mul_f32_e32 v218, v225, v10
	v_mul_f32_e32 v219, v225, v11
	v_fma_f32 v216, v216, v136, v168
	v_fma_f32 v217, v217, v137, v169
	v_fma_f32 v218, v218, v138, v170
	v_fma_f32 v219, v219, v139, v171
	v_cvt_pk_bf16_f32 v196, v216, v217
	v_cvt_pk_bf16_f32 v197, v218, v219
	global_store_dwordx2 v194, v[196:197], s[26:27] offset:1024 nt
	v_mul_f32_e32 v216, v225, v12
	v_mul_f32_e32 v217, v225, v13
	v_mul_f32_e32 v218, v225, v14
	v_mul_f32_e32 v219, v225, v15
	v_fma_f32 v216, v216, v140, v172
	v_fma_f32 v217, v217, v141, v173
	v_fma_f32 v218, v218, v142, v174
	v_fma_f32 v219, v219, v143, v175
	v_cvt_pk_bf16_f32 v220, v216, v217
	v_cvt_pk_bf16_f32 v221, v218, v219
	global_store_dwordx2 v194, v[220:221], s[26:27] offset:1536 nt
	v_mul_f32_e32 v216, v225, v16
	v_mul_f32_e32 v217, v225, v17
	v_mul_f32_e32 v218, v225, v18
	v_mul_f32_e32 v219, v225, v19
	v_fma_f32 v216, v216, v144, v176
	v_fma_f32 v217, v217, v145, v177
	v_fma_f32 v218, v218, v146, v178
	v_fma_f32 v219, v219, v147, v179
	v_cvt_pk_bf16_f32 v196, v216, v217
	v_cvt_pk_bf16_f32 v197, v218, v219
	global_store_dwordx2 v194, v[196:197], s[26:27] offset:2048 nt
	v_mul_f32_e32 v216, v225, v20
	v_mul_f32_e32 v217, v225, v21
	v_mul_f32_e32 v218, v225, v22
	v_mul_f32_e32 v219, v225, v23
	v_fma_f32 v216, v216, v148, v180
	v_fma_f32 v217, v217, v149, v181
	v_fma_f32 v218, v218, v150, v182
	v_fma_f32 v219, v219, v151, v183
	v_cvt_pk_bf16_f32 v220, v216, v217
	v_cvt_pk_bf16_f32 v221, v218, v219
	global_store_dwordx2 v194, v[220:221], s[26:27] offset:2560 nt
	v_mul_f32_e32 v216, v225, v24
	v_mul_f32_e32 v217, v225, v25
	v_mul_f32_e32 v218, v225, v26
	v_mul_f32_e32 v219, v225, v27
	v_fma_f32 v216, v216, v152, v184
	v_fma_f32 v217, v217, v153, v185
	v_fma_f32 v218, v218, v154, v186
	v_fma_f32 v219, v219, v155, v187
	v_cvt_pk_bf16_f32 v196, v216, v217
	v_cvt_pk_bf16_f32 v197, v218, v219
	global_store_dwordx2 v194, v[196:197], s[26:27] offset:3072 nt
	v_mul_f32_e32 v216, v225, v28
	v_mul_f32_e32 v217, v225, v29
	v_mul_f32_e32 v218, v225, v30
	v_mul_f32_e32 v219, v225, v31
	v_fma_f32 v216, v216, v156, v188
	v_fma_f32 v217, v217, v157, v189
	v_fma_f32 v218, v218, v158, v190
	v_fma_f32 v219, v219, v159, v191
	v_cvt_pk_bf16_f32 v220, v216, v217
	v_cvt_pk_bf16_f32 v221, v218, v219
	global_store_dwordx2 v194, v[220:221], s[26:27] offset:3584 nt
	s_add_i32 s0, s6, 2
	s_cmp_lt_u32 s0, 0x4000
	s_cselect_b32 s10, s68, s72
	s_cselect_b32 s11, s69, s73
	s_cselect_b32 s1, 0, 0x4000
	s_sub_i32 s1, s0, s1
	s_lshl_b32 s1, s1, 13
	s_add_u32 s10, s10, s1
	s_addc_u32 s11, s11, 0
	s_add_i32 s0, s6, 2
	s_lshl_b32 s1, s0, 12
	s_add_u32 s22, s84, s1
	s_addc_u32 s23, s85, 0
	s_add_u32 s22, s22, 0x11800000
	s_addc_u32 s23, s23, 0
	global_load_dwordx4 v[0:3], v192, s[10:11] offset:0 nt
	global_load_dwordx4 v[4:7], v192, s[10:11] offset:1024 nt
	global_load_dwordx4 v[8:11], v192, s[10:11] offset:2048 nt
	global_load_dwordx4 v[12:15], v192, s[10:11] offset:3072 nt
	global_load_dwordx4 v[16:19], v193, s[10:11] offset:0 nt
	global_load_dwordx4 v[20:23], v193, s[10:11] offset:1024 nt
	global_load_dwordx4 v[24:27], v193, s[10:11] offset:2048 nt
	global_load_dwordx4 v[28:31], v193, s[10:11] offset:3072 nt
	global_load_dwordx2 v[32:33], v194, s[22:23] offset:0
	global_load_dwordx2 v[34:35], v194, s[22:23] offset:512
	global_load_dwordx2 v[36:37], v194, s[22:23] offset:1024
	global_load_dwordx2 v[38:39], v194, s[22:23] offset:1536
	global_load_dwordx2 v[40:41], v194, s[22:23] offset:2048
	global_load_dwordx2 v[42:43], v194, s[22:23] offset:2560
	global_load_dwordx2 v[44:45], v194, s[22:23] offset:3072
	global_load_dwordx2 v[46:47], v194, s[22:23] offset:3584
	s_add_i32 s0, s6, 1
	s_add_i32 s0, s6, 1
	s_lshr_b32 s8, s0, 11
	s_cmp_lt_u32 s0, 0x4000
	s_cselect_b32 s8, s8, 8
	s_cmp_eq_u32 s8, s7
	s_cbranch_scc1 .Lp6_np1
; __device__ __forceinline__ unsigned cvt_pk_bf16(float lo, float hi) { unsigned r; asm volatile("v_cvt_pk_bf16_f32 %0, %1, %2" : "=v"(r) : "v"(lo), "v"(hi)); return r; }
; __device__ __forceinline__ float bf_lo(unsigned w) { return __uint_as_float(w << 16); }
; __device__ __forceinline__ float bf_hi(unsigned w) { return __uint_as_float(w & 0xffff0000u); }
; __device__ __forceinline__ void modulate_store(const f32x4 (&v)[8], float rstd, const float* pn, const float* modr, bf16_t* orow, int lane) {
; #pragma unroll
;     for (int j = 0; j < 8; ++j) { const int col = 4 * lane + 256 * j;
;         const f32x4 g = *(const f32x4*)(pn + col), sh = *(const f32x4*)(modr + col), sc = *(const f32x4*)(modr + DM + col);
;         const f32x4 hh = v[j] * rstd * g * (sc + 1.f) + sh;
;         u32x2 w; w.x = cvt_pk_bf16(hh[0], hh[1]); w.y = cvt_pk_bf16(hh[2], hh[3]);
; __global__ void __launch_bounds__(NWAVES * 64, 2) mk_fwd(Args args) {
;     ...
;                 const float* m0 = mod + (size_t)r * 6144;
; #pragma unroll
;                 for (int j = 0; j < 8; ++j) { const int col = 4 * F.lane + 256 * j; const f32x4 gt = *(const f32x4*)(m0 + 2 * DM + col), pn = *(const f32x4*)(post_norm + col);
;                     const f32x4 y4 = (f32x4){bf_lo(yw[q][j].x), bf_hi(yw[q][j].x), bf_lo(yw[q][j].y), bf_hi(yw[q][j].y)};
;                     v[q][j] = v[q][j] + gt * (y4 * rsy * pn);
	s_mov_b32 s7, s8
	s_add_i32 s1, s8, 9
	s_mul_i32 s1, s1, 0x6000
	s_add_u32 s44, s84, s1
	s_addc_u32 s45, s85, 0
	s_add_u32 s44, s44, 0x2000
	s_addc_u32 s45, s45, 0
	s_add_i32 s1, s8, 9
	s_mul_i32 s1, s1, 0x6000
	s_add_u32 s36, s84, s1
	s_addc_u32 s37, s85, 0
	s_add_u32 s38, s80, 0x2000
	s_addc_u32 s39, s81, 0
	s_mul_i32 s1, s8, 0x6000
	s_add_u32 s34, s84, s1
	s_addc_u32 s35, s85, 0
	s_add_u32 s34, s34, 0x4000
	s_addc_u32 s35, s35, 0
	global_load_dwordx4 v[96:99], v192, s[34:35] offset:0
	global_load_dwordx4 v[200:203], v192, s[82:83] offset:0
	global_load_dwordx4 v[100:103], v192, s[34:35] offset:1024
	global_load_dwordx4 v[204:207], v192, s[82:83] offset:1024
	global_load_dwordx4 v[104:107], v192, s[34:35] offset:2048
	global_load_dwordx4 v[208:211], v192, s[82:83] offset:2048
	global_load_dwordx4 v[108:111], v192, s[34:35] offset:3072
	global_load_dwordx4 v[212:215], v192, s[82:83] offset:3072
	s_waitcnt vmcnt(0)
	v_mul_f32_e32 v96, v96, v200
	v_mul_f32_e32 v97, v97, v201
	v_mul_f32_e32 v98, v98, v202
	v_mul_f32_e32 v99, v99, v203
	v_mul_f32_e32 v100, v100, v204
	v_mul_f32_e32 v101, v101, v205
	v_mul_f32_e32 v102, v102, v206
	v_mul_f32_e32 v103, v103, v207
	v_mul_f32_e32 v104, v104, v208
	v_mul_f32_e32 v105, v105, v209
	v_mul_f32_e32 v106, v106, v210
	v_mul_f32_e32 v107, v107, v211
	v_mul_f32_e32 v108, v108, v212
	v_mul_f32_e32 v109, v109, v213
	v_mul_f32_e32 v110, v110, v214
	v_mul_f32_e32 v111, v111, v215
	global_load_dwordx4 v[128:131], v192, s[38:39] offset:0
	global_load_dwordx4 v[200:203], v192, s[44:45] offset:0
	global_load_dwordx4 v[160:163], v192, s[36:37] offset:0
	global_load_dwordx4 v[132:135], v192, s[38:39] offset:1024
	global_load_dwordx4 v[204:207], v192, s[44:45] offset:1024
	global_load_dwordx4 v[164:167], v192, s[36:37] offset:1024
	global_load_dwordx4 v[136:139], v192, s[38:39] offset:2048
	global_load_dwordx4 v[208:211], v192, s[44:45] offset:2048
	global_load_dwordx4 v[168:171], v192, s[36:37] offset:2048
	global_load_dwordx4 v[140:143], v192, s[38:39] offset:3072
	global_load_dwordx4 v[212:215], v192, s[44:45] offset:3072
	global_load_dwordx4 v[172:175], v192, s[36:37] offset:3072
	s_waitcnt vmcnt(0)
	v_add_f32_e32 v200, 1.0, v200
	v_add_f32_e32 v201, 1.0, v201
	v_add_f32_e32 v202, 1.0, v202
	v_add_f32_e32 v203, 1.0, v203
	v_mul_f32_e32 v128, v128, v200
	v_mul_f32_e32 v129, v129, v201
	v_mul_f32_e32 v130, v130, v202
	v_mul_f32_e32 v131, v131, v203
	v_add_f32_e32 v204, 1.0, v204
	v_add_f32_e32 v205, 1.0, v205
	v_add_f32_e32 v206, 1.0, v206
	v_add_f32_e32 v207, 1.0, v207
	v_mul_f32_e32 v132, v132, v204
	v_mul_f32_e32 v133, v133, v205
	v_mul_f32_e32 v134, v134, v206
	v_mul_f32_e32 v135, v135, v207
	v_add_f32_e32 v208, 1.0, v208
	v_add_f32_e32 v209, 1.0, v209
	v_add_f32_e32 v210, 1.0, v210
	v_add_f32_e32 v211, 1.0, v211
	v_mul_f32_e32 v136, v136, v208
	v_mul_f32_e32 v137, v137, v209
	v_mul_f32_e32 v138, v138, v210
	v_mul_f32_e32 v139, v139, v211
	v_add_f32_e32 v212, 1.0, v212
	v_add_f32_e32 v213, 1.0, v213
	v_add_f32_e32 v214, 1.0, v214
	v_add_f32_e32 v215, 1.0, v215
	v_mul_f32_e32 v140, v140, v212
	v_mul_f32_e32 v141, v141, v213
	v_mul_f32_e32 v142, v142, v214
	v_mul_f32_e32 v143, v143, v215
	global_load_dwordx4 v[112:115], v193, s[34:35] offset:0
	global_load_dwordx4 v[200:203], v193, s[82:83] offset:0
	global_load_dwordx4 v[116:119], v193, s[34:35] offset:1024
	global_load_dwordx4 v[204:207], v193, s[82:83] offset:1024
	global_load_dwordx4 v[120:123], v193, s[34:35] offset:2048
	global_load_dwordx4 v[208:211], v193, s[82:83] offset:2048
	global_load_dwordx4 v[124:127], v193, s[34:35] offset:3072
	global_load_dwordx4 v[212:215], v193, s[82:83] offset:3072
	s_waitcnt vmcnt(0)
	v_mul_f32_e32 v112, v112, v200
	v_mul_f32_e32 v113, v113, v201
	v_mul_f32_e32 v114, v114, v202
	v_mul_f32_e32 v115, v115, v203
	v_mul_f32_e32 v116, v116, v204
	v_mul_f32_e32 v117, v117, v205
	v_mul_f32_e32 v118, v118, v206
	v_mul_f32_e32 v119, v119, v207
	v_mul_f32_e32 v120, v120, v208
	v_mul_f32_e32 v121, v121, v209
	v_mul_f32_e32 v122, v122, v210
	v_mul_f32_e32 v123, v123, v211
	v_mul_f32_e32 v124, v124, v212
	v_mul_f32_e32 v125, v125, v213
	v_mul_f32_e32 v126, v126, v214
	v_mul_f32_e32 v127, v127, v215
	global_load_dwordx4 v[144:147], v193, s[38:39] offset:0
	global_load_dwordx4 v[200:203], v193, s[44:45] offset:0
	global_load_dwordx4 v[176:179], v193, s[36:37] offset:0
	global_load_dwordx4 v[148:151], v193, s[38:39] offset:1024
	global_load_dwordx4 v[204:207], v193, s[44:45] offset:1024
	global_load_dwordx4 v[180:183], v193, s[36:37] offset:1024
	global_load_dwordx4 v[152:155], v193, s[38:39] offset:2048
	global_load_dwordx4 v[208:211], v193, s[44:45] offset:2048
	global_load_dwordx4 v[184:187], v193, s[36:37] offset:2048
	global_load_dwordx4 v[156:159], v193, s[38:39] offset:3072
	global_load_dwordx4 v[212:215], v193, s[44:45] offset:3072
	global_load_dwordx4 v[188:191], v193, s[36:37] offset:3072
	s_waitcnt vmcnt(0)
	v_add_f32_e32 v200, 1.0, v200
	v_add_f32_e32 v201, 1.0, v201
	v_add_f32_e32 v202, 1.0, v202
	v_add_f32_e32 v203, 1.0, v203
	v_mul_f32_e32 v144, v144, v200
	v_mul_f32_e32 v145, v145, v201
	v_mul_f32_e32 v146, v146, v202
	v_mul_f32_e32 v147, v147, v203
	v_add_f32_e32 v204, 1.0, v204
	v_add_f32_e32 v205, 1.0, v205
	v_add_f32_e32 v206, 1.0, v206
	v_add_f32_e32 v207, 1.0, v207
	v_mul_f32_e32 v148, v148, v204
	v_mul_f32_e32 v149, v149, v205
	v_mul_f32_e32 v150, v150, v206
	v_mul_f32_e32 v151, v151, v207
	v_add_f32_e32 v208, 1.0, v208
	v_add_f32_e32 v209, 1.0, v209
	v_add_f32_e32 v210, 1.0, v210
	v_add_f32_e32 v211, 1.0, v211
	v_mul_f32_e32 v152, v152, v208
	v_mul_f32_e32 v153, v153, v209
	v_mul_f32_e32 v154, v154, v210
	v_mul_f32_e32 v155, v155, v211
	v_add_f32_e32 v212, 1.0, v212
	v_add_f32_e32 v213, 1.0, v213
	v_add_f32_e32 v214, 1.0, v214
	v_add_f32_e32 v215, 1.0, v215
	v_mul_f32_e32 v156, v156, v212
	v_mul_f32_e32 v157, v157, v213
	v_mul_f32_e32 v158, v158, v214
	v_mul_f32_e32 v159, v159, v215
; __device__ __forceinline__ float bf_lo(unsigned w) { return __uint_as_float(w << 16); }
; __device__ __forceinline__ float bf_hi(unsigned w) { return __uint_as_float(w & 0xffff0000u); }
; __global__ void __launch_bounds__(NWAVES * 64, 2) mk_fwd(Args args) {
;     ...
;             for (int q = 0; q < 3; ++q) { const int row = row0 + q; const bool lat = row < ML; const int r = lat ? row / SEQ : 8;
;                 float sy = 0.f;
; #pragma unroll
;                 for (int j = 0; j < 8; ++j) { const float a = bf_lo(yw[q][j].x), b = bf_hi(yw[q][j].x), c2 = bf_lo(yw[q][j].y), d = bf_hi(yw[q][j].y); sy += (a * a + b * b) + (c2 * c2 + d * d); }
;                 const float rsy = __builtin_amdgcn_rsqf(wave_sum(sy) * (1.f / DM) + EPS);
;                 const float* m0 = mod + (size_t)r * 6144;
; #pragma unroll
;                 for (int j = 0; j < 8; ++j) { const int col = 4 * F.lane + 256 * j; const f32x4 gt = *(const f32x4*)(m0 + 2 * DM + col), pn = *(const f32x4*)(post_norm + col);
;                     const f32x4 y4 = (f32x4){bf_lo(yw[q][j].x), bf_hi(yw[q][j].x), bf_lo(yw[q][j].y), bf_hi(yw[q][j].y)};
;                     v[q][j] = v[q][j] + gt * (y4 * rsy * pn);
.Lp6_np1:
	s_waitcnt vmcnt(24)
	v_lshlrev_b32_e32 v216, 16, v80
	v_and_b32_e32 v217, 0xffff0000, v80
	v_lshlrev_b32_e32 v218, 16, v81
	v_and_b32_e32 v219, 0xffff0000, v81
	v_mul_f32_e32 v222, v216, v216
	v_mul_f32_e32 v223, v217, v217
	v_fmac_f32_e32 v222, v218, v218
	v_fmac_f32_e32 v223, v219, v219
	v_lshlrev_b32_e32 v216, 16, v82
	v_and_b32_e32 v217, 0xffff0000, v82
	v_lshlrev_b32_e32 v218, 16, v83
	v_and_b32_e32 v219, 0xffff0000, v83
	v_fmac_f32_e32 v222, v216, v216
	v_fmac_f32_e32 v223, v217, v217
	v_fmac_f32_e32 v222, v218, v218
	v_fmac_f32_e32 v223, v219, v219
	v_lshlrev_b32_e32 v216, 16, v84
	v_and_b32_e32 v217, 0xffff0000, v84
	v_lshlrev_b32_e32 v218, 16, v85
	v_and_b32_e32 v219, 0xffff0000, v85
	v_fmac_f32_e32 v222, v216, v216
	v_fmac_f32_e32 v223, v217, v217
	v_fmac_f32_e32 v222, v218, v218
	v_fmac_f32_e32 v223, v219, v219
	v_lshlrev_b32_e32 v216, 16, v86
	v_and_b32_e32 v217, 0xffff0000, v86
	v_lshlrev_b32_e32 v218, 16, v87
	v_and_b32_e32 v219, 0xffff0000, v87
	v_fmac_f32_e32 v222, v216, v216
	v_fmac_f32_e32 v223, v217, v217
	v_fmac_f32_e32 v222, v218, v218
	v_fmac_f32_e32 v223, v219, v219
	v_lshlrev_b32_e32 v216, 16, v88
	v_and_b32_e32 v217, 0xffff0000, v88
	v_lshlrev_b32_e32 v218, 16, v89
	v_and_b32_e32 v219, 0xffff0000, v89
	v_fmac_f32_e32 v222, v216, v216
	v_fmac_f32_e32 v223, v217, v217
	v_fmac_f32_e32 v222, v218, v218
	v_fmac_f32_e32 v223, v219, v219
	v_lshlrev_b32_e32 v216, 16, v90
	v_and_b32_e32 v217, 0xffff0000, v90
	v_lshlrev_b32_e32 v218, 16, v91
	v_and_b32_e32 v219, 0xffff0000, v91
	v_fmac_f32_e32 v222, v216, v216
	v_fmac_f32_e32 v223, v217, v217
	v_fmac_f32_e32 v222, v218, v218
	v_fmac_f32_e32 v223, v219, v219
	v_lshlrev_b32_e32 v216, 16, v92
	v_and_b32_e32 v217, 0xffff0000, v92
	v_lshlrev_b32_e32 v218, 16, v93
	v_and_b32_e32 v219, 0xffff0000, v93
	v_fmac_f32_e32 v222, v216, v216
	v_fmac_f32_e32 v223, v217, v217
	v_fmac_f32_e32 v222, v218, v218
	v_fmac_f32_e32 v223, v219, v219
	v_lshlrev_b32_e32 v216, 16, v94
	v_and_b32_e32 v217, 0xffff0000, v94
	v_lshlrev_b32_e32 v218, 16, v95
	v_and_b32_e32 v219, 0xffff0000, v95
	v_fmac_f32_e32 v222, v216, v216
	v_fmac_f32_e32 v223, v217, v217
	v_fmac_f32_e32 v222, v218, v218
	v_fmac_f32_e32 v223, v219, v219
	v_add_f32_e32 v222, v222, v223
	s_nop 1
	v_add_f32_dpp v224, v222, v222 quad_perm:[1,0,3,2] row_mask:0xf bank_mask:0xf
	s_nop 1
	v_add_f32_dpp v224, v224, v224 quad_perm:[2,3,0,1] row_mask:0xf bank_mask:0xf
	s_nop 1
	v_add_f32_dpp v224, v224, v224 row_half_mirror row_mask:0xf bank_mask:0xf
	s_nop 1
	v_add_f32_dpp v224, v224, v224 row_mirror row_mask:0xf bank_mask:0xf
	s_nop 1
	v_readlane_b32 s40, v224, 0
	v_readlane_b32 s41, v224, 16
	v_readlane_b32 s42, v224, 32
	v_readlane_b32 s43, v224, 48
	s_nop 1
	v_mov_b32_e32 v225, s40
	v_add_f32_e32 v225, s41, v225
	v_add_f32_e32 v225, s42, v225
	v_add_f32_e32 v225, s43, v225
	v_fmamk_f32 v225, v225, 0x3a000000, v195
	v_rsq_f32_e32 v225, v225
	s_nop 0
	v_lshlrev_b32_e32 v216, 16, v80
	v_and_b32_e32 v217, 0xffff0000, v80
	v_lshlrev_b32_e32 v218, 16, v81
	v_and_b32_e32 v219, 0xffff0000, v81
	v_mul_f32_e32 v216, v225, v216
	v_mul_f32_e32 v217, v225, v217
	v_mul_f32_e32 v218, v225, v218
	v_mul_f32_e32 v219, v225, v219
	v_fmac_f32_e32 v48, v96, v216
	v_fmac_f32_e32 v49, v97, v217
	v_fmac_f32_e32 v50, v98, v218
	v_fmac_f32_e32 v51, v99, v219
	v_lshlrev_b32_e32 v216, 16, v82
	v_and_b32_e32 v217, 0xffff0000, v82
	v_lshlrev_b32_e32 v218, 16, v83
	v_and_b32_e32 v219, 0xffff0000, v83
	v_mul_f32_e32 v216, v225, v216
	v_mul_f32_e32 v217, v225, v217
	v_mul_f32_e32 v218, v225, v218
	v_mul_f32_e32 v219, v225, v219
	v_fmac_f32_e32 v52, v100, v216
	v_fmac_f32_e32 v53, v101, v217
	v_fmac_f32_e32 v54, v102, v218
	v_fmac_f32_e32 v55, v103, v219
	v_lshlrev_b32_e32 v216, 16, v84
	v_and_b32_e32 v217, 0xffff0000, v84
	v_lshlrev_b32_e32 v218, 16, v85
	v_and_b32_e32 v219, 0xffff0000, v85
	v_mul_f32_e32 v216, v225, v216
	v_mul_f32_e32 v217, v225, v217
	v_mul_f32_e32 v218, v225, v218
	v_mul_f32_e32 v219, v225, v219
	v_fmac_f32_e32 v56, v104, v216
	v_fmac_f32_e32 v57, v105, v217
	v_fmac_f32_e32 v58, v106, v218
	v_fmac_f32_e32 v59, v107, v219
	v_lshlrev_b32_e32 v216, 16, v86
	v_and_b32_e32 v217, 0xffff0000, v86
	v_lshlrev_b32_e32 v218, 16, v87
	v_and_b32_e32 v219, 0xffff0000, v87
	v_mul_f32_e32 v216, v225, v216
	v_mul_f32_e32 v217, v225, v217
	v_mul_f32_e32 v218, v225, v218
	v_mul_f32_e32 v219, v225, v219
	v_fmac_f32_e32 v60, v108, v216
	v_fmac_f32_e32 v61, v109, v217
	v_fmac_f32_e32 v62, v110, v218
	v_fmac_f32_e32 v63, v111, v219
	v_lshlrev_b32_e32 v216, 16, v88
	v_and_b32_e32 v217, 0xffff0000, v88
	v_lshlrev_b32_e32 v218, 16, v89
	v_and_b32_e32 v219, 0xffff0000, v89
	v_mul_f32_e32 v216, v225, v216
	v_mul_f32_e32 v217, v225, v217
	v_mul_f32_e32 v218, v225, v218
	v_mul_f32_e32 v219, v225, v219
	v_fmac_f32_e32 v64, v112, v216
	v_fmac_f32_e32 v65, v113, v217
	v_fmac_f32_e32 v66, v114, v218
	v_fmac_f32_e32 v67, v115, v219
	v_lshlrev_b32_e32 v216, 16, v90
	v_and_b32_e32 v217, 0xffff0000, v90
	v_lshlrev_b32_e32 v218, 16, v91
	v_and_b32_e32 v219, 0xffff0000, v91
	v_mul_f32_e32 v216, v225, v216
	v_mul_f32_e32 v217, v225, v217
	v_mul_f32_e32 v218, v225, v218
	v_mul_f32_e32 v219, v225, v219
	v_fmac_f32_e32 v68, v116, v216
	v_fmac_f32_e32 v69, v117, v217
	v_fmac_f32_e32 v70, v118, v218
	v_fmac_f32_e32 v71, v119, v219
	v_lshlrev_b32_e32 v216, 16, v92
	v_and_b32_e32 v217, 0xffff0000, v92
	v_lshlrev_b32_e32 v218, 16, v93
	v_and_b32_e32 v219, 0xffff0000, v93
	v_mul_f32_e32 v216, v225, v216
	v_mul_f32_e32 v217, v225, v217
	v_mul_f32_e32 v218, v225, v218
	v_mul_f32_e32 v219, v225, v219
	v_fmac_f32_e32 v72, v120, v216
	v_fmac_f32_e32 v73, v121, v217
	v_fmac_f32_e32 v74, v122, v218
; __device__ __forceinline__ unsigned cvt_pk_bf16(float lo, float hi) { unsigned r; asm volatile("v_cvt_pk_bf16_f32 %0, %1, %2" : "=v"(r) : "v"(lo), "v"(hi)); return r; }
; __device__ __forceinline__ float bf_lo(unsigned w) { return __uint_as_float(w << 16); }
; __device__ __forceinline__ float bf_hi(unsigned w) { return __uint_as_float(w & 0xffff0000u); }
; __device__ __forceinline__ void modulate_store(const f32x4 (&v)[8], float rstd, const float* pn, const float* modr, bf16_t* orow, int lane) {
; #pragma unroll
;     for (int j = 0; j < 8; ++j) { const int col = 4 * lane + 256 * j;
;         const f32x4 g = *(const f32x4*)(pn + col), sh = *(const f32x4*)(modr + col), sc = *(const f32x4*)(modr + DM + col);
;         const f32x4 hh = v[j] * rstd * g * (sc + 1.f) + sh;
;         u32x2 w; w.x = cvt_pk_bf16(hh[0], hh[1]); w.y = cvt_pk_bf16(hh[2], hh[3]);
;         *(u32x2*)(orow + col) = w; }
; __global__ void __launch_bounds__(NWAVES * 64, 2) mk_fwd(Args args) {
;     ...
;             for (int q = 0; q < 3; ++q) { const int row = row0 + q; const bool lat = row < ML; const int r = lat ? row / SEQ : 8;
;                 float sy = 0.f;
; #pragma unroll
;                 for (int j = 0; j < 8; ++j) { const float a = bf_lo(yw[q][j].x), b = bf_hi(yw[q][j].x), c2 = bf_lo(yw[q][j].y), d = bf_hi(yw[q][j].y); sy += (a * a + b * b) + (c2 * c2 + d * d); }
;                 const float rsy = __builtin_amdgcn_rsqf(wave_sum(sy) * (1.f / DM) + EPS);
;                 const float* m0 = mod + (size_t)r * 6144;
; #pragma unroll
;                 for (int j = 0; j < 8; ++j) { const int col = 4 * F.lane + 256 * j; const f32x4 gt = *(const f32x4*)(m0 + 2 * DM + col), pn = *(const f32x4*)(post_norm + col);
;                     const f32x4 y4 = (f32x4){bf_lo(yw[q][j].x), bf_hi(yw[q][j].x), bf_lo(yw[q][j].y), bf_hi(yw[q][j].y)};
;                     v[q][j] = v[q][j] + gt * (y4 * rsy * pn);
;                     if (lat) *(f32x4*)(args.out + (size_t)row * DM + col) = v[q][j]; }
;                 const float rstd = __builtin_amdgcn_rsqf(sumsq8(v[q]) * (1.f / DM) + EPS);
;                 modulate_store(v[q], rstd, pre_norm + DM, mod + (size_t)(9 + r) * 6144, H + (size_t)row * DM, F.lane); }
	v_fmac_f32_e32 v75, v123, v219
	v_lshlrev_b32_e32 v216, 16, v94
	v_and_b32_e32 v217, 0xffff0000, v94
	v_lshlrev_b32_e32 v218, 16, v95
	v_and_b32_e32 v219, 0xffff0000, v95
	v_mul_f32_e32 v216, v225, v216
	v_mul_f32_e32 v217, v225, v217
	v_mul_f32_e32 v218, v225, v218
	v_mul_f32_e32 v219, v225, v219
	v_fmac_f32_e32 v76, v124, v216
	v_fmac_f32_e32 v77, v125, v217
	v_fmac_f32_e32 v78, v126, v218
	v_fmac_f32_e32 v79, v127, v219
	v_mul_f32_e32 v222, v48, v48
	v_mul_f32_e32 v223, v49, v49
	v_fmac_f32_e32 v222, v50, v50
	v_fmac_f32_e32 v223, v51, v51
	v_fmac_f32_e32 v222, v52, v52
	v_fmac_f32_e32 v223, v53, v53
	v_fmac_f32_e32 v222, v54, v54
	v_fmac_f32_e32 v223, v55, v55
	v_fmac_f32_e32 v222, v56, v56
	v_fmac_f32_e32 v223, v57, v57
	v_fmac_f32_e32 v222, v58, v58
	v_fmac_f32_e32 v223, v59, v59
	v_fmac_f32_e32 v222, v60, v60
	v_fmac_f32_e32 v223, v61, v61
	v_fmac_f32_e32 v222, v62, v62
	v_fmac_f32_e32 v223, v63, v63
	v_fmac_f32_e32 v222, v64, v64
	v_fmac_f32_e32 v223, v65, v65
	v_fmac_f32_e32 v222, v66, v66
	v_fmac_f32_e32 v223, v67, v67
	v_fmac_f32_e32 v222, v68, v68
	v_fmac_f32_e32 v223, v69, v69
	v_fmac_f32_e32 v222, v70, v70
	v_fmac_f32_e32 v223, v71, v71
	v_fmac_f32_e32 v222, v72, v72
	v_fmac_f32_e32 v223, v73, v73
	v_fmac_f32_e32 v222, v74, v74
	v_fmac_f32_e32 v223, v75, v75
	v_fmac_f32_e32 v222, v76, v76
	v_fmac_f32_e32 v223, v77, v77
	v_fmac_f32_e32 v222, v78, v78
	v_fmac_f32_e32 v223, v79, v79
	v_add_f32_e32 v222, v222, v223
	s_nop 1
	v_add_f32_dpp v224, v222, v222 quad_perm:[1,0,3,2] row_mask:0xf bank_mask:0xf
	s_nop 1
	v_add_f32_dpp v224, v224, v224 quad_perm:[2,3,0,1] row_mask:0xf bank_mask:0xf
	s_nop 1
	v_add_f32_dpp v224, v224, v224 row_half_mirror row_mask:0xf bank_mask:0xf
	s_nop 1
	v_add_f32_dpp v224, v224, v224 row_mirror row_mask:0xf bank_mask:0xf
	s_nop 1
	v_readlane_b32 s40, v224, 0
	v_readlane_b32 s41, v224, 16
	v_readlane_b32 s42, v224, 32
	v_readlane_b32 s43, v224, 48
	s_nop 1
	v_mov_b32_e32 v225, s40
	v_add_f32_e32 v225, s41, v225
	v_add_f32_e32 v225, s42, v225
	v_add_f32_e32 v225, s43, v225
	v_fmamk_f32 v225, v225, 0x3a000000, v195
	v_rsq_f32_e32 v225, v225
	s_nop 0
	s_add_i32 s0, s6, 1
	s_lshl_b32 s1, s0, 12
	s_add_u32 s26, s84, s1
	s_addc_u32 s27, s85, 0
	s_add_u32 s26, s26, 0x4000000
	s_addc_u32 s27, s27, 0
	v_mul_f32_e32 v216, v225, v48
	v_mul_f32_e32 v217, v225, v49
	v_mul_f32_e32 v218, v225, v50
	v_mul_f32_e32 v219, v225, v51
	v_fma_f32 v216, v216, v128, v160
	v_fma_f32 v217, v217, v129, v161
	v_fma_f32 v218, v218, v130, v162
	v_fma_f32 v219, v219, v131, v163
	v_cvt_pk_bf16_f32 v196, v216, v217
	v_cvt_pk_bf16_f32 v197, v218, v219
	global_store_dwordx2 v194, v[196:197], s[26:27] offset:0 nt
	v_mul_f32_e32 v216, v225, v52
	v_mul_f32_e32 v217, v225, v53
	v_mul_f32_e32 v218, v225, v54
	v_mul_f32_e32 v219, v225, v55
	v_fma_f32 v216, v216, v132, v164
	v_fma_f32 v217, v217, v133, v165
	v_fma_f32 v218, v218, v134, v166
	v_fma_f32 v219, v219, v135, v167
	v_cvt_pk_bf16_f32 v220, v216, v217
	v_cvt_pk_bf16_f32 v221, v218, v219
	global_store_dwordx2 v194, v[220:221], s[26:27] offset:512 nt
	v_mul_f32_e32 v216, v225, v56
	v_mul_f32_e32 v217, v225, v57
	v_mul_f32_e32 v218, v225, v58
	v_mul_f32_e32 v219, v225, v59
	v_fma_f32 v216, v216, v136, v168
	v_fma_f32 v217, v217, v137, v169
	v_fma_f32 v218, v218, v138, v170
	v_fma_f32 v219, v219, v139, v171
	v_cvt_pk_bf16_f32 v196, v216, v217
	v_cvt_pk_bf16_f32 v197, v218, v219
	global_store_dwordx2 v194, v[196:197], s[26:27] offset:1024 nt
	v_mul_f32_e32 v216, v225, v60
	v_mul_f32_e32 v217, v225, v61
	v_mul_f32_e32 v218, v225, v62
	v_mul_f32_e32 v219, v225, v63
	v_fma_f32 v216, v216, v140, v172
	v_fma_f32 v217, v217, v141, v173
	v_fma_f32 v218, v218, v142, v174
	v_fma_f32 v219, v219, v143, v175
	v_cvt_pk_bf16_f32 v220, v216, v217
	v_cvt_pk_bf16_f32 v221, v218, v219
	global_store_dwordx2 v194, v[220:221], s[26:27] offset:1536 nt
	v_mul_f32_e32 v216, v225, v64
	v_mul_f32_e32 v217, v225, v65
	v_mul_f32_e32 v218, v225, v66
	v_mul_f32_e32 v219, v225, v67
	v_fma_f32 v216, v216, v144, v176
	v_fma_f32 v217, v217, v145, v177
	v_fma_f32 v218, v218, v146, v178
	v_fma_f32 v219, v219, v147, v179
	v_cvt_pk_bf16_f32 v196, v216, v217
	v_cvt_pk_bf16_f32 v197, v218, v219
	global_store_dwordx2 v194, v[196:197], s[26:27] offset:2048 nt
	v_mul_f32_e32 v216, v225, v68
	v_mul_f32_e32 v217, v225, v69
	v_mul_f32_e32 v218, v225, v70
	v_mul_f32_e32 v219, v225, v71
	v_fma_f32 v216, v216, v148, v180
	v_fma_f32 v217, v217, v149, v181
	v_fma_f32 v218, v218, v150, v182
	v_fma_f32 v219, v219, v151, v183
	v_cvt_pk_bf16_f32 v220, v216, v217
	v_cvt_pk_bf16_f32 v221, v218, v219
	global_store_dwordx2 v194, v[220:221], s[26:27] offset:2560 nt
	v_mul_f32_e32 v216, v225, v72
	v_mul_f32_e32 v217, v225, v73
	v_mul_f32_e32 v218, v225, v74
	v_mul_f32_e32 v219, v225, v75
	v_fma_f32 v216, v216, v152, v184
	v_fma_f32 v217, v217, v153, v185
	v_fma_f32 v218, v218, v154, v186
	v_fma_f32 v219, v219, v155, v187
	v_cvt_pk_bf16_f32 v196, v216, v217
	v_cvt_pk_bf16_f32 v197, v218, v219
	global_store_dwordx2 v194, v[196:197], s[26:27] offset:3072 nt
	v_mul_f32_e32 v216, v225, v76
	v_mul_f32_e32 v217, v225, v77
	v_mul_f32_e32 v218, v225, v78
	v_mul_f32_e32 v219, v225, v79
	v_fma_f32 v216, v216, v156, v188
	v_fma_f32 v217, v217, v157, v189
	v_fma_f32 v218, v218, v158, v190
	v_fma_f32 v219, v219, v159, v191
	v_cvt_pk_bf16_f32 v220, v216, v217
	v_cvt_pk_bf16_f32 v221, v218, v219
	global_store_dwordx2 v194, v[220:221], s[26:27] offset:3584 nt
	s_add_i32 s0, s6, 3
	s_cmp_lt_u32 s0, 0x4000
	s_cselect_b32 s10, s68, s72
	s_cselect_b32 s11, s69, s73
	s_cselect_b32 s1, 0, 0x4000
	s_sub_i32 s1, s0, s1
	s_lshl_b32 s1, s1, 13
	s_add_u32 s10, s10, s1
	s_addc_u32 s11, s11, 0
	s_add_i32 s0, s6, 3
	s_lshl_b32 s1, s0, 12
	s_add_u32 s22, s84, s1
	s_addc_u32 s23, s85, 0
	s_add_u32 s22, s22, 0x11800000
	s_addc_u32 s23, s23, 0
	global_load_dwordx4 v[48:51], v192, s[10:11] offset:0 nt
	global_load_dwordx4 v[52:55], v192, s[10:11] offset:1024 nt
	global_load_dwordx4 v[56:59], v192, s[10:11] offset:2048 nt
	global_load_dwordx4 v[60:63], v192, s[10:11] offset:3072 nt
	global_load_dwordx4 v[64:67], v193, s[10:11] offset:0 nt
	global_load_dwordx4 v[68:71], v193, s[10:11] offset:1024 nt
	global_load_dwordx4 v[72:75], v193, s[10:11] offset:2048 nt
	global_load_dwordx4 v[76:79], v193, s[10:11] offset:3072 nt
	global_load_dwordx2 v[80:81], v194, s[22:23] offset:0
	global_load_dwordx2 v[82:83], v194, s[22:23] offset:512
	global_load_dwordx2 v[84:85], v194, s[22:23] offset:1024
	global_load_dwordx2 v[86:87], v194, s[22:23] offset:1536
	global_load_dwordx2 v[88:89], v194, s[22:23] offset:2048
	global_load_dwordx2 v[90:91], v194, s[22:23] offset:2560
	global_load_dwordx2 v[92:93], v194, s[22:23] offset:3072
	global_load_dwordx2 v[94:95], v194, s[22:23] offset:3584
	s_add_i32 s0, s6, 2
	s_add_i32 s0, s6, 2
	s_lshr_b32 s8, s0, 11
	s_cmp_lt_u32 s0, 0x4000
	s_cselect_b32 s8, s8, 8
	s_cmp_eq_u32 s8, s7
	s_cbranch_scc1 .Lp6_np2
; __device__ __forceinline__ unsigned cvt_pk_bf16(float lo, float hi) { unsigned r; asm volatile("v_cvt_pk_bf16_f32 %0, %1, %2" : "=v"(r) : "v"(lo), "v"(hi)); return r; }
; __device__ __forceinline__ float bf_lo(unsigned w) { return __uint_as_float(w << 16); }
; __device__ __forceinline__ float bf_hi(unsigned w) { return __uint_as_float(w & 0xffff0000u); }
; __device__ __forceinline__ void modulate_store(const f32x4 (&v)[8], float rstd, const float* pn, const float* modr, bf16_t* orow, int lane) {
; #pragma unroll
;     for (int j = 0; j < 8; ++j) { const int col = 4 * lane + 256 * j;
;         const f32x4 g = *(const f32x4*)(pn + col), sh = *(const f32x4*)(modr + col), sc = *(const f32x4*)(modr + DM + col);
;         const f32x4 hh = v[j] * rstd * g * (sc + 1.f) + sh;
;         u32x2 w; w.x = cvt_pk_bf16(hh[0], hh[1]); w.y = cvt_pk_bf16(hh[2], hh[3]);
; __global__ void __launch_bounds__(NWAVES * 64, 2) mk_fwd(Args args) {
;     ...
;                 const float* m0 = mod + (size_t)r * 6144;
; #pragma unroll
;                 for (int j = 0; j < 8; ++j) { const int col = 4 * F.lane + 256 * j; const f32x4 gt = *(const f32x4*)(m0 + 2 * DM + col), pn = *(const f32x4*)(post_norm + col);
;                     const f32x4 y4 = (f32x4){bf_lo(yw[q][j].x), bf_hi(yw[q][j].x), bf_lo(yw[q][j].y), bf_hi(yw[q][j].y)};
;                     v[q][j] = v[q][j] + gt * (y4 * rsy * pn);
	s_mov_b32 s7, s8
	s_add_i32 s1, s8, 9
	s_mul_i32 s1, s1, 0x6000
	s_add_u32 s44, s84, s1
	s_addc_u32 s45, s85, 0
	s_add_u32 s44, s44, 0x2000
	s_addc_u32 s45, s45, 0
	s_add_i32 s1, s8, 9
	s_mul_i32 s1, s1, 0x6000
	s_add_u32 s36, s84, s1
	s_addc_u32 s37, s85, 0
	s_add_u32 s38, s80, 0x2000
	s_addc_u32 s39, s81, 0
	s_mul_i32 s1, s8, 0x6000
	s_add_u32 s34, s84, s1
	s_addc_u32 s35, s85, 0
	s_add_u32 s34, s34, 0x4000
	s_addc_u32 s35, s35, 0
	global_load_dwordx4 v[96:99], v192, s[34:35] offset:0
	global_load_dwordx4 v[200:203], v192, s[82:83] offset:0
	global_load_dwordx4 v[100:103], v192, s[34:35] offset:1024
	global_load_dwordx4 v[204:207], v192, s[82:83] offset:1024
	global_load_dwordx4 v[104:107], v192, s[34:35] offset:2048
	global_load_dwordx4 v[208:211], v192, s[82:83] offset:2048
	global_load_dwordx4 v[108:111], v192, s[34:35] offset:3072
	global_load_dwordx4 v[212:215], v192, s[82:83] offset:3072
	s_waitcnt vmcnt(0)
	v_mul_f32_e32 v96, v96, v200
	v_mul_f32_e32 v97, v97, v201
	v_mul_f32_e32 v98, v98, v202
	v_mul_f32_e32 v99, v99, v203
	v_mul_f32_e32 v100, v100, v204
	v_mul_f32_e32 v101, v101, v205
	v_mul_f32_e32 v102, v102, v206
	v_mul_f32_e32 v103, v103, v207
	v_mul_f32_e32 v104, v104, v208
	v_mul_f32_e32 v105, v105, v209
	v_mul_f32_e32 v106, v106, v210
	v_mul_f32_e32 v107, v107, v211
	v_mul_f32_e32 v108, v108, v212
	v_mul_f32_e32 v109, v109, v213
	v_mul_f32_e32 v110, v110, v214
	v_mul_f32_e32 v111, v111, v215
	global_load_dwordx4 v[128:131], v192, s[38:39] offset:0
	global_load_dwordx4 v[200:203], v192, s[44:45] offset:0
	global_load_dwordx4 v[160:163], v192, s[36:37] offset:0
	global_load_dwordx4 v[132:135], v192, s[38:39] offset:1024
	global_load_dwordx4 v[204:207], v192, s[44:45] offset:1024
	global_load_dwordx4 v[164:167], v192, s[36:37] offset:1024
	global_load_dwordx4 v[136:139], v192, s[38:39] offset:2048
	global_load_dwordx4 v[208:211], v192, s[44:45] offset:2048
	global_load_dwordx4 v[168:171], v192, s[36:37] offset:2048
	global_load_dwordx4 v[140:143], v192, s[38:39] offset:3072
	global_load_dwordx4 v[212:215], v192, s[44:45] offset:3072
	global_load_dwordx4 v[172:175], v192, s[36:37] offset:3072
	s_waitcnt vmcnt(0)
	v_add_f32_e32 v200, 1.0, v200
	v_add_f32_e32 v201, 1.0, v201
	v_add_f32_e32 v202, 1.0, v202
	v_add_f32_e32 v203, 1.0, v203
	v_mul_f32_e32 v128, v128, v200
	v_mul_f32_e32 v129, v129, v201
	v_mul_f32_e32 v130, v130, v202
	v_mul_f32_e32 v131, v131, v203
	v_add_f32_e32 v204, 1.0, v204
	v_add_f32_e32 v205, 1.0, v205
	v_add_f32_e32 v206, 1.0, v206
	v_add_f32_e32 v207, 1.0, v207
	v_mul_f32_e32 v132, v132, v204
	v_mul_f32_e32 v133, v133, v205
	v_mul_f32_e32 v134, v134, v206
	v_mul_f32_e32 v135, v135, v207
	v_add_f32_e32 v208, 1.0, v208
	v_add_f32_e32 v209, 1.0, v209
	v_add_f32_e32 v210, 1.0, v210
	v_add_f32_e32 v211, 1.0, v211
	v_mul_f32_e32 v136, v136, v208
	v_mul_f32_e32 v137, v137, v209
	v_mul_f32_e32 v138, v138, v210
	v_mul_f32_e32 v139, v139, v211
	v_add_f32_e32 v212, 1.0, v212
	v_add_f32_e32 v213, 1.0, v213
	v_add_f32_e32 v214, 1.0, v214
	v_add_f32_e32 v215, 1.0, v215
	v_mul_f32_e32 v140, v140, v212
	v_mul_f32_e32 v141, v141, v213
	v_mul_f32_e32 v142, v142, v214
	v_mul_f32_e32 v143, v143, v215
	global_load_dwordx4 v[112:115], v193, s[34:35] offset:0
	global_load_dwordx4 v[200:203], v193, s[82:83] offset:0
	global_load_dwordx4 v[116:119], v193, s[34:35] offset:1024
	global_load_dwordx4 v[204:207], v193, s[82:83] offset:1024
	global_load_dwordx4 v[120:123], v193, s[34:35] offset:2048
	global_load_dwordx4 v[208:211], v193, s[82:83] offset:2048
	global_load_dwordx4 v[124:127], v193, s[34:35] offset:3072
	global_load_dwordx4 v[212:215], v193, s[82:83] offset:3072
	s_waitcnt vmcnt(0)
	v_mul_f32_e32 v112, v112, v200
	v_mul_f32_e32 v113, v113, v201
	v_mul_f32_e32 v114, v114, v202
	v_mul_f32_e32 v115, v115, v203
	v_mul_f32_e32 v116, v116, v204
	v_mul_f32_e32 v117, v117, v205
	v_mul_f32_e32 v118, v118, v206
	v_mul_f32_e32 v119, v119, v207
	v_mul_f32_e32 v120, v120, v208
	v_mul_f32_e32 v121, v121, v209
	v_mul_f32_e32 v122, v122, v210
	v_mul_f32_e32 v123, v123, v211
	v_mul_f32_e32 v124, v124, v212
	v_mul_f32_e32 v125, v125, v213
	v_mul_f32_e32 v126, v126, v214
	v_mul_f32_e32 v127, v127, v215
	global_load_dwordx4 v[144:147], v193, s[38:39] offset:0
	global_load_dwordx4 v[200:203], v193, s[44:45] offset:0
	global_load_dwordx4 v[176:179], v193, s[36:37] offset:0
	global_load_dwordx4 v[148:151], v193, s[38:39] offset:1024
	global_load_dwordx4 v[204:207], v193, s[44:45] offset:1024
	global_load_dwordx4 v[180:183], v193, s[36:37] offset:1024
	global_load_dwordx4 v[152:155], v193, s[38:39] offset:2048
	global_load_dwordx4 v[208:211], v193, s[44:45] offset:2048
	global_load_dwordx4 v[184:187], v193, s[36:37] offset:2048
	global_load_dwordx4 v[156:159], v193, s[38:39] offset:3072
	global_load_dwordx4 v[212:215], v193, s[44:45] offset:3072
	global_load_dwordx4 v[188:191], v193, s[36:37] offset:3072
	s_waitcnt vmcnt(0)
	v_add_f32_e32 v200, 1.0, v200
	v_add_f32_e32 v201, 1.0, v201
	v_add_f32_e32 v202, 1.0, v202
	v_add_f32_e32 v203, 1.0, v203
	v_mul_f32_e32 v144, v144, v200
	v_mul_f32_e32 v145, v145, v201
	v_mul_f32_e32 v146, v146, v202
	v_mul_f32_e32 v147, v147, v203
	v_add_f32_e32 v204, 1.0, v204
	v_add_f32_e32 v205, 1.0, v205
	v_add_f32_e32 v206, 1.0, v206
	v_add_f32_e32 v207, 1.0, v207
	v_mul_f32_e32 v148, v148, v204
	v_mul_f32_e32 v149, v149, v205
	v_mul_f32_e32 v150, v150, v206
	v_mul_f32_e32 v151, v151, v207
	v_add_f32_e32 v208, 1.0, v208
	v_add_f32_e32 v209, 1.0, v209
	v_add_f32_e32 v210, 1.0, v210
	v_add_f32_e32 v211, 1.0, v211
	v_mul_f32_e32 v152, v152, v208
	v_mul_f32_e32 v153, v153, v209
	v_mul_f32_e32 v154, v154, v210
	v_mul_f32_e32 v155, v155, v211
	v_add_f32_e32 v212, 1.0, v212
	v_add_f32_e32 v213, 1.0, v213
	v_add_f32_e32 v214, 1.0, v214
	v_add_f32_e32 v215, 1.0, v215
	v_mul_f32_e32 v156, v156, v212
	v_mul_f32_e32 v157, v157, v213
	v_mul_f32_e32 v158, v158, v214
	v_mul_f32_e32 v159, v159, v215
; __device__ __forceinline__ float bf_lo(unsigned w) { return __uint_as_float(w << 16); }
; __device__ __forceinline__ float bf_hi(unsigned w) { return __uint_as_float(w & 0xffff0000u); }
; __global__ void __launch_bounds__(NWAVES * 64, 2) mk_fwd(Args args) {
;     ...
;             for (int q = 0; q < 3; ++q) { const int row = row0 + q; const bool lat = row < ML; const int r = lat ? row / SEQ : 8;
;                 float sy = 0.f;
; #pragma unroll
;                 for (int j = 0; j < 8; ++j) { const float a = bf_lo(yw[q][j].x), b = bf_hi(yw[q][j].x), c2 = bf_lo(yw[q][j].y), d = bf_hi(yw[q][j].y); sy += (a * a + b * b) + (c2 * c2 + d * d); }
;                 const float rsy = __builtin_amdgcn_rsqf(wave_sum(sy) * (1.f / DM) + EPS);
;                 const float* m0 = mod + (size_t)r * 6144;
; #pragma unroll
;                 for (int j = 0; j < 8; ++j) { const int col = 4 * F.lane + 256 * j; const f32x4 gt = *(const f32x4*)(m0 + 2 * DM + col), pn = *(const f32x4*)(post_norm + col);
;                     const f32x4 y4 = (f32x4){bf_lo(yw[q][j].x), bf_hi(yw[q][j].x), bf_lo(yw[q][j].y), bf_hi(yw[q][j].y)};
;                     v[q][j] = v[q][j] + gt * (y4 * rsy * pn);
.Lp6_np2:
	s_waitcnt vmcnt(24)
	v_lshlrev_b32_e32 v216, 16, v32
	v_and_b32_e32 v217, 0xffff0000, v32
	v_lshlrev_b32_e32 v218, 16, v33
	v_and_b32_e32 v219, 0xffff0000, v33
	v_mul_f32_e32 v222, v216, v216
	v_mul_f32_e32 v223, v217, v217
	v_fmac_f32_e32 v222, v218, v218
	v_fmac_f32_e32 v223, v219, v219
	v_lshlrev_b32_e32 v216, 16, v34
	v_and_b32_e32 v217, 0xffff0000, v34
	v_lshlrev_b32_e32 v218, 16, v35
	v_and_b32_e32 v219, 0xffff0000, v35
	v_fmac_f32_e32 v222, v216, v216
	v_fmac_f32_e32 v223, v217, v217
	v_fmac_f32_e32 v222, v218, v218
	v_fmac_f32_e32 v223, v219, v219
	v_lshlrev_b32_e32 v216, 16, v36
	v_and_b32_e32 v217, 0xffff0000, v36
	v_lshlrev_b32_e32 v218, 16, v37
	v_and_b32_e32 v219, 0xffff0000, v37
	v_fmac_f32_e32 v222, v216, v216
	v_fmac_f32_e32 v223, v217, v217
	v_fmac_f32_e32 v222, v218, v218
	v_fmac_f32_e32 v223, v219, v219
	v_lshlrev_b32_e32 v216, 16, v38
	v_and_b32_e32 v217, 0xffff0000, v38
	v_lshlrev_b32_e32 v218, 16, v39
	v_and_b32_e32 v219, 0xffff0000, v39
	v_fmac_f32_e32 v222, v216, v216
	v_fmac_f32_e32 v223, v217, v217
	v_fmac_f32_e32 v222, v218, v218
	v_fmac_f32_e32 v223, v219, v219
	v_lshlrev_b32_e32 v216, 16, v40
	v_and_b32_e32 v217, 0xffff0000, v40
	v_lshlrev_b32_e32 v218, 16, v41
	v_and_b32_e32 v219, 0xffff0000, v41
	v_fmac_f32_e32 v222, v216, v216
	v_fmac_f32_e32 v223, v217, v217
	v_fmac_f32_e32 v222, v218, v218
	v_fmac_f32_e32 v223, v219, v219
	v_lshlrev_b32_e32 v216, 16, v42
	v_and_b32_e32 v217, 0xffff0000, v42
	v_lshlrev_b32_e32 v218, 16, v43
	v_and_b32_e32 v219, 0xffff0000, v43
	v_fmac_f32_e32 v222, v216, v216
	v_fmac_f32_e32 v223, v217, v217
	v_fmac_f32_e32 v222, v218, v218
	v_fmac_f32_e32 v223, v219, v219
	v_lshlrev_b32_e32 v216, 16, v44
	v_and_b32_e32 v217, 0xffff0000, v44
	v_lshlrev_b32_e32 v218, 16, v45
	v_and_b32_e32 v219, 0xffff0000, v45
	v_fmac_f32_e32 v222, v216, v216
	v_fmac_f32_e32 v223, v217, v217
	v_fmac_f32_e32 v222, v218, v218
	v_fmac_f32_e32 v223, v219, v219
	v_lshlrev_b32_e32 v216, 16, v46
	v_and_b32_e32 v217, 0xffff0000, v46
	v_lshlrev_b32_e32 v218, 16, v47
	v_and_b32_e32 v219, 0xffff0000, v47
	v_fmac_f32_e32 v222, v216, v216
	v_fmac_f32_e32 v223, v217, v217
	v_fmac_f32_e32 v222, v218, v218
	v_fmac_f32_e32 v223, v219, v219
	v_add_f32_e32 v222, v222, v223
	s_nop 1
	v_add_f32_dpp v224, v222, v222 quad_perm:[1,0,3,2] row_mask:0xf bank_mask:0xf
	s_nop 1
	v_add_f32_dpp v224, v224, v224 quad_perm:[2,3,0,1] row_mask:0xf bank_mask:0xf
	s_nop 1
	v_add_f32_dpp v224, v224, v224 row_half_mirror row_mask:0xf bank_mask:0xf
	s_nop 1
	v_add_f32_dpp v224, v224, v224 row_mirror row_mask:0xf bank_mask:0xf
	s_nop 1
	v_readlane_b32 s40, v224, 0
	v_readlane_b32 s41, v224, 16
	v_readlane_b32 s42, v224, 32
	v_readlane_b32 s43, v224, 48
	s_nop 1
	v_mov_b32_e32 v225, s40
	v_add_f32_e32 v225, s41, v225
	v_add_f32_e32 v225, s42, v225
	v_add_f32_e32 v225, s43, v225
	v_fmamk_f32 v225, v225, 0x3a000000, v195
	v_rsq_f32_e32 v225, v225
	s_nop 0
	v_lshlrev_b32_e32 v216, 16, v32
	v_and_b32_e32 v217, 0xffff0000, v32
	v_lshlrev_b32_e32 v218, 16, v33
	v_and_b32_e32 v219, 0xffff0000, v33
	v_mul_f32_e32 v216, v225, v216
	v_mul_f32_e32 v217, v225, v217
	v_mul_f32_e32 v218, v225, v218
	v_mul_f32_e32 v219, v225, v219
	v_fmac_f32_e32 v0, v96, v216
	v_fmac_f32_e32 v1, v97, v217
	v_fmac_f32_e32 v2, v98, v218
	v_fmac_f32_e32 v3, v99, v219
	v_lshlrev_b32_e32 v216, 16, v34
	v_and_b32_e32 v217, 0xffff0000, v34
	v_lshlrev_b32_e32 v218, 16, v35
	v_and_b32_e32 v219, 0xffff0000, v35
	v_mul_f32_e32 v216, v225, v216
	v_mul_f32_e32 v217, v225, v217
	v_mul_f32_e32 v218, v225, v218
	v_mul_f32_e32 v219, v225, v219
	v_fmac_f32_e32 v4, v100, v216
	v_fmac_f32_e32 v5, v101, v217
	v_fmac_f32_e32 v6, v102, v218
	v_fmac_f32_e32 v7, v103, v219
	v_lshlrev_b32_e32 v216, 16, v36
	v_and_b32_e32 v217, 0xffff0000, v36
	v_lshlrev_b32_e32 v218, 16, v37
	v_and_b32_e32 v219, 0xffff0000, v37
	v_mul_f32_e32 v216, v225, v216
	v_mul_f32_e32 v217, v225, v217
	v_mul_f32_e32 v218, v225, v218
	v_mul_f32_e32 v219, v225, v219
	v_fmac_f32_e32 v8, v104, v216
	v_fmac_f32_e32 v9, v105, v217
	v_fmac_f32_e32 v10, v106, v218
	v_fmac_f32_e32 v11, v107, v219
	v_lshlrev_b32_e32 v216, 16, v38
	v_and_b32_e32 v217, 0xffff0000, v38
	v_lshlrev_b32_e32 v218, 16, v39
	v_and_b32_e32 v219, 0xffff0000, v39
	v_mul_f32_e32 v216, v225, v216
	v_mul_f32_e32 v217, v225, v217
	v_mul_f32_e32 v218, v225, v218
	v_mul_f32_e32 v219, v225, v219
	v_fmac_f32_e32 v12, v108, v216
	v_fmac_f32_e32 v13, v109, v217
	v_fmac_f32_e32 v14, v110, v218
	v_fmac_f32_e32 v15, v111, v219
	v_lshlrev_b32_e32 v216, 16, v40
	v_and_b32_e32 v217, 0xffff0000, v40
	v_lshlrev_b32_e32 v218, 16, v41
	v_and_b32_e32 v219, 0xffff0000, v41
	v_mul_f32_e32 v216, v225, v216
	v_mul_f32_e32 v217, v225, v217
	v_mul_f32_e32 v218, v225, v218
	v_mul_f32_e32 v219, v225, v219
	v_fmac_f32_e32 v16, v112, v216
	v_fmac_f32_e32 v17, v113, v217
	v_fmac_f32_e32 v18, v114, v218
	v_fmac_f32_e32 v19, v115, v219
	v_lshlrev_b32_e32 v216, 16, v42
	v_and_b32_e32 v217, 0xffff0000, v42
	v_lshlrev_b32_e32 v218, 16, v43
	v_and_b32_e32 v219, 0xffff0000, v43
	v_mul_f32_e32 v216, v225, v216
	v_mul_f32_e32 v217, v225, v217
	v_mul_f32_e32 v218, v225, v218
	v_mul_f32_e32 v219, v225, v219
	v_fmac_f32_e32 v20, v116, v216
	v_fmac_f32_e32 v21, v117, v217
	v_fmac_f32_e32 v22, v118, v218
	v_fmac_f32_e32 v23, v119, v219
	v_lshlrev_b32_e32 v216, 16, v44
	v_and_b32_e32 v217, 0xffff0000, v44
	v_lshlrev_b32_e32 v218, 16, v45
	v_and_b32_e32 v219, 0xffff0000, v45
	v_mul_f32_e32 v216, v225, v216
	v_mul_f32_e32 v217, v225, v217
	v_mul_f32_e32 v218, v225, v218
	v_mul_f32_e32 v219, v225, v219
	v_fmac_f32_e32 v24, v120, v216
	v_fmac_f32_e32 v25, v121, v217
	v_fmac_f32_e32 v26, v122, v218
; __device__ __forceinline__ unsigned cvt_pk_bf16(float lo, float hi) { unsigned r; asm volatile("v_cvt_pk_bf16_f32 %0, %1, %2" : "=v"(r) : "v"(lo), "v"(hi)); return r; }
; __device__ __forceinline__ float bf_lo(unsigned w) { return __uint_as_float(w << 16); }
; __device__ __forceinline__ float bf_hi(unsigned w) { return __uint_as_float(w & 0xffff0000u); }
; __device__ __forceinline__ void modulate_store(const f32x4 (&v)[8], float rstd, const float* pn, const float* modr, bf16_t* orow, int lane) {
; #pragma unroll
;     for (int j = 0; j < 8; ++j) { const int col = 4 * lane + 256 * j;
;         const f32x4 g = *(const f32x4*)(pn + col), sh = *(const f32x4*)(modr + col), sc = *(const f32x4*)(modr + DM + col);
;         const f32x4 hh = v[j] * rstd * g * (sc + 1.f) + sh;
;         u32x2 w; w.x = cvt_pk_bf16(hh[0], hh[1]); w.y = cvt_pk_bf16(hh[2], hh[3]);
;         *(u32x2*)(orow + col) = w; }
; __global__ void __launch_bounds__(NWAVES * 64, 2) mk_fwd(Args args) {
;     ...
;             for (int q = 0; q < 3; ++q) { const int row = row0 + q; const bool lat = row < ML; const int r = lat ? row / SEQ : 8;
;                 float sy = 0.f;
; #pragma unroll
;                 for (int j = 0; j < 8; ++j) { const float a = bf_lo(yw[q][j].x), b = bf_hi(yw[q][j].x), c2 = bf_lo(yw[q][j].y), d = bf_hi(yw[q][j].y); sy += (a * a + b * b) + (c2 * c2 + d * d); }
;                 const float rsy = __builtin_amdgcn_rsqf(wave_sum(sy) * (1.f / DM) + EPS);
;                 const float* m0 = mod + (size_t)r * 6144;
; #pragma unroll
;                 for (int j = 0; j < 8; ++j) { const int col = 4 * F.lane + 256 * j; const f32x4 gt = *(const f32x4*)(m0 + 2 * DM + col), pn = *(const f32x4*)(post_norm + col);
;                     const f32x4 y4 = (f32x4){bf_lo(yw[q][j].x), bf_hi(yw[q][j].x), bf_lo(yw[q][j].y), bf_hi(yw[q][j].y)};
;                     v[q][j] = v[q][j] + gt * (y4 * rsy * pn);
;                     if (lat) *(f32x4*)(args.out + (size_t)row * DM + col) = v[q][j]; }
;                 const float rstd = __builtin_amdgcn_rsqf(sumsq8(v[q]) * (1.f / DM) + EPS);
;                 modulate_store(v[q], rstd, pre_norm + DM, mod + (size_t)(9 + r) * 6144, H + (size_t)row * DM, F.lane); }
	v_fmac_f32_e32 v27, v123, v219
	v_lshlrev_b32_e32 v216, 16, v46
	v_and_b32_e32 v217, 0xffff0000, v46
	v_lshlrev_b32_e32 v218, 16, v47
	v_and_b32_e32 v219, 0xffff0000, v47
	v_mul_f32_e32 v216, v225, v216
	v_mul_f32_e32 v217, v225, v217
	v_mul_f32_e32 v218, v225, v218
	v_mul_f32_e32 v219, v225, v219
	v_fmac_f32_e32 v28, v124, v216
	v_fmac_f32_e32 v29, v125, v217
	v_fmac_f32_e32 v30, v126, v218
	v_fmac_f32_e32 v31, v127, v219
	v_mul_f32_e32 v222, v0, v0
	v_mul_f32_e32 v223, v1, v1
	v_fmac_f32_e32 v222, v2, v2
	v_fmac_f32_e32 v223, v3, v3
	v_fmac_f32_e32 v222, v4, v4
	v_fmac_f32_e32 v223, v5, v5
	v_fmac_f32_e32 v222, v6, v6
	v_fmac_f32_e32 v223, v7, v7
	v_fmac_f32_e32 v222, v8, v8
	v_fmac_f32_e32 v223, v9, v9
	v_fmac_f32_e32 v222, v10, v10
	v_fmac_f32_e32 v223, v11, v11
	v_fmac_f32_e32 v222, v12, v12
	v_fmac_f32_e32 v223, v13, v13
	v_fmac_f32_e32 v222, v14, v14
	v_fmac_f32_e32 v223, v15, v15
	v_fmac_f32_e32 v222, v16, v16
	v_fmac_f32_e32 v223, v17, v17
	v_fmac_f32_e32 v222, v18, v18
	v_fmac_f32_e32 v223, v19, v19
	v_fmac_f32_e32 v222, v20, v20
	v_fmac_f32_e32 v223, v21, v21
	v_fmac_f32_e32 v222, v22, v22
	v_fmac_f32_e32 v223, v23, v23
	v_fmac_f32_e32 v222, v24, v24
	v_fmac_f32_e32 v223, v25, v25
	v_fmac_f32_e32 v222, v26, v26
	v_fmac_f32_e32 v223, v27, v27
	v_fmac_f32_e32 v222, v28, v28
	v_fmac_f32_e32 v223, v29, v29
	v_fmac_f32_e32 v222, v30, v30
	v_fmac_f32_e32 v223, v31, v31
	v_add_f32_e32 v222, v222, v223
	s_nop 1
	v_add_f32_dpp v224, v222, v222 quad_perm:[1,0,3,2] row_mask:0xf bank_mask:0xf
	s_nop 1
	v_add_f32_dpp v224, v224, v224 quad_perm:[2,3,0,1] row_mask:0xf bank_mask:0xf
	s_nop 1
	v_add_f32_dpp v224, v224, v224 row_half_mirror row_mask:0xf bank_mask:0xf
	s_nop 1
	v_add_f32_dpp v224, v224, v224 row_mirror row_mask:0xf bank_mask:0xf
	s_nop 1
	v_readlane_b32 s40, v224, 0
	v_readlane_b32 s41, v224, 16
	v_readlane_b32 s42, v224, 32
	v_readlane_b32 s43, v224, 48
	s_nop 1
	v_mov_b32_e32 v225, s40
	v_add_f32_e32 v225, s41, v225
	v_add_f32_e32 v225, s42, v225
	v_add_f32_e32 v225, s43, v225
	v_fmamk_f32 v225, v225, 0x3a000000, v195
	v_rsq_f32_e32 v225, v225
	s_nop 0
	s_add_i32 s0, s6, 2
	s_lshl_b32 s1, s0, 12
	s_add_u32 s26, s84, s1
	s_addc_u32 s27, s85, 0
	s_add_u32 s26, s26, 0x4000000
	s_addc_u32 s27, s27, 0
	v_mul_f32_e32 v216, v225, v0
	v_mul_f32_e32 v217, v225, v1
	v_mul_f32_e32 v218, v225, v2
	v_mul_f32_e32 v219, v225, v3
	v_fma_f32 v216, v216, v128, v160
	v_fma_f32 v217, v217, v129, v161
	v_fma_f32 v218, v218, v130, v162
	v_fma_f32 v219, v219, v131, v163
	v_cvt_pk_bf16_f32 v196, v216, v217
	v_cvt_pk_bf16_f32 v197, v218, v219
	global_store_dwordx2 v194, v[196:197], s[26:27] offset:0 nt
	v_mul_f32_e32 v216, v225, v4
	v_mul_f32_e32 v217, v225, v5
	v_mul_f32_e32 v218, v225, v6
	v_mul_f32_e32 v219, v225, v7
	v_fma_f32 v216, v216, v132, v164
	v_fma_f32 v217, v217, v133, v165
	v_fma_f32 v218, v218, v134, v166
	v_fma_f32 v219, v219, v135, v167
	v_cvt_pk_bf16_f32 v220, v216, v217
	v_cvt_pk_bf16_f32 v221, v218, v219
	global_store_dwordx2 v194, v[220:221], s[26:27] offset:512 nt
	v_mul_f32_e32 v216, v225, v8
	v_mul_f32_e32 v217, v225, v9
	v_mul_f32_e32 v218, v225, v10
	v_mul_f32_e32 v219, v225, v11
	v_fma_f32 v216, v216, v136, v168
	v_fma_f32 v217, v217, v137, v169
	v_fma_f32 v218, v218, v138, v170
	v_fma_f32 v219, v219, v139, v171
	v_cvt_pk_bf16_f32 v196, v216, v217
	v_cvt_pk_bf16_f32 v197, v218, v219
	global_store_dwordx2 v194, v[196:197], s[26:27] offset:1024 nt
	v_mul_f32_e32 v216, v225, v12
	v_mul_f32_e32 v217, v225, v13
	v_mul_f32_e32 v218, v225, v14
	v_mul_f32_e32 v219, v225, v15
	v_fma_f32 v216, v216, v140, v172
	v_fma_f32 v217, v217, v141, v173
	v_fma_f32 v218, v218, v142, v174
	v_fma_f32 v219, v219, v143, v175
	v_cvt_pk_bf16_f32 v220, v216, v217
	v_cvt_pk_bf16_f32 v221, v218, v219
	global_store_dwordx2 v194, v[220:221], s[26:27] offset:1536 nt
	v_mul_f32_e32 v216, v225, v16
	v_mul_f32_e32 v217, v225, v17
	v_mul_f32_e32 v218, v225, v18
	v_mul_f32_e32 v219, v225, v19
	v_fma_f32 v216, v216, v144, v176
	v_fma_f32 v217, v217, v145, v177
	v_fma_f32 v218, v218, v146, v178
	v_fma_f32 v219, v219, v147, v179
	v_cvt_pk_bf16_f32 v196, v216, v217
	v_cvt_pk_bf16_f32 v197, v218, v219
	global_store_dwordx2 v194, v[196:197], s[26:27] offset:2048 nt
	v_mul_f32_e32 v216, v225, v20
	v_mul_f32_e32 v217, v225, v21
	v_mul_f32_e32 v218, v225, v22
	v_mul_f32_e32 v219, v225, v23
	v_fma_f32 v216, v216, v148, v180
	v_fma_f32 v217, v217, v149, v181
	v_fma_f32 v218, v218, v150, v182
	v_fma_f32 v219, v219, v151, v183
	v_cvt_pk_bf16_f32 v220, v216, v217
	v_cvt_pk_bf16_f32 v221, v218, v219
	global_store_dwordx2 v194, v[220:221], s[26:27] offset:2560 nt
	v_mul_f32_e32 v216, v225, v24
	v_mul_f32_e32 v217, v225, v25
	v_mul_f32_e32 v218, v225, v26
	v_mul_f32_e32 v219, v225, v27
	v_fma_f32 v216, v216, v152, v184
	v_fma_f32 v217, v217, v153, v185
	v_fma_f32 v218, v218, v154, v186
	v_fma_f32 v219, v219, v155, v187
	v_cvt_pk_bf16_f32 v196, v216, v217
	v_cvt_pk_bf16_f32 v197, v218, v219
	global_store_dwordx2 v194, v[196:197], s[26:27] offset:3072 nt
	v_mul_f32_e32 v216, v225, v28
	v_mul_f32_e32 v217, v225, v29
	v_mul_f32_e32 v218, v225, v30
	v_mul_f32_e32 v219, v225, v31
	v_fma_f32 v216, v216, v156, v188
	v_fma_f32 v217, v217, v157, v189
	v_fma_f32 v218, v218, v158, v190
	v_fma_f32 v219, v219, v159, v191
	v_cvt_pk_bf16_f32 v220, v216, v217
	v_cvt_pk_bf16_f32 v221, v218, v219
	global_store_dwordx2 v194, v[220:221], s[26:27] offset:3584 nt
	s_add_i32 s0, s6, 4
	s_cmp_lt_u32 s0, 0x4000
	s_cselect_b32 s10, s68, s72
	s_cselect_b32 s11, s69, s73
	s_cselect_b32 s1, 0, 0x4000
	s_sub_i32 s1, s0, s1
	s_lshl_b32 s1, s1, 13
	s_add_u32 s10, s10, s1
	s_addc_u32 s11, s11, 0
	s_add_i32 s0, s6, 4
	s_lshl_b32 s1, s0, 12
	s_add_u32 s22, s84, s1
	s_addc_u32 s23, s85, 0
	s_add_u32 s22, s22, 0x11800000
	s_addc_u32 s23, s23, 0
	global_load_dwordx4 v[0:3], v192, s[10:11] offset:0 nt
	global_load_dwordx4 v[4:7], v192, s[10:11] offset:1024 nt
	global_load_dwordx4 v[8:11], v192, s[10:11] offset:2048 nt
	global_load_dwordx4 v[12:15], v192, s[10:11] offset:3072 nt
	global_load_dwordx4 v[16:19], v193, s[10:11] offset:0 nt
	global_load_dwordx4 v[20:23], v193, s[10:11] offset:1024 nt
	global_load_dwordx4 v[24:27], v193, s[10:11] offset:2048 nt
	global_load_dwordx4 v[28:31], v193, s[10:11] offset:3072 nt
	global_load_dwordx2 v[32:33], v194, s[22:23] offset:0
	global_load_dwordx2 v[34:35], v194, s[22:23] offset:512
	global_load_dwordx2 v[36:37], v194, s[22:23] offset:1024
	global_load_dwordx2 v[38:39], v194, s[22:23] offset:1536
	global_load_dwordx2 v[40:41], v194, s[22:23] offset:2048
	global_load_dwordx2 v[42:43], v194, s[22:23] offset:2560
	global_load_dwordx2 v[44:45], v194, s[22:23] offset:3072
	global_load_dwordx2 v[46:47], v194, s[22:23] offset:3584
	s_add_i32 s0, s6, 3
	s_add_i32 s0, s6, 3
	s_lshr_b32 s8, s0, 11
	s_cmp_lt_u32 s0, 0x4000
	s_cselect_b32 s8, s8, 8
	s_cmp_eq_u32 s8, s7
	s_cbranch_scc1 .Lp6_np3
; __device__ __forceinline__ unsigned cvt_pk_bf16(float lo, float hi) { unsigned r; asm volatile("v_cvt_pk_bf16_f32 %0, %1, %2" : "=v"(r) : "v"(lo), "v"(hi)); return r; }
; __device__ __forceinline__ float bf_lo(unsigned w) { return __uint_as_float(w << 16); }
; __device__ __forceinline__ float bf_hi(unsigned w) { return __uint_as_float(w & 0xffff0000u); }
; __device__ __forceinline__ void modulate_store(const f32x4 (&v)[8], float rstd, const float* pn, const float* modr, bf16_t* orow, int lane) {
; #pragma unroll
;     for (int j = 0; j < 8; ++j) { const int col = 4 * lane + 256 * j;
;         const f32x4 g = *(const f32x4*)(pn + col), sh = *(const f32x4*)(modr + col), sc = *(const f32x4*)(modr + DM + col);
;         const f32x4 hh = v[j] * rstd * g * (sc + 1.f) + sh;
;         u32x2 w; w.x = cvt_pk_bf16(hh[0], hh[1]); w.y = cvt_pk_bf16(hh[2], hh[3]);
; __global__ void __launch_bounds__(NWAVES * 64, 2) mk_fwd(Args args) {
;     ...
;                 const float* m0 = mod + (size_t)r * 6144;
; #pragma unroll
;                 for (int j = 0; j < 8; ++j) { const int col = 4 * F.lane + 256 * j; const f32x4 gt = *(const f32x4*)(m0 + 2 * DM + col), pn = *(const f32x4*)(post_norm + col);
;                     const f32x4 y4 = (f32x4){bf_lo(yw[q][j].x), bf_hi(yw[q][j].x), bf_lo(yw[q][j].y), bf_hi(yw[q][j].y)};
;                     v[q][j] = v[q][j] + gt * (y4 * rsy * pn);
	s_mov_b32 s7, s8
	s_add_i32 s1, s8, 9
	s_mul_i32 s1, s1, 0x6000
	s_add_u32 s44, s84, s1
	s_addc_u32 s45, s85, 0
	s_add_u32 s44, s44, 0x2000
	s_addc_u32 s45, s45, 0
	s_add_i32 s1, s8, 9
	s_mul_i32 s1, s1, 0x6000
	s_add_u32 s36, s84, s1
	s_addc_u32 s37, s85, 0
	s_add_u32 s38, s80, 0x2000
	s_addc_u32 s39, s81, 0
	s_mul_i32 s1, s8, 0x6000
	s_add_u32 s34, s84, s1
	s_addc_u32 s35, s85, 0
	s_add_u32 s34, s34, 0x4000
	s_addc_u32 s35, s35, 0
	global_load_dwordx4 v[96:99], v192, s[34:35] offset:0
	global_load_dwordx4 v[200:203], v192, s[82:83] offset:0
	global_load_dwordx4 v[100:103], v192, s[34:35] offset:1024
	global_load_dwordx4 v[204:207], v192, s[82:83] offset:1024
	global_load_dwordx4 v[104:107], v192, s[34:35] offset:2048
	global_load_dwordx4 v[208:211], v192, s[82:83] offset:2048
	global_load_dwordx4 v[108:111], v192, s[34:35] offset:3072
	global_load_dwordx4 v[212:215], v192, s[82:83] offset:3072
	s_waitcnt vmcnt(0)
	v_mul_f32_e32 v96, v96, v200
	v_mul_f32_e32 v97, v97, v201
	v_mul_f32_e32 v98, v98, v202
	v_mul_f32_e32 v99, v99, v203
	v_mul_f32_e32 v100, v100, v204
	v_mul_f32_e32 v101, v101, v205
	v_mul_f32_e32 v102, v102, v206
	v_mul_f32_e32 v103, v103, v207
	v_mul_f32_e32 v104, v104, v208
	v_mul_f32_e32 v105, v105, v209
	v_mul_f32_e32 v106, v106, v210
	v_mul_f32_e32 v107, v107, v211
	v_mul_f32_e32 v108, v108, v212
	v_mul_f32_e32 v109, v109, v213
	v_mul_f32_e32 v110, v110, v214
	v_mul_f32_e32 v111, v111, v215
	global_load_dwordx4 v[128:131], v192, s[38:39] offset:0
	global_load_dwordx4 v[200:203], v192, s[44:45] offset:0
	global_load_dwordx4 v[160:163], v192, s[36:37] offset:0
	global_load_dwordx4 v[132:135], v192, s[38:39] offset:1024
	global_load_dwordx4 v[204:207], v192, s[44:45] offset:1024
	global_load_dwordx4 v[164:167], v192, s[36:37] offset:1024
	global_load_dwordx4 v[136:139], v192, s[38:39] offset:2048
	global_load_dwordx4 v[208:211], v192, s[44:45] offset:2048
	global_load_dwordx4 v[168:171], v192, s[36:37] offset:2048
	global_load_dwordx4 v[140:143], v192, s[38:39] offset:3072
	global_load_dwordx4 v[212:215], v192, s[44:45] offset:3072
	global_load_dwordx4 v[172:175], v192, s[36:37] offset:3072
	s_waitcnt vmcnt(0)
	v_add_f32_e32 v200, 1.0, v200
	v_add_f32_e32 v201, 1.0, v201
	v_add_f32_e32 v202, 1.0, v202
	v_add_f32_e32 v203, 1.0, v203
	v_mul_f32_e32 v128, v128, v200
	v_mul_f32_e32 v129, v129, v201
	v_mul_f32_e32 v130, v130, v202
	v_mul_f32_e32 v131, v131, v203
	v_add_f32_e32 v204, 1.0, v204
	v_add_f32_e32 v205, 1.0, v205
	v_add_f32_e32 v206, 1.0, v206
	v_add_f32_e32 v207, 1.0, v207
	v_mul_f32_e32 v132, v132, v204
	v_mul_f32_e32 v133, v133, v205
	v_mul_f32_e32 v134, v134, v206
	v_mul_f32_e32 v135, v135, v207
	v_add_f32_e32 v208, 1.0, v208
	v_add_f32_e32 v209, 1.0, v209
	v_add_f32_e32 v210, 1.0, v210
	v_add_f32_e32 v211, 1.0, v211
	v_mul_f32_e32 v136, v136, v208
	v_mul_f32_e32 v137, v137, v209
	v_mul_f32_e32 v138, v138, v210
	v_mul_f32_e32 v139, v139, v211
	v_add_f32_e32 v212, 1.0, v212
	v_add_f32_e32 v213, 1.0, v213
	v_add_f32_e32 v214, 1.0, v214
	v_add_f32_e32 v215, 1.0, v215
	v_mul_f32_e32 v140, v140, v212
	v_mul_f32_e32 v141, v141, v213
	v_mul_f32_e32 v142, v142, v214
	v_mul_f32_e32 v143, v143, v215
	global_load_dwordx4 v[112:115], v193, s[34:35] offset:0
	global_load_dwordx4 v[200:203], v193, s[82:83] offset:0
	global_load_dwordx4 v[116:119], v193, s[34:35] offset:1024
	global_load_dwordx4 v[204:207], v193, s[82:83] offset:1024
	global_load_dwordx4 v[120:123], v193, s[34:35] offset:2048
	global_load_dwordx4 v[208:211], v193, s[82:83] offset:2048
	global_load_dwordx4 v[124:127], v193, s[34:35] offset:3072
	global_load_dwordx4 v[212:215], v193, s[82:83] offset:3072
	s_waitcnt vmcnt(0)
	v_mul_f32_e32 v112, v112, v200
	v_mul_f32_e32 v113, v113, v201
	v_mul_f32_e32 v114, v114, v202
	v_mul_f32_e32 v115, v115, v203
	v_mul_f32_e32 v116, v116, v204
	v_mul_f32_e32 v117, v117, v205
	v_mul_f32_e32 v118, v118, v206
	v_mul_f32_e32 v119, v119, v207
	v_mul_f32_e32 v120, v120, v208
	v_mul_f32_e32 v121, v121, v209
	v_mul_f32_e32 v122, v122, v210
	v_mul_f32_e32 v123, v123, v211
	v_mul_f32_e32 v124, v124, v212
	v_mul_f32_e32 v125, v125, v213
	v_mul_f32_e32 v126, v126, v214
	v_mul_f32_e32 v127, v127, v215
	global_load_dwordx4 v[144:147], v193, s[38:39] offset:0
	global_load_dwordx4 v[200:203], v193, s[44:45] offset:0
	global_load_dwordx4 v[176:179], v193, s[36:37] offset:0
	global_load_dwordx4 v[148:151], v193, s[38:39] offset:1024
	global_load_dwordx4 v[204:207], v193, s[44:45] offset:1024
	global_load_dwordx4 v[180:183], v193, s[36:37] offset:1024
	global_load_dwordx4 v[152:155], v193, s[38:39] offset:2048
	global_load_dwordx4 v[208:211], v193, s[44:45] offset:2048
	global_load_dwordx4 v[184:187], v193, s[36:37] offset:2048
	global_load_dwordx4 v[156:159], v193, s[38:39] offset:3072
	global_load_dwordx4 v[212:215], v193, s[44:45] offset:3072
	global_load_dwordx4 v[188:191], v193, s[36:37] offset:3072
	s_waitcnt vmcnt(0)
	v_add_f32_e32 v200, 1.0, v200
	v_add_f32_e32 v201, 1.0, v201
	v_add_f32_e32 v202, 1.0, v202
	v_add_f32_e32 v203, 1.0, v203
	v_mul_f32_e32 v144, v144, v200
	v_mul_f32_e32 v145, v145, v201
	v_mul_f32_e32 v146, v146, v202
	v_mul_f32_e32 v147, v147, v203
	v_add_f32_e32 v204, 1.0, v204
	v_add_f32_e32 v205, 1.0, v205
	v_add_f32_e32 v206, 1.0, v206
	v_add_f32_e32 v207, 1.0, v207
	v_mul_f32_e32 v148, v148, v204
	v_mul_f32_e32 v149, v149, v205
	v_mul_f32_e32 v150, v150, v206
	v_mul_f32_e32 v151, v151, v207
	v_add_f32_e32 v208, 1.0, v208
	v_add_f32_e32 v209, 1.0, v209
	v_add_f32_e32 v210, 1.0, v210
	v_add_f32_e32 v211, 1.0, v211
	v_mul_f32_e32 v152, v152, v208
	v_mul_f32_e32 v153, v153, v209
	v_mul_f32_e32 v154, v154, v210
	v_mul_f32_e32 v155, v155, v211
	v_add_f32_e32 v212, 1.0, v212
	v_add_f32_e32 v213, 1.0, v213
	v_add_f32_e32 v214, 1.0, v214
	v_add_f32_e32 v215, 1.0, v215
	v_mul_f32_e32 v156, v156, v212
	v_mul_f32_e32 v157, v157, v213
	v_mul_f32_e32 v158, v158, v214
	v_mul_f32_e32 v159, v159, v215
; __device__ __forceinline__ float bf_lo(unsigned w) { return __uint_as_float(w << 16); }
; __device__ __forceinline__ float bf_hi(unsigned w) { return __uint_as_float(w & 0xffff0000u); }
; __global__ void __launch_bounds__(NWAVES * 64, 2) mk_fwd(Args args) {
;     ...
;             for (int q = 0; q < 3; ++q) { const int row = row0 + q; const bool lat = row < ML; const int r = lat ? row / SEQ : 8;
;                 float sy = 0.f;
; #pragma unroll
;                 for (int j = 0; j < 8; ++j) { const float a = bf_lo(yw[q][j].x), b = bf_hi(yw[q][j].x), c2 = bf_lo(yw[q][j].y), d = bf_hi(yw[q][j].y); sy += (a * a + b * b) + (c2 * c2 + d * d); }
;                 const float rsy = __builtin_amdgcn_rsqf(wave_sum(sy) * (1.f / DM) + EPS);
;                 const float* m0 = mod + (size_t)r * 6144;
; #pragma unroll
;                 for (int j = 0; j < 8; ++j) { const int col = 4 * F.lane + 256 * j; const f32x4 gt = *(const f32x4*)(m0 + 2 * DM + col), pn = *(const f32x4*)(post_norm + col);
;                     const f32x4 y4 = (f32x4){bf_lo(yw[q][j].x), bf_hi(yw[q][j].x), bf_lo(yw[q][j].y), bf_hi(yw[q][j].y)};
;                     v[q][j] = v[q][j] + gt * (y4 * rsy * pn);
.Lp6_np3:
	s_waitcnt vmcnt(24)
	v_lshlrev_b32_e32 v216, 16, v80
	v_and_b32_e32 v217, 0xffff0000, v80
	v_lshlrev_b32_e32 v218, 16, v81
	v_and_b32_e32 v219, 0xffff0000, v81
	v_mul_f32_e32 v222, v216, v216
	v_mul_f32_e32 v223, v217, v217
	v_fmac_f32_e32 v222, v218, v218
	v_fmac_f32_e32 v223, v219, v219
	v_lshlrev_b32_e32 v216, 16, v82
	v_and_b32_e32 v217, 0xffff0000, v82
	v_lshlrev_b32_e32 v218, 16, v83
	v_and_b32_e32 v219, 0xffff0000, v83
	v_fmac_f32_e32 v222, v216, v216
	v_fmac_f32_e32 v223, v217, v217
	v_fmac_f32_e32 v222, v218, v218
	v_fmac_f32_e32 v223, v219, v219
	v_lshlrev_b32_e32 v216, 16, v84
	v_and_b32_e32 v217, 0xffff0000, v84
	v_lshlrev_b32_e32 v218, 16, v85
	v_and_b32_e32 v219, 0xffff0000, v85
	v_fmac_f32_e32 v222, v216, v216
	v_fmac_f32_e32 v223, v217, v217
	v_fmac_f32_e32 v222, v218, v218
	v_fmac_f32_e32 v223, v219, v219
	v_lshlrev_b32_e32 v216, 16, v86
	v_and_b32_e32 v217, 0xffff0000, v86
	v_lshlrev_b32_e32 v218, 16, v87
	v_and_b32_e32 v219, 0xffff0000, v87
	v_fmac_f32_e32 v222, v216, v216
	v_fmac_f32_e32 v223, v217, v217
	v_fmac_f32_e32 v222, v218, v218
	v_fmac_f32_e32 v223, v219, v219
	v_lshlrev_b32_e32 v216, 16, v88
	v_and_b32_e32 v217, 0xffff0000, v88
	v_lshlrev_b32_e32 v218, 16, v89
	v_and_b32_e32 v219, 0xffff0000, v89
	v_fmac_f32_e32 v222, v216, v216
	v_fmac_f32_e32 v223, v217, v217
	v_fmac_f32_e32 v222, v218, v218
	v_fmac_f32_e32 v223, v219, v219
	v_lshlrev_b32_e32 v216, 16, v90
	v_and_b32_e32 v217, 0xffff0000, v90
	v_lshlrev_b32_e32 v218, 16, v91
	v_and_b32_e32 v219, 0xffff0000, v91
	v_fmac_f32_e32 v222, v216, v216
	v_fmac_f32_e32 v223, v217, v217
	v_fmac_f32_e32 v222, v218, v218
	v_fmac_f32_e32 v223, v219, v219
	v_lshlrev_b32_e32 v216, 16, v92
	v_and_b32_e32 v217, 0xffff0000, v92
	v_lshlrev_b32_e32 v218, 16, v93
	v_and_b32_e32 v219, 0xffff0000, v93
	v_fmac_f32_e32 v222, v216, v216
	v_fmac_f32_e32 v223, v217, v217
	v_fmac_f32_e32 v222, v218, v218
	v_fmac_f32_e32 v223, v219, v219
	v_lshlrev_b32_e32 v216, 16, v94
	v_and_b32_e32 v217, 0xffff0000, v94
	v_lshlrev_b32_e32 v218, 16, v95
	v_and_b32_e32 v219, 0xffff0000, v95
	v_fmac_f32_e32 v222, v216, v216
	v_fmac_f32_e32 v223, v217, v217
	v_fmac_f32_e32 v222, v218, v218
	v_fmac_f32_e32 v223, v219, v219
	v_add_f32_e32 v222, v222, v223
	s_nop 1
	v_add_f32_dpp v224, v222, v222 quad_perm:[1,0,3,2] row_mask:0xf bank_mask:0xf
	s_nop 1
	v_add_f32_dpp v224, v224, v224 quad_perm:[2,3,0,1] row_mask:0xf bank_mask:0xf
	s_nop 1
	v_add_f32_dpp v224, v224, v224 row_half_mirror row_mask:0xf bank_mask:0xf
	s_nop 1
	v_add_f32_dpp v224, v224, v224 row_mirror row_mask:0xf bank_mask:0xf
	s_nop 1
	v_readlane_b32 s40, v224, 0
	v_readlane_b32 s41, v224, 16
	v_readlane_b32 s42, v224, 32
	v_readlane_b32 s43, v224, 48
	s_nop 1
	v_mov_b32_e32 v225, s40
	v_add_f32_e32 v225, s41, v225
	v_add_f32_e32 v225, s42, v225
	v_add_f32_e32 v225, s43, v225
	v_fmamk_f32 v225, v225, 0x3a000000, v195
	v_rsq_f32_e32 v225, v225
	s_nop 0
	v_lshlrev_b32_e32 v216, 16, v80
	v_and_b32_e32 v217, 0xffff0000, v80
	v_lshlrev_b32_e32 v218, 16, v81
	v_and_b32_e32 v219, 0xffff0000, v81
	v_mul_f32_e32 v216, v225, v216
	v_mul_f32_e32 v217, v225, v217
	v_mul_f32_e32 v218, v225, v218
	v_mul_f32_e32 v219, v225, v219
	v_fmac_f32_e32 v48, v96, v216
	v_fmac_f32_e32 v49, v97, v217
	v_fmac_f32_e32 v50, v98, v218
	v_fmac_f32_e32 v51, v99, v219
	v_lshlrev_b32_e32 v216, 16, v82
	v_and_b32_e32 v217, 0xffff0000, v82
	v_lshlrev_b32_e32 v218, 16, v83
	v_and_b32_e32 v219, 0xffff0000, v83
	v_mul_f32_e32 v216, v225, v216
	v_mul_f32_e32 v217, v225, v217
	v_mul_f32_e32 v218, v225, v218
	v_mul_f32_e32 v219, v225, v219
	v_fmac_f32_e32 v52, v100, v216
	v_fmac_f32_e32 v53, v101, v217
	v_fmac_f32_e32 v54, v102, v218
	v_fmac_f32_e32 v55, v103, v219
	v_lshlrev_b32_e32 v216, 16, v84
	v_and_b32_e32 v217, 0xffff0000, v84
	v_lshlrev_b32_e32 v218, 16, v85
	v_and_b32_e32 v219, 0xffff0000, v85
	v_mul_f32_e32 v216, v225, v216
	v_mul_f32_e32 v217, v225, v217
	v_mul_f32_e32 v218, v225, v218
	v_mul_f32_e32 v219, v225, v219
	v_fmac_f32_e32 v56, v104, v216
	v_fmac_f32_e32 v57, v105, v217
	v_fmac_f32_e32 v58, v106, v218
	v_fmac_f32_e32 v59, v107, v219
	v_lshlrev_b32_e32 v216, 16, v86
	v_and_b32_e32 v217, 0xffff0000, v86
	v_lshlrev_b32_e32 v218, 16, v87
	v_and_b32_e32 v219, 0xffff0000, v87
	v_mul_f32_e32 v216, v225, v216
	v_mul_f32_e32 v217, v225, v217
	v_mul_f32_e32 v218, v225, v218
	v_mul_f32_e32 v219, v225, v219
	v_fmac_f32_e32 v60, v108, v216
	v_fmac_f32_e32 v61, v109, v217
	v_fmac_f32_e32 v62, v110, v218
	v_fmac_f32_e32 v63, v111, v219
	v_lshlrev_b32_e32 v216, 16, v88
	v_and_b32_e32 v217, 0xffff0000, v88
	v_lshlrev_b32_e32 v218, 16, v89
	v_and_b32_e32 v219, 0xffff0000, v89
	v_mul_f32_e32 v216, v225, v216
	v_mul_f32_e32 v217, v225, v217
	v_mul_f32_e32 v218, v225, v218
	v_mul_f32_e32 v219, v225, v219
	v_fmac_f32_e32 v64, v112, v216
	v_fmac_f32_e32 v65, v113, v217
	v_fmac_f32_e32 v66, v114, v218
	v_fmac_f32_e32 v67, v115, v219
	v_lshlrev_b32_e32 v216, 16, v90
	v_and_b32_e32 v217, 0xffff0000, v90
	v_lshlrev_b32_e32 v218, 16, v91
	v_and_b32_e32 v219, 0xffff0000, v91
	v_mul_f32_e32 v216, v225, v216
	v_mul_f32_e32 v217, v225, v217
	v_mul_f32_e32 v218, v225, v218
	v_mul_f32_e32 v219, v225, v219
	v_fmac_f32_e32 v68, v116, v216
	v_fmac_f32_e32 v69, v117, v217
	v_fmac_f32_e32 v70, v118, v218
	v_fmac_f32_e32 v71, v119, v219
	v_lshlrev_b32_e32 v216, 16, v92
	v_and_b32_e32 v217, 0xffff0000, v92
	v_lshlrev_b32_e32 v218, 16, v93
	v_and_b32_e32 v219, 0xffff0000, v93
	v_mul_f32_e32 v216, v225, v216
	v_mul_f32_e32 v217, v225, v217
	v_mul_f32_e32 v218, v225, v218
	v_mul_f32_e32 v219, v225, v219
	v_fmac_f32_e32 v72, v120, v216
	v_fmac_f32_e32 v73, v121, v217
	v_fmac_f32_e32 v74, v122, v218
; __device__ __forceinline__ unsigned cvt_pk_bf16(float lo, float hi) { unsigned r; asm volatile("v_cvt_pk_bf16_f32 %0, %1, %2" : "=v"(r) : "v"(lo), "v"(hi)); return r; }
; __device__ __forceinline__ float bf_lo(unsigned w) { return __uint_as_float(w << 16); }
; __device__ __forceinline__ float bf_hi(unsigned w) { return __uint_as_float(w & 0xffff0000u); }
; __device__ __forceinline__ void modulate_store(const f32x4 (&v)[8], float rstd, const float* pn, const float* modr, bf16_t* orow, int lane) {
; #pragma unroll
;     for (int j = 0; j < 8; ++j) { const int col = 4 * lane + 256 * j;
;         const f32x4 g = *(const f32x4*)(pn + col), sh = *(const f32x4*)(modr + col), sc = *(const f32x4*)(modr + DM + col);
;         const f32x4 hh = v[j] * rstd * g * (sc + 1.f) + sh;
;         u32x2 w; w.x = cvt_pk_bf16(hh[0], hh[1]); w.y = cvt_pk_bf16(hh[2], hh[3]);
;         *(u32x2*)(orow + col) = w; }
; __global__ void __launch_bounds__(NWAVES * 64, 2) mk_fwd(Args args) {
;     ...
;             for (int q = 0; q < 3; ++q) { const int row = row0 + q; const bool lat = row < ML; const int r = lat ? row / SEQ : 8;
;                 float sy = 0.f;
; #pragma unroll
;                 for (int j = 0; j < 8; ++j) { const float a = bf_lo(yw[q][j].x), b = bf_hi(yw[q][j].x), c2 = bf_lo(yw[q][j].y), d = bf_hi(yw[q][j].y); sy += (a * a + b * b) + (c2 * c2 + d * d); }
;                 const float rsy = __builtin_amdgcn_rsqf(wave_sum(sy) * (1.f / DM) + EPS);
;                 const float* m0 = mod + (size_t)r * 6144;
; #pragma unroll
;                 for (int j = 0; j < 8; ++j) { const int col = 4 * F.lane + 256 * j; const f32x4 gt = *(const f32x4*)(m0 + 2 * DM + col), pn = *(const f32x4*)(post_norm + col);
;                     const f32x4 y4 = (f32x4){bf_lo(yw[q][j].x), bf_hi(yw[q][j].x), bf_lo(yw[q][j].y), bf_hi(yw[q][j].y)};
;                     v[q][j] = v[q][j] + gt * (y4 * rsy * pn);
;                     if (lat) *(f32x4*)(args.out + (size_t)row * DM + col) = v[q][j]; }
;                 const float rstd = __builtin_amdgcn_rsqf(sumsq8(v[q]) * (1.f / DM) + EPS);
;                 modulate_store(v[q], rstd, pre_norm + DM, mod + (size_t)(9 + r) * 6144, H + (size_t)row * DM, F.lane); }
	v_fmac_f32_e32 v75, v123, v219
	v_lshlrev_b32_e32 v216, 16, v94
	v_and_b32_e32 v217, 0xffff0000, v94
	v_lshlrev_b32_e32 v218, 16, v95
	v_and_b32_e32 v219, 0xffff0000, v95
	v_mul_f32_e32 v216, v225, v216
	v_mul_f32_e32 v217, v225, v217
	v_mul_f32_e32 v218, v225, v218
	v_mul_f32_e32 v219, v225, v219
	v_fmac_f32_e32 v76, v124, v216
	v_fmac_f32_e32 v77, v125, v217
	v_fmac_f32_e32 v78, v126, v218
	v_fmac_f32_e32 v79, v127, v219
	v_mul_f32_e32 v222, v48, v48
	v_mul_f32_e32 v223, v49, v49
	v_fmac_f32_e32 v222, v50, v50
	v_fmac_f32_e32 v223, v51, v51
	v_fmac_f32_e32 v222, v52, v52
	v_fmac_f32_e32 v223, v53, v53
	v_fmac_f32_e32 v222, v54, v54
	v_fmac_f32_e32 v223, v55, v55
	v_fmac_f32_e32 v222, v56, v56
	v_fmac_f32_e32 v223, v57, v57
	v_fmac_f32_e32 v222, v58, v58
	v_fmac_f32_e32 v223, v59, v59
	v_fmac_f32_e32 v222, v60, v60
	v_fmac_f32_e32 v223, v61, v61
	v_fmac_f32_e32 v222, v62, v62
	v_fmac_f32_e32 v223, v63, v63
	v_fmac_f32_e32 v222, v64, v64
	v_fmac_f32_e32 v223, v65, v65
	v_fmac_f32_e32 v222, v66, v66
	v_fmac_f32_e32 v223, v67, v67
	v_fmac_f32_e32 v222, v68, v68
	v_fmac_f32_e32 v223, v69, v69
	v_fmac_f32_e32 v222, v70, v70
	v_fmac_f32_e32 v223, v71, v71
	v_fmac_f32_e32 v222, v72, v72
	v_fmac_f32_e32 v223, v73, v73
	v_fmac_f32_e32 v222, v74, v74
	v_fmac_f32_e32 v223, v75, v75
	v_fmac_f32_e32 v222, v76, v76
	v_fmac_f32_e32 v223, v77, v77
	v_fmac_f32_e32 v222, v78, v78
	v_fmac_f32_e32 v223, v79, v79
	v_add_f32_e32 v222, v222, v223
	s_nop 1
	v_add_f32_dpp v224, v222, v222 quad_perm:[1,0,3,2] row_mask:0xf bank_mask:0xf
	s_nop 1
	v_add_f32_dpp v224, v224, v224 quad_perm:[2,3,0,1] row_mask:0xf bank_mask:0xf
	s_nop 1
	v_add_f32_dpp v224, v224, v224 row_half_mirror row_mask:0xf bank_mask:0xf
	s_nop 1
	v_add_f32_dpp v224, v224, v224 row_mirror row_mask:0xf bank_mask:0xf
	s_nop 1
	v_readlane_b32 s40, v224, 0
	v_readlane_b32 s41, v224, 16
	v_readlane_b32 s42, v224, 32
	v_readlane_b32 s43, v224, 48
	s_nop 1
	v_mov_b32_e32 v225, s40
	v_add_f32_e32 v225, s41, v225
	v_add_f32_e32 v225, s42, v225
	v_add_f32_e32 v225, s43, v225
	v_fmamk_f32 v225, v225, 0x3a000000, v195
	v_rsq_f32_e32 v225, v225
	s_nop 0
	s_add_i32 s0, s6, 3
	s_lshl_b32 s1, s0, 12
	s_add_u32 s26, s84, s1
	s_addc_u32 s27, s85, 0
	s_add_u32 s26, s26, 0x4000000
	s_addc_u32 s27, s27, 0
	v_mul_f32_e32 v216, v225, v48
	v_mul_f32_e32 v217, v225, v49
	v_mul_f32_e32 v218, v225, v50
	v_mul_f32_e32 v219, v225, v51
	v_fma_f32 v216, v216, v128, v160
	v_fma_f32 v217, v217, v129, v161
	v_fma_f32 v218, v218, v130, v162
	v_fma_f32 v219, v219, v131, v163
	v_cvt_pk_bf16_f32 v196, v216, v217
	v_cvt_pk_bf16_f32 v197, v218, v219
	global_store_dwordx2 v194, v[196:197], s[26:27] offset:0 nt
	v_mul_f32_e32 v216, v225, v52
	v_mul_f32_e32 v217, v225, v53
	v_mul_f32_e32 v218, v225, v54
	v_mul_f32_e32 v219, v225, v55
	v_fma_f32 v216, v216, v132, v164
	v_fma_f32 v217, v217, v133, v165
	v_fma_f32 v218, v218, v134, v166
	v_fma_f32 v219, v219, v135, v167
	v_cvt_pk_bf16_f32 v220, v216, v217
	v_cvt_pk_bf16_f32 v221, v218, v219
	global_store_dwordx2 v194, v[220:221], s[26:27] offset:512 nt
	v_mul_f32_e32 v216, v225, v56
	v_mul_f32_e32 v217, v225, v57
	v_mul_f32_e32 v218, v225, v58
	v_mul_f32_e32 v219, v225, v59
	v_fma_f32 v216, v216, v136, v168
	v_fma_f32 v217, v217, v137, v169
	v_fma_f32 v218, v218, v138, v170
	v_fma_f32 v219, v219, v139, v171
	v_cvt_pk_bf16_f32 v196, v216, v217
	v_cvt_pk_bf16_f32 v197, v218, v219
	global_store_dwordx2 v194, v[196:197], s[26:27] offset:1024 nt
	v_mul_f32_e32 v216, v225, v60
	v_mul_f32_e32 v217, v225, v61
	v_mul_f32_e32 v218, v225, v62
	v_mul_f32_e32 v219, v225, v63
	v_fma_f32 v216, v216, v140, v172
	v_fma_f32 v217, v217, v141, v173
	v_fma_f32 v218, v218, v142, v174
	v_fma_f32 v219, v219, v143, v175
	v_cvt_pk_bf16_f32 v220, v216, v217
	v_cvt_pk_bf16_f32 v221, v218, v219
	global_store_dwordx2 v194, v[220:221], s[26:27] offset:1536 nt
	v_mul_f32_e32 v216, v225, v64
	v_mul_f32_e32 v217, v225, v65
	v_mul_f32_e32 v218, v225, v66
	v_mul_f32_e32 v219, v225, v67
	v_fma_f32 v216, v216, v144, v176
	v_fma_f32 v217, v217, v145, v177
	v_fma_f32 v218, v218, v146, v178
	v_fma_f32 v219, v219, v147, v179
	v_cvt_pk_bf16_f32 v196, v216, v217
	v_cvt_pk_bf16_f32 v197, v218, v219
	global_store_dwordx2 v194, v[196:197], s[26:27] offset:2048 nt
	v_mul_f32_e32 v216, v225, v68
	v_mul_f32_e32 v217, v225, v69
	v_mul_f32_e32 v218, v225, v70
	v_mul_f32_e32 v219, v225, v71
	v_fma_f32 v216, v216, v148, v180
	v_fma_f32 v217, v217, v149, v181
	v_fma_f32 v218, v218, v150, v182
	v_fma_f32 v219, v219, v151, v183
	v_cvt_pk_bf16_f32 v220, v216, v217
	v_cvt_pk_bf16_f32 v221, v218, v219
	global_store_dwordx2 v194, v[220:221], s[26:27] offset:2560 nt
	v_mul_f32_e32 v216, v225, v72
	v_mul_f32_e32 v217, v225, v73
	v_mul_f32_e32 v218, v225, v74
	v_mul_f32_e32 v219, v225, v75
	v_fma_f32 v216, v216, v152, v184
	v_fma_f32 v217, v217, v153, v185
	v_fma_f32 v218, v218, v154, v186
	v_fma_f32 v219, v219, v155, v187
	v_cvt_pk_bf16_f32 v196, v216, v217
	v_cvt_pk_bf16_f32 v197, v218, v219
	global_store_dwordx2 v194, v[196:197], s[26:27] offset:3072 nt
	v_mul_f32_e32 v216, v225, v76
	v_mul_f32_e32 v217, v225, v77
	v_mul_f32_e32 v218, v225, v78
	v_mul_f32_e32 v219, v225, v79
	v_fma_f32 v216, v216, v156, v188
	v_fma_f32 v217, v217, v157, v189
	v_fma_f32 v218, v218, v158, v190
	v_fma_f32 v219, v219, v159, v191
	v_cvt_pk_bf16_f32 v220, v216, v217
	v_cvt_pk_bf16_f32 v221, v218, v219
	global_store_dwordx2 v194, v[220:221], s[26:27] offset:3584 nt
	s_add_i32 s0, s6, 5
	s_cmp_lt_u32 s0, 0x4000
	s_cselect_b32 s10, s68, s72
	s_cselect_b32 s11, s69, s73
	s_cselect_b32 s1, 0, 0x4000
	s_sub_i32 s1, s0, s1
	s_lshl_b32 s1, s1, 13
	s_add_u32 s10, s10, s1
	s_addc_u32 s11, s11, 0
	s_add_i32 s0, s6, 5
	s_lshl_b32 s1, s0, 12
	s_add_u32 s22, s84, s1
	s_addc_u32 s23, s85, 0
	s_add_u32 s22, s22, 0x11800000
	s_addc_u32 s23, s23, 0
	global_load_dwordx4 v[48:51], v192, s[10:11] offset:0 nt
	global_load_dwordx4 v[52:55], v192, s[10:11] offset:1024 nt
	global_load_dwordx4 v[56:59], v192, s[10:11] offset:2048 nt
	global_load_dwordx4 v[60:63], v192, s[10:11] offset:3072 nt
	global_load_dwordx4 v[64:67], v193, s[10:11] offset:0 nt
	global_load_dwordx4 v[68:71], v193, s[10:11] offset:1024 nt
	global_load_dwordx4 v[72:75], v193, s[10:11] offset:2048 nt
	global_load_dwordx4 v[76:79], v193, s[10:11] offset:3072 nt
	global_load_dwordx2 v[80:81], v194, s[22:23] offset:0
	global_load_dwordx2 v[82:83], v194, s[22:23] offset:512
	global_load_dwordx2 v[84:85], v194, s[22:23] offset:1024
	global_load_dwordx2 v[86:87], v194, s[22:23] offset:1536
	global_load_dwordx2 v[88:89], v194, s[22:23] offset:2048
	global_load_dwordx2 v[90:91], v194, s[22:23] offset:2560
	global_load_dwordx2 v[92:93], v194, s[22:23] offset:3072
	global_load_dwordx2 v[94:95], v194, s[22:23] offset:3584
	s_add_i32 s0, s6, 4
	s_add_i32 s0, s6, 4
	s_lshr_b32 s8, s0, 11
	s_cmp_lt_u32 s0, 0x4000
	s_cselect_b32 s8, s8, 8
	s_cmp_eq_u32 s8, s7
	s_cbranch_scc1 .Lp6_np4
; __device__ __forceinline__ unsigned cvt_pk_bf16(float lo, float hi) { unsigned r; asm volatile("v_cvt_pk_bf16_f32 %0, %1, %2" : "=v"(r) : "v"(lo), "v"(hi)); return r; }
; __device__ __forceinline__ float bf_lo(unsigned w) { return __uint_as_float(w << 16); }
; __device__ __forceinline__ float bf_hi(unsigned w) { return __uint_as_float(w & 0xffff0000u); }
; __device__ __forceinline__ void modulate_store(const f32x4 (&v)[8], float rstd, const float* pn, const float* modr, bf16_t* orow, int lane) {
; #pragma unroll
;     for (int j = 0; j < 8; ++j) { const int col = 4 * lane + 256 * j;
;         const f32x4 g = *(const f32x4*)(pn + col), sh = *(const f32x4*)(modr + col), sc = *(const f32x4*)(modr + DM + col);
;         const f32x4 hh = v[j] * rstd * g * (sc + 1.f) + sh;
;         u32x2 w; w.x = cvt_pk_bf16(hh[0], hh[1]); w.y = cvt_pk_bf16(hh[2], hh[3]);
; __global__ void __launch_bounds__(NWAVES * 64, 2) mk_fwd(Args args) {
;     ...
;                 const float* m0 = mod + (size_t)r * 6144;
; #pragma unroll
;                 for (int j = 0; j < 8; ++j) { const int col = 4 * F.lane + 256 * j; const f32x4 gt = *(const f32x4*)(m0 + 2 * DM + col), pn = *(const f32x4*)(post_norm + col);
;                     const f32x4 y4 = (f32x4){bf_lo(yw[q][j].x), bf_hi(yw[q][j].x), bf_lo(yw[q][j].y), bf_hi(yw[q][j].y)};
;                     v[q][j] = v[q][j] + gt * (y4 * rsy * pn);
	s_mov_b32 s7, s8
	s_add_i32 s1, s8, 9
	s_mul_i32 s1, s1, 0x6000
	s_add_u32 s44, s84, s1
	s_addc_u32 s45, s85, 0
	s_add_u32 s44, s44, 0x2000
	s_addc_u32 s45, s45, 0
	s_add_i32 s1, s8, 9
	s_mul_i32 s1, s1, 0x6000
	s_add_u32 s36, s84, s1
	s_addc_u32 s37, s85, 0
	s_add_u32 s38, s80, 0x2000
	s_addc_u32 s39, s81, 0
	s_mul_i32 s1, s8, 0x6000
	s_add_u32 s34, s84, s1
	s_addc_u32 s35, s85, 0
	s_add_u32 s34, s34, 0x4000
	s_addc_u32 s35, s35, 0
	global_load_dwordx4 v[96:99], v192, s[34:35] offset:0
	global_load_dwordx4 v[200:203], v192, s[82:83] offset:0
	global_load_dwordx4 v[100:103], v192, s[34:35] offset:1024
	global_load_dwordx4 v[204:207], v192, s[82:83] offset:1024
	global_load_dwordx4 v[104:107], v192, s[34:35] offset:2048
	global_load_dwordx4 v[208:211], v192, s[82:83] offset:2048
	global_load_dwordx4 v[108:111], v192, s[34:35] offset:3072
	global_load_dwordx4 v[212:215], v192, s[82:83] offset:3072
	s_waitcnt vmcnt(0)
	v_mul_f32_e32 v96, v96, v200
	v_mul_f32_e32 v97, v97, v201
	v_mul_f32_e32 v98, v98, v202
	v_mul_f32_e32 v99, v99, v203
	v_mul_f32_e32 v100, v100, v204
	v_mul_f32_e32 v101, v101, v205
	v_mul_f32_e32 v102, v102, v206
	v_mul_f32_e32 v103, v103, v207
	v_mul_f32_e32 v104, v104, v208
	v_mul_f32_e32 v105, v105, v209
	v_mul_f32_e32 v106, v106, v210
	v_mul_f32_e32 v107, v107, v211
	v_mul_f32_e32 v108, v108, v212
	v_mul_f32_e32 v109, v109, v213
	v_mul_f32_e32 v110, v110, v214
	v_mul_f32_e32 v111, v111, v215
	global_load_dwordx4 v[128:131], v192, s[38:39] offset:0
	global_load_dwordx4 v[200:203], v192, s[44:45] offset:0
	global_load_dwordx4 v[160:163], v192, s[36:37] offset:0
	global_load_dwordx4 v[132:135], v192, s[38:39] offset:1024
	global_load_dwordx4 v[204:207], v192, s[44:45] offset:1024
	global_load_dwordx4 v[164:167], v192, s[36:37] offset:1024
	global_load_dwordx4 v[136:139], v192, s[38:39] offset:2048
	global_load_dwordx4 v[208:211], v192, s[44:45] offset:2048
	global_load_dwordx4 v[168:171], v192, s[36:37] offset:2048
	global_load_dwordx4 v[140:143], v192, s[38:39] offset:3072
	global_load_dwordx4 v[212:215], v192, s[44:45] offset:3072
	global_load_dwordx4 v[172:175], v192, s[36:37] offset:3072
	s_waitcnt vmcnt(0)
	v_add_f32_e32 v200, 1.0, v200
	v_add_f32_e32 v201, 1.0, v201
	v_add_f32_e32 v202, 1.0, v202
	v_add_f32_e32 v203, 1.0, v203
	v_mul_f32_e32 v128, v128, v200
	v_mul_f32_e32 v129, v129, v201
	v_mul_f32_e32 v130, v130, v202
	v_mul_f32_e32 v131, v131, v203
	v_add_f32_e32 v204, 1.0, v204
	v_add_f32_e32 v205, 1.0, v205
	v_add_f32_e32 v206, 1.0, v206
	v_add_f32_e32 v207, 1.0, v207
	v_mul_f32_e32 v132, v132, v204
	v_mul_f32_e32 v133, v133, v205
	v_mul_f32_e32 v134, v134, v206
	v_mul_f32_e32 v135, v135, v207
	v_add_f32_e32 v208, 1.0, v208
	v_add_f32_e32 v209, 1.0, v209
	v_add_f32_e32 v210, 1.0, v210
	v_add_f32_e32 v211, 1.0, v211
	v_mul_f32_e32 v136, v136, v208
	v_mul_f32_e32 v137, v137, v209
	v_mul_f32_e32 v138, v138, v210
	v_mul_f32_e32 v139, v139, v211
	v_add_f32_e32 v212, 1.0, v212
	v_add_f32_e32 v213, 1.0, v213
	v_add_f32_e32 v214, 1.0, v214
	v_add_f32_e32 v215, 1.0, v215
	v_mul_f32_e32 v140, v140, v212
	v_mul_f32_e32 v141, v141, v213
	v_mul_f32_e32 v142, v142, v214
	v_mul_f32_e32 v143, v143, v215
	global_load_dwordx4 v[112:115], v193, s[34:35] offset:0
	global_load_dwordx4 v[200:203], v193, s[82:83] offset:0
	global_load_dwordx4 v[116:119], v193, s[34:35] offset:1024
	global_load_dwordx4 v[204:207], v193, s[82:83] offset:1024
	global_load_dwordx4 v[120:123], v193, s[34:35] offset:2048
	global_load_dwordx4 v[208:211], v193, s[82:83] offset:2048
	global_load_dwordx4 v[124:127], v193, s[34:35] offset:3072
	global_load_dwordx4 v[212:215], v193, s[82:83] offset:3072
	s_waitcnt vmcnt(0)
	v_mul_f32_e32 v112, v112, v200
	v_mul_f32_e32 v113, v113, v201
	v_mul_f32_e32 v114, v114, v202
	v_mul_f32_e32 v115, v115, v203
	v_mul_f32_e32 v116, v116, v204
	v_mul_f32_e32 v117, v117, v205
	v_mul_f32_e32 v118, v118, v206
	v_mul_f32_e32 v119, v119, v207
	v_mul_f32_e32 v120, v120, v208
	v_mul_f32_e32 v121, v121, v209
	v_mul_f32_e32 v122, v122, v210
	v_mul_f32_e32 v123, v123, v211
	v_mul_f32_e32 v124, v124, v212
	v_mul_f32_e32 v125, v125, v213
	v_mul_f32_e32 v126, v126, v214
	v_mul_f32_e32 v127, v127, v215
	global_load_dwordx4 v[144:147], v193, s[38:39] offset:0
	global_load_dwordx4 v[200:203], v193, s[44:45] offset:0
	global_load_dwordx4 v[176:179], v193, s[36:37] offset:0
	global_load_dwordx4 v[148:151], v193, s[38:39] offset:1024
	global_load_dwordx4 v[204:207], v193, s[44:45] offset:1024
	global_load_dwordx4 v[180:183], v193, s[36:37] offset:1024
	global_load_dwordx4 v[152:155], v193, s[38:39] offset:2048
	global_load_dwordx4 v[208:211], v193, s[44:45] offset:2048
	global_load_dwordx4 v[184:187], v193, s[36:37] offset:2048
	global_load_dwordx4 v[156:159], v193, s[38:39] offset:3072
	global_load_dwordx4 v[212:215], v193, s[44:45] offset:3072
	global_load_dwordx4 v[188:191], v193, s[36:37] offset:3072
	s_waitcnt vmcnt(0)
	v_add_f32_e32 v200, 1.0, v200
	v_add_f32_e32 v201, 1.0, v201
	v_add_f32_e32 v202, 1.0, v202
	v_add_f32_e32 v203, 1.0, v203
	v_mul_f32_e32 v144, v144, v200
	v_mul_f32_e32 v145, v145, v201
	v_mul_f32_e32 v146, v146, v202
	v_mul_f32_e32 v147, v147, v203
	v_add_f32_e32 v204, 1.0, v204
	v_add_f32_e32 v205, 1.0, v205
	v_add_f32_e32 v206, 1.0, v206
	v_add_f32_e32 v207, 1.0, v207
	v_mul_f32_e32 v148, v148, v204
	v_mul_f32_e32 v149, v149, v205
	v_mul_f32_e32 v150, v150, v206
	v_mul_f32_e32 v151, v151, v207
	v_add_f32_e32 v208, 1.0, v208
	v_add_f32_e32 v209, 1.0, v209
	v_add_f32_e32 v210, 1.0, v210
	v_add_f32_e32 v211, 1.0, v211
	v_mul_f32_e32 v152, v152, v208
	v_mul_f32_e32 v153, v153, v209
	v_mul_f32_e32 v154, v154, v210
	v_mul_f32_e32 v155, v155, v211
	v_add_f32_e32 v212, 1.0, v212
	v_add_f32_e32 v213, 1.0, v213
	v_add_f32_e32 v214, 1.0, v214
	v_add_f32_e32 v215, 1.0, v215
	v_mul_f32_e32 v156, v156, v212
	v_mul_f32_e32 v157, v157, v213
	v_mul_f32_e32 v158, v158, v214
	v_mul_f32_e32 v159, v159, v215
; __device__ __forceinline__ float bf_lo(unsigned w) { return __uint_as_float(w << 16); }
; __device__ __forceinline__ float bf_hi(unsigned w) { return __uint_as_float(w & 0xffff0000u); }
; __global__ void __launch_bounds__(NWAVES * 64, 2) mk_fwd(Args args) {
;     ...
;             for (int q = 0; q < 3; ++q) { const int row = row0 + q; const bool lat = row < ML; const int r = lat ? row / SEQ : 8;
;                 float sy = 0.f;
; #pragma unroll
;                 for (int j = 0; j < 8; ++j) { const float a = bf_lo(yw[q][j].x), b = bf_hi(yw[q][j].x), c2 = bf_lo(yw[q][j].y), d = bf_hi(yw[q][j].y); sy += (a * a + b * b) + (c2 * c2 + d * d); }
;                 const float rsy = __builtin_amdgcn_rsqf(wave_sum(sy) * (1.f / DM) + EPS);
;                 const float* m0 = mod + (size_t)r * 6144;
; #pragma unroll
;                 for (int j = 0; j < 8; ++j) { const int col = 4 * F.lane + 256 * j; const f32x4 gt = *(const f32x4*)(m0 + 2 * DM + col), pn = *(const f32x4*)(post_norm + col);
;                     const f32x4 y4 = (f32x4){bf_lo(yw[q][j].x), bf_hi(yw[q][j].x), bf_lo(yw[q][j].y), bf_hi(yw[q][j].y)};
;                     v[q][j] = v[q][j] + gt * (y4 * rsy * pn);
;                     if (lat) *(f32x4*)(args.out + (size_t)row * DM + col) = v[q][j]; }
.Lp6_np4:
	s_waitcnt vmcnt(24)
	v_lshlrev_b32_e32 v216, 16, v32
	v_and_b32_e32 v217, 0xffff0000, v32
	v_lshlrev_b32_e32 v218, 16, v33
	v_and_b32_e32 v219, 0xffff0000, v33
	v_mul_f32_e32 v222, v216, v216
	v_mul_f32_e32 v223, v217, v217
	v_fmac_f32_e32 v222, v218, v218
	v_fmac_f32_e32 v223, v219, v219
	v_lshlrev_b32_e32 v216, 16, v34
	v_and_b32_e32 v217, 0xffff0000, v34
	v_lshlrev_b32_e32 v218, 16, v35
	v_and_b32_e32 v219, 0xffff0000, v35
	v_fmac_f32_e32 v222, v216, v216
	v_fmac_f32_e32 v223, v217, v217
	v_fmac_f32_e32 v222, v218, v218
	v_fmac_f32_e32 v223, v219, v219
	v_lshlrev_b32_e32 v216, 16, v36
	v_and_b32_e32 v217, 0xffff0000, v36
	v_lshlrev_b32_e32 v218, 16, v37
	v_and_b32_e32 v219, 0xffff0000, v37
	v_fmac_f32_e32 v222, v216, v216
	v_fmac_f32_e32 v223, v217, v217
	v_fmac_f32_e32 v222, v218, v218
	v_fmac_f32_e32 v223, v219, v219
	v_lshlrev_b32_e32 v216, 16, v38
	v_and_b32_e32 v217, 0xffff0000, v38
	v_lshlrev_b32_e32 v218, 16, v39
	v_and_b32_e32 v219, 0xffff0000, v39
	v_fmac_f32_e32 v222, v216, v216
	v_fmac_f32_e32 v223, v217, v217
	v_fmac_f32_e32 v222, v218, v218
	v_fmac_f32_e32 v223, v219, v219
	v_lshlrev_b32_e32 v216, 16, v40
	v_and_b32_e32 v217, 0xffff0000, v40
	v_lshlrev_b32_e32 v218, 16, v41
	v_and_b32_e32 v219, 0xffff0000, v41
	v_fmac_f32_e32 v222, v216, v216
	v_fmac_f32_e32 v223, v217, v217
	v_fmac_f32_e32 v222, v218, v218
	v_fmac_f32_e32 v223, v219, v219
	v_lshlrev_b32_e32 v216, 16, v42
	v_and_b32_e32 v217, 0xffff0000, v42
	v_lshlrev_b32_e32 v218, 16, v43
	v_and_b32_e32 v219, 0xffff0000, v43
	v_fmac_f32_e32 v222, v216, v216
	v_fmac_f32_e32 v223, v217, v217
	v_fmac_f32_e32 v222, v218, v218
	v_fmac_f32_e32 v223, v219, v219
	v_lshlrev_b32_e32 v216, 16, v44
	v_and_b32_e32 v217, 0xffff0000, v44
	v_lshlrev_b32_e32 v218, 16, v45
	v_and_b32_e32 v219, 0xffff0000, v45
	v_fmac_f32_e32 v222, v216, v216
	v_fmac_f32_e32 v223, v217, v217
	v_fmac_f32_e32 v222, v218, v218
	v_fmac_f32_e32 v223, v219, v219
	v_lshlrev_b32_e32 v216, 16, v46
	v_and_b32_e32 v217, 0xffff0000, v46
	v_lshlrev_b32_e32 v218, 16, v47
	v_and_b32_e32 v219, 0xffff0000, v47
	v_fmac_f32_e32 v222, v216, v216
	v_fmac_f32_e32 v223, v217, v217
	v_fmac_f32_e32 v222, v218, v218
	v_fmac_f32_e32 v223, v219, v219
	v_add_f32_e32 v222, v222, v223
	s_nop 1
	v_add_f32_dpp v224, v222, v222 quad_perm:[1,0,3,2] row_mask:0xf bank_mask:0xf
	s_nop 1
	v_add_f32_dpp v224, v224, v224 quad_perm:[2,3,0,1] row_mask:0xf bank_mask:0xf
	s_nop 1
	v_add_f32_dpp v224, v224, v224 row_half_mirror row_mask:0xf bank_mask:0xf
	s_nop 1
	v_add_f32_dpp v224, v224, v224 row_mirror row_mask:0xf bank_mask:0xf
	s_nop 1
	v_readlane_b32 s40, v224, 0
	v_readlane_b32 s41, v224, 16
	v_readlane_b32 s42, v224, 32
	v_readlane_b32 s43, v224, 48
	s_nop 1
	v_mov_b32_e32 v225, s40
	v_add_f32_e32 v225, s41, v225
	v_add_f32_e32 v225, s42, v225
	v_add_f32_e32 v225, s43, v225
	v_fmamk_f32 v225, v225, 0x3a000000, v195
	v_rsq_f32_e32 v225, v225
	s_nop 0
	v_lshlrev_b32_e32 v216, 16, v32
	v_and_b32_e32 v217, 0xffff0000, v32
	v_lshlrev_b32_e32 v218, 16, v33
	v_and_b32_e32 v219, 0xffff0000, v33
	v_mul_f32_e32 v216, v225, v216
	v_mul_f32_e32 v217, v225, v217
	v_mul_f32_e32 v218, v225, v218
	v_mul_f32_e32 v219, v225, v219
	v_fmac_f32_e32 v0, v96, v216
	v_fmac_f32_e32 v1, v97, v217
	v_fmac_f32_e32 v2, v98, v218
	v_fmac_f32_e32 v3, v99, v219
	v_lshlrev_b32_e32 v216, 16, v34
	v_and_b32_e32 v217, 0xffff0000, v34
	v_lshlrev_b32_e32 v218, 16, v35
	v_and_b32_e32 v219, 0xffff0000, v35
	v_mul_f32_e32 v216, v225, v216
	v_mul_f32_e32 v217, v225, v217
	v_mul_f32_e32 v218, v225, v218
	v_mul_f32_e32 v219, v225, v219
	v_fmac_f32_e32 v4, v100, v216
	v_fmac_f32_e32 v5, v101, v217
	v_fmac_f32_e32 v6, v102, v218
	v_fmac_f32_e32 v7, v103, v219
	v_lshlrev_b32_e32 v216, 16, v36
	v_and_b32_e32 v217, 0xffff0000, v36
	v_lshlrev_b32_e32 v218, 16, v37
	v_and_b32_e32 v219, 0xffff0000, v37
	v_mul_f32_e32 v216, v225, v216
	v_mul_f32_e32 v217, v225, v217
	v_mul_f32_e32 v218, v225, v218
	v_mul_f32_e32 v219, v225, v219
	v_fmac_f32_e32 v8, v104, v216
	v_fmac_f32_e32 v9, v105, v217
	v_fmac_f32_e32 v10, v106, v218
	v_fmac_f32_e32 v11, v107, v219
	v_lshlrev_b32_e32 v216, 16, v38
	v_and_b32_e32 v217, 0xffff0000, v38
	v_lshlrev_b32_e32 v218, 16, v39
	v_and_b32_e32 v219, 0xffff0000, v39
	v_mul_f32_e32 v216, v225, v216
	v_mul_f32_e32 v217, v225, v217
	v_mul_f32_e32 v218, v225, v218
	v_mul_f32_e32 v219, v225, v219
	v_fmac_f32_e32 v12, v108, v216
	v_fmac_f32_e32 v13, v109, v217
	v_fmac_f32_e32 v14, v110, v218
	v_fmac_f32_e32 v15, v111, v219
	v_lshlrev_b32_e32 v216, 16, v40
	v_and_b32_e32 v217, 0xffff0000, v40
	v_lshlrev_b32_e32 v218, 16, v41
	v_and_b32_e32 v219, 0xffff0000, v41
	v_mul_f32_e32 v216, v225, v216
	v_mul_f32_e32 v217, v225, v217
	v_mul_f32_e32 v218, v225, v218
	v_mul_f32_e32 v219, v225, v219
	v_fmac_f32_e32 v16, v112, v216
	v_fmac_f32_e32 v17, v113, v217
	v_fmac_f32_e32 v18, v114, v218
	v_fmac_f32_e32 v19, v115, v219
	v_lshlrev_b32_e32 v216, 16, v42
	v_and_b32_e32 v217, 0xffff0000, v42
	v_lshlrev_b32_e32 v218, 16, v43
	v_and_b32_e32 v219, 0xffff0000, v43
	v_mul_f32_e32 v216, v225, v216
	v_mul_f32_e32 v217, v225, v217
	v_mul_f32_e32 v218, v225, v218
	v_mul_f32_e32 v219, v225, v219
	v_fmac_f32_e32 v20, v116, v216
	v_fmac_f32_e32 v21, v117, v217
	v_fmac_f32_e32 v22, v118, v218
	v_fmac_f32_e32 v23, v119, v219
	v_lshlrev_b32_e32 v216, 16, v44
	v_and_b32_e32 v217, 0xffff0000, v44
	v_lshlrev_b32_e32 v218, 16, v45
	v_and_b32_e32 v219, 0xffff0000, v45
	v_mul_f32_e32 v216, v225, v216
	v_mul_f32_e32 v217, v225, v217
	v_mul_f32_e32 v218, v225, v218
	v_mul_f32_e32 v219, v225, v219
	v_fmac_f32_e32 v24, v120, v216
	v_fmac_f32_e32 v25, v121, v217
	v_fmac_f32_e32 v26, v122, v218
; __device__ __forceinline__ unsigned cvt_pk_bf16(float lo, float hi) { unsigned r; asm volatile("v_cvt_pk_bf16_f32 %0, %1, %2" : "=v"(r) : "v"(lo), "v"(hi)); return r; }
; __device__ __forceinline__ float bf_lo(unsigned w) { return __uint_as_float(w << 16); }
; __device__ __forceinline__ float bf_hi(unsigned w) { return __uint_as_float(w & 0xffff0000u); }
; __device__ __forceinline__ float sumsq8(const f32x4 (&v)[8]) {
;     float s = 0.f;
; #pragma unroll
;     for (int j = 0; j < 8; ++j) s += (v[j][0] * v[j][0] + v[j][1] * v[j][1]) + (v[j][2] * v[j][2] + v[j][3] * v[j][3]);
;     return wave_sum(s);
; }
; __device__ __forceinline__ void modulate_store(const f32x4 (&v)[8], float rstd, const float* pn, const float* modr, bf16_t* orow, int lane) {
; #pragma unroll
;     for (int j = 0; j < 8; ++j) { const int col = 4 * lane + 256 * j;
;         const f32x4 g = *(const f32x4*)(pn + col), sh = *(const f32x4*)(modr + col), sc = *(const f32x4*)(modr + DM + col);
;         const f32x4 hh = v[j] * rstd * g * (sc + 1.f) + sh;
;         u32x2 w; w.x = cvt_pk_bf16(hh[0], hh[1]); w.y = cvt_pk_bf16(hh[2], hh[3]);
;         *(u32x2*)(orow + col) = w; }
; }
; __global__ void __launch_bounds__(NWAVES * 64, 2) mk_fwd(Args args) {
;     ...
;                 for (int j = 0; j < 8; ++j) { const int col = 4 * F.lane + 256 * j; const f32x4 gt = *(const f32x4*)(m0 + 2 * DM + col), pn = *(const f32x4*)(post_norm + col);
;                     const f32x4 y4 = (f32x4){bf_lo(yw[q][j].x), bf_hi(yw[q][j].x), bf_lo(yw[q][j].y), bf_hi(yw[q][j].y)};
;                     v[q][j] = v[q][j] + gt * (y4 * rsy * pn);
;                     if (lat) *(f32x4*)(args.out + (size_t)row * DM + col) = v[q][j]; }
;                 const float rstd = __builtin_amdgcn_rsqf(sumsq8(v[q]) * (1.f / DM) + EPS);
;                 modulate_store(v[q], rstd, pre_norm + DM, mod + (size_t)(9 + r) * 6144, H + (size_t)row * DM, F.lane); }
	v_fmac_f32_e32 v27, v123, v219
	v_lshlrev_b32_e32 v216, 16, v46
	v_and_b32_e32 v217, 0xffff0000, v46
	v_lshlrev_b32_e32 v218, 16, v47
	v_and_b32_e32 v219, 0xffff0000, v47
	v_mul_f32_e32 v216, v225, v216
	v_mul_f32_e32 v217, v225, v217
	v_mul_f32_e32 v218, v225, v218
	v_mul_f32_e32 v219, v225, v219
	v_fmac_f32_e32 v28, v124, v216
	v_fmac_f32_e32 v29, v125, v217
	v_fmac_f32_e32 v30, v126, v218
	v_fmac_f32_e32 v31, v127, v219
	v_mul_f32_e32 v222, v0, v0
	v_mul_f32_e32 v223, v1, v1
	v_fmac_f32_e32 v222, v2, v2
	v_fmac_f32_e32 v223, v3, v3
	v_fmac_f32_e32 v222, v4, v4
	v_fmac_f32_e32 v223, v5, v5
	v_fmac_f32_e32 v222, v6, v6
	v_fmac_f32_e32 v223, v7, v7
	v_fmac_f32_e32 v222, v8, v8
	v_fmac_f32_e32 v223, v9, v9
	v_fmac_f32_e32 v222, v10, v10
	v_fmac_f32_e32 v223, v11, v11
	v_fmac_f32_e32 v222, v12, v12
	v_fmac_f32_e32 v223, v13, v13
	v_fmac_f32_e32 v222, v14, v14
	v_fmac_f32_e32 v223, v15, v15
	v_fmac_f32_e32 v222, v16, v16
	v_fmac_f32_e32 v223, v17, v17
	v_fmac_f32_e32 v222, v18, v18
	v_fmac_f32_e32 v223, v19, v19
	v_fmac_f32_e32 v222, v20, v20
	v_fmac_f32_e32 v223, v21, v21
	v_fmac_f32_e32 v222, v22, v22
	v_fmac_f32_e32 v223, v23, v23
	v_fmac_f32_e32 v222, v24, v24
	v_fmac_f32_e32 v223, v25, v25
	v_fmac_f32_e32 v222, v26, v26
	v_fmac_f32_e32 v223, v27, v27
	v_fmac_f32_e32 v222, v28, v28
	v_fmac_f32_e32 v223, v29, v29
	v_fmac_f32_e32 v222, v30, v30
	v_fmac_f32_e32 v223, v31, v31
	v_add_f32_e32 v222, v222, v223
	s_nop 1
	v_add_f32_dpp v224, v222, v222 quad_perm:[1,0,3,2] row_mask:0xf bank_mask:0xf
	s_nop 1
	v_add_f32_dpp v224, v224, v224 quad_perm:[2,3,0,1] row_mask:0xf bank_mask:0xf
	s_nop 1
	v_add_f32_dpp v224, v224, v224 row_half_mirror row_mask:0xf bank_mask:0xf
	s_nop 1
	v_add_f32_dpp v224, v224, v224 row_mirror row_mask:0xf bank_mask:0xf
	s_nop 1
	v_readlane_b32 s40, v224, 0
	v_readlane_b32 s41, v224, 16
	v_readlane_b32 s42, v224, 32
	v_readlane_b32 s43, v224, 48
	s_nop 1
	v_mov_b32_e32 v225, s40
	v_add_f32_e32 v225, s41, v225
	v_add_f32_e32 v225, s42, v225
	v_add_f32_e32 v225, s43, v225
	v_fmamk_f32 v225, v225, 0x3a000000, v195
	v_rsq_f32_e32 v225, v225
	s_nop 0
	s_add_i32 s0, s6, 4
	s_lshl_b32 s1, s0, 12
	s_add_u32 s26, s84, s1
	s_addc_u32 s27, s85, 0
	s_add_u32 s26, s26, 0x4000000
	s_addc_u32 s27, s27, 0
	v_mul_f32_e32 v216, v225, v0
	v_mul_f32_e32 v217, v225, v1
	v_mul_f32_e32 v218, v225, v2
	v_mul_f32_e32 v219, v225, v3
	v_fma_f32 v216, v216, v128, v160
	v_fma_f32 v217, v217, v129, v161
	v_fma_f32 v218, v218, v130, v162
	v_fma_f32 v219, v219, v131, v163
	v_cvt_pk_bf16_f32 v196, v216, v217
	v_cvt_pk_bf16_f32 v197, v218, v219
	global_store_dwordx2 v194, v[196:197], s[26:27] offset:0 nt
	v_mul_f32_e32 v216, v225, v4
	v_mul_f32_e32 v217, v225, v5
	v_mul_f32_e32 v218, v225, v6
	v_mul_f32_e32 v219, v225, v7
	v_fma_f32 v216, v216, v132, v164
	v_fma_f32 v217, v217, v133, v165
	v_fma_f32 v218, v218, v134, v166
	v_fma_f32 v219, v219, v135, v167
	v_cvt_pk_bf16_f32 v220, v216, v217
	v_cvt_pk_bf16_f32 v221, v218, v219
	global_store_dwordx2 v194, v[220:221], s[26:27] offset:512 nt
	v_mul_f32_e32 v216, v225, v8
	v_mul_f32_e32 v217, v225, v9
	v_mul_f32_e32 v218, v225, v10
	v_mul_f32_e32 v219, v225, v11
	v_fma_f32 v216, v216, v136, v168
	v_fma_f32 v217, v217, v137, v169
	v_fma_f32 v218, v218, v138, v170
	v_fma_f32 v219, v219, v139, v171
	v_cvt_pk_bf16_f32 v196, v216, v217
	v_cvt_pk_bf16_f32 v197, v218, v219
	global_store_dwordx2 v194, v[196:197], s[26:27] offset:1024 nt
	v_mul_f32_e32 v216, v225, v12
	v_mul_f32_e32 v217, v225, v13
	v_mul_f32_e32 v218, v225, v14
	v_mul_f32_e32 v219, v225, v15
	v_fma_f32 v216, v216, v140, v172
	v_fma_f32 v217, v217, v141, v173
	v_fma_f32 v218, v218, v142, v174
	v_fma_f32 v219, v219, v143, v175
	v_cvt_pk_bf16_f32 v220, v216, v217
	v_cvt_pk_bf16_f32 v221, v218, v219
	global_store_dwordx2 v194, v[220:221], s[26:27] offset:1536 nt
	v_mul_f32_e32 v216, v225, v16
	v_mul_f32_e32 v217, v225, v17
	v_mul_f32_e32 v218, v225, v18
	v_mul_f32_e32 v219, v225, v19
	v_fma_f32 v216, v216, v144, v176
	v_fma_f32 v217, v217, v145, v177
	v_fma_f32 v218, v218, v146, v178
	v_fma_f32 v219, v219, v147, v179
	v_cvt_pk_bf16_f32 v196, v216, v217
	v_cvt_pk_bf16_f32 v197, v218, v219
	global_store_dwordx2 v194, v[196:197], s[26:27] offset:2048 nt
	v_mul_f32_e32 v216, v225, v20
	v_mul_f32_e32 v217, v225, v21
	v_mul_f32_e32 v218, v225, v22
	v_mul_f32_e32 v219, v225, v23
	v_fma_f32 v216, v216, v148, v180
	v_fma_f32 v217, v217, v149, v181
	v_fma_f32 v218, v218, v150, v182
	v_fma_f32 v219, v219, v151, v183
	v_cvt_pk_bf16_f32 v220, v216, v217
	v_cvt_pk_bf16_f32 v221, v218, v219
	global_store_dwordx2 v194, v[220:221], s[26:27] offset:2560 nt
	v_mul_f32_e32 v216, v225, v24
	v_mul_f32_e32 v217, v225, v25
	v_mul_f32_e32 v218, v225, v26
	v_mul_f32_e32 v219, v225, v27
	v_fma_f32 v216, v216, v152, v184
	v_fma_f32 v217, v217, v153, v185
	v_fma_f32 v218, v218, v154, v186
	v_fma_f32 v219, v219, v155, v187
	v_cvt_pk_bf16_f32 v196, v216, v217
	v_cvt_pk_bf16_f32 v197, v218, v219
	global_store_dwordx2 v194, v[196:197], s[26:27] offset:3072 nt
	v_mul_f32_e32 v216, v225, v28
	v_mul_f32_e32 v217, v225, v29
	v_mul_f32_e32 v218, v225, v30
	v_mul_f32_e32 v219, v225, v31
	v_fma_f32 v216, v216, v156, v188
	v_fma_f32 v217, v217, v157, v189
	v_fma_f32 v218, v218, v158, v190
	v_fma_f32 v219, v219, v159, v191
	v_cvt_pk_bf16_f32 v220, v216, v217
	v_cvt_pk_bf16_f32 v221, v218, v219
	global_store_dwordx2 v194, v[220:221], s[26:27] offset:3584 nt
	s_add_i32 s0, s6, 6
	s_cmp_lt_u32 s0, 0x4000
	s_cselect_b32 s10, s68, s72
	s_cselect_b32 s11, s69, s73
	s_cselect_b32 s1, 0, 0x4000
	s_sub_i32 s1, s0, s1
	s_lshl_b32 s1, s1, 13
	s_add_u32 s10, s10, s1
	s_addc_u32 s11, s11, 0
	s_add_i32 s0, s6, 6
	s_lshl_b32 s1, s0, 12
	s_add_u32 s22, s84, s1
	s_addc_u32 s23, s85, 0
	s_add_u32 s22, s22, 0x11800000
	s_addc_u32 s23, s23, 0
	global_load_dwordx4 v[0:3], v192, s[10:11] offset:0 nt
	global_load_dwordx4 v[4:7], v192, s[10:11] offset:1024 nt
	global_load_dwordx4 v[8:11], v192, s[10:11] offset:2048 nt
	global_load_dwordx4 v[12:15], v192, s[10:11] offset:3072 nt
	global_load_dwordx4 v[16:19], v193, s[10:11] offset:0 nt
	global_load_dwordx4 v[20:23], v193, s[10:11] offset:1024 nt
	global_load_dwordx4 v[24:27], v193, s[10:11] offset:2048 nt
	global_load_dwordx4 v[28:31], v193, s[10:11] offset:3072 nt
	global_load_dwordx2 v[32:33], v194, s[22:23] offset:0
	global_load_dwordx2 v[34:35], v194, s[22:23] offset:512
	global_load_dwordx2 v[36:37], v194, s[22:23] offset:1024
	global_load_dwordx2 v[38:39], v194, s[22:23] offset:1536
	global_load_dwordx2 v[40:41], v194, s[22:23] offset:2048
	global_load_dwordx2 v[42:43], v194, s[22:23] offset:2560
	global_load_dwordx2 v[44:45], v194, s[22:23] offset:3072
	global_load_dwordx2 v[46:47], v194, s[22:23] offset:3584
	s_add_i32 s0, s6, 5
	s_add_i32 s0, s6, 5
	s_lshr_b32 s8, s0, 11
	s_cmp_lt_u32 s0, 0x4000
	s_cselect_b32 s8, s8, 8
	s_cmp_eq_u32 s8, s7
	s_cbranch_scc1 .Lp6_np5
; __device__ __forceinline__ unsigned cvt_pk_bf16(float lo, float hi) { unsigned r; asm volatile("v_cvt_pk_bf16_f32 %0, %1, %2" : "=v"(r) : "v"(lo), "v"(hi)); return r; }
; __device__ __forceinline__ float bf_lo(unsigned w) { return __uint_as_float(w << 16); }
; __device__ __forceinline__ float bf_hi(unsigned w) { return __uint_as_float(w & 0xffff0000u); }
; __device__ __forceinline__ void modulate_store(const f32x4 (&v)[8], float rstd, const float* pn, const float* modr, bf16_t* orow, int lane) {
; #pragma unroll
;     for (int j = 0; j < 8; ++j) { const int col = 4 * lane + 256 * j;
;         const f32x4 g = *(const f32x4*)(pn + col), sh = *(const f32x4*)(modr + col), sc = *(const f32x4*)(modr + DM + col);
;         const f32x4 hh = v[j] * rstd * g * (sc + 1.f) + sh;
;         u32x2 w; w.x = cvt_pk_bf16(hh[0], hh[1]); w.y = cvt_pk_bf16(hh[2], hh[3]);
; __global__ void __launch_bounds__(NWAVES * 64, 2) mk_fwd(Args args) {
;     ...
;                 const float* m0 = mod + (size_t)r * 6144;
; #pragma unroll
;                 for (int j = 0; j < 8; ++j) { const int col = 4 * F.lane + 256 * j; const f32x4 gt = *(const f32x4*)(m0 + 2 * DM + col), pn = *(const f32x4*)(post_norm + col);
;                     const f32x4 y4 = (f32x4){bf_lo(yw[q][j].x), bf_hi(yw[q][j].x), bf_lo(yw[q][j].y), bf_hi(yw[q][j].y)};
;                     v[q][j] = v[q][j] + gt * (y4 * rsy * pn);
	s_mov_b32 s7, s8
	s_add_i32 s1, s8, 9
	s_mul_i32 s1, s1, 0x6000
	s_add_u32 s44, s84, s1
	s_addc_u32 s45, s85, 0
	s_add_u32 s44, s44, 0x2000
	s_addc_u32 s45, s45, 0
	s_add_i32 s1, s8, 9
	s_mul_i32 s1, s1, 0x6000
	s_add_u32 s36, s84, s1
	s_addc_u32 s37, s85, 0
	s_add_u32 s38, s80, 0x2000
	s_addc_u32 s39, s81, 0
	s_mul_i32 s1, s8, 0x6000
	s_add_u32 s34, s84, s1
	s_addc_u32 s35, s85, 0
	s_add_u32 s34, s34, 0x4000
	s_addc_u32 s35, s35, 0
	global_load_dwordx4 v[96:99], v192, s[34:35] offset:0
	global_load_dwordx4 v[200:203], v192, s[82:83] offset:0
	global_load_dwordx4 v[100:103], v192, s[34:35] offset:1024
	global_load_dwordx4 v[204:207], v192, s[82:83] offset:1024
	global_load_dwordx4 v[104:107], v192, s[34:35] offset:2048
	global_load_dwordx4 v[208:211], v192, s[82:83] offset:2048
	global_load_dwordx4 v[108:111], v192, s[34:35] offset:3072
	global_load_dwordx4 v[212:215], v192, s[82:83] offset:3072
	s_waitcnt vmcnt(0)
	v_mul_f32_e32 v96, v96, v200
	v_mul_f32_e32 v97, v97, v201
	v_mul_f32_e32 v98, v98, v202
	v_mul_f32_e32 v99, v99, v203
	v_mul_f32_e32 v100, v100, v204
	v_mul_f32_e32 v101, v101, v205
	v_mul_f32_e32 v102, v102, v206
	v_mul_f32_e32 v103, v103, v207
	v_mul_f32_e32 v104, v104, v208
	v_mul_f32_e32 v105, v105, v209
	v_mul_f32_e32 v106, v106, v210
	v_mul_f32_e32 v107, v107, v211
	v_mul_f32_e32 v108, v108, v212
	v_mul_f32_e32 v109, v109, v213
	v_mul_f32_e32 v110, v110, v214
	v_mul_f32_e32 v111, v111, v215
	global_load_dwordx4 v[128:131], v192, s[38:39] offset:0
	global_load_dwordx4 v[200:203], v192, s[44:45] offset:0
	global_load_dwordx4 v[160:163], v192, s[36:37] offset:0
	global_load_dwordx4 v[132:135], v192, s[38:39] offset:1024
	global_load_dwordx4 v[204:207], v192, s[44:45] offset:1024
	global_load_dwordx4 v[164:167], v192, s[36:37] offset:1024
	global_load_dwordx4 v[136:139], v192, s[38:39] offset:2048
	global_load_dwordx4 v[208:211], v192, s[44:45] offset:2048
	global_load_dwordx4 v[168:171], v192, s[36:37] offset:2048
	global_load_dwordx4 v[140:143], v192, s[38:39] offset:3072
	global_load_dwordx4 v[212:215], v192, s[44:45] offset:3072
	global_load_dwordx4 v[172:175], v192, s[36:37] offset:3072
	s_waitcnt vmcnt(0)
	v_add_f32_e32 v200, 1.0, v200
	v_add_f32_e32 v201, 1.0, v201
	v_add_f32_e32 v202, 1.0, v202
	v_add_f32_e32 v203, 1.0, v203
	v_mul_f32_e32 v128, v128, v200
	v_mul_f32_e32 v129, v129, v201
	v_mul_f32_e32 v130, v130, v202
	v_mul_f32_e32 v131, v131, v203
	v_add_f32_e32 v204, 1.0, v204
	v_add_f32_e32 v205, 1.0, v205
	v_add_f32_e32 v206, 1.0, v206
	v_add_f32_e32 v207, 1.0, v207
	v_mul_f32_e32 v132, v132, v204
	v_mul_f32_e32 v133, v133, v205
	v_mul_f32_e32 v134, v134, v206
	v_mul_f32_e32 v135, v135, v207
	v_add_f32_e32 v208, 1.0, v208
	v_add_f32_e32 v209, 1.0, v209
	v_add_f32_e32 v210, 1.0, v210
	v_add_f32_e32 v211, 1.0, v211
	v_mul_f32_e32 v136, v136, v208
	v_mul_f32_e32 v137, v137, v209
	v_mul_f32_e32 v138, v138, v210
	v_mul_f32_e32 v139, v139, v211
	v_add_f32_e32 v212, 1.0, v212
	v_add_f32_e32 v213, 1.0, v213
	v_add_f32_e32 v214, 1.0, v214
	v_add_f32_e32 v215, 1.0, v215
	v_mul_f32_e32 v140, v140, v212
	v_mul_f32_e32 v141, v141, v213
	v_mul_f32_e32 v142, v142, v214
	v_mul_f32_e32 v143, v143, v215
	global_load_dwordx4 v[112:115], v193, s[34:35] offset:0
	global_load_dwordx4 v[200:203], v193, s[82:83] offset:0
	global_load_dwordx4 v[116:119], v193, s[34:35] offset:1024
	global_load_dwordx4 v[204:207], v193, s[82:83] offset:1024
	global_load_dwordx4 v[120:123], v193, s[34:35] offset:2048
	global_load_dwordx4 v[208:211], v193, s[82:83] offset:2048
	global_load_dwordx4 v[124:127], v193, s[34:35] offset:3072
	global_load_dwordx4 v[212:215], v193, s[82:83] offset:3072
	s_waitcnt vmcnt(0)
	v_mul_f32_e32 v112, v112, v200
	v_mul_f32_e32 v113, v113, v201
	v_mul_f32_e32 v114, v114, v202
	v_mul_f32_e32 v115, v115, v203
	v_mul_f32_e32 v116, v116, v204
	v_mul_f32_e32 v117, v117, v205
	v_mul_f32_e32 v118, v118, v206
	v_mul_f32_e32 v119, v119, v207
	v_mul_f32_e32 v120, v120, v208
	v_mul_f32_e32 v121, v121, v209
	v_mul_f32_e32 v122, v122, v210
	v_mul_f32_e32 v123, v123, v211
	v_mul_f32_e32 v124, v124, v212
	v_mul_f32_e32 v125, v125, v213
	v_mul_f32_e32 v126, v126, v214
	v_mul_f32_e32 v127, v127, v215
	global_load_dwordx4 v[144:147], v193, s[38:39] offset:0
	global_load_dwordx4 v[200:203], v193, s[44:45] offset:0
	global_load_dwordx4 v[176:179], v193, s[36:37] offset:0
	global_load_dwordx4 v[148:151], v193, s[38:39] offset:1024
	global_load_dwordx4 v[204:207], v193, s[44:45] offset:1024
	global_load_dwordx4 v[180:183], v193, s[36:37] offset:1024
	global_load_dwordx4 v[152:155], v193, s[38:39] offset:2048
	global_load_dwordx4 v[208:211], v193, s[44:45] offset:2048
	global_load_dwordx4 v[184:187], v193, s[36:37] offset:2048
	global_load_dwordx4 v[156:159], v193, s[38:39] offset:3072
	global_load_dwordx4 v[212:215], v193, s[44:45] offset:3072
	global_load_dwordx4 v[188:191], v193, s[36:37] offset:3072
	s_waitcnt vmcnt(0)
	v_add_f32_e32 v200, 1.0, v200
	v_add_f32_e32 v201, 1.0, v201
	v_add_f32_e32 v202, 1.0, v202
	v_add_f32_e32 v203, 1.0, v203
	v_mul_f32_e32 v144, v144, v200
	v_mul_f32_e32 v145, v145, v201
	v_mul_f32_e32 v146, v146, v202
	v_mul_f32_e32 v147, v147, v203
	v_add_f32_e32 v204, 1.0, v204
	v_add_f32_e32 v205, 1.0, v205
	v_add_f32_e32 v206, 1.0, v206
	v_add_f32_e32 v207, 1.0, v207
	v_mul_f32_e32 v148, v148, v204
	v_mul_f32_e32 v149, v149, v205
	v_mul_f32_e32 v150, v150, v206
	v_mul_f32_e32 v151, v151, v207
	v_add_f32_e32 v208, 1.0, v208
	v_add_f32_e32 v209, 1.0, v209
	v_add_f32_e32 v210, 1.0, v210
	v_add_f32_e32 v211, 1.0, v211
	v_mul_f32_e32 v152, v152, v208
	v_mul_f32_e32 v153, v153, v209
	v_mul_f32_e32 v154, v154, v210
	v_mul_f32_e32 v155, v155, v211
	v_add_f32_e32 v212, 1.0, v212
	v_add_f32_e32 v213, 1.0, v213
	v_add_f32_e32 v214, 1.0, v214
	v_add_f32_e32 v215, 1.0, v215
	v_mul_f32_e32 v156, v156, v212
	v_mul_f32_e32 v157, v157, v213
	v_mul_f32_e32 v158, v158, v214
	v_mul_f32_e32 v159, v159, v215
; __device__ __forceinline__ float bf_lo(unsigned w) { return __uint_as_float(w << 16); }
; __device__ __forceinline__ float bf_hi(unsigned w) { return __uint_as_float(w & 0xffff0000u); }
; __global__ void __launch_bounds__(NWAVES * 64, 2) mk_fwd(Args args) {
;     ...
;             for (int q = 0; q < 3; ++q) { const int row = row0 + q; const bool lat = row < ML; const int r = lat ? row / SEQ : 8;
;                 float sy = 0.f;
; #pragma unroll
;                 for (int j = 0; j < 8; ++j) { const float a = bf_lo(yw[q][j].x), b = bf_hi(yw[q][j].x), c2 = bf_lo(yw[q][j].y), d = bf_hi(yw[q][j].y); sy += (a * a + b * b) + (c2 * c2 + d * d); }
;                 const float rsy = __builtin_amdgcn_rsqf(wave_sum(sy) * (1.f / DM) + EPS);
;                 const float* m0 = mod + (size_t)r * 6144;
; #pragma unroll
;                 for (int j = 0; j < 8; ++j) { const int col = 4 * F.lane + 256 * j; const f32x4 gt = *(const f32x4*)(m0 + 2 * DM + col), pn = *(const f32x4*)(post_norm + col);
;                     const f32x4 y4 = (f32x4){bf_lo(yw[q][j].x), bf_hi(yw[q][j].x), bf_lo(yw[q][j].y), bf_hi(yw[q][j].y)};
;                     v[q][j] = v[q][j] + gt * (y4 * rsy * pn);
;                     if (lat) *(f32x4*)(args.out + (size_t)row * DM + col) = v[q][j]; }
.Lp6_np5:
	s_waitcnt vmcnt(24)
	v_lshlrev_b32_e32 v216, 16, v80
	v_and_b32_e32 v217, 0xffff0000, v80
	v_lshlrev_b32_e32 v218, 16, v81
	v_and_b32_e32 v219, 0xffff0000, v81
	v_mul_f32_e32 v222, v216, v216
	v_mul_f32_e32 v223, v217, v217
	v_fmac_f32_e32 v222, v218, v218
	v_fmac_f32_e32 v223, v219, v219
	v_lshlrev_b32_e32 v216, 16, v82
	v_and_b32_e32 v217, 0xffff0000, v82
	v_lshlrev_b32_e32 v218, 16, v83
	v_and_b32_e32 v219, 0xffff0000, v83
	v_fmac_f32_e32 v222, v216, v216
	v_fmac_f32_e32 v223, v217, v217
	v_fmac_f32_e32 v222, v218, v218
	v_fmac_f32_e32 v223, v219, v219
	v_lshlrev_b32_e32 v216, 16, v84
	v_and_b32_e32 v217, 0xffff0000, v84
	v_lshlrev_b32_e32 v218, 16, v85
	v_and_b32_e32 v219, 0xffff0000, v85
	v_fmac_f32_e32 v222, v216, v216
	v_fmac_f32_e32 v223, v217, v217
	v_fmac_f32_e32 v222, v218, v218
	v_fmac_f32_e32 v223, v219, v219
	v_lshlrev_b32_e32 v216, 16, v86
	v_and_b32_e32 v217, 0xffff0000, v86
	v_lshlrev_b32_e32 v218, 16, v87
	v_and_b32_e32 v219, 0xffff0000, v87
	v_fmac_f32_e32 v222, v216, v216
	v_fmac_f32_e32 v223, v217, v217
	v_fmac_f32_e32 v222, v218, v218
	v_fmac_f32_e32 v223, v219, v219
	v_lshlrev_b32_e32 v216, 16, v88
	v_and_b32_e32 v217, 0xffff0000, v88
	v_lshlrev_b32_e32 v218, 16, v89
	v_and_b32_e32 v219, 0xffff0000, v89
	v_fmac_f32_e32 v222, v216, v216
	v_fmac_f32_e32 v223, v217, v217
	v_fmac_f32_e32 v222, v218, v218
	v_fmac_f32_e32 v223, v219, v219
	v_lshlrev_b32_e32 v216, 16, v90
	v_and_b32_e32 v217, 0xffff0000, v90
	v_lshlrev_b32_e32 v218, 16, v91
	v_and_b32_e32 v219, 0xffff0000, v91
	v_fmac_f32_e32 v222, v216, v216
	v_fmac_f32_e32 v223, v217, v217
	v_fmac_f32_e32 v222, v218, v218
	v_fmac_f32_e32 v223, v219, v219
	v_lshlrev_b32_e32 v216, 16, v92
	v_and_b32_e32 v217, 0xffff0000, v92
	v_lshlrev_b32_e32 v218, 16, v93
	v_and_b32_e32 v219, 0xffff0000, v93
	v_fmac_f32_e32 v222, v216, v216
	v_fmac_f32_e32 v223, v217, v217
	v_fmac_f32_e32 v222, v218, v218
	v_fmac_f32_e32 v223, v219, v219
	v_lshlrev_b32_e32 v216, 16, v94
	v_and_b32_e32 v217, 0xffff0000, v94
	v_lshlrev_b32_e32 v218, 16, v95
	v_and_b32_e32 v219, 0xffff0000, v95
	v_fmac_f32_e32 v222, v216, v216
	v_fmac_f32_e32 v223, v217, v217
	v_fmac_f32_e32 v222, v218, v218
	v_fmac_f32_e32 v223, v219, v219
	v_add_f32_e32 v222, v222, v223
	s_nop 1
	v_add_f32_dpp v224, v222, v222 quad_perm:[1,0,3,2] row_mask:0xf bank_mask:0xf
	s_nop 1
	v_add_f32_dpp v224, v224, v224 quad_perm:[2,3,0,1] row_mask:0xf bank_mask:0xf
	s_nop 1
	v_add_f32_dpp v224, v224, v224 row_half_mirror row_mask:0xf bank_mask:0xf
	s_nop 1
	v_add_f32_dpp v224, v224, v224 row_mirror row_mask:0xf bank_mask:0xf
	s_nop 1
	v_readlane_b32 s40, v224, 0
	v_readlane_b32 s41, v224, 16
	v_readlane_b32 s42, v224, 32
	v_readlane_b32 s43, v224, 48
	s_nop 1
	v_mov_b32_e32 v225, s40
	v_add_f32_e32 v225, s41, v225
	v_add_f32_e32 v225, s42, v225
	v_add_f32_e32 v225, s43, v225
	v_fmamk_f32 v225, v225, 0x3a000000, v195
	v_rsq_f32_e32 v225, v225
	s_nop 0
	v_lshlrev_b32_e32 v216, 16, v80
	v_and_b32_e32 v217, 0xffff0000, v80
	v_lshlrev_b32_e32 v218, 16, v81
	v_and_b32_e32 v219, 0xffff0000, v81
	v_mul_f32_e32 v216, v225, v216
	v_mul_f32_e32 v217, v225, v217
	v_mul_f32_e32 v218, v225, v218
	v_mul_f32_e32 v219, v225, v219
	v_fmac_f32_e32 v48, v96, v216
	v_fmac_f32_e32 v49, v97, v217
	v_fmac_f32_e32 v50, v98, v218
	v_fmac_f32_e32 v51, v99, v219
	v_lshlrev_b32_e32 v216, 16, v82
	v_and_b32_e32 v217, 0xffff0000, v82
	v_lshlrev_b32_e32 v218, 16, v83
	v_and_b32_e32 v219, 0xffff0000, v83
	v_mul_f32_e32 v216, v225, v216
	v_mul_f32_e32 v217, v225, v217
	v_mul_f32_e32 v218, v225, v218
	v_mul_f32_e32 v219, v225, v219
	v_fmac_f32_e32 v52, v100, v216
	v_fmac_f32_e32 v53, v101, v217
	v_fmac_f32_e32 v54, v102, v218
	v_fmac_f32_e32 v55, v103, v219
	v_lshlrev_b32_e32 v216, 16, v84
	v_and_b32_e32 v217, 0xffff0000, v84
	v_lshlrev_b32_e32 v218, 16, v85
	v_and_b32_e32 v219, 0xffff0000, v85
	v_mul_f32_e32 v216, v225, v216
	v_mul_f32_e32 v217, v225, v217
	v_mul_f32_e32 v218, v225, v218
	v_mul_f32_e32 v219, v225, v219
	v_fmac_f32_e32 v56, v104, v216
	v_fmac_f32_e32 v57, v105, v217
	v_fmac_f32_e32 v58, v106, v218
	v_fmac_f32_e32 v59, v107, v219
	v_lshlrev_b32_e32 v216, 16, v86
	v_and_b32_e32 v217, 0xffff0000, v86
	v_lshlrev_b32_e32 v218, 16, v87
	v_and_b32_e32 v219, 0xffff0000, v87
	v_mul_f32_e32 v216, v225, v216
	v_mul_f32_e32 v217, v225, v217
	v_mul_f32_e32 v218, v225, v218
	v_mul_f32_e32 v219, v225, v219
	v_fmac_f32_e32 v60, v108, v216
	v_fmac_f32_e32 v61, v109, v217
	v_fmac_f32_e32 v62, v110, v218
	v_fmac_f32_e32 v63, v111, v219
	v_lshlrev_b32_e32 v216, 16, v88
	v_and_b32_e32 v217, 0xffff0000, v88
	v_lshlrev_b32_e32 v218, 16, v89
	v_and_b32_e32 v219, 0xffff0000, v89
	v_mul_f32_e32 v216, v225, v216
	v_mul_f32_e32 v217, v225, v217
	v_mul_f32_e32 v218, v225, v218
	v_mul_f32_e32 v219, v225, v219
	v_fmac_f32_e32 v64, v112, v216
	v_fmac_f32_e32 v65, v113, v217
	v_fmac_f32_e32 v66, v114, v218
	v_fmac_f32_e32 v67, v115, v219
	v_lshlrev_b32_e32 v216, 16, v90
	v_and_b32_e32 v217, 0xffff0000, v90
	v_lshlrev_b32_e32 v218, 16, v91
	v_and_b32_e32 v219, 0xffff0000, v91
	v_mul_f32_e32 v216, v225, v216
	v_mul_f32_e32 v217, v225, v217
	v_mul_f32_e32 v218, v225, v218
	v_mul_f32_e32 v219, v225, v219
	v_fmac_f32_e32 v68, v116, v216
	v_fmac_f32_e32 v69, v117, v217
	v_fmac_f32_e32 v70, v118, v218
	v_fmac_f32_e32 v71, v119, v219
	v_lshlrev_b32_e32 v216, 16, v92
	v_and_b32_e32 v217, 0xffff0000, v92
	v_lshlrev_b32_e32 v218, 16, v93
	v_and_b32_e32 v219, 0xffff0000, v93
	v_mul_f32_e32 v216, v225, v216
	v_mul_f32_e32 v217, v225, v217
	v_mul_f32_e32 v218, v225, v218
	v_mul_f32_e32 v219, v225, v219
	v_fmac_f32_e32 v72, v120, v216
	v_fmac_f32_e32 v73, v121, v217
	v_fmac_f32_e32 v74, v122, v218
; __device__ __forceinline__ unsigned cvt_pk_bf16(float lo, float hi) { unsigned r; asm volatile("v_cvt_pk_bf16_f32 %0, %1, %2" : "=v"(r) : "v"(lo), "v"(hi)); return r; }
; __device__ __forceinline__ float bf_lo(unsigned w) { return __uint_as_float(w << 16); }
; __device__ __forceinline__ float bf_hi(unsigned w) { return __uint_as_float(w & 0xffff0000u); }
; __device__ __forceinline__ float sumsq8(const f32x4 (&v)[8]) {
;     float s = 0.f;
; #pragma unroll
;     for (int j = 0; j < 8; ++j) s += (v[j][0] * v[j][0] + v[j][1] * v[j][1]) + (v[j][2] * v[j][2] + v[j][3] * v[j][3]);
;     return wave_sum(s);
; }
; __device__ __forceinline__ void modulate_store(const f32x4 (&v)[8], float rstd, const float* pn, const float* modr, bf16_t* orow, int lane) {
; #pragma unroll
;     for (int j = 0; j < 8; ++j) { const int col = 4 * lane + 256 * j;
;         const f32x4 g = *(const f32x4*)(pn + col), sh = *(const f32x4*)(modr + col), sc = *(const f32x4*)(modr + DM + col);
;         const f32x4 hh = v[j] * rstd * g * (sc + 1.f) + sh;
;         u32x2 w; w.x = cvt_pk_bf16(hh[0], hh[1]); w.y = cvt_pk_bf16(hh[2], hh[3]);
;         *(u32x2*)(orow + col) = w; }
; }
; __global__ void __launch_bounds__(NWAVES * 64, 2) mk_fwd(Args args) {
;     ...
;                 for (int j = 0; j < 8; ++j) { const int col = 4 * F.lane + 256 * j; const f32x4 gt = *(const f32x4*)(m0 + 2 * DM + col), pn = *(const f32x4*)(post_norm + col);
;                     const f32x4 y4 = (f32x4){bf_lo(yw[q][j].x), bf_hi(yw[q][j].x), bf_lo(yw[q][j].y), bf_hi(yw[q][j].y)};
;                     v[q][j] = v[q][j] + gt * (y4 * rsy * pn);
;                     if (lat) *(f32x4*)(args.out + (size_t)row * DM + col) = v[q][j]; }
;                 const float rstd = __builtin_amdgcn_rsqf(sumsq8(v[q]) * (1.f / DM) + EPS);
;                 modulate_store(v[q], rstd, pre_norm + DM, mod + (size_t)(9 + r) * 6144, H + (size_t)row * DM, F.lane); }
	v_fmac_f32_e32 v75, v123, v219
	v_lshlrev_b32_e32 v216, 16, v94
	v_and_b32_e32 v217, 0xffff0000, v94
	v_lshlrev_b32_e32 v218, 16, v95
	v_and_b32_e32 v219, 0xffff0000, v95
	v_mul_f32_e32 v216, v225, v216
	v_mul_f32_e32 v217, v225, v217
	v_mul_f32_e32 v218, v225, v218
	v_mul_f32_e32 v219, v225, v219
	v_fmac_f32_e32 v76, v124, v216
	v_fmac_f32_e32 v77, v125, v217
	v_fmac_f32_e32 v78, v126, v218
	v_fmac_f32_e32 v79, v127, v219
	v_mul_f32_e32 v222, v48, v48
	v_mul_f32_e32 v223, v49, v49
	v_fmac_f32_e32 v222, v50, v50
	v_fmac_f32_e32 v223, v51, v51
	v_fmac_f32_e32 v222, v52, v52
	v_fmac_f32_e32 v223, v53, v53
	v_fmac_f32_e32 v222, v54, v54
	v_fmac_f32_e32 v223, v55, v55
	v_fmac_f32_e32 v222, v56, v56
	v_fmac_f32_e32 v223, v57, v57
	v_fmac_f32_e32 v222, v58, v58
	v_fmac_f32_e32 v223, v59, v59
	v_fmac_f32_e32 v222, v60, v60
	v_fmac_f32_e32 v223, v61, v61
	v_fmac_f32_e32 v222, v62, v62
	v_fmac_f32_e32 v223, v63, v63
	v_fmac_f32_e32 v222, v64, v64
	v_fmac_f32_e32 v223, v65, v65
	v_fmac_f32_e32 v222, v66, v66
	v_fmac_f32_e32 v223, v67, v67
	v_fmac_f32_e32 v222, v68, v68
	v_fmac_f32_e32 v223, v69, v69
	v_fmac_f32_e32 v222, v70, v70
	v_fmac_f32_e32 v223, v71, v71
	v_fmac_f32_e32 v222, v72, v72
	v_fmac_f32_e32 v223, v73, v73
	v_fmac_f32_e32 v222, v74, v74
	v_fmac_f32_e32 v223, v75, v75
	v_fmac_f32_e32 v222, v76, v76
	v_fmac_f32_e32 v223, v77, v77
	v_fmac_f32_e32 v222, v78, v78
	v_fmac_f32_e32 v223, v79, v79
	v_add_f32_e32 v222, v222, v223
	s_nop 1
	v_add_f32_dpp v224, v222, v222 quad_perm:[1,0,3,2] row_mask:0xf bank_mask:0xf
	s_nop 1
	v_add_f32_dpp v224, v224, v224 quad_perm:[2,3,0,1] row_mask:0xf bank_mask:0xf
	s_nop 1
	v_add_f32_dpp v224, v224, v224 row_half_mirror row_mask:0xf bank_mask:0xf
	s_nop 1
	v_add_f32_dpp v224, v224, v224 row_mirror row_mask:0xf bank_mask:0xf
	s_nop 1
	v_readlane_b32 s40, v224, 0
	v_readlane_b32 s41, v224, 16
	v_readlane_b32 s42, v224, 32
	v_readlane_b32 s43, v224, 48
	s_nop 1
	v_mov_b32_e32 v225, s40
	v_add_f32_e32 v225, s41, v225
	v_add_f32_e32 v225, s42, v225
	v_add_f32_e32 v225, s43, v225
	v_fmamk_f32 v225, v225, 0x3a000000, v195
	v_rsq_f32_e32 v225, v225
	s_nop 0
	s_add_i32 s0, s6, 5
	s_lshl_b32 s1, s0, 12
	s_add_u32 s26, s84, s1
	s_addc_u32 s27, s85, 0
	s_add_u32 s26, s26, 0x4000000
	s_addc_u32 s27, s27, 0
	v_mul_f32_e32 v216, v225, v48
	v_mul_f32_e32 v217, v225, v49
	v_mul_f32_e32 v218, v225, v50
	v_mul_f32_e32 v219, v225, v51
	v_fma_f32 v216, v216, v128, v160
	v_fma_f32 v217, v217, v129, v161
	v_fma_f32 v218, v218, v130, v162
	v_fma_f32 v219, v219, v131, v163
	v_cvt_pk_bf16_f32 v196, v216, v217
	v_cvt_pk_bf16_f32 v197, v218, v219
	global_store_dwordx2 v194, v[196:197], s[26:27] offset:0 nt
	v_mul_f32_e32 v216, v225, v52
	v_mul_f32_e32 v217, v225, v53
	v_mul_f32_e32 v218, v225, v54
	v_mul_f32_e32 v219, v225, v55
	v_fma_f32 v216, v216, v132, v164
	v_fma_f32 v217, v217, v133, v165
	v_fma_f32 v218, v218, v134, v166
	v_fma_f32 v219, v219, v135, v167
	v_cvt_pk_bf16_f32 v220, v216, v217
	v_cvt_pk_bf16_f32 v221, v218, v219
	global_store_dwordx2 v194, v[220:221], s[26:27] offset:512 nt
	v_mul_f32_e32 v216, v225, v56
	v_mul_f32_e32 v217, v225, v57
	v_mul_f32_e32 v218, v225, v58
	v_mul_f32_e32 v219, v225, v59
	v_fma_f32 v216, v216, v136, v168
	v_fma_f32 v217, v217, v137, v169
	v_fma_f32 v218, v218, v138, v170
	v_fma_f32 v219, v219, v139, v171
	v_cvt_pk_bf16_f32 v196, v216, v217
	v_cvt_pk_bf16_f32 v197, v218, v219
	global_store_dwordx2 v194, v[196:197], s[26:27] offset:1024 nt
	v_mul_f32_e32 v216, v225, v60
	v_mul_f32_e32 v217, v225, v61
	v_mul_f32_e32 v218, v225, v62
	v_mul_f32_e32 v219, v225, v63
	v_fma_f32 v216, v216, v140, v172
	v_fma_f32 v217, v217, v141, v173
	v_fma_f32 v218, v218, v142, v174
	v_fma_f32 v219, v219, v143, v175
	v_cvt_pk_bf16_f32 v220, v216, v217
	v_cvt_pk_bf16_f32 v221, v218, v219
	global_store_dwordx2 v194, v[220:221], s[26:27] offset:1536 nt
	v_mul_f32_e32 v216, v225, v64
	v_mul_f32_e32 v217, v225, v65
	v_mul_f32_e32 v218, v225, v66
	v_mul_f32_e32 v219, v225, v67
	v_fma_f32 v216, v216, v144, v176
	v_fma_f32 v217, v217, v145, v177
	v_fma_f32 v218, v218, v146, v178
	v_fma_f32 v219, v219, v147, v179
	v_cvt_pk_bf16_f32 v196, v216, v217
	v_cvt_pk_bf16_f32 v197, v218, v219
	global_store_dwordx2 v194, v[196:197], s[26:27] offset:2048 nt
	v_mul_f32_e32 v216, v225, v68
	v_mul_f32_e32 v217, v225, v69
	v_mul_f32_e32 v218, v225, v70
	v_mul_f32_e32 v219, v225, v71
	v_fma_f32 v216, v216, v148, v180
	v_fma_f32 v217, v217, v149, v181
	v_fma_f32 v218, v218, v150, v182
	v_fma_f32 v219, v219, v151, v183
	v_cvt_pk_bf16_f32 v220, v216, v217
	v_cvt_pk_bf16_f32 v221, v218, v219
	global_store_dwordx2 v194, v[220:221], s[26:27] offset:2560 nt
	v_mul_f32_e32 v216, v225, v72
	v_mul_f32_e32 v217, v225, v73
	v_mul_f32_e32 v218, v225, v74
	v_mul_f32_e32 v219, v225, v75
	v_fma_f32 v216, v216, v152, v184
	v_fma_f32 v217, v217, v153, v185
	v_fma_f32 v218, v218, v154, v186
	v_fma_f32 v219, v219, v155, v187
	v_cvt_pk_bf16_f32 v196, v216, v217
	v_cvt_pk_bf16_f32 v197, v218, v219
	global_store_dwordx2 v194, v[196:197], s[26:27] offset:3072 nt
	v_mul_f32_e32 v216, v225, v76
	v_mul_f32_e32 v217, v225, v77
	v_mul_f32_e32 v218, v225, v78
	v_mul_f32_e32 v219, v225, v79
	v_fma_f32 v216, v216, v156, v188
	v_fma_f32 v217, v217, v157, v189
	v_fma_f32 v218, v218, v158, v190
	v_fma_f32 v219, v219, v159, v191
	v_cvt_pk_bf16_f32 v220, v216, v217
	v_cvt_pk_bf16_f32 v221, v218, v219
	global_store_dwordx2 v194, v[220:221], s[26:27] offset:3584 nt
	s_add_i32 s0, s6, 7
	s_cmp_lt_u32 s0, 0x4000
	s_cselect_b32 s10, s68, s72
	s_cselect_b32 s11, s69, s73
	s_cselect_b32 s1, 0, 0x4000
	s_sub_i32 s1, s0, s1
	s_lshl_b32 s1, s1, 13
	s_add_u32 s10, s10, s1
	s_addc_u32 s11, s11, 0
	s_add_i32 s0, s6, 7
	s_lshl_b32 s1, s0, 12
	s_add_u32 s22, s84, s1
	s_addc_u32 s23, s85, 0
	s_add_u32 s22, s22, 0x11800000
	s_addc_u32 s23, s23, 0
	global_load_dwordx4 v[48:51], v192, s[10:11] offset:0 nt
	global_load_dwordx4 v[52:55], v192, s[10:11] offset:1024 nt
	global_load_dwordx4 v[56:59], v192, s[10:11] offset:2048 nt
	global_load_dwordx4 v[60:63], v192, s[10:11] offset:3072 nt
	global_load_dwordx4 v[64:67], v193, s[10:11] offset:0 nt
	global_load_dwordx4 v[68:71], v193, s[10:11] offset:1024 nt
	global_load_dwordx4 v[72:75], v193, s[10:11] offset:2048 nt
	global_load_dwordx4 v[76:79], v193, s[10:11] offset:3072 nt
	global_load_dwordx2 v[80:81], v194, s[22:23] offset:0
	global_load_dwordx2 v[82:83], v194, s[22:23] offset:512
	global_load_dwordx2 v[84:85], v194, s[22:23] offset:1024
	global_load_dwordx2 v[86:87], v194, s[22:23] offset:1536
	global_load_dwordx2 v[88:89], v194, s[22:23] offset:2048
	global_load_dwordx2 v[90:91], v194, s[22:23] offset:2560
	global_load_dwordx2 v[92:93], v194, s[22:23] offset:3072
	global_load_dwordx2 v[94:95], v194, s[22:23] offset:3584
	s_add_i32 s0, s6, 6
	s_add_i32 s0, s6, 6
	s_lshr_b32 s8, s0, 11
	s_cmp_lt_u32 s0, 0x4000
	s_cselect_b32 s8, s8, 8
	s_cmp_eq_u32 s8, s7
	s_cbranch_scc1 .Lp6_np6
; __device__ __forceinline__ unsigned cvt_pk_bf16(float lo, float hi) { unsigned r; asm volatile("v_cvt_pk_bf16_f32 %0, %1, %2" : "=v"(r) : "v"(lo), "v"(hi)); return r; }
; __device__ __forceinline__ float bf_lo(unsigned w) { return __uint_as_float(w << 16); }
; __device__ __forceinline__ float bf_hi(unsigned w) { return __uint_as_float(w & 0xffff0000u); }
; __device__ __forceinline__ void modulate_store(const f32x4 (&v)[8], float rstd, const float* pn, const float* modr, bf16_t* orow, int lane) {
; #pragma unroll
;     for (int j = 0; j < 8; ++j) { const int col = 4 * lane + 256 * j;
;         const f32x4 g = *(const f32x4*)(pn + col), sh = *(const f32x4*)(modr + col), sc = *(const f32x4*)(modr + DM + col);
;         const f32x4 hh = v[j] * rstd * g * (sc + 1.f) + sh;
;         u32x2 w; w.x = cvt_pk_bf16(hh[0], hh[1]); w.y = cvt_pk_bf16(hh[2], hh[3]);
; __global__ void __launch_bounds__(NWAVES * 64, 2) mk_fwd(Args args) {
;     ...
;                 const float* m0 = mod + (size_t)r * 6144;
; #pragma unroll
;                 for (int j = 0; j < 8; ++j) { const int col = 4 * F.lane + 256 * j; const f32x4 gt = *(const f32x4*)(m0 + 2 * DM + col), pn = *(const f32x4*)(post_norm + col);
;                     const f32x4 y4 = (f32x4){bf_lo(yw[q][j].x), bf_hi(yw[q][j].x), bf_lo(yw[q][j].y), bf_hi(yw[q][j].y)};
;                     v[q][j] = v[q][j] + gt * (y4 * rsy * pn);
	s_mov_b32 s7, s8
	s_add_i32 s1, s8, 9
	s_mul_i32 s1, s1, 0x6000
	s_add_u32 s44, s84, s1
	s_addc_u32 s45, s85, 0
	s_add_u32 s44, s44, 0x2000
	s_addc_u32 s45, s45, 0
	s_add_i32 s1, s8, 9
	s_mul_i32 s1, s1, 0x6000
	s_add_u32 s36, s84, s1
	s_addc_u32 s37, s85, 0
	s_add_u32 s38, s80, 0x2000
	s_addc_u32 s39, s81, 0
	s_mul_i32 s1, s8, 0x6000
	s_add_u32 s34, s84, s1
	s_addc_u32 s35, s85, 0
	s_add_u32 s34, s34, 0x4000
	s_addc_u32 s35, s35, 0
	global_load_dwordx4 v[96:99], v192, s[34:35] offset:0
	global_load_dwordx4 v[200:203], v192, s[82:83] offset:0
	global_load_dwordx4 v[100:103], v192, s[34:35] offset:1024
	global_load_dwordx4 v[204:207], v192, s[82:83] offset:1024
	global_load_dwordx4 v[104:107], v192, s[34:35] offset:2048
	global_load_dwordx4 v[208:211], v192, s[82:83] offset:2048
	global_load_dwordx4 v[108:111], v192, s[34:35] offset:3072
	global_load_dwordx4 v[212:215], v192, s[82:83] offset:3072
	s_waitcnt vmcnt(0)
	v_mul_f32_e32 v96, v96, v200
	v_mul_f32_e32 v97, v97, v201
	v_mul_f32_e32 v98, v98, v202
	v_mul_f32_e32 v99, v99, v203
	v_mul_f32_e32 v100, v100, v204
	v_mul_f32_e32 v101, v101, v205
	v_mul_f32_e32 v102, v102, v206
	v_mul_f32_e32 v103, v103, v207
	v_mul_f32_e32 v104, v104, v208
	v_mul_f32_e32 v105, v105, v209
	v_mul_f32_e32 v106, v106, v210
	v_mul_f32_e32 v107, v107, v211
	v_mul_f32_e32 v108, v108, v212
	v_mul_f32_e32 v109, v109, v213
	v_mul_f32_e32 v110, v110, v214
	v_mul_f32_e32 v111, v111, v215
	global_load_dwordx4 v[128:131], v192, s[38:39] offset:0
	global_load_dwordx4 v[200:203], v192, s[44:45] offset:0
	global_load_dwordx4 v[160:163], v192, s[36:37] offset:0
	global_load_dwordx4 v[132:135], v192, s[38:39] offset:1024
	global_load_dwordx4 v[204:207], v192, s[44:45] offset:1024
	global_load_dwordx4 v[164:167], v192, s[36:37] offset:1024
	global_load_dwordx4 v[136:139], v192, s[38:39] offset:2048
	global_load_dwordx4 v[208:211], v192, s[44:45] offset:2048
	global_load_dwordx4 v[168:171], v192, s[36:37] offset:2048
	global_load_dwordx4 v[140:143], v192, s[38:39] offset:3072
	global_load_dwordx4 v[212:215], v192, s[44:45] offset:3072
	global_load_dwordx4 v[172:175], v192, s[36:37] offset:3072
	s_waitcnt vmcnt(0)
	v_add_f32_e32 v200, 1.0, v200
	v_add_f32_e32 v201, 1.0, v201
	v_add_f32_e32 v202, 1.0, v202
	v_add_f32_e32 v203, 1.0, v203
	v_mul_f32_e32 v128, v128, v200
	v_mul_f32_e32 v129, v129, v201
	v_mul_f32_e32 v130, v130, v202
	v_mul_f32_e32 v131, v131, v203
	v_add_f32_e32 v204, 1.0, v204
	v_add_f32_e32 v205, 1.0, v205
	v_add_f32_e32 v206, 1.0, v206
	v_add_f32_e32 v207, 1.0, v207
	v_mul_f32_e32 v132, v132, v204
	v_mul_f32_e32 v133, v133, v205
	v_mul_f32_e32 v134, v134, v206
	v_mul_f32_e32 v135, v135, v207
	v_add_f32_e32 v208, 1.0, v208
	v_add_f32_e32 v209, 1.0, v209
	v_add_f32_e32 v210, 1.0, v210
	v_add_f32_e32 v211, 1.0, v211
	v_mul_f32_e32 v136, v136, v208
	v_mul_f32_e32 v137, v137, v209
	v_mul_f32_e32 v138, v138, v210
	v_mul_f32_e32 v139, v139, v211
	v_add_f32_e32 v212, 1.0, v212
	v_add_f32_e32 v213, 1.0, v213
	v_add_f32_e32 v214, 1.0, v214
	v_add_f32_e32 v215, 1.0, v215
	v_mul_f32_e32 v140, v140, v212
	v_mul_f32_e32 v141, v141, v213
	v_mul_f32_e32 v142, v142, v214
	v_mul_f32_e32 v143, v143, v215
	global_load_dwordx4 v[112:115], v193, s[34:35] offset:0
	global_load_dwordx4 v[200:203], v193, s[82:83] offset:0
	global_load_dwordx4 v[116:119], v193, s[34:35] offset:1024
	global_load_dwordx4 v[204:207], v193, s[82:83] offset:1024
	global_load_dwordx4 v[120:123], v193, s[34:35] offset:2048
	global_load_dwordx4 v[208:211], v193, s[82:83] offset:2048
	global_load_dwordx4 v[124:127], v193, s[34:35] offset:3072
	global_load_dwordx4 v[212:215], v193, s[82:83] offset:3072
	s_waitcnt vmcnt(0)
	v_mul_f32_e32 v112, v112, v200
	v_mul_f32_e32 v113, v113, v201
	v_mul_f32_e32 v114, v114, v202
	v_mul_f32_e32 v115, v115, v203
	v_mul_f32_e32 v116, v116, v204
	v_mul_f32_e32 v117, v117, v205
	v_mul_f32_e32 v118, v118, v206
	v_mul_f32_e32 v119, v119, v207
	v_mul_f32_e32 v120, v120, v208
	v_mul_f32_e32 v121, v121, v209
	v_mul_f32_e32 v122, v122, v210
	v_mul_f32_e32 v123, v123, v211
	v_mul_f32_e32 v124, v124, v212
	v_mul_f32_e32 v125, v125, v213
	v_mul_f32_e32 v126, v126, v214
	v_mul_f32_e32 v127, v127, v215
	global_load_dwordx4 v[144:147], v193, s[38:39] offset:0
	global_load_dwordx4 v[200:203], v193, s[44:45] offset:0
	global_load_dwordx4 v[176:179], v193, s[36:37] offset:0
	global_load_dwordx4 v[148:151], v193, s[38:39] offset:1024
	global_load_dwordx4 v[204:207], v193, s[44:45] offset:1024
	global_load_dwordx4 v[180:183], v193, s[36:37] offset:1024
	global_load_dwordx4 v[152:155], v193, s[38:39] offset:2048
	global_load_dwordx4 v[208:211], v193, s[44:45] offset:2048
	global_load_dwordx4 v[184:187], v193, s[36:37] offset:2048
	global_load_dwordx4 v[156:159], v193, s[38:39] offset:3072
	global_load_dwordx4 v[212:215], v193, s[44:45] offset:3072
	global_load_dwordx4 v[188:191], v193, s[36:37] offset:3072
	s_waitcnt vmcnt(0)
	v_add_f32_e32 v200, 1.0, v200
	v_add_f32_e32 v201, 1.0, v201
	v_add_f32_e32 v202, 1.0, v202
	v_add_f32_e32 v203, 1.0, v203
	v_mul_f32_e32 v144, v144, v200
	v_mul_f32_e32 v145, v145, v201
	v_mul_f32_e32 v146, v146, v202
	v_mul_f32_e32 v147, v147, v203
	v_add_f32_e32 v204, 1.0, v204
	v_add_f32_e32 v205, 1.0, v205
	v_add_f32_e32 v206, 1.0, v206
	v_add_f32_e32 v207, 1.0, v207
	v_mul_f32_e32 v148, v148, v204
	v_mul_f32_e32 v149, v149, v205
	v_mul_f32_e32 v150, v150, v206
	v_mul_f32_e32 v151, v151, v207
	v_add_f32_e32 v208, 1.0, v208
	v_add_f32_e32 v209, 1.0, v209
	v_add_f32_e32 v210, 1.0, v210
	v_add_f32_e32 v211, 1.0, v211
	v_mul_f32_e32 v152, v152, v208
	v_mul_f32_e32 v153, v153, v209
	v_mul_f32_e32 v154, v154, v210
	v_mul_f32_e32 v155, v155, v211
	v_add_f32_e32 v212, 1.0, v212
	v_add_f32_e32 v213, 1.0, v213
	v_add_f32_e32 v214, 1.0, v214
	v_add_f32_e32 v215, 1.0, v215
	v_mul_f32_e32 v156, v156, v212
	v_mul_f32_e32 v157, v157, v213
	v_mul_f32_e32 v158, v158, v214
	v_mul_f32_e32 v159, v159, v215
; __device__ __forceinline__ float bf_lo(unsigned w) { return __uint_as_float(w << 16); }
; __device__ __forceinline__ float bf_hi(unsigned w) { return __uint_as_float(w & 0xffff0000u); }
; __global__ void __launch_bounds__(NWAVES * 64, 2) mk_fwd(Args args) {
;     ...
;             for (int q = 0; q < 3; ++q) { const int row = row0 + q; const bool lat = row < ML; const int r = lat ? row / SEQ : 8;
;                 float sy = 0.f;
; #pragma unroll
;                 for (int j = 0; j < 8; ++j) { const float a = bf_lo(yw[q][j].x), b = bf_hi(yw[q][j].x), c2 = bf_lo(yw[q][j].y), d = bf_hi(yw[q][j].y); sy += (a * a + b * b) + (c2 * c2 + d * d); }
;                 const float rsy = __builtin_amdgcn_rsqf(wave_sum(sy) * (1.f / DM) + EPS);
;                 const float* m0 = mod + (size_t)r * 6144;
; #pragma unroll
;                 for (int j = 0; j < 8; ++j) { const int col = 4 * F.lane + 256 * j; const f32x4 gt = *(const f32x4*)(m0 + 2 * DM + col), pn = *(const f32x4*)(post_norm + col);
;                     const f32x4 y4 = (f32x4){bf_lo(yw[q][j].x), bf_hi(yw[q][j].x), bf_lo(yw[q][j].y), bf_hi(yw[q][j].y)};
;                     v[q][j] = v[q][j] + gt * (y4 * rsy * pn);
;                     if (lat) *(f32x4*)(args.out + (size_t)row * DM + col) = v[q][j]; }
.Lp6_np6:
	s_waitcnt vmcnt(24)
	v_lshlrev_b32_e32 v216, 16, v32
	v_and_b32_e32 v217, 0xffff0000, v32
	v_lshlrev_b32_e32 v218, 16, v33
	v_and_b32_e32 v219, 0xffff0000, v33
	v_mul_f32_e32 v222, v216, v216
	v_mul_f32_e32 v223, v217, v217
	v_fmac_f32_e32 v222, v218, v218
	v_fmac_f32_e32 v223, v219, v219
	v_lshlrev_b32_e32 v216, 16, v34
	v_and_b32_e32 v217, 0xffff0000, v34
	v_lshlrev_b32_e32 v218, 16, v35
	v_and_b32_e32 v219, 0xffff0000, v35
	v_fmac_f32_e32 v222, v216, v216
	v_fmac_f32_e32 v223, v217, v217
	v_fmac_f32_e32 v222, v218, v218
	v_fmac_f32_e32 v223, v219, v219
	v_lshlrev_b32_e32 v216, 16, v36
	v_and_b32_e32 v217, 0xffff0000, v36
	v_lshlrev_b32_e32 v218, 16, v37
	v_and_b32_e32 v219, 0xffff0000, v37
	v_fmac_f32_e32 v222, v216, v216
	v_fmac_f32_e32 v223, v217, v217
	v_fmac_f32_e32 v222, v218, v218
	v_fmac_f32_e32 v223, v219, v219
	v_lshlrev_b32_e32 v216, 16, v38
	v_and_b32_e32 v217, 0xffff0000, v38
	v_lshlrev_b32_e32 v218, 16, v39
	v_and_b32_e32 v219, 0xffff0000, v39
	v_fmac_f32_e32 v222, v216, v216
	v_fmac_f32_e32 v223, v217, v217
	v_fmac_f32_e32 v222, v218, v218
	v_fmac_f32_e32 v223, v219, v219
	v_lshlrev_b32_e32 v216, 16, v40
	v_and_b32_e32 v217, 0xffff0000, v40
	v_lshlrev_b32_e32 v218, 16, v41
	v_and_b32_e32 v219, 0xffff0000, v41
	v_fmac_f32_e32 v222, v216, v216
	v_fmac_f32_e32 v223, v217, v217
	v_fmac_f32_e32 v222, v218, v218
	v_fmac_f32_e32 v223, v219, v219
	v_lshlrev_b32_e32 v216, 16, v42
	v_and_b32_e32 v217, 0xffff0000, v42
	v_lshlrev_b32_e32 v218, 16, v43
	v_and_b32_e32 v219, 0xffff0000, v43
	v_fmac_f32_e32 v222, v216, v216
	v_fmac_f32_e32 v223, v217, v217
	v_fmac_f32_e32 v222, v218, v218
	v_fmac_f32_e32 v223, v219, v219
	v_lshlrev_b32_e32 v216, 16, v44
	v_and_b32_e32 v217, 0xffff0000, v44
	v_lshlrev_b32_e32 v218, 16, v45
	v_and_b32_e32 v219, 0xffff0000, v45
	v_fmac_f32_e32 v222, v216, v216
	v_fmac_f32_e32 v223, v217, v217
	v_fmac_f32_e32 v222, v218, v218
	v_fmac_f32_e32 v223, v219, v219
	v_lshlrev_b32_e32 v216, 16, v46
	v_and_b32_e32 v217, 0xffff0000, v46
	v_lshlrev_b32_e32 v218, 16, v47
	v_and_b32_e32 v219, 0xffff0000, v47
	v_fmac_f32_e32 v222, v216, v216
	v_fmac_f32_e32 v223, v217, v217
	v_fmac_f32_e32 v222, v218, v218
	v_fmac_f32_e32 v223, v219, v219
	v_add_f32_e32 v222, v222, v223
	s_nop 1
	v_add_f32_dpp v224, v222, v222 quad_perm:[1,0,3,2] row_mask:0xf bank_mask:0xf
	s_nop 1
	v_add_f32_dpp v224, v224, v224 quad_perm:[2,3,0,1] row_mask:0xf bank_mask:0xf
	s_nop 1
	v_add_f32_dpp v224, v224, v224 row_half_mirror row_mask:0xf bank_mask:0xf
	s_nop 1
	v_add_f32_dpp v224, v224, v224 row_mirror row_mask:0xf bank_mask:0xf
	s_nop 1
	v_readlane_b32 s40, v224, 0
	v_readlane_b32 s41, v224, 16
	v_readlane_b32 s42, v224, 32
	v_readlane_b32 s43, v224, 48
	s_nop 1
	v_mov_b32_e32 v225, s40
	v_add_f32_e32 v225, s41, v225
	v_add_f32_e32 v225, s42, v225
	v_add_f32_e32 v225, s43, v225
	v_fmamk_f32 v225, v225, 0x3a000000, v195
	v_rsq_f32_e32 v225, v225
	s_nop 0
	v_lshlrev_b32_e32 v216, 16, v32
	v_and_b32_e32 v217, 0xffff0000, v32
	v_lshlrev_b32_e32 v218, 16, v33
	v_and_b32_e32 v219, 0xffff0000, v33
	v_mul_f32_e32 v216, v225, v216
	v_mul_f32_e32 v217, v225, v217
	v_mul_f32_e32 v218, v225, v218
	v_mul_f32_e32 v219, v225, v219
	v_fmac_f32_e32 v0, v96, v216
	v_fmac_f32_e32 v1, v97, v217
	v_fmac_f32_e32 v2, v98, v218
	v_fmac_f32_e32 v3, v99, v219
	v_lshlrev_b32_e32 v216, 16, v34
	v_and_b32_e32 v217, 0xffff0000, v34
	v_lshlrev_b32_e32 v218, 16, v35
	v_and_b32_e32 v219, 0xffff0000, v35
	v_mul_f32_e32 v216, v225, v216
	v_mul_f32_e32 v217, v225, v217
	v_mul_f32_e32 v218, v225, v218
	v_mul_f32_e32 v219, v225, v219
	v_fmac_f32_e32 v4, v100, v216
	v_fmac_f32_e32 v5, v101, v217
	v_fmac_f32_e32 v6, v102, v218
	v_fmac_f32_e32 v7, v103, v219
	v_lshlrev_b32_e32 v216, 16, v36
	v_and_b32_e32 v217, 0xffff0000, v36
	v_lshlrev_b32_e32 v218, 16, v37
	v_and_b32_e32 v219, 0xffff0000, v37
	v_mul_f32_e32 v216, v225, v216
	v_mul_f32_e32 v217, v225, v217
	v_mul_f32_e32 v218, v225, v218
	v_mul_f32_e32 v219, v225, v219
	v_fmac_f32_e32 v8, v104, v216
	v_fmac_f32_e32 v9, v105, v217
	v_fmac_f32_e32 v10, v106, v218
	v_fmac_f32_e32 v11, v107, v219
	v_lshlrev_b32_e32 v216, 16, v38
	v_and_b32_e32 v217, 0xffff0000, v38
	v_lshlrev_b32_e32 v218, 16, v39
	v_and_b32_e32 v219, 0xffff0000, v39
	v_mul_f32_e32 v216, v225, v216
	v_mul_f32_e32 v217, v225, v217
	v_mul_f32_e32 v218, v225, v218
	v_mul_f32_e32 v219, v225, v219
	v_fmac_f32_e32 v12, v108, v216
	v_fmac_f32_e32 v13, v109, v217
	v_fmac_f32_e32 v14, v110, v218
	v_fmac_f32_e32 v15, v111, v219
	v_lshlrev_b32_e32 v216, 16, v40
	v_and_b32_e32 v217, 0xffff0000, v40
	v_lshlrev_b32_e32 v218, 16, v41
	v_and_b32_e32 v219, 0xffff0000, v41
	v_mul_f32_e32 v216, v225, v216
	v_mul_f32_e32 v217, v225, v217
	v_mul_f32_e32 v218, v225, v218
	v_mul_f32_e32 v219, v225, v219
	v_fmac_f32_e32 v16, v112, v216
	v_fmac_f32_e32 v17, v113, v217
	v_fmac_f32_e32 v18, v114, v218
	v_fmac_f32_e32 v19, v115, v219
	v_lshlrev_b32_e32 v216, 16, v42
	v_and_b32_e32 v217, 0xffff0000, v42
	v_lshlrev_b32_e32 v218, 16, v43
	v_and_b32_e32 v219, 0xffff0000, v43
	v_mul_f32_e32 v216, v225, v216
	v_mul_f32_e32 v217, v225, v217
	v_mul_f32_e32 v218, v225, v218
	v_mul_f32_e32 v219, v225, v219
	v_fmac_f32_e32 v20, v116, v216
	v_fmac_f32_e32 v21, v117, v217
	v_fmac_f32_e32 v22, v118, v218
	v_fmac_f32_e32 v23, v119, v219
	v_lshlrev_b32_e32 v216, 16, v44
	v_and_b32_e32 v217, 0xffff0000, v44
	v_lshlrev_b32_e32 v218, 16, v45
	v_and_b32_e32 v219, 0xffff0000, v45
	v_mul_f32_e32 v216, v225, v216
	v_mul_f32_e32 v217, v225, v217
	v_mul_f32_e32 v218, v225, v218
	v_mul_f32_e32 v219, v225, v219
	v_fmac_f32_e32 v24, v120, v216
	v_fmac_f32_e32 v25, v121, v217
	v_fmac_f32_e32 v26, v122, v218
; __device__ __forceinline__ unsigned cvt_pk_bf16(float lo, float hi) { unsigned r; asm volatile("v_cvt_pk_bf16_f32 %0, %1, %2" : "=v"(r) : "v"(lo), "v"(hi)); return r; }
; __device__ __forceinline__ float bf_lo(unsigned w) { return __uint_as_float(w << 16); }
; __device__ __forceinline__ float bf_hi(unsigned w) { return __uint_as_float(w & 0xffff0000u); }
; __device__ __forceinline__ float sumsq8(const f32x4 (&v)[8]) {
;     float s = 0.f;
; #pragma unroll
;     for (int j = 0; j < 8; ++j) s += (v[j][0] * v[j][0] + v[j][1] * v[j][1]) + (v[j][2] * v[j][2] + v[j][3] * v[j][3]);
;     return wave_sum(s);
; }
; __device__ __forceinline__ void modulate_store(const f32x4 (&v)[8], float rstd, const float* pn, const float* modr, bf16_t* orow, int lane) {
; #pragma unroll
;     for (int j = 0; j < 8; ++j) { const int col = 4 * lane + 256 * j;
;         const f32x4 g = *(const f32x4*)(pn + col), sh = *(const f32x4*)(modr + col), sc = *(const f32x4*)(modr + DM + col);
;         const f32x4 hh = v[j] * rstd * g * (sc + 1.f) + sh;
;         u32x2 w; w.x = cvt_pk_bf16(hh[0], hh[1]); w.y = cvt_pk_bf16(hh[2], hh[3]);
;         *(u32x2*)(orow + col) = w; }
; }
; __global__ void __launch_bounds__(NWAVES * 64, 2) mk_fwd(Args args) {
;     ...
;                 for (int j = 0; j < 8; ++j) { const int col = 4 * F.lane + 256 * j; const f32x4 gt = *(const f32x4*)(m0 + 2 * DM + col), pn = *(const f32x4*)(post_norm + col);
;                     const f32x4 y4 = (f32x4){bf_lo(yw[q][j].x), bf_hi(yw[q][j].x), bf_lo(yw[q][j].y), bf_hi(yw[q][j].y)};
;                     v[q][j] = v[q][j] + gt * (y4 * rsy * pn);
;                     if (lat) *(f32x4*)(args.out + (size_t)row * DM + col) = v[q][j]; }
;                 const float rstd = __builtin_amdgcn_rsqf(sumsq8(v[q]) * (1.f / DM) + EPS);
;                 modulate_store(v[q], rstd, pre_norm + DM, mod + (size_t)(9 + r) * 6144, H + (size_t)row * DM, F.lane); }
	v_fmac_f32_e32 v27, v123, v219
	v_lshlrev_b32_e32 v216, 16, v46
	v_and_b32_e32 v217, 0xffff0000, v46
	v_lshlrev_b32_e32 v218, 16, v47
	v_and_b32_e32 v219, 0xffff0000, v47
	v_mul_f32_e32 v216, v225, v216
	v_mul_f32_e32 v217, v225, v217
	v_mul_f32_e32 v218, v225, v218
	v_mul_f32_e32 v219, v225, v219
	v_fmac_f32_e32 v28, v124, v216
	v_fmac_f32_e32 v29, v125, v217
	v_fmac_f32_e32 v30, v126, v218
	v_fmac_f32_e32 v31, v127, v219
	v_mul_f32_e32 v222, v0, v0
	v_mul_f32_e32 v223, v1, v1
	v_fmac_f32_e32 v222, v2, v2
	v_fmac_f32_e32 v223, v3, v3
	v_fmac_f32_e32 v222, v4, v4
	v_fmac_f32_e32 v223, v5, v5
	v_fmac_f32_e32 v222, v6, v6
	v_fmac_f32_e32 v223, v7, v7
	v_fmac_f32_e32 v222, v8, v8
	v_fmac_f32_e32 v223, v9, v9
	v_fmac_f32_e32 v222, v10, v10
	v_fmac_f32_e32 v223, v11, v11
	v_fmac_f32_e32 v222, v12, v12
	v_fmac_f32_e32 v223, v13, v13
	v_fmac_f32_e32 v222, v14, v14
	v_fmac_f32_e32 v223, v15, v15
	v_fmac_f32_e32 v222, v16, v16
	v_fmac_f32_e32 v223, v17, v17
	v_fmac_f32_e32 v222, v18, v18
	v_fmac_f32_e32 v223, v19, v19
	v_fmac_f32_e32 v222, v20, v20
	v_fmac_f32_e32 v223, v21, v21
	v_fmac_f32_e32 v222, v22, v22
	v_fmac_f32_e32 v223, v23, v23
	v_fmac_f32_e32 v222, v24, v24
	v_fmac_f32_e32 v223, v25, v25
	v_fmac_f32_e32 v222, v26, v26
	v_fmac_f32_e32 v223, v27, v27
	v_fmac_f32_e32 v222, v28, v28
	v_fmac_f32_e32 v223, v29, v29
	v_fmac_f32_e32 v222, v30, v30
	v_fmac_f32_e32 v223, v31, v31
	v_add_f32_e32 v222, v222, v223
	s_nop 1
	v_add_f32_dpp v224, v222, v222 quad_perm:[1,0,3,2] row_mask:0xf bank_mask:0xf
	s_nop 1
	v_add_f32_dpp v224, v224, v224 quad_perm:[2,3,0,1] row_mask:0xf bank_mask:0xf
	s_nop 1
	v_add_f32_dpp v224, v224, v224 row_half_mirror row_mask:0xf bank_mask:0xf
	s_nop 1
	v_add_f32_dpp v224, v224, v224 row_mirror row_mask:0xf bank_mask:0xf
	s_nop 1
	v_readlane_b32 s40, v224, 0
	v_readlane_b32 s41, v224, 16
	v_readlane_b32 s42, v224, 32
	v_readlane_b32 s43, v224, 48
	s_nop 1
	v_mov_b32_e32 v225, s40
	v_add_f32_e32 v225, s41, v225
	v_add_f32_e32 v225, s42, v225
	v_add_f32_e32 v225, s43, v225
	v_fmamk_f32 v225, v225, 0x3a000000, v195
	v_rsq_f32_e32 v225, v225
	s_nop 0
	s_add_i32 s0, s6, 6
	s_lshl_b32 s1, s0, 12
	s_add_u32 s26, s84, s1
	s_addc_u32 s27, s85, 0
	s_add_u32 s26, s26, 0x4000000
	s_addc_u32 s27, s27, 0
	v_mul_f32_e32 v216, v225, v0
	v_mul_f32_e32 v217, v225, v1
	v_mul_f32_e32 v218, v225, v2
	v_mul_f32_e32 v219, v225, v3
	v_fma_f32 v216, v216, v128, v160
	v_fma_f32 v217, v217, v129, v161
	v_fma_f32 v218, v218, v130, v162
	v_fma_f32 v219, v219, v131, v163
	v_cvt_pk_bf16_f32 v196, v216, v217
	v_cvt_pk_bf16_f32 v197, v218, v219
	global_store_dwordx2 v194, v[196:197], s[26:27] offset:0 nt
	v_mul_f32_e32 v216, v225, v4
	v_mul_f32_e32 v217, v225, v5
	v_mul_f32_e32 v218, v225, v6
	v_mul_f32_e32 v219, v225, v7
	v_fma_f32 v216, v216, v132, v164
	v_fma_f32 v217, v217, v133, v165
	v_fma_f32 v218, v218, v134, v166
	v_fma_f32 v219, v219, v135, v167
	v_cvt_pk_bf16_f32 v220, v216, v217
	v_cvt_pk_bf16_f32 v221, v218, v219
	global_store_dwordx2 v194, v[220:221], s[26:27] offset:512 nt
	v_mul_f32_e32 v216, v225, v8
	v_mul_f32_e32 v217, v225, v9
	v_mul_f32_e32 v218, v225, v10
	v_mul_f32_e32 v219, v225, v11
	v_fma_f32 v216, v216, v136, v168
	v_fma_f32 v217, v217, v137, v169
	v_fma_f32 v218, v218, v138, v170
	v_fma_f32 v219, v219, v139, v171
	v_cvt_pk_bf16_f32 v196, v216, v217
	v_cvt_pk_bf16_f32 v197, v218, v219
	global_store_dwordx2 v194, v[196:197], s[26:27] offset:1024 nt
	v_mul_f32_e32 v216, v225, v12
	v_mul_f32_e32 v217, v225, v13
	v_mul_f32_e32 v218, v225, v14
	v_mul_f32_e32 v219, v225, v15
	v_fma_f32 v216, v216, v140, v172
	v_fma_f32 v217, v217, v141, v173
	v_fma_f32 v218, v218, v142, v174
	v_fma_f32 v219, v219, v143, v175
	v_cvt_pk_bf16_f32 v220, v216, v217
	v_cvt_pk_bf16_f32 v221, v218, v219
	global_store_dwordx2 v194, v[220:221], s[26:27] offset:1536 nt
	v_mul_f32_e32 v216, v225, v16
	v_mul_f32_e32 v217, v225, v17
	v_mul_f32_e32 v218, v225, v18
	v_mul_f32_e32 v219, v225, v19
	v_fma_f32 v216, v216, v144, v176
	v_fma_f32 v217, v217, v145, v177
	v_fma_f32 v218, v218, v146, v178
	v_fma_f32 v219, v219, v147, v179
	v_cvt_pk_bf16_f32 v196, v216, v217
	v_cvt_pk_bf16_f32 v197, v218, v219
	global_store_dwordx2 v194, v[196:197], s[26:27] offset:2048 nt
	v_mul_f32_e32 v216, v225, v20
	v_mul_f32_e32 v217, v225, v21
	v_mul_f32_e32 v218, v225, v22
	v_mul_f32_e32 v219, v225, v23
	v_fma_f32 v216, v216, v148, v180
	v_fma_f32 v217, v217, v149, v181
	v_fma_f32 v218, v218, v150, v182
	v_fma_f32 v219, v219, v151, v183
	v_cvt_pk_bf16_f32 v220, v216, v217
	v_cvt_pk_bf16_f32 v221, v218, v219
	global_store_dwordx2 v194, v[220:221], s[26:27] offset:2560 nt
	v_mul_f32_e32 v216, v225, v24
	v_mul_f32_e32 v217, v225, v25
	v_mul_f32_e32 v218, v225, v26
	v_mul_f32_e32 v219, v225, v27
	v_fma_f32 v216, v216, v152, v184
	v_fma_f32 v217, v217, v153, v185
	v_fma_f32 v218, v218, v154, v186
	v_fma_f32 v219, v219, v155, v187
	v_cvt_pk_bf16_f32 v196, v216, v217
	v_cvt_pk_bf16_f32 v197, v218, v219
	global_store_dwordx2 v194, v[196:197], s[26:27] offset:3072 nt
	v_mul_f32_e32 v216, v225, v28
	v_mul_f32_e32 v217, v225, v29
	v_mul_f32_e32 v218, v225, v30
	v_mul_f32_e32 v219, v225, v31
	v_fma_f32 v216, v216, v156, v188
	v_fma_f32 v217, v217, v157, v189
	v_fma_f32 v218, v218, v158, v190
	v_fma_f32 v219, v219, v159, v191
	v_cvt_pk_bf16_f32 v220, v216, v217
	v_cvt_pk_bf16_f32 v221, v218, v219
	global_store_dwordx2 v194, v[220:221], s[26:27] offset:3584 nt
	s_add_i32 s0, s6, 8
	s_cmp_lt_u32 s0, 0x4000
	s_cselect_b32 s10, s68, s72
	s_cselect_b32 s11, s69, s73
	s_cselect_b32 s1, 0, 0x4000
	s_sub_i32 s1, s0, s1
	s_lshl_b32 s1, s1, 13
	s_add_u32 s10, s10, s1
	s_addc_u32 s11, s11, 0
	s_add_i32 s0, s6, 8
	s_lshl_b32 s1, s0, 12
	s_add_u32 s22, s84, s1
	s_addc_u32 s23, s85, 0
	s_add_u32 s22, s22, 0x11800000
	s_addc_u32 s23, s23, 0
	global_load_dwordx4 v[0:3], v192, s[10:11] offset:0 nt
	global_load_dwordx4 v[4:7], v192, s[10:11] offset:1024 nt
	global_load_dwordx4 v[8:11], v192, s[10:11] offset:2048 nt
	global_load_dwordx4 v[12:15], v192, s[10:11] offset:3072 nt
	global_load_dwordx4 v[16:19], v193, s[10:11] offset:0 nt
	global_load_dwordx4 v[20:23], v193, s[10:11] offset:1024 nt
	global_load_dwordx4 v[24:27], v193, s[10:11] offset:2048 nt
	global_load_dwordx4 v[28:31], v193, s[10:11] offset:3072 nt
	global_load_dwordx2 v[32:33], v194, s[22:23] offset:0
	global_load_dwordx2 v[34:35], v194, s[22:23] offset:512
	global_load_dwordx2 v[36:37], v194, s[22:23] offset:1024
	global_load_dwordx2 v[38:39], v194, s[22:23] offset:1536
	global_load_dwordx2 v[40:41], v194, s[22:23] offset:2048
	global_load_dwordx2 v[42:43], v194, s[22:23] offset:2560
	global_load_dwordx2 v[44:45], v194, s[22:23] offset:3072
	global_load_dwordx2 v[46:47], v194, s[22:23] offset:3584
	s_add_i32 s0, s6, 7
	s_add_i32 s0, s6, 7
	s_lshr_b32 s8, s0, 11
	s_cmp_lt_u32 s0, 0x4000
	s_cselect_b32 s8, s8, 8
	s_cmp_eq_u32 s8, s7
	s_cbranch_scc1 .Lp6_np7
; __device__ __forceinline__ unsigned cvt_pk_bf16(float lo, float hi) { unsigned r; asm volatile("v_cvt_pk_bf16_f32 %0, %1, %2" : "=v"(r) : "v"(lo), "v"(hi)); return r; }
; __device__ __forceinline__ float bf_lo(unsigned w) { return __uint_as_float(w << 16); }
; __device__ __forceinline__ float bf_hi(unsigned w) { return __uint_as_float(w & 0xffff0000u); }
; __device__ __forceinline__ void modulate_store(const f32x4 (&v)[8], float rstd, const float* pn, const float* modr, bf16_t* orow, int lane) {
; #pragma unroll
;     for (int j = 0; j < 8; ++j) { const int col = 4 * lane + 256 * j;
;         const f32x4 g = *(const f32x4*)(pn + col), sh = *(const f32x4*)(modr + col), sc = *(const f32x4*)(modr + DM + col);
;         const f32x4 hh = v[j] * rstd * g * (sc + 1.f) + sh;
;         u32x2 w; w.x = cvt_pk_bf16(hh[0], hh[1]); w.y = cvt_pk_bf16(hh[2], hh[3]);
; __global__ void __launch_bounds__(NWAVES * 64, 2) mk_fwd(Args args) {
;     ...
;                 const float* m0 = mod + (size_t)r * 6144;
; #pragma unroll
;                 for (int j = 0; j < 8; ++j) { const int col = 4 * F.lane + 256 * j; const f32x4 gt = *(const f32x4*)(m0 + 2 * DM + col), pn = *(const f32x4*)(post_norm + col);
;                     const f32x4 y4 = (f32x4){bf_lo(yw[q][j].x), bf_hi(yw[q][j].x), bf_lo(yw[q][j].y), bf_hi(yw[q][j].y)};
;                     v[q][j] = v[q][j] + gt * (y4 * rsy * pn);
	s_mov_b32 s7, s8
	s_add_i32 s1, s8, 9
	s_mul_i32 s1, s1, 0x6000
	s_add_u32 s44, s84, s1
	s_addc_u32 s45, s85, 0
	s_add_u32 s44, s44, 0x2000
	s_addc_u32 s45, s45, 0
	s_add_i32 s1, s8, 9
	s_mul_i32 s1, s1, 0x6000
	s_add_u32 s36, s84, s1
	s_addc_u32 s37, s85, 0
	s_add_u32 s38, s80, 0x2000
	s_addc_u32 s39, s81, 0
	s_mul_i32 s1, s8, 0x6000
	s_add_u32 s34, s84, s1
	s_addc_u32 s35, s85, 0
	s_add_u32 s34, s34, 0x4000
	s_addc_u32 s35, s35, 0
	global_load_dwordx4 v[96:99], v192, s[34:35] offset:0
	global_load_dwordx4 v[200:203], v192, s[82:83] offset:0
	global_load_dwordx4 v[100:103], v192, s[34:35] offset:1024
	global_load_dwordx4 v[204:207], v192, s[82:83] offset:1024
	global_load_dwordx4 v[104:107], v192, s[34:35] offset:2048
	global_load_dwordx4 v[208:211], v192, s[82:83] offset:2048
	global_load_dwordx4 v[108:111], v192, s[34:35] offset:3072
	global_load_dwordx4 v[212:215], v192, s[82:83] offset:3072
	s_waitcnt vmcnt(0)
	v_mul_f32_e32 v96, v96, v200
	v_mul_f32_e32 v97, v97, v201
	v_mul_f32_e32 v98, v98, v202
	v_mul_f32_e32 v99, v99, v203
	v_mul_f32_e32 v100, v100, v204
	v_mul_f32_e32 v101, v101, v205
	v_mul_f32_e32 v102, v102, v206
	v_mul_f32_e32 v103, v103, v207
	v_mul_f32_e32 v104, v104, v208
	v_mul_f32_e32 v105, v105, v209
	v_mul_f32_e32 v106, v106, v210
	v_mul_f32_e32 v107, v107, v211
	v_mul_f32_e32 v108, v108, v212
	v_mul_f32_e32 v109, v109, v213
	v_mul_f32_e32 v110, v110, v214
	v_mul_f32_e32 v111, v111, v215
	global_load_dwordx4 v[128:131], v192, s[38:39] offset:0
	global_load_dwordx4 v[200:203], v192, s[44:45] offset:0
	global_load_dwordx4 v[160:163], v192, s[36:37] offset:0
	global_load_dwordx4 v[132:135], v192, s[38:39] offset:1024
	global_load_dwordx4 v[204:207], v192, s[44:45] offset:1024
	global_load_dwordx4 v[164:167], v192, s[36:37] offset:1024
	global_load_dwordx4 v[136:139], v192, s[38:39] offset:2048
	global_load_dwordx4 v[208:211], v192, s[44:45] offset:2048
	global_load_dwordx4 v[168:171], v192, s[36:37] offset:2048
	global_load_dwordx4 v[140:143], v192, s[38:39] offset:3072
	global_load_dwordx4 v[212:215], v192, s[44:45] offset:3072
	global_load_dwordx4 v[172:175], v192, s[36:37] offset:3072
	s_waitcnt vmcnt(0)
	v_add_f32_e32 v200, 1.0, v200
	v_add_f32_e32 v201, 1.0, v201
	v_add_f32_e32 v202, 1.0, v202
	v_add_f32_e32 v203, 1.0, v203
	v_mul_f32_e32 v128, v128, v200
	v_mul_f32_e32 v129, v129, v201
	v_mul_f32_e32 v130, v130, v202
	v_mul_f32_e32 v131, v131, v203
	v_add_f32_e32 v204, 1.0, v204
	v_add_f32_e32 v205, 1.0, v205
	v_add_f32_e32 v206, 1.0, v206
	v_add_f32_e32 v207, 1.0, v207
	v_mul_f32_e32 v132, v132, v204
	v_mul_f32_e32 v133, v133, v205
	v_mul_f32_e32 v134, v134, v206
	v_mul_f32_e32 v135, v135, v207
	v_add_f32_e32 v208, 1.0, v208
	v_add_f32_e32 v209, 1.0, v209
	v_add_f32_e32 v210, 1.0, v210
	v_add_f32_e32 v211, 1.0, v211
	v_mul_f32_e32 v136, v136, v208
	v_mul_f32_e32 v137, v137, v209
	v_mul_f32_e32 v138, v138, v210
	v_mul_f32_e32 v139, v139, v211
	v_add_f32_e32 v212, 1.0, v212
	v_add_f32_e32 v213, 1.0, v213
	v_add_f32_e32 v214, 1.0, v214
	v_add_f32_e32 v215, 1.0, v215
	v_mul_f32_e32 v140, v140, v212
	v_mul_f32_e32 v141, v141, v213
	v_mul_f32_e32 v142, v142, v214
	v_mul_f32_e32 v143, v143, v215
	global_load_dwordx4 v[112:115], v193, s[34:35] offset:0
	global_load_dwordx4 v[200:203], v193, s[82:83] offset:0
	global_load_dwordx4 v[116:119], v193, s[34:35] offset:1024
	global_load_dwordx4 v[204:207], v193, s[82:83] offset:1024
	global_load_dwordx4 v[120:123], v193, s[34:35] offset:2048
	global_load_dwordx4 v[208:211], v193, s[82:83] offset:2048
	global_load_dwordx4 v[124:127], v193, s[34:35] offset:3072
	global_load_dwordx4 v[212:215], v193, s[82:83] offset:3072
	s_waitcnt vmcnt(0)
	v_mul_f32_e32 v112, v112, v200
	v_mul_f32_e32 v113, v113, v201
	v_mul_f32_e32 v114, v114, v202
	v_mul_f32_e32 v115, v115, v203
	v_mul_f32_e32 v116, v116, v204
	v_mul_f32_e32 v117, v117, v205
	v_mul_f32_e32 v118, v118, v206
	v_mul_f32_e32 v119, v119, v207
	v_mul_f32_e32 v120, v120, v208
	v_mul_f32_e32 v121, v121, v209
	v_mul_f32_e32 v122, v122, v210
	v_mul_f32_e32 v123, v123, v211
	v_mul_f32_e32 v124, v124, v212
	v_mul_f32_e32 v125, v125, v213
	v_mul_f32_e32 v126, v126, v214
	v_mul_f32_e32 v127, v127, v215
	global_load_dwordx4 v[144:147], v193, s[38:39] offset:0
	global_load_dwordx4 v[200:203], v193, s[44:45] offset:0
	global_load_dwordx4 v[176:179], v193, s[36:37] offset:0
	global_load_dwordx4 v[148:151], v193, s[38:39] offset:1024
	global_load_dwordx4 v[204:207], v193, s[44:45] offset:1024
	global_load_dwordx4 v[180:183], v193, s[36:37] offset:1024
	global_load_dwordx4 v[152:155], v193, s[38:39] offset:2048
	global_load_dwordx4 v[208:211], v193, s[44:45] offset:2048
	global_load_dwordx4 v[184:187], v193, s[36:37] offset:2048
	global_load_dwordx4 v[156:159], v193, s[38:39] offset:3072
	global_load_dwordx4 v[212:215], v193, s[44:45] offset:3072
	global_load_dwordx4 v[188:191], v193, s[36:37] offset:3072
	s_waitcnt vmcnt(0)
	v_add_f32_e32 v200, 1.0, v200
	v_add_f32_e32 v201, 1.0, v201
	v_add_f32_e32 v202, 1.0, v202
	v_add_f32_e32 v203, 1.0, v203
	v_mul_f32_e32 v144, v144, v200
	v_mul_f32_e32 v145, v145, v201
	v_mul_f32_e32 v146, v146, v202
	v_mul_f32_e32 v147, v147, v203
	v_add_f32_e32 v204, 1.0, v204
	v_add_f32_e32 v205, 1.0, v205
	v_add_f32_e32 v206, 1.0, v206
	v_add_f32_e32 v207, 1.0, v207
	v_mul_f32_e32 v148, v148, v204
	v_mul_f32_e32 v149, v149, v205
	v_mul_f32_e32 v150, v150, v206
	v_mul_f32_e32 v151, v151, v207
	v_add_f32_e32 v208, 1.0, v208
	v_add_f32_e32 v209, 1.0, v209
	v_add_f32_e32 v210, 1.0, v210
	v_add_f32_e32 v211, 1.0, v211
	v_mul_f32_e32 v152, v152, v208
	v_mul_f32_e32 v153, v153, v209
	v_mul_f32_e32 v154, v154, v210
	v_mul_f32_e32 v155, v155, v211
	v_add_f32_e32 v212, 1.0, v212
	v_add_f32_e32 v213, 1.0, v213
	v_add_f32_e32 v214, 1.0, v214
	v_add_f32_e32 v215, 1.0, v215
	v_mul_f32_e32 v156, v156, v212
	v_mul_f32_e32 v157, v157, v213
	v_mul_f32_e32 v158, v158, v214
	v_mul_f32_e32 v159, v159, v215
; __device__ __forceinline__ float bf_lo(unsigned w) { return __uint_as_float(w << 16); }
; __device__ __forceinline__ float bf_hi(unsigned w) { return __uint_as_float(w & 0xffff0000u); }
; __global__ void __launch_bounds__(NWAVES * 64, 2) mk_fwd(Args args) {
;     ...
;             for (int q = 0; q < 3; ++q) { const int row = row0 + q; const bool lat = row < ML; const int r = lat ? row / SEQ : 8;
;                 float sy = 0.f;
; #pragma unroll
;                 for (int j = 0; j < 8; ++j) { const float a = bf_lo(yw[q][j].x), b = bf_hi(yw[q][j].x), c2 = bf_lo(yw[q][j].y), d = bf_hi(yw[q][j].y); sy += (a * a + b * b) + (c2 * c2 + d * d); }
;                 const float rsy = __builtin_amdgcn_rsqf(wave_sum(sy) * (1.f / DM) + EPS);
;                 const float* m0 = mod + (size_t)r * 6144;
; #pragma unroll
;                 for (int j = 0; j < 8; ++j) { const int col = 4 * F.lane + 256 * j; const f32x4 gt = *(const f32x4*)(m0 + 2 * DM + col), pn = *(const f32x4*)(post_norm + col);
;                     const f32x4 y4 = (f32x4){bf_lo(yw[q][j].x), bf_hi(yw[q][j].x), bf_lo(yw[q][j].y), bf_hi(yw[q][j].y)};
;                     v[q][j] = v[q][j] + gt * (y4 * rsy * pn);
;                     if (lat) *(f32x4*)(args.out + (size_t)row * DM + col) = v[q][j]; }
.Lp6_np7:
	s_waitcnt vmcnt(24)
	v_lshlrev_b32_e32 v216, 16, v80
	v_and_b32_e32 v217, 0xffff0000, v80
	v_lshlrev_b32_e32 v218, 16, v81
	v_and_b32_e32 v219, 0xffff0000, v81
	v_mul_f32_e32 v222, v216, v216
	v_mul_f32_e32 v223, v217, v217
	v_fmac_f32_e32 v222, v218, v218
	v_fmac_f32_e32 v223, v219, v219
	v_lshlrev_b32_e32 v216, 16, v82
	v_and_b32_e32 v217, 0xffff0000, v82
	v_lshlrev_b32_e32 v218, 16, v83
	v_and_b32_e32 v219, 0xffff0000, v83
	v_fmac_f32_e32 v222, v216, v216
	v_fmac_f32_e32 v223, v217, v217
	v_fmac_f32_e32 v222, v218, v218
	v_fmac_f32_e32 v223, v219, v219
	v_lshlrev_b32_e32 v216, 16, v84
	v_and_b32_e32 v217, 0xffff0000, v84
	v_lshlrev_b32_e32 v218, 16, v85
	v_and_b32_e32 v219, 0xffff0000, v85
	v_fmac_f32_e32 v222, v216, v216
	v_fmac_f32_e32 v223, v217, v217
	v_fmac_f32_e32 v222, v218, v218
	v_fmac_f32_e32 v223, v219, v219
	v_lshlrev_b32_e32 v216, 16, v86
	v_and_b32_e32 v217, 0xffff0000, v86
	v_lshlrev_b32_e32 v218, 16, v87
	v_and_b32_e32 v219, 0xffff0000, v87
	v_fmac_f32_e32 v222, v216, v216
	v_fmac_f32_e32 v223, v217, v217
	v_fmac_f32_e32 v222, v218, v218
	v_fmac_f32_e32 v223, v219, v219
	v_lshlrev_b32_e32 v216, 16, v88
	v_and_b32_e32 v217, 0xffff0000, v88
	v_lshlrev_b32_e32 v218, 16, v89
	v_and_b32_e32 v219, 0xffff0000, v89
	v_fmac_f32_e32 v222, v216, v216
	v_fmac_f32_e32 v223, v217, v217
	v_fmac_f32_e32 v222, v218, v218
	v_fmac_f32_e32 v223, v219, v219
	v_lshlrev_b32_e32 v216, 16, v90
	v_and_b32_e32 v217, 0xffff0000, v90
	v_lshlrev_b32_e32 v218, 16, v91
	v_and_b32_e32 v219, 0xffff0000, v91
	v_fmac_f32_e32 v222, v216, v216
	v_fmac_f32_e32 v223, v217, v217
	v_fmac_f32_e32 v222, v218, v218
	v_fmac_f32_e32 v223, v219, v219
	v_lshlrev_b32_e32 v216, 16, v92
	v_and_b32_e32 v217, 0xffff0000, v92
	v_lshlrev_b32_e32 v218, 16, v93
	v_and_b32_e32 v219, 0xffff0000, v93
	v_fmac_f32_e32 v222, v216, v216
	v_fmac_f32_e32 v223, v217, v217
	v_fmac_f32_e32 v222, v218, v218
	v_fmac_f32_e32 v223, v219, v219
	v_lshlrev_b32_e32 v216, 16, v94
	v_and_b32_e32 v217, 0xffff0000, v94
	v_lshlrev_b32_e32 v218, 16, v95
	v_and_b32_e32 v219, 0xffff0000, v95
	v_fmac_f32_e32 v222, v216, v216
	v_fmac_f32_e32 v223, v217, v217
	v_fmac_f32_e32 v222, v218, v218
	v_fmac_f32_e32 v223, v219, v219
	v_add_f32_e32 v222, v222, v223
	s_nop 1
	v_add_f32_dpp v224, v222, v222 quad_perm:[1,0,3,2] row_mask:0xf bank_mask:0xf
	s_nop 1
	v_add_f32_dpp v224, v224, v224 quad_perm:[2,3,0,1] row_mask:0xf bank_mask:0xf
	s_nop 1
	v_add_f32_dpp v224, v224, v224 row_half_mirror row_mask:0xf bank_mask:0xf
	s_nop 1
	v_add_f32_dpp v224, v224, v224 row_mirror row_mask:0xf bank_mask:0xf
	s_nop 1
	v_readlane_b32 s40, v224, 0
	v_readlane_b32 s41, v224, 16
	v_readlane_b32 s42, v224, 32
	v_readlane_b32 s43, v224, 48
	s_nop 1
	v_mov_b32_e32 v225, s40
	v_add_f32_e32 v225, s41, v225
	v_add_f32_e32 v225, s42, v225
	v_add_f32_e32 v225, s43, v225
	v_fmamk_f32 v225, v225, 0x3a000000, v195
	v_rsq_f32_e32 v225, v225
	s_nop 0
	v_lshlrev_b32_e32 v216, 16, v80
	v_and_b32_e32 v217, 0xffff0000, v80
	v_lshlrev_b32_e32 v218, 16, v81
	v_and_b32_e32 v219, 0xffff0000, v81
	v_mul_f32_e32 v216, v225, v216
	v_mul_f32_e32 v217, v225, v217
	v_mul_f32_e32 v218, v225, v218
	v_mul_f32_e32 v219, v225, v219
	v_fmac_f32_e32 v48, v96, v216
	v_fmac_f32_e32 v49, v97, v217
	v_fmac_f32_e32 v50, v98, v218
	v_fmac_f32_e32 v51, v99, v219
	v_lshlrev_b32_e32 v216, 16, v82
	v_and_b32_e32 v217, 0xffff0000, v82
	v_lshlrev_b32_e32 v218, 16, v83
	v_and_b32_e32 v219, 0xffff0000, v83
	v_mul_f32_e32 v216, v225, v216
	v_mul_f32_e32 v217, v225, v217
	v_mul_f32_e32 v218, v225, v218
	v_mul_f32_e32 v219, v225, v219
	v_fmac_f32_e32 v52, v100, v216
	v_fmac_f32_e32 v53, v101, v217
	v_fmac_f32_e32 v54, v102, v218
	v_fmac_f32_e32 v55, v103, v219
	v_lshlrev_b32_e32 v216, 16, v84
	v_and_b32_e32 v217, 0xffff0000, v84
	v_lshlrev_b32_e32 v218, 16, v85
	v_and_b32_e32 v219, 0xffff0000, v85
	v_mul_f32_e32 v216, v225, v216
	v_mul_f32_e32 v217, v225, v217
	v_mul_f32_e32 v218, v225, v218
	v_mul_f32_e32 v219, v225, v219
	v_fmac_f32_e32 v56, v104, v216
	v_fmac_f32_e32 v57, v105, v217
	v_fmac_f32_e32 v58, v106, v218
	v_fmac_f32_e32 v59, v107, v219
	v_lshlrev_b32_e32 v216, 16, v86
	v_and_b32_e32 v217, 0xffff0000, v86
	v_lshlrev_b32_e32 v218, 16, v87
	v_and_b32_e32 v219, 0xffff0000, v87
	v_mul_f32_e32 v216, v225, v216
	v_mul_f32_e32 v217, v225, v217
	v_mul_f32_e32 v218, v225, v218
	v_mul_f32_e32 v219, v225, v219
	v_fmac_f32_e32 v60, v108, v216
	v_fmac_f32_e32 v61, v109, v217
	v_fmac_f32_e32 v62, v110, v218
	v_fmac_f32_e32 v63, v111, v219
	v_lshlrev_b32_e32 v216, 16, v88
	v_and_b32_e32 v217, 0xffff0000, v88
	v_lshlrev_b32_e32 v218, 16, v89
	v_and_b32_e32 v219, 0xffff0000, v89
	v_mul_f32_e32 v216, v225, v216
	v_mul_f32_e32 v217, v225, v217
	v_mul_f32_e32 v218, v225, v218
	v_mul_f32_e32 v219, v225, v219
	v_fmac_f32_e32 v64, v112, v216
	v_fmac_f32_e32 v65, v113, v217
	v_fmac_f32_e32 v66, v114, v218
	v_fmac_f32_e32 v67, v115, v219
	v_lshlrev_b32_e32 v216, 16, v90
	v_and_b32_e32 v217, 0xffff0000, v90
	v_lshlrev_b32_e32 v218, 16, v91
	v_and_b32_e32 v219, 0xffff0000, v91
	v_mul_f32_e32 v216, v225, v216
	v_mul_f32_e32 v217, v225, v217
	v_mul_f32_e32 v218, v225, v218
	v_mul_f32_e32 v219, v225, v219
	v_fmac_f32_e32 v68, v116, v216
	v_fmac_f32_e32 v69, v117, v217
	v_fmac_f32_e32 v70, v118, v218
	v_fmac_f32_e32 v71, v119, v219
	v_lshlrev_b32_e32 v216, 16, v92
	v_and_b32_e32 v217, 0xffff0000, v92
	v_lshlrev_b32_e32 v218, 16, v93
	v_and_b32_e32 v219, 0xffff0000, v93
	v_mul_f32_e32 v216, v225, v216
	v_mul_f32_e32 v217, v225, v217
	v_mul_f32_e32 v218, v225, v218
	v_mul_f32_e32 v219, v225, v219
	v_fmac_f32_e32 v72, v120, v216
	v_fmac_f32_e32 v73, v121, v217
	v_fmac_f32_e32 v74, v122, v218
; __device__ __forceinline__ unsigned cvt_pk_bf16(float lo, float hi) { unsigned r; asm volatile("v_cvt_pk_bf16_f32 %0, %1, %2" : "=v"(r) : "v"(lo), "v"(hi)); return r; }
; __device__ __forceinline__ float bf_lo(unsigned w) { return __uint_as_float(w << 16); }
; __device__ __forceinline__ float bf_hi(unsigned w) { return __uint_as_float(w & 0xffff0000u); }
; __device__ __forceinline__ float sumsq8(const f32x4 (&v)[8]) {
;     float s = 0.f;
; #pragma unroll
;     for (int j = 0; j < 8; ++j) s += (v[j][0] * v[j][0] + v[j][1] * v[j][1]) + (v[j][2] * v[j][2] + v[j][3] * v[j][3]);
;     return wave_sum(s);
; }
; __device__ __forceinline__ void modulate_store(const f32x4 (&v)[8], float rstd, const float* pn, const float* modr, bf16_t* orow, int lane) {
; #pragma unroll
;     for (int j = 0; j < 8; ++j) { const int col = 4 * lane + 256 * j;
;         const f32x4 g = *(const f32x4*)(pn + col), sh = *(const f32x4*)(modr + col), sc = *(const f32x4*)(modr + DM + col);
;         const f32x4 hh = v[j] * rstd * g * (sc + 1.f) + sh;
;         u32x2 w; w.x = cvt_pk_bf16(hh[0], hh[1]); w.y = cvt_pk_bf16(hh[2], hh[3]);
;         *(u32x2*)(orow + col) = w; }
; }
; __global__ void __launch_bounds__(NWAVES * 64, 2) mk_fwd(Args args) {
;     ...
;                 for (int j = 0; j < 8; ++j) { const int col = 4 * F.lane + 256 * j; const f32x4 gt = *(const f32x4*)(m0 + 2 * DM + col), pn = *(const f32x4*)(post_norm + col);
;                     const f32x4 y4 = (f32x4){bf_lo(yw[q][j].x), bf_hi(yw[q][j].x), bf_lo(yw[q][j].y), bf_hi(yw[q][j].y)};
;                     v[q][j] = v[q][j] + gt * (y4 * rsy * pn);
;                     if (lat) *(f32x4*)(args.out + (size_t)row * DM + col) = v[q][j]; }
;                 const float rstd = __builtin_amdgcn_rsqf(sumsq8(v[q]) * (1.f / DM) + EPS);
;                 modulate_store(v[q], rstd, pre_norm + DM, mod + (size_t)(9 + r) * 6144, H + (size_t)row * DM, F.lane); }
	v_fmac_f32_e32 v75, v123, v219
	v_lshlrev_b32_e32 v216, 16, v94
	v_and_b32_e32 v217, 0xffff0000, v94
	v_lshlrev_b32_e32 v218, 16, v95
	v_and_b32_e32 v219, 0xffff0000, v95
	v_mul_f32_e32 v216, v225, v216
	v_mul_f32_e32 v217, v225, v217
	v_mul_f32_e32 v218, v225, v218
	v_mul_f32_e32 v219, v225, v219
	v_fmac_f32_e32 v76, v124, v216
	v_fmac_f32_e32 v77, v125, v217
	v_fmac_f32_e32 v78, v126, v218
	v_fmac_f32_e32 v79, v127, v219
	v_mul_f32_e32 v222, v48, v48
	v_mul_f32_e32 v223, v49, v49
	v_fmac_f32_e32 v222, v50, v50
	v_fmac_f32_e32 v223, v51, v51
	v_fmac_f32_e32 v222, v52, v52
	v_fmac_f32_e32 v223, v53, v53
	v_fmac_f32_e32 v222, v54, v54
	v_fmac_f32_e32 v223, v55, v55
	v_fmac_f32_e32 v222, v56, v56
	v_fmac_f32_e32 v223, v57, v57
	v_fmac_f32_e32 v222, v58, v58
	v_fmac_f32_e32 v223, v59, v59
	v_fmac_f32_e32 v222, v60, v60
	v_fmac_f32_e32 v223, v61, v61
	v_fmac_f32_e32 v222, v62, v62
	v_fmac_f32_e32 v223, v63, v63
	v_fmac_f32_e32 v222, v64, v64
	v_fmac_f32_e32 v223, v65, v65
	v_fmac_f32_e32 v222, v66, v66
	v_fmac_f32_e32 v223, v67, v67
	v_fmac_f32_e32 v222, v68, v68
	v_fmac_f32_e32 v223, v69, v69
	v_fmac_f32_e32 v222, v70, v70
	v_fmac_f32_e32 v223, v71, v71
	v_fmac_f32_e32 v222, v72, v72
	v_fmac_f32_e32 v223, v73, v73
	v_fmac_f32_e32 v222, v74, v74
	v_fmac_f32_e32 v223, v75, v75
	v_fmac_f32_e32 v222, v76, v76
	v_fmac_f32_e32 v223, v77, v77
	v_fmac_f32_e32 v222, v78, v78
	v_fmac_f32_e32 v223, v79, v79
	v_add_f32_e32 v222, v222, v223
	s_nop 1
	v_add_f32_dpp v224, v222, v222 quad_perm:[1,0,3,2] row_mask:0xf bank_mask:0xf
	s_nop 1
	v_add_f32_dpp v224, v224, v224 quad_perm:[2,3,0,1] row_mask:0xf bank_mask:0xf
	s_nop 1
	v_add_f32_dpp v224, v224, v224 row_half_mirror row_mask:0xf bank_mask:0xf
	s_nop 1
	v_add_f32_dpp v224, v224, v224 row_mirror row_mask:0xf bank_mask:0xf
	s_nop 1
	v_readlane_b32 s40, v224, 0
	v_readlane_b32 s41, v224, 16
	v_readlane_b32 s42, v224, 32
	v_readlane_b32 s43, v224, 48
	s_nop 1
	v_mov_b32_e32 v225, s40
	v_add_f32_e32 v225, s41, v225
	v_add_f32_e32 v225, s42, v225
	v_add_f32_e32 v225, s43, v225
	v_fmamk_f32 v225, v225, 0x3a000000, v195
	v_rsq_f32_e32 v225, v225
	s_nop 0
	s_add_i32 s0, s6, 7
	s_lshl_b32 s1, s0, 12
	s_add_u32 s26, s84, s1
	s_addc_u32 s27, s85, 0
	s_add_u32 s26, s26, 0x4000000
	s_addc_u32 s27, s27, 0
	v_mul_f32_e32 v216, v225, v48
	v_mul_f32_e32 v217, v225, v49
	v_mul_f32_e32 v218, v225, v50
	v_mul_f32_e32 v219, v225, v51
	v_fma_f32 v216, v216, v128, v160
	v_fma_f32 v217, v217, v129, v161
	v_fma_f32 v218, v218, v130, v162
	v_fma_f32 v219, v219, v131, v163
	v_cvt_pk_bf16_f32 v196, v216, v217
	v_cvt_pk_bf16_f32 v197, v218, v219
	global_store_dwordx2 v194, v[196:197], s[26:27] offset:0 nt
	v_mul_f32_e32 v216, v225, v52
	v_mul_f32_e32 v217, v225, v53
	v_mul_f32_e32 v218, v225, v54
	v_mul_f32_e32 v219, v225, v55
	v_fma_f32 v216, v216, v132, v164
	v_fma_f32 v217, v217, v133, v165
	v_fma_f32 v218, v218, v134, v166
	v_fma_f32 v219, v219, v135, v167
	v_cvt_pk_bf16_f32 v220, v216, v217
	v_cvt_pk_bf16_f32 v221, v218, v219
	global_store_dwordx2 v194, v[220:221], s[26:27] offset:512 nt
	v_mul_f32_e32 v216, v225, v56
	v_mul_f32_e32 v217, v225, v57
	v_mul_f32_e32 v218, v225, v58
	v_mul_f32_e32 v219, v225, v59
	v_fma_f32 v216, v216, v136, v168
	v_fma_f32 v217, v217, v137, v169
	v_fma_f32 v218, v218, v138, v170
	v_fma_f32 v219, v219, v139, v171
	v_cvt_pk_bf16_f32 v196, v216, v217
	v_cvt_pk_bf16_f32 v197, v218, v219
	global_store_dwordx2 v194, v[196:197], s[26:27] offset:1024 nt
	v_mul_f32_e32 v216, v225, v60
	v_mul_f32_e32 v217, v225, v61
	v_mul_f32_e32 v218, v225, v62
	v_mul_f32_e32 v219, v225, v63
	v_fma_f32 v216, v216, v140, v172
	v_fma_f32 v217, v217, v141, v173
	v_fma_f32 v218, v218, v142, v174
	v_fma_f32 v219, v219, v143, v175
	v_cvt_pk_bf16_f32 v220, v216, v217
	v_cvt_pk_bf16_f32 v221, v218, v219
	global_store_dwordx2 v194, v[220:221], s[26:27] offset:1536 nt
	v_mul_f32_e32 v216, v225, v64
	v_mul_f32_e32 v217, v225, v65
	v_mul_f32_e32 v218, v225, v66
	v_mul_f32_e32 v219, v225, v67
	v_fma_f32 v216, v216, v144, v176
	v_fma_f32 v217, v217, v145, v177
	v_fma_f32 v218, v218, v146, v178
	v_fma_f32 v219, v219, v147, v179
	v_cvt_pk_bf16_f32 v196, v216, v217
	v_cvt_pk_bf16_f32 v197, v218, v219
	global_store_dwordx2 v194, v[196:197], s[26:27] offset:2048 nt
	v_mul_f32_e32 v216, v225, v68
	v_mul_f32_e32 v217, v225, v69
	v_mul_f32_e32 v218, v225, v70
	v_mul_f32_e32 v219, v225, v71
	v_fma_f32 v216, v216, v148, v180
	v_fma_f32 v217, v217, v149, v181
	v_fma_f32 v218, v218, v150, v182
	v_fma_f32 v219, v219, v151, v183
	v_cvt_pk_bf16_f32 v220, v216, v217
	v_cvt_pk_bf16_f32 v221, v218, v219
	global_store_dwordx2 v194, v[220:221], s[26:27] offset:2560 nt
	v_mul_f32_e32 v216, v225, v72
	v_mul_f32_e32 v217, v225, v73
	v_mul_f32_e32 v218, v225, v74
	v_mul_f32_e32 v219, v225, v75
	v_fma_f32 v216, v216, v152, v184
	v_fma_f32 v217, v217, v153, v185
	v_fma_f32 v218, v218, v154, v186
	v_fma_f32 v219, v219, v155, v187
	v_cvt_pk_bf16_f32 v196, v216, v217
	v_cvt_pk_bf16_f32 v197, v218, v219
	global_store_dwordx2 v194, v[196:197], s[26:27] offset:3072 nt
	v_mul_f32_e32 v216, v225, v76
	v_mul_f32_e32 v217, v225, v77
	v_mul_f32_e32 v218, v225, v78
	v_mul_f32_e32 v219, v225, v79
	v_fma_f32 v216, v216, v156, v188
	v_fma_f32 v217, v217, v157, v189
	v_fma_f32 v218, v218, v158, v190
	v_fma_f32 v219, v219, v159, v191
	v_cvt_pk_bf16_f32 v220, v216, v217
	v_cvt_pk_bf16_f32 v221, v218, v219
	global_store_dwordx2 v194, v[220:221], s[26:27] offset:3584 nt
	s_add_i32 s0, s6, 8
	s_add_i32 s0, s6, 8
	s_lshr_b32 s8, s0, 11
	s_cmp_lt_u32 s0, 0x4000
	s_cselect_b32 s8, s8, 8
	s_cmp_eq_u32 s8, s7
	s_cbranch_scc1 .Lp6_np8
; __device__ __forceinline__ unsigned cvt_pk_bf16(float lo, float hi) { unsigned r; asm volatile("v_cvt_pk_bf16_f32 %0, %1, %2" : "=v"(r) : "v"(lo), "v"(hi)); return r; }
; __device__ __forceinline__ float bf_lo(unsigned w) { return __uint_as_float(w << 16); }
; __device__ __forceinline__ float bf_hi(unsigned w) { return __uint_as_float(w & 0xffff0000u); }
; __device__ __forceinline__ void modulate_store(const f32x4 (&v)[8], float rstd, const float* pn, const float* modr, bf16_t* orow, int lane) {
; #pragma unroll
;     for (int j = 0; j < 8; ++j) { const int col = 4 * lane + 256 * j;
;         const f32x4 g = *(const f32x4*)(pn + col), sh = *(const f32x4*)(modr + col), sc = *(const f32x4*)(modr + DM + col);
;         const f32x4 hh = v[j] * rstd * g * (sc + 1.f) + sh;
;         u32x2 w; w.x = cvt_pk_bf16(hh[0], hh[1]); w.y = cvt_pk_bf16(hh[2], hh[3]);
; __global__ void __launch_bounds__(NWAVES * 64, 2) mk_fwd(Args args) {
;     ...
;                 const float* m0 = mod + (size_t)r * 6144;
; #pragma unroll
;                 for (int j = 0; j < 8; ++j) { const int col = 4 * F.lane + 256 * j; const f32x4 gt = *(const f32x4*)(m0 + 2 * DM + col), pn = *(const f32x4*)(post_norm + col);
;                     const f32x4 y4 = (f32x4){bf_lo(yw[q][j].x), bf_hi(yw[q][j].x), bf_lo(yw[q][j].y), bf_hi(yw[q][j].y)};
;                     v[q][j] = v[q][j] + gt * (y4 * rsy * pn);
	s_mov_b32 s7, s8
	s_add_i32 s1, s8, 9
	s_mul_i32 s1, s1, 0x6000
	s_add_u32 s44, s84, s1
	s_addc_u32 s45, s85, 0
	s_add_u32 s44, s44, 0x2000
	s_addc_u32 s45, s45, 0
	s_add_i32 s1, s8, 9
	s_mul_i32 s1, s1, 0x6000
	s_add_u32 s36, s84, s1
	s_addc_u32 s37, s85, 0
	s_add_u32 s38, s80, 0x2000
	s_addc_u32 s39, s81, 0
	s_mul_i32 s1, s8, 0x6000
	s_add_u32 s34, s84, s1
	s_addc_u32 s35, s85, 0
	s_add_u32 s34, s34, 0x4000
	s_addc_u32 s35, s35, 0
	global_load_dwordx4 v[96:99], v192, s[34:35] offset:0
	global_load_dwordx4 v[200:203], v192, s[82:83] offset:0
	global_load_dwordx4 v[100:103], v192, s[34:35] offset:1024
	global_load_dwordx4 v[204:207], v192, s[82:83] offset:1024
	global_load_dwordx4 v[104:107], v192, s[34:35] offset:2048
	global_load_dwordx4 v[208:211], v192, s[82:83] offset:2048
	global_load_dwordx4 v[108:111], v192, s[34:35] offset:3072
	global_load_dwordx4 v[212:215], v192, s[82:83] offset:3072
	s_waitcnt vmcnt(0)
	v_mul_f32_e32 v96, v96, v200
	v_mul_f32_e32 v97, v97, v201
	v_mul_f32_e32 v98, v98, v202
	v_mul_f32_e32 v99, v99, v203
	v_mul_f32_e32 v100, v100, v204
	v_mul_f32_e32 v101, v101, v205
	v_mul_f32_e32 v102, v102, v206
	v_mul_f32_e32 v103, v103, v207
	v_mul_f32_e32 v104, v104, v208
	v_mul_f32_e32 v105, v105, v209
	v_mul_f32_e32 v106, v106, v210
	v_mul_f32_e32 v107, v107, v211
	v_mul_f32_e32 v108, v108, v212
	v_mul_f32_e32 v109, v109, v213
	v_mul_f32_e32 v110, v110, v214
	v_mul_f32_e32 v111, v111, v215
	global_load_dwordx4 v[128:131], v192, s[38:39] offset:0
	global_load_dwordx4 v[200:203], v192, s[44:45] offset:0
	global_load_dwordx4 v[160:163], v192, s[36:37] offset:0
	global_load_dwordx4 v[132:135], v192, s[38:39] offset:1024
	global_load_dwordx4 v[204:207], v192, s[44:45] offset:1024
	global_load_dwordx4 v[164:167], v192, s[36:37] offset:1024
	global_load_dwordx4 v[136:139], v192, s[38:39] offset:2048
	global_load_dwordx4 v[208:211], v192, s[44:45] offset:2048
	global_load_dwordx4 v[168:171], v192, s[36:37] offset:2048
	global_load_dwordx4 v[140:143], v192, s[38:39] offset:3072
	global_load_dwordx4 v[212:215], v192, s[44:45] offset:3072
	global_load_dwordx4 v[172:175], v192, s[36:37] offset:3072
	s_waitcnt vmcnt(0)
	v_add_f32_e32 v200, 1.0, v200
	v_add_f32_e32 v201, 1.0, v201
	v_add_f32_e32 v202, 1.0, v202
	v_add_f32_e32 v203, 1.0, v203
	v_mul_f32_e32 v128, v128, v200
	v_mul_f32_e32 v129, v129, v201
	v_mul_f32_e32 v130, v130, v202
	v_mul_f32_e32 v131, v131, v203
	v_add_f32_e32 v204, 1.0, v204
	v_add_f32_e32 v205, 1.0, v205
	v_add_f32_e32 v206, 1.0, v206
	v_add_f32_e32 v207, 1.0, v207
	v_mul_f32_e32 v132, v132, v204
	v_mul_f32_e32 v133, v133, v205
	v_mul_f32_e32 v134, v134, v206
	v_mul_f32_e32 v135, v135, v207
	v_add_f32_e32 v208, 1.0, v208
	v_add_f32_e32 v209, 1.0, v209
	v_add_f32_e32 v210, 1.0, v210
	v_add_f32_e32 v211, 1.0, v211
	v_mul_f32_e32 v136, v136, v208
	v_mul_f32_e32 v137, v137, v209
	v_mul_f32_e32 v138, v138, v210
	v_mul_f32_e32 v139, v139, v211
	v_add_f32_e32 v212, 1.0, v212
	v_add_f32_e32 v213, 1.0, v213
	v_add_f32_e32 v214, 1.0, v214
	v_add_f32_e32 v215, 1.0, v215
	v_mul_f32_e32 v140, v140, v212
	v_mul_f32_e32 v141, v141, v213
	v_mul_f32_e32 v142, v142, v214
	v_mul_f32_e32 v143, v143, v215
	global_load_dwordx4 v[112:115], v193, s[34:35] offset:0
	global_load_dwordx4 v[200:203], v193, s[82:83] offset:0
	global_load_dwordx4 v[116:119], v193, s[34:35] offset:1024
	global_load_dwordx4 v[204:207], v193, s[82:83] offset:1024
	global_load_dwordx4 v[120:123], v193, s[34:35] offset:2048
	global_load_dwordx4 v[208:211], v193, s[82:83] offset:2048
	global_load_dwordx4 v[124:127], v193, s[34:35] offset:3072
	global_load_dwordx4 v[212:215], v193, s[82:83] offset:3072
	s_waitcnt vmcnt(0)
	v_mul_f32_e32 v112, v112, v200
	v_mul_f32_e32 v113, v113, v201
	v_mul_f32_e32 v114, v114, v202
	v_mul_f32_e32 v115, v115, v203
	v_mul_f32_e32 v116, v116, v204
	v_mul_f32_e32 v117, v117, v205
	v_mul_f32_e32 v118, v118, v206
	v_mul_f32_e32 v119, v119, v207
	v_mul_f32_e32 v120, v120, v208
	v_mul_f32_e32 v121, v121, v209
	v_mul_f32_e32 v122, v122, v210
	v_mul_f32_e32 v123, v123, v211
	v_mul_f32_e32 v124, v124, v212
	v_mul_f32_e32 v125, v125, v213
	v_mul_f32_e32 v126, v126, v214
	v_mul_f32_e32 v127, v127, v215
	global_load_dwordx4 v[144:147], v193, s[38:39] offset:0
	global_load_dwordx4 v[200:203], v193, s[44:45] offset:0
	global_load_dwordx4 v[176:179], v193, s[36:37] offset:0
	global_load_dwordx4 v[148:151], v193, s[38:39] offset:1024
	global_load_dwordx4 v[204:207], v193, s[44:45] offset:1024
	global_load_dwordx4 v[180:183], v193, s[36:37] offset:1024
	global_load_dwordx4 v[152:155], v193, s[38:39] offset:2048
	global_load_dwordx4 v[208:211], v193, s[44:45] offset:2048
	global_load_dwordx4 v[184:187], v193, s[36:37] offset:2048
	global_load_dwordx4 v[156:159], v193, s[38:39] offset:3072
	global_load_dwordx4 v[212:215], v193, s[44:45] offset:3072
	global_load_dwordx4 v[188:191], v193, s[36:37] offset:3072
	s_waitcnt vmcnt(0)
	v_add_f32_e32 v200, 1.0, v200
	v_add_f32_e32 v201, 1.0, v201
	v_add_f32_e32 v202, 1.0, v202
	v_add_f32_e32 v203, 1.0, v203
	v_mul_f32_e32 v144, v144, v200
	v_mul_f32_e32 v145, v145, v201
	v_mul_f32_e32 v146, v146, v202
	v_mul_f32_e32 v147, v147, v203
	v_add_f32_e32 v204, 1.0, v204
	v_add_f32_e32 v205, 1.0, v205
	v_add_f32_e32 v206, 1.0, v206
	v_add_f32_e32 v207, 1.0, v207
	v_mul_f32_e32 v148, v148, v204
	v_mul_f32_e32 v149, v149, v205
	v_mul_f32_e32 v150, v150, v206
	v_mul_f32_e32 v151, v151, v207
	v_add_f32_e32 v208, 1.0, v208
	v_add_f32_e32 v209, 1.0, v209
	v_add_f32_e32 v210, 1.0, v210
	v_add_f32_e32 v211, 1.0, v211
	v_mul_f32_e32 v152, v152, v208
	v_mul_f32_e32 v153, v153, v209
	v_mul_f32_e32 v154, v154, v210
	v_mul_f32_e32 v155, v155, v211
	v_add_f32_e32 v212, 1.0, v212
	v_add_f32_e32 v213, 1.0, v213
	v_add_f32_e32 v214, 1.0, v214
	v_add_f32_e32 v215, 1.0, v215
	v_mul_f32_e32 v156, v156, v212
	v_mul_f32_e32 v157, v157, v213
	v_mul_f32_e32 v158, v158, v214
	v_mul_f32_e32 v159, v159, v215
; __device__ __forceinline__ float bf_lo(unsigned w) { return __uint_as_float(w << 16); }
; __device__ __forceinline__ float bf_hi(unsigned w) { return __uint_as_float(w & 0xffff0000u); }
; __global__ void __launch_bounds__(NWAVES * 64, 2) mk_fwd(Args args) {
;     ...
;             for (int q = 0; q < 3; ++q) { const int row = row0 + q; const bool lat = row < ML; const int r = lat ? row / SEQ : 8;
;                 float sy = 0.f;
; #pragma unroll
;                 for (int j = 0; j < 8; ++j) { const float a = bf_lo(yw[q][j].x), b = bf_hi(yw[q][j].x), c2 = bf_lo(yw[q][j].y), d = bf_hi(yw[q][j].y); sy += (a * a + b * b) + (c2 * c2 + d * d); }
;                 const float rsy = __builtin_amdgcn_rsqf(wave_sum(sy) * (1.f / DM) + EPS);
;                 const float* m0 = mod + (size_t)r * 6144;
; #pragma unroll
;                 for (int j = 0; j < 8; ++j) { const int col = 4 * F.lane + 256 * j; const f32x4 gt = *(const f32x4*)(m0 + 2 * DM + col), pn = *(const f32x4*)(post_norm + col);
;                     const f32x4 y4 = (f32x4){bf_lo(yw[q][j].x), bf_hi(yw[q][j].x), bf_lo(yw[q][j].y), bf_hi(yw[q][j].y)};
;                     v[q][j] = v[q][j] + gt * (y4 * rsy * pn);
;                     if (lat) *(f32x4*)(args.out + (size_t)row * DM + col) = v[q][j]; }
.Lp6_np8:
	s_waitcnt vmcnt(8)
	v_lshlrev_b32_e32 v216, 16, v32
	v_and_b32_e32 v217, 0xffff0000, v32
	v_lshlrev_b32_e32 v218, 16, v33
	v_and_b32_e32 v219, 0xffff0000, v33
	v_mul_f32_e32 v222, v216, v216
	v_mul_f32_e32 v223, v217, v217
	v_fmac_f32_e32 v222, v218, v218
	v_fmac_f32_e32 v223, v219, v219
	v_lshlrev_b32_e32 v216, 16, v34
	v_and_b32_e32 v217, 0xffff0000, v34
	v_lshlrev_b32_e32 v218, 16, v35
	v_and_b32_e32 v219, 0xffff0000, v35
	v_fmac_f32_e32 v222, v216, v216
	v_fmac_f32_e32 v223, v217, v217
	v_fmac_f32_e32 v222, v218, v218
	v_fmac_f32_e32 v223, v219, v219
	v_lshlrev_b32_e32 v216, 16, v36
	v_and_b32_e32 v217, 0xffff0000, v36
	v_lshlrev_b32_e32 v218, 16, v37
	v_and_b32_e32 v219, 0xffff0000, v37
	v_fmac_f32_e32 v222, v216, v216
	v_fmac_f32_e32 v223, v217, v217
	v_fmac_f32_e32 v222, v218, v218
	v_fmac_f32_e32 v223, v219, v219
	v_lshlrev_b32_e32 v216, 16, v38
	v_and_b32_e32 v217, 0xffff0000, v38
	v_lshlrev_b32_e32 v218, 16, v39
	v_and_b32_e32 v219, 0xffff0000, v39
	v_fmac_f32_e32 v222, v216, v216
	v_fmac_f32_e32 v223, v217, v217
	v_fmac_f32_e32 v222, v218, v218
	v_fmac_f32_e32 v223, v219, v219
	v_lshlrev_b32_e32 v216, 16, v40
	v_and_b32_e32 v217, 0xffff0000, v40
	v_lshlrev_b32_e32 v218, 16, v41
	v_and_b32_e32 v219, 0xffff0000, v41
	v_fmac_f32_e32 v222, v216, v216
	v_fmac_f32_e32 v223, v217, v217
	v_fmac_f32_e32 v222, v218, v218
	v_fmac_f32_e32 v223, v219, v219
	v_lshlrev_b32_e32 v216, 16, v42
	v_and_b32_e32 v217, 0xffff0000, v42
	v_lshlrev_b32_e32 v218, 16, v43
	v_and_b32_e32 v219, 0xffff0000, v43
	v_fmac_f32_e32 v222, v216, v216
	v_fmac_f32_e32 v223, v217, v217
	v_fmac_f32_e32 v222, v218, v218
	v_fmac_f32_e32 v223, v219, v219
	v_lshlrev_b32_e32 v216, 16, v44
	v_and_b32_e32 v217, 0xffff0000, v44
	v_lshlrev_b32_e32 v218, 16, v45
	v_and_b32_e32 v219, 0xffff0000, v45
	v_fmac_f32_e32 v222, v216, v216
	v_fmac_f32_e32 v223, v217, v217
	v_fmac_f32_e32 v222, v218, v218
	v_fmac_f32_e32 v223, v219, v219
	v_lshlrev_b32_e32 v216, 16, v46
	v_and_b32_e32 v217, 0xffff0000, v46
	v_lshlrev_b32_e32 v218, 16, v47
	v_and_b32_e32 v219, 0xffff0000, v47
	v_fmac_f32_e32 v222, v216, v216
	v_fmac_f32_e32 v223, v217, v217
	v_fmac_f32_e32 v222, v218, v218
	v_fmac_f32_e32 v223, v219, v219
	v_add_f32_e32 v222, v222, v223
	s_nop 1
	v_add_f32_dpp v224, v222, v222 quad_perm:[1,0,3,2] row_mask:0xf bank_mask:0xf
	s_nop 1
	v_add_f32_dpp v224, v224, v224 quad_perm:[2,3,0,1] row_mask:0xf bank_mask:0xf
	s_nop 1
	v_add_f32_dpp v224, v224, v224 row_half_mirror row_mask:0xf bank_mask:0xf
	s_nop 1
	v_add_f32_dpp v224, v224, v224 row_mirror row_mask:0xf bank_mask:0xf
	s_nop 1
	v_readlane_b32 s40, v224, 0
	v_readlane_b32 s41, v224, 16
	v_readlane_b32 s42, v224, 32
	v_readlane_b32 s43, v224, 48
	s_nop 1
	v_mov_b32_e32 v225, s40
	v_add_f32_e32 v225, s41, v225
	v_add_f32_e32 v225, s42, v225
	v_add_f32_e32 v225, s43, v225
	v_fmamk_f32 v225, v225, 0x3a000000, v195
	v_rsq_f32_e32 v225, v225
	s_nop 0
	v_lshlrev_b32_e32 v216, 16, v32
	v_and_b32_e32 v217, 0xffff0000, v32
	v_lshlrev_b32_e32 v218, 16, v33
	v_and_b32_e32 v219, 0xffff0000, v33
	v_mul_f32_e32 v216, v225, v216
	v_mul_f32_e32 v217, v225, v217
	v_mul_f32_e32 v218, v225, v218
	v_mul_f32_e32 v219, v225, v219
	v_fmac_f32_e32 v0, v96, v216
	v_fmac_f32_e32 v1, v97, v217
	v_fmac_f32_e32 v2, v98, v218
	v_fmac_f32_e32 v3, v99, v219
	v_lshlrev_b32_e32 v216, 16, v34
	v_and_b32_e32 v217, 0xffff0000, v34
	v_lshlrev_b32_e32 v218, 16, v35
	v_and_b32_e32 v219, 0xffff0000, v35
	v_mul_f32_e32 v216, v225, v216
	v_mul_f32_e32 v217, v225, v217
	v_mul_f32_e32 v218, v225, v218
	v_mul_f32_e32 v219, v225, v219
	v_fmac_f32_e32 v4, v100, v216
	v_fmac_f32_e32 v5, v101, v217
	v_fmac_f32_e32 v6, v102, v218
	v_fmac_f32_e32 v7, v103, v219
	v_lshlrev_b32_e32 v216, 16, v36
	v_and_b32_e32 v217, 0xffff0000, v36
	v_lshlrev_b32_e32 v218, 16, v37
	v_and_b32_e32 v219, 0xffff0000, v37
	v_mul_f32_e32 v216, v225, v216
	v_mul_f32_e32 v217, v225, v217
	v_mul_f32_e32 v218, v225, v218
	v_mul_f32_e32 v219, v225, v219
	v_fmac_f32_e32 v8, v104, v216
	v_fmac_f32_e32 v9, v105, v217
	v_fmac_f32_e32 v10, v106, v218
	v_fmac_f32_e32 v11, v107, v219
	v_lshlrev_b32_e32 v216, 16, v38
	v_and_b32_e32 v217, 0xffff0000, v38
	v_lshlrev_b32_e32 v218, 16, v39
	v_and_b32_e32 v219, 0xffff0000, v39
	v_mul_f32_e32 v216, v225, v216
	v_mul_f32_e32 v217, v225, v217
	v_mul_f32_e32 v218, v225, v218
	v_mul_f32_e32 v219, v225, v219
	v_fmac_f32_e32 v12, v108, v216
	v_fmac_f32_e32 v13, v109, v217
	v_fmac_f32_e32 v14, v110, v218
	v_fmac_f32_e32 v15, v111, v219
	v_lshlrev_b32_e32 v216, 16, v40
	v_and_b32_e32 v217, 0xffff0000, v40
	v_lshlrev_b32_e32 v218, 16, v41
	v_and_b32_e32 v219, 0xffff0000, v41
	v_mul_f32_e32 v216, v225, v216
	v_mul_f32_e32 v217, v225, v217
	v_mul_f32_e32 v218, v225, v218
	v_mul_f32_e32 v219, v225, v219
	v_fmac_f32_e32 v16, v112, v216
	v_fmac_f32_e32 v17, v113, v217
	v_fmac_f32_e32 v18, v114, v218
	v_fmac_f32_e32 v19, v115, v219
	v_lshlrev_b32_e32 v216, 16, v42
	v_and_b32_e32 v217, 0xffff0000, v42
	v_lshlrev_b32_e32 v218, 16, v43
	v_and_b32_e32 v219, 0xffff0000, v43
	v_mul_f32_e32 v216, v225, v216
	v_mul_f32_e32 v217, v225, v217
	v_mul_f32_e32 v218, v225, v218
	v_mul_f32_e32 v219, v225, v219
	v_fmac_f32_e32 v20, v116, v216
	v_fmac_f32_e32 v21, v117, v217
	v_fmac_f32_e32 v22, v118, v218
	v_fmac_f32_e32 v23, v119, v219
	v_lshlrev_b32_e32 v216, 16, v44
	v_and_b32_e32 v217, 0xffff0000, v44
	v_lshlrev_b32_e32 v218, 16, v45
	v_and_b32_e32 v219, 0xffff0000, v45
	v_mul_f32_e32 v216, v225, v216
	v_mul_f32_e32 v217, v225, v217
	v_mul_f32_e32 v218, v225, v218
	v_mul_f32_e32 v219, v225, v219
; __device__ __forceinline__ unsigned cvt_pk_bf16(float lo, float hi) { unsigned r; asm volatile("v_cvt_pk_bf16_f32 %0, %1, %2" : "=v"(r) : "v"(lo), "v"(hi)); return r; }
; __device__ __forceinline__ float bf_lo(unsigned w) { return __uint_as_float(w << 16); }
; __device__ __forceinline__ float bf_hi(unsigned w) { return __uint_as_float(w & 0xffff0000u); }
; __device__ __forceinline__ float sumsq8(const f32x4 (&v)[8]) {
;     float s = 0.f;
; #pragma unroll
;     for (int j = 0; j < 8; ++j) s += (v[j][0] * v[j][0] + v[j][1] * v[j][1]) + (v[j][2] * v[j][2] + v[j][3] * v[j][3]);
;     return wave_sum(s);
; }
; __device__ __forceinline__ void modulate_store(const f32x4 (&v)[8], float rstd, const float* pn, const float* modr, bf16_t* orow, int lane) {
; #pragma unroll
;     for (int j = 0; j < 8; ++j) { const int col = 4 * lane + 256 * j;
;         const f32x4 g = *(const f32x4*)(pn + col), sh = *(const f32x4*)(modr + col), sc = *(const f32x4*)(modr + DM + col);
;         const f32x4 hh = v[j] * rstd * g * (sc + 1.f) + sh;
;         u32x2 w; w.x = cvt_pk_bf16(hh[0], hh[1]); w.y = cvt_pk_bf16(hh[2], hh[3]);
;         *(u32x2*)(orow + col) = w; }
; }
; __global__ void __launch_bounds__(NWAVES * 64, 2) mk_fwd(Args args) {
;     ...
;                 for (int j = 0; j < 8; ++j) { const int col = 4 * F.lane + 256 * j; const f32x4 gt = *(const f32x4*)(m0 + 2 * DM + col), pn = *(const f32x4*)(post_norm + col);
;                     const f32x4 y4 = (f32x4){bf_lo(yw[q][j].x), bf_hi(yw[q][j].x), bf_lo(yw[q][j].y), bf_hi(yw[q][j].y)};
;                     v[q][j] = v[q][j] + gt * (y4 * rsy * pn);
;                     if (lat) *(f32x4*)(args.out + (size_t)row * DM + col) = v[q][j]; }
;                 const float rstd = __builtin_amdgcn_rsqf(sumsq8(v[q]) * (1.f / DM) + EPS);
;                 modulate_store(v[q], rstd, pre_norm + DM, mod + (size_t)(9 + r) * 6144, H + (size_t)row * DM, F.lane); }
	v_fmac_f32_e32 v24, v120, v216
	v_fmac_f32_e32 v25, v121, v217
	v_fmac_f32_e32 v26, v122, v218
	v_fmac_f32_e32 v27, v123, v219
	v_lshlrev_b32_e32 v216, 16, v46
	v_and_b32_e32 v217, 0xffff0000, v46
	v_lshlrev_b32_e32 v218, 16, v47
	v_and_b32_e32 v219, 0xffff0000, v47
	v_mul_f32_e32 v216, v225, v216
	v_mul_f32_e32 v217, v225, v217
	v_mul_f32_e32 v218, v225, v218
	v_mul_f32_e32 v219, v225, v219
	v_fmac_f32_e32 v28, v124, v216
	v_fmac_f32_e32 v29, v125, v217
	v_fmac_f32_e32 v30, v126, v218
	v_fmac_f32_e32 v31, v127, v219
	v_mul_f32_e32 v222, v0, v0
	v_mul_f32_e32 v223, v1, v1
	v_fmac_f32_e32 v222, v2, v2
	v_fmac_f32_e32 v223, v3, v3
	v_fmac_f32_e32 v222, v4, v4
	v_fmac_f32_e32 v223, v5, v5
	v_fmac_f32_e32 v222, v6, v6
	v_fmac_f32_e32 v223, v7, v7
	v_fmac_f32_e32 v222, v8, v8
	v_fmac_f32_e32 v223, v9, v9
	v_fmac_f32_e32 v222, v10, v10
	v_fmac_f32_e32 v223, v11, v11
	v_fmac_f32_e32 v222, v12, v12
	v_fmac_f32_e32 v223, v13, v13
	v_fmac_f32_e32 v222, v14, v14
	v_fmac_f32_e32 v223, v15, v15
	v_fmac_f32_e32 v222, v16, v16
	v_fmac_f32_e32 v223, v17, v17
	v_fmac_f32_e32 v222, v18, v18
	v_fmac_f32_e32 v223, v19, v19
	v_fmac_f32_e32 v222, v20, v20
	v_fmac_f32_e32 v223, v21, v21
	v_fmac_f32_e32 v222, v22, v22
	v_fmac_f32_e32 v223, v23, v23
	v_fmac_f32_e32 v222, v24, v24
	v_fmac_f32_e32 v223, v25, v25
	v_fmac_f32_e32 v222, v26, v26
	v_fmac_f32_e32 v223, v27, v27
	v_fmac_f32_e32 v222, v28, v28
	v_fmac_f32_e32 v223, v29, v29
	v_fmac_f32_e32 v222, v30, v30
	v_fmac_f32_e32 v223, v31, v31
	v_add_f32_e32 v222, v222, v223
	s_nop 1
	v_add_f32_dpp v224, v222, v222 quad_perm:[1,0,3,2] row_mask:0xf bank_mask:0xf
	s_nop 1
	v_add_f32_dpp v224, v224, v224 quad_perm:[2,3,0,1] row_mask:0xf bank_mask:0xf
	s_nop 1
	v_add_f32_dpp v224, v224, v224 row_half_mirror row_mask:0xf bank_mask:0xf
	s_nop 1
	v_add_f32_dpp v224, v224, v224 row_mirror row_mask:0xf bank_mask:0xf
	s_nop 1
	v_readlane_b32 s40, v224, 0
	v_readlane_b32 s41, v224, 16
	v_readlane_b32 s42, v224, 32
	v_readlane_b32 s43, v224, 48
	s_nop 1
	v_mov_b32_e32 v225, s40
	v_add_f32_e32 v225, s41, v225
	v_add_f32_e32 v225, s42, v225
	v_add_f32_e32 v225, s43, v225
	v_fmamk_f32 v225, v225, 0x3a000000, v195
	v_rsq_f32_e32 v225, v225
	s_nop 0
	s_add_i32 s0, s6, 8
	s_lshl_b32 s1, s0, 12
	s_add_u32 s26, s84, s1
	s_addc_u32 s27, s85, 0
	s_add_u32 s26, s26, 0x4000000
	s_addc_u32 s27, s27, 0
	v_mul_f32_e32 v216, v225, v0
	v_mul_f32_e32 v217, v225, v1
	v_mul_f32_e32 v218, v225, v2
	v_mul_f32_e32 v219, v225, v3
	v_fma_f32 v216, v216, v128, v160
	v_fma_f32 v217, v217, v129, v161
	v_fma_f32 v218, v218, v130, v162
	v_fma_f32 v219, v219, v131, v163
	v_cvt_pk_bf16_f32 v196, v216, v217
	v_cvt_pk_bf16_f32 v197, v218, v219
	global_store_dwordx2 v194, v[196:197], s[26:27] offset:0 nt
	v_mul_f32_e32 v216, v225, v4
	v_mul_f32_e32 v217, v225, v5
	v_mul_f32_e32 v218, v225, v6
	v_mul_f32_e32 v219, v225, v7
	v_fma_f32 v216, v216, v132, v164
	v_fma_f32 v217, v217, v133, v165
	v_fma_f32 v218, v218, v134, v166
	v_fma_f32 v219, v219, v135, v167
	v_cvt_pk_bf16_f32 v220, v216, v217
	v_cvt_pk_bf16_f32 v221, v218, v219
	global_store_dwordx2 v194, v[220:221], s[26:27] offset:512 nt
	v_mul_f32_e32 v216, v225, v8
	v_mul_f32_e32 v217, v225, v9
	v_mul_f32_e32 v218, v225, v10
	v_mul_f32_e32 v219, v225, v11
	v_fma_f32 v216, v216, v136, v168
	v_fma_f32 v217, v217, v137, v169
	v_fma_f32 v218, v218, v138, v170
	v_fma_f32 v219, v219, v139, v171
	v_cvt_pk_bf16_f32 v196, v216, v217
	v_cvt_pk_bf16_f32 v197, v218, v219
	global_store_dwordx2 v194, v[196:197], s[26:27] offset:1024 nt
	v_mul_f32_e32 v216, v225, v12
	v_mul_f32_e32 v217, v225, v13
	v_mul_f32_e32 v218, v225, v14
	v_mul_f32_e32 v219, v225, v15
	v_fma_f32 v216, v216, v140, v172
	v_fma_f32 v217, v217, v141, v173
	v_fma_f32 v218, v218, v142, v174
	v_fma_f32 v219, v219, v143, v175
	v_cvt_pk_bf16_f32 v220, v216, v217
	v_cvt_pk_bf16_f32 v221, v218, v219
	global_store_dwordx2 v194, v[220:221], s[26:27] offset:1536 nt
	v_mul_f32_e32 v216, v225, v16
	v_mul_f32_e32 v217, v225, v17
	v_mul_f32_e32 v218, v225, v18
	v_mul_f32_e32 v219, v225, v19
	v_fma_f32 v216, v216, v144, v176
	v_fma_f32 v217, v217, v145, v177
	v_fma_f32 v218, v218, v146, v178
	v_fma_f32 v219, v219, v147, v179
	v_cvt_pk_bf16_f32 v196, v216, v217
	v_cvt_pk_bf16_f32 v197, v218, v219
	global_store_dwordx2 v194, v[196:197], s[26:27] offset:2048 nt
	v_mul_f32_e32 v216, v225, v20
	v_mul_f32_e32 v217, v225, v21
	v_mul_f32_e32 v218, v225, v22
	v_mul_f32_e32 v219, v225, v23
	v_fma_f32 v216, v216, v148, v180
	v_fma_f32 v217, v217, v149, v181
	v_fma_f32 v218, v218, v150, v182
	v_fma_f32 v219, v219, v151, v183
	v_cvt_pk_bf16_f32 v220, v216, v217
	v_cvt_pk_bf16_f32 v221, v218, v219
	global_store_dwordx2 v194, v[220:221], s[26:27] offset:2560 nt
	v_mul_f32_e32 v216, v225, v24
	v_mul_f32_e32 v217, v225, v25
	v_mul_f32_e32 v218, v225, v26
	v_mul_f32_e32 v219, v225, v27
	v_fma_f32 v216, v216, v152, v184
	v_fma_f32 v217, v217, v153, v185
	v_fma_f32 v218, v218, v154, v186
	v_fma_f32 v219, v219, v155, v187
	v_cvt_pk_bf16_f32 v196, v216, v217
	v_cvt_pk_bf16_f32 v197, v218, v219
	global_store_dwordx2 v194, v[196:197], s[26:27] offset:3072 nt
	v_mul_f32_e32 v216, v225, v28
	v_mul_f32_e32 v217, v225, v29
	v_mul_f32_e32 v218, v225, v30
	v_mul_f32_e32 v219, v225, v31
	v_fma_f32 v216, v216, v156, v188
	v_fma_f32 v217, v217, v157, v189
	v_fma_f32 v218, v218, v158, v190
	v_fma_f32 v219, v219, v159, v191
	v_cvt_pk_bf16_f32 v220, v216, v217
	v_cvt_pk_bf16_f32 v221, v218, v219
	global_store_dwordx2 v194, v[220:221], s[26:27] offset:3584 nt
	s_branch .LBB0_778
